# rows phases k4,k7,k11,k14 hand-rewritten (batched loads, double-buffered row pairs); FFN-up sample rows as split-K prepass (k5,k12); sgemm rewrite kept
# speedup vs baseline: 1.0591x; 1.0291x over previous
_Z10fwd_kernelILi4ELi5EEv4Args:
	s_load_dword s3, s[0:1], 0xe8
	s_load_dwordx4 s[4:7], s[0:1], 0xd0
	s_load_dwordx2 s[8:9], s[0:1], 0xa8
	s_load_dwordx2 s[10:11], s[0:1], 0xb0
	s_load_dwordx4 s[12:15], s[0:1], 0x0
	s_waitcnt lgkmcnt(0)
	s_cmp_lg_u32 s3, 0x100
	s_cbranch_scc1 .Lrows4_orig
	v_readfirstlane_b32 s16, v0
	s_lshr_b32 s16, s16, 6
	s_lshl_b32 s18, s2, 3
	s_add_u32 s16, s16, s18
	s_mov_b32 s17, 0x3a800000
	v_mov_b32_e32 v3, 0x358637bd
	v_and_b32_e32 v10, 63, v0
	v_lshlrev_b32_e32 v1, 4, v10
	v_lshlrev_b32_e32 v2, 3, v10
	v_xor_b32_e32 v4, 1, v10
	v_xor_b32_e32 v5, 2, v10
	v_xor_b32_e32 v6, 4, v10
	v_xor_b32_e32 v7, 8, v10
	v_xor_b32_e32 v8, 16, v10
	v_xor_b32_e32 v9, 32, v10
	v_lshlrev_b32_e32 v4, 2, v4
	v_lshlrev_b32_e32 v5, 2, v5
	v_lshlrev_b32_e32 v6, 2, v6
	v_lshlrev_b32_e32 v7, 2, v7
	v_lshlrev_b32_e32 v8, 2, v8
	v_lshlrev_b32_e32 v9, 2, v9
	global_load_dwordx4 v[20:23], v1, s[8:9] offset:0
	global_load_dwordx4 v[24:27], v1, s[8:9] offset:1024
	global_load_dwordx4 v[28:31], v1, s[8:9] offset:2048
	global_load_dwordx4 v[32:35], v1, s[8:9] offset:3072
	global_load_dwordx4 v[36:39], v1, s[10:11] offset:0
	global_load_dwordx4 v[40:43], v1, s[10:11] offset:1024
	global_load_dwordx4 v[44:47], v1, s[10:11] offset:2048
	global_load_dwordx4 v[48:51], v1, s[10:11] offset:3072
	s_add_u32 s53, s16, 0x0
	s_lshl_b32 s18, s53, 12
	s_lshl_b32 s19, s53, 11
	s_add_u32 s20, s12, s18
	s_addc_u32 s21, s13, 0
	s_add_u32 s22, s6, s19
	s_addc_u32 s23, s7, 0
	s_add_u32 s22, s22, 0x5200000
	s_addc_u32 s23, s23, 0
	s_add_u32 s24, s4, s18
	s_addc_u32 s25, s5, 0
	s_add_u32 s26, s6, s19
	s_addc_u32 s27, s7, 0
	s_add_u32 s26, s26, 0x3100000
	s_addc_u32 s27, s27, 0
	global_load_dwordx2 v[66:67], v2, s[22:23] offset:0
	global_load_dwordx2 v[70:71], v2, s[22:23] offset:512
	global_load_dwordx2 v[74:75], v2, s[22:23] offset:1024
	global_load_dwordx2 v[78:79], v2, s[22:23] offset:1536
	global_load_dwordx4 v[80:83], v1, s[20:21] offset:0
	global_load_dwordx4 v[84:87], v1, s[20:21] offset:1024
	global_load_dwordx4 v[88:91], v1, s[20:21] offset:2048
	global_load_dwordx4 v[92:95], v1, s[20:21] offset:3072
	s_add_u32 s53, s16, 0x800
	s_lshl_b32 s18, s53, 12
	s_lshl_b32 s19, s53, 11
	s_add_u32 s28, s12, s18
	s_addc_u32 s29, s13, 0
	s_add_u32 s30, s6, s19
	s_addc_u32 s31, s7, 0
	s_add_u32 s30, s30, 0x5200000
	s_addc_u32 s31, s31, 0
	s_add_u32 s32, s4, s18
	s_addc_u32 s33, s5, 0
	s_add_u32 s34, s6, s19
	s_addc_u32 s35, s7, 0
	s_add_u32 s34, s34, 0x3100000
	s_addc_u32 s35, s35, 0
	global_load_dwordx2 v[98:99], v2, s[30:31] offset:0
	global_load_dwordx2 v[102:103], v2, s[30:31] offset:512
	global_load_dwordx2 v[106:107], v2, s[30:31] offset:1024
	global_load_dwordx2 v[110:111], v2, s[30:31] offset:1536
	global_load_dwordx4 v[112:115], v1, s[28:29] offset:0
	global_load_dwordx4 v[116:119], v1, s[28:29] offset:1024
	global_load_dwordx4 v[120:123], v1, s[28:29] offset:2048
	global_load_dwordx4 v[124:127], v1, s[28:29] offset:3072
	s_add_u32 s53, s16, 0x1000
	s_lshl_b32 s18, s53, 12
	s_lshl_b32 s19, s53, 11
	s_add_u32 s36, s12, s18
	s_addc_u32 s37, s13, 0
	s_add_u32 s38, s6, s19
	s_addc_u32 s39, s7, 0
	s_add_u32 s38, s38, 0x5200000
	s_addc_u32 s39, s39, 0
	s_add_u32 s40, s4, s18
	s_addc_u32 s41, s5, 0
	s_add_u32 s42, s6, s19
	s_addc_u32 s43, s7, 0
	s_add_u32 s42, s42, 0x3100000
	s_addc_u32 s43, s43, 0
	global_load_dwordx2 v[130:131], v2, s[38:39] offset:0
	global_load_dwordx2 v[134:135], v2, s[38:39] offset:512
	global_load_dwordx2 v[138:139], v2, s[38:39] offset:1024
	global_load_dwordx2 v[142:143], v2, s[38:39] offset:1536
	global_load_dwordx4 v[144:147], v1, s[36:37] offset:0
	global_load_dwordx4 v[148:151], v1, s[36:37] offset:1024
	global_load_dwordx4 v[152:155], v1, s[36:37] offset:2048
	global_load_dwordx4 v[156:159], v1, s[36:37] offset:3072
	s_add_u32 s53, s16, 0x1800
	s_lshl_b32 s18, s53, 12
	s_lshl_b32 s19, s53, 11
	s_add_u32 s44, s12, s18
	s_addc_u32 s45, s13, 0
	s_add_u32 s46, s6, s19
	s_addc_u32 s47, s7, 0
	s_add_u32 s46, s46, 0x5200000
	s_addc_u32 s47, s47, 0
	s_add_u32 s48, s4, s18
	s_addc_u32 s49, s5, 0
	s_add_u32 s50, s6, s19
	s_addc_u32 s51, s7, 0
	s_add_u32 s50, s50, 0x3100000
	s_addc_u32 s51, s51, 0
	global_load_dwordx2 v[162:163], v2, s[46:47] offset:0
	global_load_dwordx2 v[166:167], v2, s[46:47] offset:512
	global_load_dwordx2 v[170:171], v2, s[46:47] offset:1024
	global_load_dwordx2 v[174:175], v2, s[46:47] offset:1536
	global_load_dwordx4 v[176:179], v1, s[44:45] offset:0
	global_load_dwordx4 v[180:183], v1, s[44:45] offset:1024
	global_load_dwordx4 v[184:187], v1, s[44:45] offset:2048
	global_load_dwordx4 v[188:191], v1, s[44:45] offset:3072
	s_waitcnt vmcnt(16)
	v_lshlrev_b32_e32 v64, 16, v66
	v_and_b32_e32 v65, 0xffff0000, v66
	v_lshlrev_b32_e32 v66, 16, v67
	v_and_b32_e32 v67, 0xffff0000, v67
	v_lshlrev_b32_e32 v68, 16, v70
	v_and_b32_e32 v69, 0xffff0000, v70
	v_lshlrev_b32_e32 v70, 16, v71
	v_and_b32_e32 v71, 0xffff0000, v71
	v_lshlrev_b32_e32 v72, 16, v74
	v_and_b32_e32 v73, 0xffff0000, v74
	v_lshlrev_b32_e32 v74, 16, v75
	v_and_b32_e32 v75, 0xffff0000, v75
	v_lshlrev_b32_e32 v76, 16, v78
	v_and_b32_e32 v77, 0xffff0000, v78
	v_lshlrev_b32_e32 v78, 16, v79
	v_and_b32_e32 v79, 0xffff0000, v79
	v_lshlrev_b32_e32 v96, 16, v98
	v_and_b32_e32 v97, 0xffff0000, v98
	v_lshlrev_b32_e32 v98, 16, v99
	v_and_b32_e32 v99, 0xffff0000, v99
	v_lshlrev_b32_e32 v100, 16, v102
	v_and_b32_e32 v101, 0xffff0000, v102
	v_lshlrev_b32_e32 v102, 16, v103
	v_and_b32_e32 v103, 0xffff0000, v103
	v_lshlrev_b32_e32 v104, 16, v106
	v_and_b32_e32 v105, 0xffff0000, v106
	v_lshlrev_b32_e32 v106, 16, v107
	v_and_b32_e32 v107, 0xffff0000, v107
	v_lshlrev_b32_e32 v108, 16, v110
	v_and_b32_e32 v109, 0xffff0000, v110
	v_lshlrev_b32_e32 v110, 16, v111
	v_and_b32_e32 v111, 0xffff0000, v111
	v_mul_f32_e32 v10, v64, v64
	v_fmac_f32_e32 v10, v65, v65
	v_fmac_f32_e32 v10, v66, v66
	v_fmac_f32_e32 v10, v67, v67
	v_fmac_f32_e32 v10, v68, v68
	v_fmac_f32_e32 v10, v69, v69
	v_fmac_f32_e32 v10, v70, v70
	v_fmac_f32_e32 v10, v71, v71
	v_fmac_f32_e32 v10, v72, v72
	v_fmac_f32_e32 v10, v73, v73
	v_fmac_f32_e32 v10, v74, v74
	v_fmac_f32_e32 v10, v75, v75
	v_fmac_f32_e32 v10, v76, v76
	v_fmac_f32_e32 v10, v77, v77
	v_fmac_f32_e32 v10, v78, v78
	v_fmac_f32_e32 v10, v79, v79
	v_mul_f32_e32 v11, v96, v96
	v_fmac_f32_e32 v11, v97, v97
	v_fmac_f32_e32 v11, v98, v98
	v_fmac_f32_e32 v11, v99, v99
	v_fmac_f32_e32 v11, v100, v100
	v_fmac_f32_e32 v11, v101, v101
	v_fmac_f32_e32 v11, v102, v102
	v_fmac_f32_e32 v11, v103, v103
	v_fmac_f32_e32 v11, v104, v104
	v_fmac_f32_e32 v11, v105, v105
	v_fmac_f32_e32 v11, v106, v106
	v_fmac_f32_e32 v11, v107, v107
	v_fmac_f32_e32 v11, v108, v108
	v_fmac_f32_e32 v11, v109, v109
	v_fmac_f32_e32 v11, v110, v110
	v_fmac_f32_e32 v11, v111, v111
	ds_bpermute_b32 v12, v4, v10
	ds_bpermute_b32 v13, v4, v11
	s_waitcnt lgkmcnt(0)
	v_add_f32_e32 v10, v10, v12
	v_add_f32_e32 v11, v11, v13
	ds_bpermute_b32 v12, v5, v10
	ds_bpermute_b32 v13, v5, v11
	s_waitcnt lgkmcnt(0)
	v_add_f32_e32 v10, v10, v12
	v_add_f32_e32 v11, v11, v13
	ds_bpermute_b32 v12, v6, v10
	ds_bpermute_b32 v13, v6, v11
	s_waitcnt lgkmcnt(0)
	v_add_f32_e32 v10, v10, v12
	v_add_f32_e32 v11, v11, v13
	ds_bpermute_b32 v12, v7, v10
	ds_bpermute_b32 v13, v7, v11
	s_waitcnt lgkmcnt(0)
	v_add_f32_e32 v10, v10, v12
	v_add_f32_e32 v11, v11, v13
	ds_bpermute_b32 v12, v8, v10
	ds_bpermute_b32 v13, v8, v11
	s_waitcnt lgkmcnt(0)
	v_add_f32_e32 v10, v10, v12
	v_add_f32_e32 v11, v11, v13
	ds_bpermute_b32 v12, v9, v10
	ds_bpermute_b32 v13, v9, v11
	s_waitcnt lgkmcnt(0)
	v_add_f32_e32 v10, v10, v12
	v_add_f32_e32 v11, v11, v13
	v_fma_f32 v14, v10, s17, v3
	v_fma_f32 v15, v11, s17, v3
	v_rsq_f32_e32 v14, v14
	v_rsq_f32_e32 v15, v15
	s_nop 0
	v_mul_f32_e32 v64, v64, v14
	v_mul_f32_e32 v65, v65, v14
	v_mul_f32_e32 v66, v66, v14
	v_mul_f32_e32 v67, v67, v14
	v_mul_f32_e32 v68, v68, v14
	v_mul_f32_e32 v69, v69, v14
	v_mul_f32_e32 v70, v70, v14
	v_mul_f32_e32 v71, v71, v14
	v_mul_f32_e32 v72, v72, v14
	v_mul_f32_e32 v73, v73, v14
	v_mul_f32_e32 v74, v74, v14
	v_mul_f32_e32 v75, v75, v14
	v_mul_f32_e32 v76, v76, v14
	v_mul_f32_e32 v77, v77, v14
	v_mul_f32_e32 v78, v78, v14
	v_mul_f32_e32 v79, v79, v14
	v_fmac_f32_e32 v80, v64, v20
	v_fmac_f32_e32 v81, v65, v21
	v_fmac_f32_e32 v82, v66, v22
	v_fmac_f32_e32 v83, v67, v23
	v_fmac_f32_e32 v84, v68, v24
	v_fmac_f32_e32 v85, v69, v25
	v_fmac_f32_e32 v86, v70, v26
	v_fmac_f32_e32 v87, v71, v27
	v_fmac_f32_e32 v88, v72, v28
	v_fmac_f32_e32 v89, v73, v29
	v_fmac_f32_e32 v90, v74, v30
	v_fmac_f32_e32 v91, v75, v31
	v_fmac_f32_e32 v92, v76, v32
	v_fmac_f32_e32 v93, v77, v33
	v_fmac_f32_e32 v94, v78, v34
	v_fmac_f32_e32 v95, v79, v35
	global_store_dwordx4 v1, v[80:83], s[24:25] offset:0
	global_store_dwordx4 v1, v[84:87], s[24:25] offset:1024
	global_store_dwordx4 v1, v[88:91], s[24:25] offset:2048
	global_store_dwordx4 v1, v[92:95], s[24:25] offset:3072
	v_mul_f32_e32 v96, v96, v15
	v_mul_f32_e32 v97, v97, v15
	v_mul_f32_e32 v98, v98, v15
	v_mul_f32_e32 v99, v99, v15
	v_mul_f32_e32 v100, v100, v15
	v_mul_f32_e32 v101, v101, v15
	v_mul_f32_e32 v102, v102, v15
	v_mul_f32_e32 v103, v103, v15
	v_mul_f32_e32 v104, v104, v15
	v_mul_f32_e32 v105, v105, v15
	v_mul_f32_e32 v106, v106, v15
	v_mul_f32_e32 v107, v107, v15
	v_mul_f32_e32 v108, v108, v15
	v_mul_f32_e32 v109, v109, v15
	v_mul_f32_e32 v110, v110, v15
	v_mul_f32_e32 v111, v111, v15
	v_fmac_f32_e32 v112, v96, v20
	v_fmac_f32_e32 v113, v97, v21
	v_fmac_f32_e32 v114, v98, v22
	v_fmac_f32_e32 v115, v99, v23
	v_fmac_f32_e32 v116, v100, v24
	v_fmac_f32_e32 v117, v101, v25
	v_fmac_f32_e32 v118, v102, v26
	v_fmac_f32_e32 v119, v103, v27
	v_fmac_f32_e32 v120, v104, v28
	v_fmac_f32_e32 v121, v105, v29
	v_fmac_f32_e32 v122, v106, v30
	v_fmac_f32_e32 v123, v107, v31
	v_fmac_f32_e32 v124, v108, v32
	v_fmac_f32_e32 v125, v109, v33
	v_fmac_f32_e32 v126, v110, v34
	v_fmac_f32_e32 v127, v111, v35
	global_store_dwordx4 v1, v[112:115], s[32:33] offset:0
	global_store_dwordx4 v1, v[116:119], s[32:33] offset:1024
	global_store_dwordx4 v1, v[120:123], s[32:33] offset:2048
	global_store_dwordx4 v1, v[124:127], s[32:33] offset:3072
	v_mul_f32_e32 v10, v80, v80
	v_fmac_f32_e32 v10, v81, v81
	v_fmac_f32_e32 v10, v82, v82
	v_fmac_f32_e32 v10, v83, v83
	v_fmac_f32_e32 v10, v84, v84
	v_fmac_f32_e32 v10, v85, v85
	v_fmac_f32_e32 v10, v86, v86
	v_fmac_f32_e32 v10, v87, v87
	v_fmac_f32_e32 v10, v88, v88
	v_fmac_f32_e32 v10, v89, v89
	v_fmac_f32_e32 v10, v90, v90
	v_fmac_f32_e32 v10, v91, v91
	v_fmac_f32_e32 v10, v92, v92
	v_fmac_f32_e32 v10, v93, v93
	v_fmac_f32_e32 v10, v94, v94
	v_fmac_f32_e32 v10, v95, v95
	v_mul_f32_e32 v11, v112, v112
	v_fmac_f32_e32 v11, v113, v113
	v_fmac_f32_e32 v11, v114, v114
	v_fmac_f32_e32 v11, v115, v115
	v_fmac_f32_e32 v11, v116, v116
	v_fmac_f32_e32 v11, v117, v117
	v_fmac_f32_e32 v11, v118, v118
	v_fmac_f32_e32 v11, v119, v119
	v_fmac_f32_e32 v11, v120, v120
	v_fmac_f32_e32 v11, v121, v121
	v_fmac_f32_e32 v11, v122, v122
	v_fmac_f32_e32 v11, v123, v123
	v_fmac_f32_e32 v11, v124, v124
	v_fmac_f32_e32 v11, v125, v125
	v_fmac_f32_e32 v11, v126, v126
	v_fmac_f32_e32 v11, v127, v127
	ds_bpermute_b32 v12, v4, v10
	ds_bpermute_b32 v13, v4, v11
	s_waitcnt lgkmcnt(0)
	v_add_f32_e32 v10, v10, v12
	v_add_f32_e32 v11, v11, v13
	ds_bpermute_b32 v12, v5, v10
	ds_bpermute_b32 v13, v5, v11
	s_waitcnt lgkmcnt(0)
	v_add_f32_e32 v10, v10, v12
	v_add_f32_e32 v11, v11, v13
	ds_bpermute_b32 v12, v6, v10
	ds_bpermute_b32 v13, v6, v11
	s_waitcnt lgkmcnt(0)
	v_add_f32_e32 v10, v10, v12
	v_add_f32_e32 v11, v11, v13
	ds_bpermute_b32 v12, v7, v10
	ds_bpermute_b32 v13, v7, v11
	s_waitcnt lgkmcnt(0)
	v_add_f32_e32 v10, v10, v12
	v_add_f32_e32 v11, v11, v13
	ds_bpermute_b32 v12, v8, v10
	ds_bpermute_b32 v13, v8, v11
	s_waitcnt lgkmcnt(0)
	v_add_f32_e32 v10, v10, v12
	v_add_f32_e32 v11, v11, v13
	ds_bpermute_b32 v12, v9, v10
	ds_bpermute_b32 v13, v9, v11
	s_waitcnt lgkmcnt(0)
	v_add_f32_e32 v10, v10, v12
	v_add_f32_e32 v11, v11, v13
	v_fma_f32 v14, v10, s17, v3
	v_fma_f32 v15, v11, s17, v3
	v_rsq_f32_e32 v14, v14
	v_rsq_f32_e32 v15, v15
	s_nop 0
	v_mul_f32_e32 v64, v80, v14
	v_mul_f32_e32 v65, v81, v14
	v_mul_f32_e32 v66, v82, v14
	v_mul_f32_e32 v67, v83, v14
	v_mul_f32_e32 v68, v84, v14
	v_mul_f32_e32 v69, v85, v14
	v_mul_f32_e32 v70, v86, v14
	v_mul_f32_e32 v71, v87, v14
	v_mul_f32_e32 v72, v88, v14
	v_mul_f32_e32 v73, v89, v14
	v_mul_f32_e32 v74, v90, v14
	v_mul_f32_e32 v75, v91, v14
	v_mul_f32_e32 v76, v92, v14
	v_mul_f32_e32 v77, v93, v14
	v_mul_f32_e32 v78, v94, v14
	v_mul_f32_e32 v79, v95, v14
	v_mul_f32_e32 v64, v64, v36
	v_mul_f32_e32 v65, v65, v37
	v_mul_f32_e32 v66, v66, v38
	v_mul_f32_e32 v67, v67, v39
	v_mul_f32_e32 v68, v68, v40
	v_mul_f32_e32 v69, v69, v41
	v_mul_f32_e32 v70, v70, v42
	v_mul_f32_e32 v71, v71, v43
	v_mul_f32_e32 v72, v72, v44
	v_mul_f32_e32 v73, v73, v45
	v_mul_f32_e32 v74, v74, v46
	v_mul_f32_e32 v75, v75, v47
	v_mul_f32_e32 v76, v76, v48
	v_mul_f32_e32 v77, v77, v49
	v_mul_f32_e32 v78, v78, v50
	v_mul_f32_e32 v79, v79, v51
	v_cvt_pk_bf16_f32 v64, v64, v65
	v_cvt_pk_bf16_f32 v65, v66, v67
	v_cvt_pk_bf16_f32 v68, v68, v69
	v_cvt_pk_bf16_f32 v69, v70, v71
	v_cvt_pk_bf16_f32 v72, v72, v73
	v_cvt_pk_bf16_f32 v73, v74, v75
	v_cvt_pk_bf16_f32 v76, v76, v77
	v_cvt_pk_bf16_f32 v77, v78, v79
	global_store_dwordx2 v2, v[64:65], s[26:27] offset:0
	global_store_dwordx2 v2, v[68:69], s[26:27] offset:512
	global_store_dwordx2 v2, v[72:73], s[26:27] offset:1024
	global_store_dwordx2 v2, v[76:77], s[26:27] offset:1536
	v_mul_f32_e32 v96, v112, v15
	v_mul_f32_e32 v97, v113, v15
	v_mul_f32_e32 v98, v114, v15
	v_mul_f32_e32 v99, v115, v15
	v_mul_f32_e32 v100, v116, v15
	v_mul_f32_e32 v101, v117, v15
	v_mul_f32_e32 v102, v118, v15
	v_mul_f32_e32 v103, v119, v15
	v_mul_f32_e32 v104, v120, v15
	v_mul_f32_e32 v105, v121, v15
	v_mul_f32_e32 v106, v122, v15
	v_mul_f32_e32 v107, v123, v15
	v_mul_f32_e32 v108, v124, v15
	v_mul_f32_e32 v109, v125, v15
	v_mul_f32_e32 v110, v126, v15
	v_mul_f32_e32 v111, v127, v15
	v_mul_f32_e32 v96, v96, v36
	v_mul_f32_e32 v97, v97, v37
	v_mul_f32_e32 v98, v98, v38
	v_mul_f32_e32 v99, v99, v39
	v_mul_f32_e32 v100, v100, v40
	v_mul_f32_e32 v101, v101, v41
	v_mul_f32_e32 v102, v102, v42
	v_mul_f32_e32 v103, v103, v43
	v_mul_f32_e32 v104, v104, v44
	v_mul_f32_e32 v105, v105, v45
	v_mul_f32_e32 v106, v106, v46
	v_mul_f32_e32 v107, v107, v47
	v_mul_f32_e32 v108, v108, v48
	v_mul_f32_e32 v109, v109, v49
	v_mul_f32_e32 v110, v110, v50
	v_mul_f32_e32 v111, v111, v51
	v_cvt_pk_bf16_f32 v96, v96, v97
	v_cvt_pk_bf16_f32 v97, v98, v99
	v_cvt_pk_bf16_f32 v100, v100, v101
	v_cvt_pk_bf16_f32 v101, v102, v103
	v_cvt_pk_bf16_f32 v104, v104, v105
	v_cvt_pk_bf16_f32 v105, v106, v107
	v_cvt_pk_bf16_f32 v108, v108, v109
	v_cvt_pk_bf16_f32 v109, v110, v111
	global_store_dwordx2 v2, v[96:97], s[34:35] offset:0
	global_store_dwordx2 v2, v[100:101], s[34:35] offset:512
	global_store_dwordx2 v2, v[104:105], s[34:35] offset:1024
	global_store_dwordx2 v2, v[108:109], s[34:35] offset:1536
	s_add_u32 s53, s16, 0x2000
	s_lshl_b32 s18, s53, 12
	s_lshl_b32 s19, s53, 11
	s_add_u32 s20, s12, s18
	s_addc_u32 s21, s13, 0
	s_add_u32 s22, s6, s19
	s_addc_u32 s23, s7, 0
	s_add_u32 s22, s22, 0x5200000
	s_addc_u32 s23, s23, 0
	s_add_u32 s24, s4, s18
	s_addc_u32 s25, s5, 0
	s_add_u32 s26, s6, s19
	s_addc_u32 s27, s7, 0
	s_add_u32 s26, s26, 0x3100000
	s_addc_u32 s27, s27, 0
	global_load_dwordx2 v[66:67], v2, s[22:23] offset:0
	global_load_dwordx2 v[70:71], v2, s[22:23] offset:512
	global_load_dwordx2 v[74:75], v2, s[22:23] offset:1024
	global_load_dwordx2 v[78:79], v2, s[22:23] offset:1536
	global_load_dwordx4 v[80:83], v1, s[20:21] offset:0
	global_load_dwordx4 v[84:87], v1, s[20:21] offset:1024
	global_load_dwordx4 v[88:91], v1, s[20:21] offset:2048
	global_load_dwordx4 v[92:95], v1, s[20:21] offset:3072
	s_add_u32 s53, s16, 0x2800
	s_lshl_b32 s18, s53, 12
	s_lshl_b32 s19, s53, 11
	s_add_u32 s28, s12, s18
	s_addc_u32 s29, s13, 0
	s_add_u32 s30, s6, s19
	s_addc_u32 s31, s7, 0
	s_add_u32 s30, s30, 0x5200000
	s_addc_u32 s31, s31, 0
	s_add_u32 s32, s4, s18
	s_addc_u32 s33, s5, 0
	s_add_u32 s34, s6, s19
	s_addc_u32 s35, s7, 0
	s_add_u32 s34, s34, 0x3100000
	s_addc_u32 s35, s35, 0
	global_load_dwordx2 v[98:99], v2, s[30:31] offset:0
	global_load_dwordx2 v[102:103], v2, s[30:31] offset:512
	global_load_dwordx2 v[106:107], v2, s[30:31] offset:1024
	global_load_dwordx2 v[110:111], v2, s[30:31] offset:1536
	global_load_dwordx4 v[112:115], v1, s[28:29] offset:0
	global_load_dwordx4 v[116:119], v1, s[28:29] offset:1024
	global_load_dwordx4 v[120:123], v1, s[28:29] offset:2048
	global_load_dwordx4 v[124:127], v1, s[28:29] offset:3072
	s_waitcnt vmcnt(32)
	v_lshlrev_b32_e32 v128, 16, v130
	v_and_b32_e32 v129, 0xffff0000, v130
	v_lshlrev_b32_e32 v130, 16, v131
	v_and_b32_e32 v131, 0xffff0000, v131
	v_lshlrev_b32_e32 v132, 16, v134
	v_and_b32_e32 v133, 0xffff0000, v134
	v_lshlrev_b32_e32 v134, 16, v135
	v_and_b32_e32 v135, 0xffff0000, v135
	v_lshlrev_b32_e32 v136, 16, v138
	v_and_b32_e32 v137, 0xffff0000, v138
	v_lshlrev_b32_e32 v138, 16, v139
	v_and_b32_e32 v139, 0xffff0000, v139
	v_lshlrev_b32_e32 v140, 16, v142
	v_and_b32_e32 v141, 0xffff0000, v142
	v_lshlrev_b32_e32 v142, 16, v143
	v_and_b32_e32 v143, 0xffff0000, v143
	v_lshlrev_b32_e32 v160, 16, v162
	v_and_b32_e32 v161, 0xffff0000, v162
	v_lshlrev_b32_e32 v162, 16, v163
	v_and_b32_e32 v163, 0xffff0000, v163
	v_lshlrev_b32_e32 v164, 16, v166
	v_and_b32_e32 v165, 0xffff0000, v166
	v_lshlrev_b32_e32 v166, 16, v167
	v_and_b32_e32 v167, 0xffff0000, v167
	v_lshlrev_b32_e32 v168, 16, v170
	v_and_b32_e32 v169, 0xffff0000, v170
	v_lshlrev_b32_e32 v170, 16, v171
	v_and_b32_e32 v171, 0xffff0000, v171
	v_lshlrev_b32_e32 v172, 16, v174
	v_and_b32_e32 v173, 0xffff0000, v174
	v_lshlrev_b32_e32 v174, 16, v175
	v_and_b32_e32 v175, 0xffff0000, v175
	v_mul_f32_e32 v10, v128, v128
	v_fmac_f32_e32 v10, v129, v129
	v_fmac_f32_e32 v10, v130, v130
	v_fmac_f32_e32 v10, v131, v131
	v_fmac_f32_e32 v10, v132, v132
	v_fmac_f32_e32 v10, v133, v133
	v_fmac_f32_e32 v10, v134, v134
	v_fmac_f32_e32 v10, v135, v135
	v_fmac_f32_e32 v10, v136, v136
	v_fmac_f32_e32 v10, v137, v137
	v_fmac_f32_e32 v10, v138, v138
	v_fmac_f32_e32 v10, v139, v139
	v_fmac_f32_e32 v10, v140, v140
	v_fmac_f32_e32 v10, v141, v141
	v_fmac_f32_e32 v10, v142, v142
	v_fmac_f32_e32 v10, v143, v143
	v_mul_f32_e32 v11, v160, v160
	v_fmac_f32_e32 v11, v161, v161
	v_fmac_f32_e32 v11, v162, v162
	v_fmac_f32_e32 v11, v163, v163
	v_fmac_f32_e32 v11, v164, v164
	v_fmac_f32_e32 v11, v165, v165
	v_fmac_f32_e32 v11, v166, v166
	v_fmac_f32_e32 v11, v167, v167
	v_fmac_f32_e32 v11, v168, v168
	v_fmac_f32_e32 v11, v169, v169
	v_fmac_f32_e32 v11, v170, v170
	v_fmac_f32_e32 v11, v171, v171
	v_fmac_f32_e32 v11, v172, v172
	v_fmac_f32_e32 v11, v173, v173
	v_fmac_f32_e32 v11, v174, v174
	v_fmac_f32_e32 v11, v175, v175
	ds_bpermute_b32 v12, v4, v10
	ds_bpermute_b32 v13, v4, v11
	s_waitcnt lgkmcnt(0)
	v_add_f32_e32 v10, v10, v12
	v_add_f32_e32 v11, v11, v13
	ds_bpermute_b32 v12, v5, v10
	ds_bpermute_b32 v13, v5, v11
	s_waitcnt lgkmcnt(0)
	v_add_f32_e32 v10, v10, v12
	v_add_f32_e32 v11, v11, v13
	ds_bpermute_b32 v12, v6, v10
	ds_bpermute_b32 v13, v6, v11
	s_waitcnt lgkmcnt(0)
	v_add_f32_e32 v10, v10, v12
	v_add_f32_e32 v11, v11, v13
	ds_bpermute_b32 v12, v7, v10
	ds_bpermute_b32 v13, v7, v11
	s_waitcnt lgkmcnt(0)
	v_add_f32_e32 v10, v10, v12
	v_add_f32_e32 v11, v11, v13
	ds_bpermute_b32 v12, v8, v10
	ds_bpermute_b32 v13, v8, v11
	s_waitcnt lgkmcnt(0)
	v_add_f32_e32 v10, v10, v12
	v_add_f32_e32 v11, v11, v13
	ds_bpermute_b32 v12, v9, v10
	ds_bpermute_b32 v13, v9, v11
	s_waitcnt lgkmcnt(0)
	v_add_f32_e32 v10, v10, v12
	v_add_f32_e32 v11, v11, v13
	v_fma_f32 v14, v10, s17, v3
	v_fma_f32 v15, v11, s17, v3
	v_rsq_f32_e32 v14, v14
	v_rsq_f32_e32 v15, v15
	s_nop 0
	v_mul_f32_e32 v128, v128, v14
	v_mul_f32_e32 v129, v129, v14
	v_mul_f32_e32 v130, v130, v14
	v_mul_f32_e32 v131, v131, v14
	v_mul_f32_e32 v132, v132, v14
	v_mul_f32_e32 v133, v133, v14
	v_mul_f32_e32 v134, v134, v14
	v_mul_f32_e32 v135, v135, v14
	v_mul_f32_e32 v136, v136, v14
	v_mul_f32_e32 v137, v137, v14
	v_mul_f32_e32 v138, v138, v14
	v_mul_f32_e32 v139, v139, v14
	v_mul_f32_e32 v140, v140, v14
	v_mul_f32_e32 v141, v141, v14
	v_mul_f32_e32 v142, v142, v14
	v_mul_f32_e32 v143, v143, v14
	v_fmac_f32_e32 v144, v128, v20
	v_fmac_f32_e32 v145, v129, v21
	v_fmac_f32_e32 v146, v130, v22
	v_fmac_f32_e32 v147, v131, v23
	v_fmac_f32_e32 v148, v132, v24
	v_fmac_f32_e32 v149, v133, v25
	v_fmac_f32_e32 v150, v134, v26
	v_fmac_f32_e32 v151, v135, v27
	v_fmac_f32_e32 v152, v136, v28
	v_fmac_f32_e32 v153, v137, v29
	v_fmac_f32_e32 v154, v138, v30
	v_fmac_f32_e32 v155, v139, v31
	v_fmac_f32_e32 v156, v140, v32
	v_fmac_f32_e32 v157, v141, v33
	v_fmac_f32_e32 v158, v142, v34
	v_fmac_f32_e32 v159, v143, v35
	global_store_dwordx4 v1, v[144:147], s[40:41] offset:0
	global_store_dwordx4 v1, v[148:151], s[40:41] offset:1024
	global_store_dwordx4 v1, v[152:155], s[40:41] offset:2048
	global_store_dwordx4 v1, v[156:159], s[40:41] offset:3072
	v_mul_f32_e32 v160, v160, v15
	v_mul_f32_e32 v161, v161, v15
	v_mul_f32_e32 v162, v162, v15
	v_mul_f32_e32 v163, v163, v15
	v_mul_f32_e32 v164, v164, v15
	v_mul_f32_e32 v165, v165, v15
	v_mul_f32_e32 v166, v166, v15
	v_mul_f32_e32 v167, v167, v15
	v_mul_f32_e32 v168, v168, v15
	v_mul_f32_e32 v169, v169, v15
	v_mul_f32_e32 v170, v170, v15
	v_mul_f32_e32 v171, v171, v15
	v_mul_f32_e32 v172, v172, v15
	v_mul_f32_e32 v173, v173, v15
	v_mul_f32_e32 v174, v174, v15
	v_mul_f32_e32 v175, v175, v15
	v_fmac_f32_e32 v176, v160, v20
	v_fmac_f32_e32 v177, v161, v21
	v_fmac_f32_e32 v178, v162, v22
	v_fmac_f32_e32 v179, v163, v23
	v_fmac_f32_e32 v180, v164, v24
	v_fmac_f32_e32 v181, v165, v25
	v_fmac_f32_e32 v182, v166, v26
	v_fmac_f32_e32 v183, v167, v27
	v_fmac_f32_e32 v184, v168, v28
	v_fmac_f32_e32 v185, v169, v29
	v_fmac_f32_e32 v186, v170, v30
	v_fmac_f32_e32 v187, v171, v31
	v_fmac_f32_e32 v188, v172, v32
	v_fmac_f32_e32 v189, v173, v33
	v_fmac_f32_e32 v190, v174, v34
	v_fmac_f32_e32 v191, v175, v35
	global_store_dwordx4 v1, v[176:179], s[48:49] offset:0
	global_store_dwordx4 v1, v[180:183], s[48:49] offset:1024
	global_store_dwordx4 v1, v[184:187], s[48:49] offset:2048
	global_store_dwordx4 v1, v[188:191], s[48:49] offset:3072
	v_mul_f32_e32 v10, v144, v144
	v_fmac_f32_e32 v10, v145, v145
	v_fmac_f32_e32 v10, v146, v146
	v_fmac_f32_e32 v10, v147, v147
	v_fmac_f32_e32 v10, v148, v148
	v_fmac_f32_e32 v10, v149, v149
	v_fmac_f32_e32 v10, v150, v150
	v_fmac_f32_e32 v10, v151, v151
	v_fmac_f32_e32 v10, v152, v152
	v_fmac_f32_e32 v10, v153, v153
	v_fmac_f32_e32 v10, v154, v154
	v_fmac_f32_e32 v10, v155, v155
	v_fmac_f32_e32 v10, v156, v156
	v_fmac_f32_e32 v10, v157, v157
	v_fmac_f32_e32 v10, v158, v158
	v_fmac_f32_e32 v10, v159, v159
	v_mul_f32_e32 v11, v176, v176
	v_fmac_f32_e32 v11, v177, v177
	v_fmac_f32_e32 v11, v178, v178
	v_fmac_f32_e32 v11, v179, v179
	v_fmac_f32_e32 v11, v180, v180
	v_fmac_f32_e32 v11, v181, v181
	v_fmac_f32_e32 v11, v182, v182
	v_fmac_f32_e32 v11, v183, v183
	v_fmac_f32_e32 v11, v184, v184
	v_fmac_f32_e32 v11, v185, v185
	v_fmac_f32_e32 v11, v186, v186
	v_fmac_f32_e32 v11, v187, v187
	v_fmac_f32_e32 v11, v188, v188
	v_fmac_f32_e32 v11, v189, v189
	v_fmac_f32_e32 v11, v190, v190
	v_fmac_f32_e32 v11, v191, v191
	ds_bpermute_b32 v12, v4, v10
	ds_bpermute_b32 v13, v4, v11
	s_waitcnt lgkmcnt(0)
	v_add_f32_e32 v10, v10, v12
	v_add_f32_e32 v11, v11, v13
	ds_bpermute_b32 v12, v5, v10
	ds_bpermute_b32 v13, v5, v11
	s_waitcnt lgkmcnt(0)
	v_add_f32_e32 v10, v10, v12
	v_add_f32_e32 v11, v11, v13
	ds_bpermute_b32 v12, v6, v10
	ds_bpermute_b32 v13, v6, v11
	s_waitcnt lgkmcnt(0)
	v_add_f32_e32 v10, v10, v12
	v_add_f32_e32 v11, v11, v13
	ds_bpermute_b32 v12, v7, v10
	ds_bpermute_b32 v13, v7, v11
	s_waitcnt lgkmcnt(0)
	v_add_f32_e32 v10, v10, v12
	v_add_f32_e32 v11, v11, v13
	ds_bpermute_b32 v12, v8, v10
	ds_bpermute_b32 v13, v8, v11
	s_waitcnt lgkmcnt(0)
	v_add_f32_e32 v10, v10, v12
	v_add_f32_e32 v11, v11, v13
	ds_bpermute_b32 v12, v9, v10
	ds_bpermute_b32 v13, v9, v11
	s_waitcnt lgkmcnt(0)
	v_add_f32_e32 v10, v10, v12
	v_add_f32_e32 v11, v11, v13
	v_fma_f32 v14, v10, s17, v3
	v_fma_f32 v15, v11, s17, v3
	v_rsq_f32_e32 v14, v14
	v_rsq_f32_e32 v15, v15
	s_nop 0
	v_mul_f32_e32 v128, v144, v14
	v_mul_f32_e32 v129, v145, v14
	v_mul_f32_e32 v130, v146, v14
	v_mul_f32_e32 v131, v147, v14
	v_mul_f32_e32 v132, v148, v14
	v_mul_f32_e32 v133, v149, v14
	v_mul_f32_e32 v134, v150, v14
	v_mul_f32_e32 v135, v151, v14
	v_mul_f32_e32 v136, v152, v14
	v_mul_f32_e32 v137, v153, v14
	v_mul_f32_e32 v138, v154, v14
	v_mul_f32_e32 v139, v155, v14
	v_mul_f32_e32 v140, v156, v14
	v_mul_f32_e32 v141, v157, v14
	v_mul_f32_e32 v142, v158, v14
	v_mul_f32_e32 v143, v159, v14
	v_mul_f32_e32 v128, v128, v36
	v_mul_f32_e32 v129, v129, v37
	v_mul_f32_e32 v130, v130, v38
	v_mul_f32_e32 v131, v131, v39
	v_mul_f32_e32 v132, v132, v40
	v_mul_f32_e32 v133, v133, v41
	v_mul_f32_e32 v134, v134, v42
	v_mul_f32_e32 v135, v135, v43
	v_mul_f32_e32 v136, v136, v44
	v_mul_f32_e32 v137, v137, v45
	v_mul_f32_e32 v138, v138, v46
	v_mul_f32_e32 v139, v139, v47
	v_mul_f32_e32 v140, v140, v48
	v_mul_f32_e32 v141, v141, v49
	v_mul_f32_e32 v142, v142, v50
	v_mul_f32_e32 v143, v143, v51
	v_cvt_pk_bf16_f32 v128, v128, v129
	v_cvt_pk_bf16_f32 v129, v130, v131
	v_cvt_pk_bf16_f32 v132, v132, v133
	v_cvt_pk_bf16_f32 v133, v134, v135
	v_cvt_pk_bf16_f32 v136, v136, v137
	v_cvt_pk_bf16_f32 v137, v138, v139
	v_cvt_pk_bf16_f32 v140, v140, v141
	v_cvt_pk_bf16_f32 v141, v142, v143
	global_store_dwordx2 v2, v[128:129], s[42:43] offset:0
	global_store_dwordx2 v2, v[132:133], s[42:43] offset:512
	global_store_dwordx2 v2, v[136:137], s[42:43] offset:1024
	global_store_dwordx2 v2, v[140:141], s[42:43] offset:1536
	v_mul_f32_e32 v160, v176, v15
	v_mul_f32_e32 v161, v177, v15
	v_mul_f32_e32 v162, v178, v15
	v_mul_f32_e32 v163, v179, v15
	v_mul_f32_e32 v164, v180, v15
	v_mul_f32_e32 v165, v181, v15
	v_mul_f32_e32 v166, v182, v15
	v_mul_f32_e32 v167, v183, v15
	v_mul_f32_e32 v168, v184, v15
	v_mul_f32_e32 v169, v185, v15
	v_mul_f32_e32 v170, v186, v15
	v_mul_f32_e32 v171, v187, v15
	v_mul_f32_e32 v172, v188, v15
	v_mul_f32_e32 v173, v189, v15
	v_mul_f32_e32 v174, v190, v15
	v_mul_f32_e32 v175, v191, v15
	v_mul_f32_e32 v160, v160, v36
	v_mul_f32_e32 v161, v161, v37
	v_mul_f32_e32 v162, v162, v38
	v_mul_f32_e32 v163, v163, v39
	v_mul_f32_e32 v164, v164, v40
	v_mul_f32_e32 v165, v165, v41
	v_mul_f32_e32 v166, v166, v42
	v_mul_f32_e32 v167, v167, v43
	v_mul_f32_e32 v168, v168, v44
	v_mul_f32_e32 v169, v169, v45
	v_mul_f32_e32 v170, v170, v46
	v_mul_f32_e32 v171, v171, v47
	v_mul_f32_e32 v172, v172, v48
	v_mul_f32_e32 v173, v173, v49
	v_mul_f32_e32 v174, v174, v50
	v_mul_f32_e32 v175, v175, v51
	v_cvt_pk_bf16_f32 v160, v160, v161
	v_cvt_pk_bf16_f32 v161, v162, v163
	v_cvt_pk_bf16_f32 v164, v164, v165
	v_cvt_pk_bf16_f32 v165, v166, v167
	v_cvt_pk_bf16_f32 v168, v168, v169
	v_cvt_pk_bf16_f32 v169, v170, v171
	v_cvt_pk_bf16_f32 v172, v172, v173
	v_cvt_pk_bf16_f32 v173, v174, v175
	global_store_dwordx2 v2, v[160:161], s[50:51] offset:0
	global_store_dwordx2 v2, v[164:165], s[50:51] offset:512
	global_store_dwordx2 v2, v[168:169], s[50:51] offset:1024
	global_store_dwordx2 v2, v[172:173], s[50:51] offset:1536
	s_add_u32 s53, s16, 0x3000
	s_lshl_b32 s18, s53, 12
	s_lshl_b32 s19, s53, 11
	s_add_u32 s36, s12, s18
	s_addc_u32 s37, s13, 0
	s_add_u32 s38, s6, s19
	s_addc_u32 s39, s7, 0
	s_add_u32 s38, s38, 0x5200000
	s_addc_u32 s39, s39, 0
	s_add_u32 s40, s4, s18
	s_addc_u32 s41, s5, 0
	s_add_u32 s42, s6, s19
	s_addc_u32 s43, s7, 0
	s_add_u32 s42, s42, 0x3100000
	s_addc_u32 s43, s43, 0
	global_load_dwordx2 v[130:131], v2, s[38:39] offset:0
	global_load_dwordx2 v[134:135], v2, s[38:39] offset:512
	global_load_dwordx2 v[138:139], v2, s[38:39] offset:1024
	global_load_dwordx2 v[142:143], v2, s[38:39] offset:1536
	global_load_dwordx4 v[144:147], v1, s[36:37] offset:0
	global_load_dwordx4 v[148:151], v1, s[36:37] offset:1024
	global_load_dwordx4 v[152:155], v1, s[36:37] offset:2048
	global_load_dwordx4 v[156:159], v1, s[36:37] offset:3072
	s_add_u32 s53, s16, 0x3800
	s_lshl_b32 s18, s53, 12
	s_lshl_b32 s19, s53, 11
	s_add_u32 s44, s12, s18
	s_addc_u32 s45, s13, 0
	s_add_u32 s46, s6, s19
	s_addc_u32 s47, s7, 0
	s_add_u32 s46, s46, 0x5200000
	s_addc_u32 s47, s47, 0
	s_add_u32 s48, s4, s18
	s_addc_u32 s49, s5, 0
	s_add_u32 s50, s6, s19
	s_addc_u32 s51, s7, 0
	s_add_u32 s50, s50, 0x3100000
	s_addc_u32 s51, s51, 0
	global_load_dwordx2 v[162:163], v2, s[46:47] offset:0
	global_load_dwordx2 v[166:167], v2, s[46:47] offset:512
	global_load_dwordx2 v[170:171], v2, s[46:47] offset:1024
	global_load_dwordx2 v[174:175], v2, s[46:47] offset:1536
	global_load_dwordx4 v[176:179], v1, s[44:45] offset:0
	global_load_dwordx4 v[180:183], v1, s[44:45] offset:1024
	global_load_dwordx4 v[184:187], v1, s[44:45] offset:2048
	global_load_dwordx4 v[188:191], v1, s[44:45] offset:3072
	s_waitcnt vmcnt(32)
	v_lshlrev_b32_e32 v64, 16, v66
	v_and_b32_e32 v65, 0xffff0000, v66
	v_lshlrev_b32_e32 v66, 16, v67
	v_and_b32_e32 v67, 0xffff0000, v67
	v_lshlrev_b32_e32 v68, 16, v70
	v_and_b32_e32 v69, 0xffff0000, v70
	v_lshlrev_b32_e32 v70, 16, v71
	v_and_b32_e32 v71, 0xffff0000, v71
	v_lshlrev_b32_e32 v72, 16, v74
	v_and_b32_e32 v73, 0xffff0000, v74
	v_lshlrev_b32_e32 v74, 16, v75
	v_and_b32_e32 v75, 0xffff0000, v75
	v_lshlrev_b32_e32 v76, 16, v78
	v_and_b32_e32 v77, 0xffff0000, v78
	v_lshlrev_b32_e32 v78, 16, v79
	v_and_b32_e32 v79, 0xffff0000, v79
	v_lshlrev_b32_e32 v96, 16, v98
	v_and_b32_e32 v97, 0xffff0000, v98
	v_lshlrev_b32_e32 v98, 16, v99
	v_and_b32_e32 v99, 0xffff0000, v99
	v_lshlrev_b32_e32 v100, 16, v102
	v_and_b32_e32 v101, 0xffff0000, v102
	v_lshlrev_b32_e32 v102, 16, v103
	v_and_b32_e32 v103, 0xffff0000, v103
	v_lshlrev_b32_e32 v104, 16, v106
	v_and_b32_e32 v105, 0xffff0000, v106
	v_lshlrev_b32_e32 v106, 16, v107
	v_and_b32_e32 v107, 0xffff0000, v107
	v_lshlrev_b32_e32 v108, 16, v110
	v_and_b32_e32 v109, 0xffff0000, v110
	v_lshlrev_b32_e32 v110, 16, v111
	v_and_b32_e32 v111, 0xffff0000, v111
	v_mul_f32_e32 v10, v64, v64
	v_fmac_f32_e32 v10, v65, v65
	v_fmac_f32_e32 v10, v66, v66
	v_fmac_f32_e32 v10, v67, v67
	v_fmac_f32_e32 v10, v68, v68
	v_fmac_f32_e32 v10, v69, v69
	v_fmac_f32_e32 v10, v70, v70
	v_fmac_f32_e32 v10, v71, v71
	v_fmac_f32_e32 v10, v72, v72
	v_fmac_f32_e32 v10, v73, v73
	v_fmac_f32_e32 v10, v74, v74
	v_fmac_f32_e32 v10, v75, v75
	v_fmac_f32_e32 v10, v76, v76
	v_fmac_f32_e32 v10, v77, v77
	v_fmac_f32_e32 v10, v78, v78
	v_fmac_f32_e32 v10, v79, v79
	v_mul_f32_e32 v11, v96, v96
	v_fmac_f32_e32 v11, v97, v97
	v_fmac_f32_e32 v11, v98, v98
	v_fmac_f32_e32 v11, v99, v99
	v_fmac_f32_e32 v11, v100, v100
	v_fmac_f32_e32 v11, v101, v101
	v_fmac_f32_e32 v11, v102, v102
	v_fmac_f32_e32 v11, v103, v103
	v_fmac_f32_e32 v11, v104, v104
	v_fmac_f32_e32 v11, v105, v105
	v_fmac_f32_e32 v11, v106, v106
	v_fmac_f32_e32 v11, v107, v107
	v_fmac_f32_e32 v11, v108, v108
	v_fmac_f32_e32 v11, v109, v109
	v_fmac_f32_e32 v11, v110, v110
	v_fmac_f32_e32 v11, v111, v111
	ds_bpermute_b32 v12, v4, v10
	ds_bpermute_b32 v13, v4, v11
	s_waitcnt lgkmcnt(0)
	v_add_f32_e32 v10, v10, v12
	v_add_f32_e32 v11, v11, v13
	ds_bpermute_b32 v12, v5, v10
	ds_bpermute_b32 v13, v5, v11
	s_waitcnt lgkmcnt(0)
	v_add_f32_e32 v10, v10, v12
	v_add_f32_e32 v11, v11, v13
	ds_bpermute_b32 v12, v6, v10
	ds_bpermute_b32 v13, v6, v11
	s_waitcnt lgkmcnt(0)
	v_add_f32_e32 v10, v10, v12
	v_add_f32_e32 v11, v11, v13
	ds_bpermute_b32 v12, v7, v10
	ds_bpermute_b32 v13, v7, v11
	s_waitcnt lgkmcnt(0)
	v_add_f32_e32 v10, v10, v12
	v_add_f32_e32 v11, v11, v13
	ds_bpermute_b32 v12, v8, v10
	ds_bpermute_b32 v13, v8, v11
	s_waitcnt lgkmcnt(0)
	v_add_f32_e32 v10, v10, v12
	v_add_f32_e32 v11, v11, v13
	ds_bpermute_b32 v12, v9, v10
	ds_bpermute_b32 v13, v9, v11
	s_waitcnt lgkmcnt(0)
	v_add_f32_e32 v10, v10, v12
	v_add_f32_e32 v11, v11, v13
	v_fma_f32 v14, v10, s17, v3
	v_fma_f32 v15, v11, s17, v3
	v_rsq_f32_e32 v14, v14
	v_rsq_f32_e32 v15, v15
	s_nop 0
	v_mul_f32_e32 v64, v64, v14
	v_mul_f32_e32 v65, v65, v14
	v_mul_f32_e32 v66, v66, v14
	v_mul_f32_e32 v67, v67, v14
	v_mul_f32_e32 v68, v68, v14
	v_mul_f32_e32 v69, v69, v14
	v_mul_f32_e32 v70, v70, v14
	v_mul_f32_e32 v71, v71, v14
	v_mul_f32_e32 v72, v72, v14
	v_mul_f32_e32 v73, v73, v14
	v_mul_f32_e32 v74, v74, v14
	v_mul_f32_e32 v75, v75, v14
	v_mul_f32_e32 v76, v76, v14
	v_mul_f32_e32 v77, v77, v14
	v_mul_f32_e32 v78, v78, v14
	v_mul_f32_e32 v79, v79, v14
	v_fmac_f32_e32 v80, v64, v20
	v_fmac_f32_e32 v81, v65, v21
	v_fmac_f32_e32 v82, v66, v22
	v_fmac_f32_e32 v83, v67, v23
	v_fmac_f32_e32 v84, v68, v24
	v_fmac_f32_e32 v85, v69, v25
	v_fmac_f32_e32 v86, v70, v26
	v_fmac_f32_e32 v87, v71, v27
	v_fmac_f32_e32 v88, v72, v28
	v_fmac_f32_e32 v89, v73, v29
	v_fmac_f32_e32 v90, v74, v30
	v_fmac_f32_e32 v91, v75, v31
	v_fmac_f32_e32 v92, v76, v32
	v_fmac_f32_e32 v93, v77, v33
	v_fmac_f32_e32 v94, v78, v34
	v_fmac_f32_e32 v95, v79, v35
	global_store_dwordx4 v1, v[80:83], s[24:25] offset:0
	global_store_dwordx4 v1, v[84:87], s[24:25] offset:1024
	global_store_dwordx4 v1, v[88:91], s[24:25] offset:2048
	global_store_dwordx4 v1, v[92:95], s[24:25] offset:3072
	v_mul_f32_e32 v96, v96, v15
	v_mul_f32_e32 v97, v97, v15
	v_mul_f32_e32 v98, v98, v15
	v_mul_f32_e32 v99, v99, v15
	v_mul_f32_e32 v100, v100, v15
	v_mul_f32_e32 v101, v101, v15
	v_mul_f32_e32 v102, v102, v15
	v_mul_f32_e32 v103, v103, v15
	v_mul_f32_e32 v104, v104, v15
	v_mul_f32_e32 v105, v105, v15
	v_mul_f32_e32 v106, v106, v15
	v_mul_f32_e32 v107, v107, v15
	v_mul_f32_e32 v108, v108, v15
	v_mul_f32_e32 v109, v109, v15
	v_mul_f32_e32 v110, v110, v15
	v_mul_f32_e32 v111, v111, v15
	v_fmac_f32_e32 v112, v96, v20
	v_fmac_f32_e32 v113, v97, v21
	v_fmac_f32_e32 v114, v98, v22
	v_fmac_f32_e32 v115, v99, v23
	v_fmac_f32_e32 v116, v100, v24
	v_fmac_f32_e32 v117, v101, v25
	v_fmac_f32_e32 v118, v102, v26
	v_fmac_f32_e32 v119, v103, v27
	v_fmac_f32_e32 v120, v104, v28
	v_fmac_f32_e32 v121, v105, v29
	v_fmac_f32_e32 v122, v106, v30
	v_fmac_f32_e32 v123, v107, v31
	v_fmac_f32_e32 v124, v108, v32
	v_fmac_f32_e32 v125, v109, v33
	v_fmac_f32_e32 v126, v110, v34
	v_fmac_f32_e32 v127, v111, v35
	global_store_dwordx4 v1, v[112:115], s[32:33] offset:0
	global_store_dwordx4 v1, v[116:119], s[32:33] offset:1024
	global_store_dwordx4 v1, v[120:123], s[32:33] offset:2048
	global_store_dwordx4 v1, v[124:127], s[32:33] offset:3072
	v_mul_f32_e32 v10, v80, v80
	v_fmac_f32_e32 v10, v81, v81
	v_fmac_f32_e32 v10, v82, v82
	v_fmac_f32_e32 v10, v83, v83
	v_fmac_f32_e32 v10, v84, v84
	v_fmac_f32_e32 v10, v85, v85
	v_fmac_f32_e32 v10, v86, v86
	v_fmac_f32_e32 v10, v87, v87
	v_fmac_f32_e32 v10, v88, v88
	v_fmac_f32_e32 v10, v89, v89
	v_fmac_f32_e32 v10, v90, v90
	v_fmac_f32_e32 v10, v91, v91
	v_fmac_f32_e32 v10, v92, v92
	v_fmac_f32_e32 v10, v93, v93
	v_fmac_f32_e32 v10, v94, v94
	v_fmac_f32_e32 v10, v95, v95
	v_mul_f32_e32 v11, v112, v112
	v_fmac_f32_e32 v11, v113, v113
	v_fmac_f32_e32 v11, v114, v114
	v_fmac_f32_e32 v11, v115, v115
	v_fmac_f32_e32 v11, v116, v116
	v_fmac_f32_e32 v11, v117, v117
	v_fmac_f32_e32 v11, v118, v118
	v_fmac_f32_e32 v11, v119, v119
	v_fmac_f32_e32 v11, v120, v120
	v_fmac_f32_e32 v11, v121, v121
	v_fmac_f32_e32 v11, v122, v122
	v_fmac_f32_e32 v11, v123, v123
	v_fmac_f32_e32 v11, v124, v124
	v_fmac_f32_e32 v11, v125, v125
	v_fmac_f32_e32 v11, v126, v126
	v_fmac_f32_e32 v11, v127, v127
	ds_bpermute_b32 v12, v4, v10
	ds_bpermute_b32 v13, v4, v11
	s_waitcnt lgkmcnt(0)
	v_add_f32_e32 v10, v10, v12
	v_add_f32_e32 v11, v11, v13
	ds_bpermute_b32 v12, v5, v10
	ds_bpermute_b32 v13, v5, v11
	s_waitcnt lgkmcnt(0)
	v_add_f32_e32 v10, v10, v12
	v_add_f32_e32 v11, v11, v13
	ds_bpermute_b32 v12, v6, v10
	ds_bpermute_b32 v13, v6, v11
	s_waitcnt lgkmcnt(0)
	v_add_f32_e32 v10, v10, v12
	v_add_f32_e32 v11, v11, v13
	ds_bpermute_b32 v12, v7, v10
	ds_bpermute_b32 v13, v7, v11
	s_waitcnt lgkmcnt(0)
	v_add_f32_e32 v10, v10, v12
	v_add_f32_e32 v11, v11, v13
	ds_bpermute_b32 v12, v8, v10
	ds_bpermute_b32 v13, v8, v11
	s_waitcnt lgkmcnt(0)
	v_add_f32_e32 v10, v10, v12
	v_add_f32_e32 v11, v11, v13
	ds_bpermute_b32 v12, v9, v10
	ds_bpermute_b32 v13, v9, v11
	s_waitcnt lgkmcnt(0)
	v_add_f32_e32 v10, v10, v12
	v_add_f32_e32 v11, v11, v13
	v_fma_f32 v14, v10, s17, v3
	v_fma_f32 v15, v11, s17, v3
	v_rsq_f32_e32 v14, v14
	v_rsq_f32_e32 v15, v15
	s_nop 0
	v_mul_f32_e32 v64, v80, v14
	v_mul_f32_e32 v65, v81, v14
	v_mul_f32_e32 v66, v82, v14
	v_mul_f32_e32 v67, v83, v14
	v_mul_f32_e32 v68, v84, v14
	v_mul_f32_e32 v69, v85, v14
	v_mul_f32_e32 v70, v86, v14
	v_mul_f32_e32 v71, v87, v14
	v_mul_f32_e32 v72, v88, v14
	v_mul_f32_e32 v73, v89, v14
	v_mul_f32_e32 v74, v90, v14
	v_mul_f32_e32 v75, v91, v14
	v_mul_f32_e32 v76, v92, v14
	v_mul_f32_e32 v77, v93, v14
	v_mul_f32_e32 v78, v94, v14
	v_mul_f32_e32 v79, v95, v14
	v_mul_f32_e32 v64, v64, v36
	v_mul_f32_e32 v65, v65, v37
	v_mul_f32_e32 v66, v66, v38
	v_mul_f32_e32 v67, v67, v39
	v_mul_f32_e32 v68, v68, v40
	v_mul_f32_e32 v69, v69, v41
	v_mul_f32_e32 v70, v70, v42
	v_mul_f32_e32 v71, v71, v43
	v_mul_f32_e32 v72, v72, v44
	v_mul_f32_e32 v73, v73, v45
	v_mul_f32_e32 v74, v74, v46
	v_mul_f32_e32 v75, v75, v47
	v_mul_f32_e32 v76, v76, v48
	v_mul_f32_e32 v77, v77, v49
	v_mul_f32_e32 v78, v78, v50
	v_mul_f32_e32 v79, v79, v51
	v_cvt_pk_bf16_f32 v64, v64, v65
	v_cvt_pk_bf16_f32 v65, v66, v67
	v_cvt_pk_bf16_f32 v68, v68, v69
	v_cvt_pk_bf16_f32 v69, v70, v71
	v_cvt_pk_bf16_f32 v72, v72, v73
	v_cvt_pk_bf16_f32 v73, v74, v75
	v_cvt_pk_bf16_f32 v76, v76, v77
	v_cvt_pk_bf16_f32 v77, v78, v79
	global_store_dwordx2 v2, v[64:65], s[26:27] offset:0
	global_store_dwordx2 v2, v[68:69], s[26:27] offset:512
	global_store_dwordx2 v2, v[72:73], s[26:27] offset:1024
	global_store_dwordx2 v2, v[76:77], s[26:27] offset:1536
	v_mul_f32_e32 v96, v112, v15
	v_mul_f32_e32 v97, v113, v15
	v_mul_f32_e32 v98, v114, v15
	v_mul_f32_e32 v99, v115, v15
	v_mul_f32_e32 v100, v116, v15
	v_mul_f32_e32 v101, v117, v15
	v_mul_f32_e32 v102, v118, v15
	v_mul_f32_e32 v103, v119, v15
	v_mul_f32_e32 v104, v120, v15
	v_mul_f32_e32 v105, v121, v15
	v_mul_f32_e32 v106, v122, v15
	v_mul_f32_e32 v107, v123, v15
	v_mul_f32_e32 v108, v124, v15
	v_mul_f32_e32 v109, v125, v15
	v_mul_f32_e32 v110, v126, v15
	v_mul_f32_e32 v111, v127, v15
	v_mul_f32_e32 v96, v96, v36
	v_mul_f32_e32 v97, v97, v37
	v_mul_f32_e32 v98, v98, v38
	v_mul_f32_e32 v99, v99, v39
	v_mul_f32_e32 v100, v100, v40
	v_mul_f32_e32 v101, v101, v41
	v_mul_f32_e32 v102, v102, v42
	v_mul_f32_e32 v103, v103, v43
	v_mul_f32_e32 v104, v104, v44
	v_mul_f32_e32 v105, v105, v45
	v_mul_f32_e32 v106, v106, v46
	v_mul_f32_e32 v107, v107, v47
	v_mul_f32_e32 v108, v108, v48
	v_mul_f32_e32 v109, v109, v49
	v_mul_f32_e32 v110, v110, v50
	v_mul_f32_e32 v111, v111, v51
	v_cvt_pk_bf16_f32 v96, v96, v97
	v_cvt_pk_bf16_f32 v97, v98, v99
	v_cvt_pk_bf16_f32 v100, v100, v101
	v_cvt_pk_bf16_f32 v101, v102, v103
	v_cvt_pk_bf16_f32 v104, v104, v105
	v_cvt_pk_bf16_f32 v105, v106, v107
	v_cvt_pk_bf16_f32 v108, v108, v109
	v_cvt_pk_bf16_f32 v109, v110, v111
	global_store_dwordx2 v2, v[96:97], s[34:35] offset:0
	global_store_dwordx2 v2, v[100:101], s[34:35] offset:512
	global_store_dwordx2 v2, v[104:105], s[34:35] offset:1024
	global_store_dwordx2 v2, v[108:109], s[34:35] offset:1536
	s_waitcnt vmcnt(16)
	v_lshlrev_b32_e32 v128, 16, v130
	v_and_b32_e32 v129, 0xffff0000, v130
	v_lshlrev_b32_e32 v130, 16, v131
	v_and_b32_e32 v131, 0xffff0000, v131
	v_lshlrev_b32_e32 v132, 16, v134
	v_and_b32_e32 v133, 0xffff0000, v134
	v_lshlrev_b32_e32 v134, 16, v135
	v_and_b32_e32 v135, 0xffff0000, v135
	v_lshlrev_b32_e32 v136, 16, v138
	v_and_b32_e32 v137, 0xffff0000, v138
	v_lshlrev_b32_e32 v138, 16, v139
	v_and_b32_e32 v139, 0xffff0000, v139
	v_lshlrev_b32_e32 v140, 16, v142
	v_and_b32_e32 v141, 0xffff0000, v142
	v_lshlrev_b32_e32 v142, 16, v143
	v_and_b32_e32 v143, 0xffff0000, v143
	v_lshlrev_b32_e32 v160, 16, v162
	v_and_b32_e32 v161, 0xffff0000, v162
	v_lshlrev_b32_e32 v162, 16, v163
	v_and_b32_e32 v163, 0xffff0000, v163
	v_lshlrev_b32_e32 v164, 16, v166
	v_and_b32_e32 v165, 0xffff0000, v166
	v_lshlrev_b32_e32 v166, 16, v167
	v_and_b32_e32 v167, 0xffff0000, v167
	v_lshlrev_b32_e32 v168, 16, v170
	v_and_b32_e32 v169, 0xffff0000, v170
	v_lshlrev_b32_e32 v170, 16, v171
	v_and_b32_e32 v171, 0xffff0000, v171
	v_lshlrev_b32_e32 v172, 16, v174
	v_and_b32_e32 v173, 0xffff0000, v174
	v_lshlrev_b32_e32 v174, 16, v175
	v_and_b32_e32 v175, 0xffff0000, v175
	v_mul_f32_e32 v10, v128, v128
	v_fmac_f32_e32 v10, v129, v129
	v_fmac_f32_e32 v10, v130, v130
	v_fmac_f32_e32 v10, v131, v131
	v_fmac_f32_e32 v10, v132, v132
	v_fmac_f32_e32 v10, v133, v133
	v_fmac_f32_e32 v10, v134, v134
	v_fmac_f32_e32 v10, v135, v135
	v_fmac_f32_e32 v10, v136, v136
	v_fmac_f32_e32 v10, v137, v137
	v_fmac_f32_e32 v10, v138, v138
	v_fmac_f32_e32 v10, v139, v139
	v_fmac_f32_e32 v10, v140, v140
	v_fmac_f32_e32 v10, v141, v141
	v_fmac_f32_e32 v10, v142, v142
	v_fmac_f32_e32 v10, v143, v143
	v_mul_f32_e32 v11, v160, v160
	v_fmac_f32_e32 v11, v161, v161
	v_fmac_f32_e32 v11, v162, v162
	v_fmac_f32_e32 v11, v163, v163
	v_fmac_f32_e32 v11, v164, v164
	v_fmac_f32_e32 v11, v165, v165
	v_fmac_f32_e32 v11, v166, v166
	v_fmac_f32_e32 v11, v167, v167
	v_fmac_f32_e32 v11, v168, v168
	v_fmac_f32_e32 v11, v169, v169
	v_fmac_f32_e32 v11, v170, v170
	v_fmac_f32_e32 v11, v171, v171
	v_fmac_f32_e32 v11, v172, v172
	v_fmac_f32_e32 v11, v173, v173
	v_fmac_f32_e32 v11, v174, v174
	v_fmac_f32_e32 v11, v175, v175
	ds_bpermute_b32 v12, v4, v10
	ds_bpermute_b32 v13, v4, v11
	s_waitcnt lgkmcnt(0)
	v_add_f32_e32 v10, v10, v12
	v_add_f32_e32 v11, v11, v13
	ds_bpermute_b32 v12, v5, v10
	ds_bpermute_b32 v13, v5, v11
	s_waitcnt lgkmcnt(0)
	v_add_f32_e32 v10, v10, v12
	v_add_f32_e32 v11, v11, v13
	ds_bpermute_b32 v12, v6, v10
	ds_bpermute_b32 v13, v6, v11
	s_waitcnt lgkmcnt(0)
	v_add_f32_e32 v10, v10, v12
	v_add_f32_e32 v11, v11, v13
	ds_bpermute_b32 v12, v7, v10
	ds_bpermute_b32 v13, v7, v11
	s_waitcnt lgkmcnt(0)
	v_add_f32_e32 v10, v10, v12
	v_add_f32_e32 v11, v11, v13
	ds_bpermute_b32 v12, v8, v10
	ds_bpermute_b32 v13, v8, v11
	s_waitcnt lgkmcnt(0)
	v_add_f32_e32 v10, v10, v12
	v_add_f32_e32 v11, v11, v13
	ds_bpermute_b32 v12, v9, v10
	ds_bpermute_b32 v13, v9, v11
	s_waitcnt lgkmcnt(0)
	v_add_f32_e32 v10, v10, v12
	v_add_f32_e32 v11, v11, v13
	v_fma_f32 v14, v10, s17, v3
	v_fma_f32 v15, v11, s17, v3
	v_rsq_f32_e32 v14, v14
	v_rsq_f32_e32 v15, v15
	s_nop 0
	v_mul_f32_e32 v128, v128, v14
	v_mul_f32_e32 v129, v129, v14
	v_mul_f32_e32 v130, v130, v14
	v_mul_f32_e32 v131, v131, v14
	v_mul_f32_e32 v132, v132, v14
	v_mul_f32_e32 v133, v133, v14
	v_mul_f32_e32 v134, v134, v14
	v_mul_f32_e32 v135, v135, v14
	v_mul_f32_e32 v136, v136, v14
	v_mul_f32_e32 v137, v137, v14
	v_mul_f32_e32 v138, v138, v14
	v_mul_f32_e32 v139, v139, v14
	v_mul_f32_e32 v140, v140, v14
	v_mul_f32_e32 v141, v141, v14
	v_mul_f32_e32 v142, v142, v14
	v_mul_f32_e32 v143, v143, v14
	v_fmac_f32_e32 v144, v128, v20
	v_fmac_f32_e32 v145, v129, v21
	v_fmac_f32_e32 v146, v130, v22
	v_fmac_f32_e32 v147, v131, v23
	v_fmac_f32_e32 v148, v132, v24
	v_fmac_f32_e32 v149, v133, v25
	v_fmac_f32_e32 v150, v134, v26
	v_fmac_f32_e32 v151, v135, v27
	v_fmac_f32_e32 v152, v136, v28
	v_fmac_f32_e32 v153, v137, v29
	v_fmac_f32_e32 v154, v138, v30
	v_fmac_f32_e32 v155, v139, v31
	v_fmac_f32_e32 v156, v140, v32
	v_fmac_f32_e32 v157, v141, v33
	v_fmac_f32_e32 v158, v142, v34
	v_fmac_f32_e32 v159, v143, v35
	global_store_dwordx4 v1, v[144:147], s[40:41] offset:0
	global_store_dwordx4 v1, v[148:151], s[40:41] offset:1024
	global_store_dwordx4 v1, v[152:155], s[40:41] offset:2048
	global_store_dwordx4 v1, v[156:159], s[40:41] offset:3072
	v_mul_f32_e32 v160, v160, v15
	v_mul_f32_e32 v161, v161, v15
	v_mul_f32_e32 v162, v162, v15
	v_mul_f32_e32 v163, v163, v15
	v_mul_f32_e32 v164, v164, v15
	v_mul_f32_e32 v165, v165, v15
	v_mul_f32_e32 v166, v166, v15
	v_mul_f32_e32 v167, v167, v15
	v_mul_f32_e32 v168, v168, v15
	v_mul_f32_e32 v169, v169, v15
	v_mul_f32_e32 v170, v170, v15
	v_mul_f32_e32 v171, v171, v15
	v_mul_f32_e32 v172, v172, v15
	v_mul_f32_e32 v173, v173, v15
	v_mul_f32_e32 v174, v174, v15
	v_mul_f32_e32 v175, v175, v15
	v_fmac_f32_e32 v176, v160, v20
	v_fmac_f32_e32 v177, v161, v21
	v_fmac_f32_e32 v178, v162, v22
	v_fmac_f32_e32 v179, v163, v23
	v_fmac_f32_e32 v180, v164, v24
	v_fmac_f32_e32 v181, v165, v25
	v_fmac_f32_e32 v182, v166, v26
	v_fmac_f32_e32 v183, v167, v27
	v_fmac_f32_e32 v184, v168, v28
	v_fmac_f32_e32 v185, v169, v29
	v_fmac_f32_e32 v186, v170, v30
	v_fmac_f32_e32 v187, v171, v31
	v_fmac_f32_e32 v188, v172, v32
	v_fmac_f32_e32 v189, v173, v33
	v_fmac_f32_e32 v190, v174, v34
	v_fmac_f32_e32 v191, v175, v35
	global_store_dwordx4 v1, v[176:179], s[48:49] offset:0
	global_store_dwordx4 v1, v[180:183], s[48:49] offset:1024
	global_store_dwordx4 v1, v[184:187], s[48:49] offset:2048
	global_store_dwordx4 v1, v[188:191], s[48:49] offset:3072
	v_mul_f32_e32 v10, v144, v144
	v_fmac_f32_e32 v10, v145, v145
	v_fmac_f32_e32 v10, v146, v146
	v_fmac_f32_e32 v10, v147, v147
	v_fmac_f32_e32 v10, v148, v148
	v_fmac_f32_e32 v10, v149, v149
	v_fmac_f32_e32 v10, v150, v150
	v_fmac_f32_e32 v10, v151, v151
	v_fmac_f32_e32 v10, v152, v152
	v_fmac_f32_e32 v10, v153, v153
	v_fmac_f32_e32 v10, v154, v154
	v_fmac_f32_e32 v10, v155, v155
	v_fmac_f32_e32 v10, v156, v156
	v_fmac_f32_e32 v10, v157, v157
	v_fmac_f32_e32 v10, v158, v158
	v_fmac_f32_e32 v10, v159, v159
	v_mul_f32_e32 v11, v176, v176
	v_fmac_f32_e32 v11, v177, v177
	v_fmac_f32_e32 v11, v178, v178
	v_fmac_f32_e32 v11, v179, v179
	v_fmac_f32_e32 v11, v180, v180
	v_fmac_f32_e32 v11, v181, v181
	v_fmac_f32_e32 v11, v182, v182
	v_fmac_f32_e32 v11, v183, v183
	v_fmac_f32_e32 v11, v184, v184
	v_fmac_f32_e32 v11, v185, v185
	v_fmac_f32_e32 v11, v186, v186
	v_fmac_f32_e32 v11, v187, v187
	v_fmac_f32_e32 v11, v188, v188
	v_fmac_f32_e32 v11, v189, v189
	v_fmac_f32_e32 v11, v190, v190
	v_fmac_f32_e32 v11, v191, v191
	ds_bpermute_b32 v12, v4, v10
	ds_bpermute_b32 v13, v4, v11
	s_waitcnt lgkmcnt(0)
	v_add_f32_e32 v10, v10, v12
	v_add_f32_e32 v11, v11, v13
	ds_bpermute_b32 v12, v5, v10
	ds_bpermute_b32 v13, v5, v11
	s_waitcnt lgkmcnt(0)
	v_add_f32_e32 v10, v10, v12
	v_add_f32_e32 v11, v11, v13
	ds_bpermute_b32 v12, v6, v10
	ds_bpermute_b32 v13, v6, v11
	s_waitcnt lgkmcnt(0)
	v_add_f32_e32 v10, v10, v12
	v_add_f32_e32 v11, v11, v13
	ds_bpermute_b32 v12, v7, v10
	ds_bpermute_b32 v13, v7, v11
	s_waitcnt lgkmcnt(0)
	v_add_f32_e32 v10, v10, v12
	v_add_f32_e32 v11, v11, v13
	ds_bpermute_b32 v12, v8, v10
	ds_bpermute_b32 v13, v8, v11
	s_waitcnt lgkmcnt(0)
	v_add_f32_e32 v10, v10, v12
	v_add_f32_e32 v11, v11, v13
	ds_bpermute_b32 v12, v9, v10
	ds_bpermute_b32 v13, v9, v11
	s_waitcnt lgkmcnt(0)
	v_add_f32_e32 v10, v10, v12
	v_add_f32_e32 v11, v11, v13
	v_fma_f32 v14, v10, s17, v3
	v_fma_f32 v15, v11, s17, v3
	v_rsq_f32_e32 v14, v14
	v_rsq_f32_e32 v15, v15
	s_nop 0
	v_mul_f32_e32 v128, v144, v14
	v_mul_f32_e32 v129, v145, v14
	v_mul_f32_e32 v130, v146, v14
	v_mul_f32_e32 v131, v147, v14
	v_mul_f32_e32 v132, v148, v14
	v_mul_f32_e32 v133, v149, v14
	v_mul_f32_e32 v134, v150, v14
	v_mul_f32_e32 v135, v151, v14
	v_mul_f32_e32 v136, v152, v14
	v_mul_f32_e32 v137, v153, v14
	v_mul_f32_e32 v138, v154, v14
	v_mul_f32_e32 v139, v155, v14
	v_mul_f32_e32 v140, v156, v14
	v_mul_f32_e32 v141, v157, v14
	v_mul_f32_e32 v142, v158, v14
	v_mul_f32_e32 v143, v159, v14
	v_mul_f32_e32 v128, v128, v36
	v_mul_f32_e32 v129, v129, v37
	v_mul_f32_e32 v130, v130, v38
	v_mul_f32_e32 v131, v131, v39
	v_mul_f32_e32 v132, v132, v40
	v_mul_f32_e32 v133, v133, v41
	v_mul_f32_e32 v134, v134, v42
	v_mul_f32_e32 v135, v135, v43
	v_mul_f32_e32 v136, v136, v44
	v_mul_f32_e32 v137, v137, v45
	v_mul_f32_e32 v138, v138, v46
	v_mul_f32_e32 v139, v139, v47
	v_mul_f32_e32 v140, v140, v48
	v_mul_f32_e32 v141, v141, v49
	v_mul_f32_e32 v142, v142, v50
	v_mul_f32_e32 v143, v143, v51
	v_cvt_pk_bf16_f32 v128, v128, v129
	v_cvt_pk_bf16_f32 v129, v130, v131
	v_cvt_pk_bf16_f32 v132, v132, v133
	v_cvt_pk_bf16_f32 v133, v134, v135
	v_cvt_pk_bf16_f32 v136, v136, v137
	v_cvt_pk_bf16_f32 v137, v138, v139
	v_cvt_pk_bf16_f32 v140, v140, v141
	v_cvt_pk_bf16_f32 v141, v142, v143
	global_store_dwordx2 v2, v[128:129], s[42:43] offset:0
	global_store_dwordx2 v2, v[132:133], s[42:43] offset:512
	global_store_dwordx2 v2, v[136:137], s[42:43] offset:1024
	global_store_dwordx2 v2, v[140:141], s[42:43] offset:1536
	v_mul_f32_e32 v160, v176, v15
	v_mul_f32_e32 v161, v177, v15
	v_mul_f32_e32 v162, v178, v15
	v_mul_f32_e32 v163, v179, v15
	v_mul_f32_e32 v164, v180, v15
	v_mul_f32_e32 v165, v181, v15
	v_mul_f32_e32 v166, v182, v15
	v_mul_f32_e32 v167, v183, v15
	v_mul_f32_e32 v168, v184, v15
	v_mul_f32_e32 v169, v185, v15
	v_mul_f32_e32 v170, v186, v15
	v_mul_f32_e32 v171, v187, v15
	v_mul_f32_e32 v172, v188, v15
	v_mul_f32_e32 v173, v189, v15
	v_mul_f32_e32 v174, v190, v15
	v_mul_f32_e32 v175, v191, v15
	v_mul_f32_e32 v160, v160, v36
	v_mul_f32_e32 v161, v161, v37
	v_mul_f32_e32 v162, v162, v38
	v_mul_f32_e32 v163, v163, v39
	v_mul_f32_e32 v164, v164, v40
	v_mul_f32_e32 v165, v165, v41
	v_mul_f32_e32 v166, v166, v42
	v_mul_f32_e32 v167, v167, v43
	v_mul_f32_e32 v168, v168, v44
	v_mul_f32_e32 v169, v169, v45
	v_mul_f32_e32 v170, v170, v46
	v_mul_f32_e32 v171, v171, v47
	v_mul_f32_e32 v172, v172, v48
	v_mul_f32_e32 v173, v173, v49
	v_mul_f32_e32 v174, v174, v50
	v_mul_f32_e32 v175, v175, v51
	v_cvt_pk_bf16_f32 v160, v160, v161
	v_cvt_pk_bf16_f32 v161, v162, v163
	v_cvt_pk_bf16_f32 v164, v164, v165
	v_cvt_pk_bf16_f32 v165, v166, v167
	v_cvt_pk_bf16_f32 v168, v168, v169
	v_cvt_pk_bf16_f32 v169, v170, v171
	v_cvt_pk_bf16_f32 v172, v172, v173
	v_cvt_pk_bf16_f32 v173, v174, v175
	global_store_dwordx2 v2, v[160:161], s[50:51] offset:0
	global_store_dwordx2 v2, v[164:165], s[50:51] offset:512
	global_store_dwordx2 v2, v[168:169], s[50:51] offset:1024
	global_store_dwordx2 v2, v[172:173], s[50:51] offset:1536
	s_and_b32 s18, s16, 3
	s_cmp_lg_u32 s18, 0
	s_cbranch_scc1 .Lrows4_end
	s_lshr_b32 s54, s16, 2
	s_add_u32 s53, s54, 0x4000
	s_lshl_b32 s18, s53, 12
	s_lshl_b32 s19, s53, 11
	s_sub_u32 s52, s18, 0x4000000
	s_add_u32 s20, s14, s52
	s_addc_u32 s21, s15, 0
	s_add_u32 s24, s4, s18
	s_addc_u32 s25, s5, 0
	s_add_u32 s26, s6, s19
	s_addc_u32 s27, s7, 0
	s_add_u32 s26, s26, 0x3100000
	s_addc_u32 s27, s27, 0
	s_lshl_b32 s18, s54, 12
	s_add_u32 s22, s6, s18
	s_addc_u32 s23, s7, 0
	s_add_u32 s22, s22, 0x7400000
	s_addc_u32 s23, s23, 0
	global_load_dwordx4 v[64:67], v1, s[22:23] offset:0
	global_load_dwordx4 v[68:71], v1, s[22:23] offset:1024
	global_load_dwordx4 v[72:75], v1, s[22:23] offset:2048
	global_load_dwordx4 v[76:79], v1, s[22:23] offset:3072
	s_add_u32 s22, s22, 0x200000
	s_addc_u32 s23, s23, 0
	global_load_dwordx4 v[80:83], v1, s[22:23] offset:0
	global_load_dwordx4 v[84:87], v1, s[22:23] offset:1024
	global_load_dwordx4 v[88:91], v1, s[22:23] offset:2048
	global_load_dwordx4 v[92:95], v1, s[22:23] offset:3072
	global_load_dwordx4 v[192:195], v1, s[20:21] offset:0
	global_load_dwordx4 v[196:199], v1, s[20:21] offset:1024
	global_load_dwordx4 v[200:203], v1, s[20:21] offset:2048
	global_load_dwordx4 v[204:207], v1, s[20:21] offset:3072
	s_waitcnt vmcnt(0)
	v_add_f32_e32 v64, v64, v80
	v_add_f32_e32 v65, v65, v81
	v_add_f32_e32 v66, v66, v82
	v_add_f32_e32 v67, v67, v83
	v_add_f32_e32 v68, v68, v84
	v_add_f32_e32 v69, v69, v85
	v_add_f32_e32 v70, v70, v86
	v_add_f32_e32 v71, v71, v87
	v_add_f32_e32 v72, v72, v88
	v_add_f32_e32 v73, v73, v89
	v_add_f32_e32 v74, v74, v90
	v_add_f32_e32 v75, v75, v91
	v_add_f32_e32 v76, v76, v92
	v_add_f32_e32 v77, v77, v93
	v_add_f32_e32 v78, v78, v94
	v_add_f32_e32 v79, v79, v95
	v_mul_f32_e32 v10, v64, v64
	v_fmac_f32_e32 v10, v65, v65
	v_fmac_f32_e32 v10, v66, v66
	v_fmac_f32_e32 v10, v67, v67
	v_fmac_f32_e32 v10, v68, v68
	v_fmac_f32_e32 v10, v69, v69
	v_fmac_f32_e32 v10, v70, v70
	v_fmac_f32_e32 v10, v71, v71
	v_fmac_f32_e32 v10, v72, v72
	v_fmac_f32_e32 v10, v73, v73
	v_fmac_f32_e32 v10, v74, v74
	v_fmac_f32_e32 v10, v75, v75
	v_fmac_f32_e32 v10, v76, v76
	v_fmac_f32_e32 v10, v77, v77
	v_fmac_f32_e32 v10, v78, v78
	v_fmac_f32_e32 v10, v79, v79
	ds_bpermute_b32 v12, v4, v10
	s_waitcnt lgkmcnt(0)
	v_add_f32_e32 v10, v10, v12
	ds_bpermute_b32 v12, v5, v10
	s_waitcnt lgkmcnt(0)
	v_add_f32_e32 v10, v10, v12
	ds_bpermute_b32 v12, v6, v10
	s_waitcnt lgkmcnt(0)
	v_add_f32_e32 v10, v10, v12
	ds_bpermute_b32 v12, v7, v10
	s_waitcnt lgkmcnt(0)
	v_add_f32_e32 v10, v10, v12
	ds_bpermute_b32 v12, v8, v10
	s_waitcnt lgkmcnt(0)
	v_add_f32_e32 v10, v10, v12
	ds_bpermute_b32 v12, v9, v10
	s_waitcnt lgkmcnt(0)
	v_add_f32_e32 v10, v10, v12
	v_fma_f32 v14, v10, s17, v3
	v_rsq_f32_e32 v14, v14
	s_nop 0
	v_mul_f32_e32 v64, v64, v14
	v_mul_f32_e32 v65, v65, v14
	v_mul_f32_e32 v66, v66, v14
	v_mul_f32_e32 v67, v67, v14
	v_mul_f32_e32 v68, v68, v14
	v_mul_f32_e32 v69, v69, v14
	v_mul_f32_e32 v70, v70, v14
	v_mul_f32_e32 v71, v71, v14
	v_mul_f32_e32 v72, v72, v14
	v_mul_f32_e32 v73, v73, v14
	v_mul_f32_e32 v74, v74, v14
	v_mul_f32_e32 v75, v75, v14
	v_mul_f32_e32 v76, v76, v14
	v_mul_f32_e32 v77, v77, v14
	v_mul_f32_e32 v78, v78, v14
	v_mul_f32_e32 v79, v79, v14
	v_fmac_f32_e32 v192, v64, v20
	v_fmac_f32_e32 v193, v65, v21
	v_fmac_f32_e32 v194, v66, v22
	v_fmac_f32_e32 v195, v67, v23
	v_fmac_f32_e32 v196, v68, v24
	v_fmac_f32_e32 v197, v69, v25
	v_fmac_f32_e32 v198, v70, v26
	v_fmac_f32_e32 v199, v71, v27
	v_fmac_f32_e32 v200, v72, v28
	v_fmac_f32_e32 v201, v73, v29
	v_fmac_f32_e32 v202, v74, v30
	v_fmac_f32_e32 v203, v75, v31
	v_fmac_f32_e32 v204, v76, v32
	v_fmac_f32_e32 v205, v77, v33
	v_fmac_f32_e32 v206, v78, v34
	v_fmac_f32_e32 v207, v79, v35
	global_store_dwordx4 v1, v[192:195], s[24:25] offset:0
	global_store_dwordx4 v1, v[196:199], s[24:25] offset:1024
	global_store_dwordx4 v1, v[200:203], s[24:25] offset:2048
	global_store_dwordx4 v1, v[204:207], s[24:25] offset:3072
	v_mul_f32_e32 v10, v192, v192
	v_fmac_f32_e32 v10, v193, v193
	v_fmac_f32_e32 v10, v194, v194
	v_fmac_f32_e32 v10, v195, v195
	v_fmac_f32_e32 v10, v196, v196
	v_fmac_f32_e32 v10, v197, v197
	v_fmac_f32_e32 v10, v198, v198
	v_fmac_f32_e32 v10, v199, v199
	v_fmac_f32_e32 v10, v200, v200
	v_fmac_f32_e32 v10, v201, v201
	v_fmac_f32_e32 v10, v202, v202
	v_fmac_f32_e32 v10, v203, v203
	v_fmac_f32_e32 v10, v204, v204
	v_fmac_f32_e32 v10, v205, v205
	v_fmac_f32_e32 v10, v206, v206
	v_fmac_f32_e32 v10, v207, v207
	ds_bpermute_b32 v12, v4, v10
	s_waitcnt lgkmcnt(0)
	v_add_f32_e32 v10, v10, v12
	ds_bpermute_b32 v12, v5, v10
	s_waitcnt lgkmcnt(0)
	v_add_f32_e32 v10, v10, v12
	ds_bpermute_b32 v12, v6, v10
	s_waitcnt lgkmcnt(0)
	v_add_f32_e32 v10, v10, v12
	ds_bpermute_b32 v12, v7, v10
	s_waitcnt lgkmcnt(0)
	v_add_f32_e32 v10, v10, v12
	ds_bpermute_b32 v12, v8, v10
	s_waitcnt lgkmcnt(0)
	v_add_f32_e32 v10, v10, v12
	ds_bpermute_b32 v12, v9, v10
	s_waitcnt lgkmcnt(0)
	v_add_f32_e32 v10, v10, v12
	v_fma_f32 v14, v10, s17, v3
	v_rsq_f32_e32 v14, v14
	s_nop 0
	v_mul_f32_e32 v64, v192, v14
	v_mul_f32_e32 v65, v193, v14
	v_mul_f32_e32 v66, v194, v14
	v_mul_f32_e32 v67, v195, v14
	v_mul_f32_e32 v68, v196, v14
	v_mul_f32_e32 v69, v197, v14
	v_mul_f32_e32 v70, v198, v14
	v_mul_f32_e32 v71, v199, v14
	v_mul_f32_e32 v72, v200, v14
	v_mul_f32_e32 v73, v201, v14
	v_mul_f32_e32 v74, v202, v14
	v_mul_f32_e32 v75, v203, v14
	v_mul_f32_e32 v76, v204, v14
	v_mul_f32_e32 v77, v205, v14
	v_mul_f32_e32 v78, v206, v14
	v_mul_f32_e32 v79, v207, v14
	v_mul_f32_e32 v64, v64, v36
	v_mul_f32_e32 v65, v65, v37
	v_mul_f32_e32 v66, v66, v38
	v_mul_f32_e32 v67, v67, v39
	v_mul_f32_e32 v68, v68, v40
	v_mul_f32_e32 v69, v69, v41
	v_mul_f32_e32 v70, v70, v42
	v_mul_f32_e32 v71, v71, v43
	v_mul_f32_e32 v72, v72, v44
	v_mul_f32_e32 v73, v73, v45
	v_mul_f32_e32 v74, v74, v46
	v_mul_f32_e32 v75, v75, v47
	v_mul_f32_e32 v76, v76, v48
	v_mul_f32_e32 v77, v77, v49
	v_mul_f32_e32 v78, v78, v50
	v_mul_f32_e32 v79, v79, v51
	v_cvt_pk_bf16_f32 v64, v64, v65
	v_cvt_pk_bf16_f32 v65, v66, v67
	v_cvt_pk_bf16_f32 v68, v68, v69
	v_cvt_pk_bf16_f32 v69, v70, v71
	v_cvt_pk_bf16_f32 v72, v72, v73
	v_cvt_pk_bf16_f32 v73, v74, v75
	v_cvt_pk_bf16_f32 v76, v76, v77
	v_cvt_pk_bf16_f32 v77, v78, v79
	global_store_dwordx2 v2, v[64:65], s[26:27] offset:0
	global_store_dwordx2 v2, v[68:69], s[26:27] offset:512
	global_store_dwordx2 v2, v[72:73], s[26:27] offset:1024
	global_store_dwordx2 v2, v[76:77], s[26:27] offset:1536

.Lrows4_orig:
	s_load_dword s3, s[0:1], 0xe8
	s_load_dwordx4 s[8:11], s[0:1], 0xa8
	s_mov_b32 s4, s2
	s_waitcnt lgkmcnt(0)
	s_mov_b32 s4, s3
	s_cmp_lg_u64 s[10:11], 0
	v_and_b32_e32 v32, 63, v0
	s_cselect_b64 s[4:5], -1, 0
	v_readfirstlane_b32 s12, v0
	v_mov_b32_e32 v113, 0
	s_and_b64 vcc, exec, s[4:5]
	v_lshlrev_b32_e32 v112, 4, v32
	v_mov_b32_e32 v0, 0
	v_mov_b32_e32 v1, 0
	v_mov_b32_e32 v2, 0
	v_mov_b32_e32 v3, 0
	s_cbranch_vccz .LBB4_2
	global_load_dwordx4 v[0:3], v112, s[10:11]

	.amdhsa_kernel _Z10fwd_kernelILi4ELi5EEv4Args
		.amdhsa_group_segment_fixed_size 0
		.amdhsa_private_segment_fixed_size 0
		.amdhsa_kernarg_size 488
		.amdhsa_user_sgpr_count 2
		.amdhsa_user_sgpr_dispatch_ptr 0
		.amdhsa_user_sgpr_queue_ptr 0
		.amdhsa_user_sgpr_kernarg_segment_ptr 1
		.amdhsa_user_sgpr_dispatch_id 0
		.amdhsa_user_sgpr_kernarg_preload_length 0
		.amdhsa_user_sgpr_kernarg_preload_offset 0
		.amdhsa_user_sgpr_private_segment_size 0
		.amdhsa_uses_dynamic_stack 0
		.amdhsa_enable_private_segment 0
		.amdhsa_system_sgpr_workgroup_id_x 1
		.amdhsa_system_sgpr_workgroup_id_y 0
		.amdhsa_system_sgpr_workgroup_id_z 0
		.amdhsa_system_sgpr_workgroup_info 0
		.amdhsa_system_vgpr_workitem_id 0
		.amdhsa_next_free_vgpr 208
		.amdhsa_next_free_sgpr 56
		.amdhsa_accum_offset 208
		.amdhsa_reserve_vcc 1
		.amdhsa_float_round_mode_32 0
		.amdhsa_float_round_mode_16_64 0
		.amdhsa_float_denorm_mode_32 3
		.amdhsa_float_denorm_mode_16_64 3
		.amdhsa_dx10_clamp 1
		.amdhsa_ieee_mode 1
		.amdhsa_fp16_overflow 0
		.amdhsa_tg_split 0
		.amdhsa_exception_fp_ieee_invalid_op 0
		.amdhsa_exception_fp_denorm_src 0
		.amdhsa_exception_fp_ieee_div_zero 0
		.amdhsa_exception_fp_ieee_overflow 0
		.amdhsa_exception_fp_ieee_underflow 0
		.amdhsa_exception_fp_ieee_inexact 0
		.amdhsa_exception_int_div_zero 0
	.end_amdhsa_kernel

_Z10fwd_kernelILi5ELi6EEv4Args:
	s_load_dword s3, s[0:1], 0xe8
	v_mov_b32_e32 v1, v0
	s_waitcnt lgkmcnt(0)
	s_load_dwordx2 s[16:17], s[0:1], 0xd8
	v_readfirstlane_b32 s4, v0
	s_lshr_b32 s4, s4, 6
	s_and_b32 s5, s4, 3
	s_lshr_b32 s6, s4, 2
	s_mov_b32 s12, s2
	s_cmpk_gt_u32 s12, 0xff
	s_cbranch_scc1 .Lsmp5_done
	v_and_b32_e32 v202, 15, v0
	v_bfe_u32 v203, v0, 4, 2
	v_and_b32_e32 v205, 63, v0
	v_lshlrev_b32_e32 v204, 11, v202
	v_lshl_add_u32 v204, v203, 4, v204
	s_lshl_b32 s7, s5, 9
	v_add_u32_e32 v204, s7, v204
	s_lshl_b32 s7, s4, 14
	v_lshl_add_u32 v206, v205, 4, s7
	s_lshl_b32 s7, s6, 16
	s_lshl_b32 s8, s5, 12
	s_add_u32 s7, s7, s8
	v_lshl_add_u32 v207, v205, 4, s7
	s_waitcnt lgkmcnt(0)
	v_lshlrev_b32_e32 v208, 13, v202
	v_lshl_add_u32 v208, v203, 3, v208
	s_lshl_b32 s7, s5, 17
	v_add_u32_e32 v208, s7, v208
.Lsmp5_unit:
	s_add_u32 s20, s16, 0x5100000
	s_addc_u32 s21, s17, 0
	s_add_u32 s22, s16, 0x900000
	s_addc_u32 s23, s17, 0
	s_add_u32 s24, s16, 0xf400000
	s_addc_u32 s25, s17, 0
	s_and_b32 s28, s12, 7
	s_lshr_b32 s29, s12, 3
	s_lshl_b32 s29, s29, 1
	s_add_u32 s29, s29, s6
	s_lshr_b32 s30, s29, 3
	s_lshl_b32 s28, s28, 3
	s_add_u32 s30, s30, s28
	s_and_b32 s31, s29, 7
	s_lshl_b32 s33, s31, 17
	s_lshl_b32 s34, s30, 17
	v_add_u32_e32 v194, s33, v204
	v_add_u32_e32 v198, s34, v204
	v_add_u32_e32 v195, s33, v204
	v_add_u32_e32 v199, s34, v204
	v_add_u32_e32 v196, s33, v204
	v_add_u32_e32 v200, s34, v204
	v_add_u32_e32 v197, s33, v204
	v_add_u32_e32 v201, s34, v204
	v_add_u32_e32 v195, 0x8000, v195
	v_add_u32_e32 v199, 0x8000, v199
	v_add_u32_e32 v196, 0x10000, v196
	v_add_u32_e32 v200, 0x10000, v200
	v_add_u32_e32 v197, 0x18000, v197
	v_add_u32_e32 v201, 0x18000, v201
	s_lshl_b32 s33, s31, 19
	s_lshl_b32 s34, s30, 7
	s_add_u32 s33, s33, s34
	v_add_u32_e32 v209, s33, v208
	global_load_dwordx4 v[66:69], v194, s[20:21] offset:0
	global_load_dwordx4 v[82:85], v198, s[22:23] offset:0
	global_load_dwordx4 v[70:73], v195, s[20:21] offset:0
	global_load_dwordx4 v[86:89], v199, s[22:23] offset:0
	global_load_dwordx4 v[74:77], v196, s[20:21] offset:0
	global_load_dwordx4 v[90:93], v200, s[22:23] offset:0
	global_load_dwordx4 v[78:81], v197, s[20:21] offset:0
	global_load_dwordx4 v[94:97], v201, s[22:23] offset:0
	global_load_dwordx4 v[98:101], v194, s[20:21] offset:64
	global_load_dwordx4 v[114:117], v198, s[22:23] offset:64
	global_load_dwordx4 v[102:105], v195, s[20:21] offset:64
	global_load_dwordx4 v[118:121], v199, s[22:23] offset:64
	global_load_dwordx4 v[106:109], v196, s[20:21] offset:64
	global_load_dwordx4 v[122:125], v200, s[22:23] offset:64
	global_load_dwordx4 v[110:113], v197, s[20:21] offset:64
	global_load_dwordx4 v[126:129], v201, s[22:23] offset:64
	global_load_dwordx4 v[130:133], v194, s[20:21] offset:128
	global_load_dwordx4 v[146:149], v198, s[22:23] offset:128
	global_load_dwordx4 v[134:137], v195, s[20:21] offset:128
	global_load_dwordx4 v[150:153], v199, s[22:23] offset:128
	global_load_dwordx4 v[138:141], v196, s[20:21] offset:128
	global_load_dwordx4 v[154:157], v200, s[22:23] offset:128
	global_load_dwordx4 v[142:145], v197, s[20:21] offset:128
	global_load_dwordx4 v[158:161], v201, s[22:23] offset:128
	global_load_dwordx4 v[162:165], v194, s[20:21] offset:192
	global_load_dwordx4 v[178:181], v198, s[22:23] offset:192
	global_load_dwordx4 v[166:169], v195, s[20:21] offset:192
	global_load_dwordx4 v[182:185], v199, s[22:23] offset:192
	global_load_dwordx4 v[170:173], v196, s[20:21] offset:192
	global_load_dwordx4 v[186:189], v200, s[22:23] offset:192
	global_load_dwordx4 v[174:177], v197, s[20:21] offset:192
	global_load_dwordx4 v[190:193], v201, s[22:23] offset:192
	s_waitcnt vmcnt(28)
	v_mfma_f32_16x16x32_bf16 v[2:5], v[82:85], v[66:69], 0
	v_mfma_f32_16x16x32_bf16 v[6:9], v[86:89], v[66:69], 0
	v_mfma_f32_16x16x32_bf16 v[18:21], v[82:85], v[70:73], 0
	v_mfma_f32_16x16x32_bf16 v[22:25], v[86:89], v[70:73], 0
	s_waitcnt vmcnt(24)
	v_mfma_f32_16x16x32_bf16 v[10:13], v[90:93], v[66:69], 0
	v_mfma_f32_16x16x32_bf16 v[14:17], v[94:97], v[66:69], 0
	v_mfma_f32_16x16x32_bf16 v[26:29], v[90:93], v[70:73], 0
	v_mfma_f32_16x16x32_bf16 v[30:33], v[94:97], v[70:73], 0
	v_mfma_f32_16x16x32_bf16 v[34:37], v[82:85], v[74:77], 0
	v_mfma_f32_16x16x32_bf16 v[38:41], v[86:89], v[74:77], 0
	v_mfma_f32_16x16x32_bf16 v[42:45], v[90:93], v[74:77], 0
	v_mfma_f32_16x16x32_bf16 v[46:49], v[94:97], v[74:77], 0
	v_mfma_f32_16x16x32_bf16 v[50:53], v[82:85], v[78:81], 0
	v_mfma_f32_16x16x32_bf16 v[54:57], v[86:89], v[78:81], 0
	v_mfma_f32_16x16x32_bf16 v[58:61], v[90:93], v[78:81], 0
	v_mfma_f32_16x16x32_bf16 v[62:65], v[94:97], v[78:81], 0
	global_load_dwordx4 v[66:69], v194, s[20:21] offset:256
	global_load_dwordx4 v[82:85], v198, s[22:23] offset:256
	global_load_dwordx4 v[70:73], v195, s[20:21] offset:256
	global_load_dwordx4 v[86:89], v199, s[22:23] offset:256
	global_load_dwordx4 v[74:77], v196, s[20:21] offset:256
	global_load_dwordx4 v[90:93], v200, s[22:23] offset:256
	global_load_dwordx4 v[78:81], v197, s[20:21] offset:256
	global_load_dwordx4 v[94:97], v201, s[22:23] offset:256
	s_waitcnt vmcnt(28)
	v_mfma_f32_16x16x32_bf16 v[2:5], v[114:117], v[98:101], v[2:5]
	v_mfma_f32_16x16x32_bf16 v[6:9], v[118:121], v[98:101], v[6:9]
	v_mfma_f32_16x16x32_bf16 v[18:21], v[114:117], v[102:105], v[18:21]
	v_mfma_f32_16x16x32_bf16 v[22:25], v[118:121], v[102:105], v[22:25]
	s_waitcnt vmcnt(24)
	v_mfma_f32_16x16x32_bf16 v[10:13], v[122:125], v[98:101], v[10:13]
	v_mfma_f32_16x16x32_bf16 v[14:17], v[126:129], v[98:101], v[14:17]
	v_mfma_f32_16x16x32_bf16 v[26:29], v[122:125], v[102:105], v[26:29]
	v_mfma_f32_16x16x32_bf16 v[30:33], v[126:129], v[102:105], v[30:33]
	v_mfma_f32_16x16x32_bf16 v[34:37], v[114:117], v[106:109], v[34:37]
	v_mfma_f32_16x16x32_bf16 v[38:41], v[118:121], v[106:109], v[38:41]
	v_mfma_f32_16x16x32_bf16 v[42:45], v[122:125], v[106:109], v[42:45]
	v_mfma_f32_16x16x32_bf16 v[46:49], v[126:129], v[106:109], v[46:49]
	v_mfma_f32_16x16x32_bf16 v[50:53], v[114:117], v[110:113], v[50:53]
	v_mfma_f32_16x16x32_bf16 v[54:57], v[118:121], v[110:113], v[54:57]
	v_mfma_f32_16x16x32_bf16 v[58:61], v[122:125], v[110:113], v[58:61]
	v_mfma_f32_16x16x32_bf16 v[62:65], v[126:129], v[110:113], v[62:65]
	global_load_dwordx4 v[98:101], v194, s[20:21] offset:320
	global_load_dwordx4 v[114:117], v198, s[22:23] offset:320
	global_load_dwordx4 v[102:105], v195, s[20:21] offset:320
	global_load_dwordx4 v[118:121], v199, s[22:23] offset:320
	global_load_dwordx4 v[106:109], v196, s[20:21] offset:320
	global_load_dwordx4 v[122:125], v200, s[22:23] offset:320
	global_load_dwordx4 v[110:113], v197, s[20:21] offset:320
	global_load_dwordx4 v[126:129], v201, s[22:23] offset:320
	s_waitcnt vmcnt(28)
	v_mfma_f32_16x16x32_bf16 v[2:5], v[146:149], v[130:133], v[2:5]
	v_mfma_f32_16x16x32_bf16 v[6:9], v[150:153], v[130:133], v[6:9]
	v_mfma_f32_16x16x32_bf16 v[18:21], v[146:149], v[134:137], v[18:21]
	v_mfma_f32_16x16x32_bf16 v[22:25], v[150:153], v[134:137], v[22:25]
	s_waitcnt vmcnt(24)
	v_mfma_f32_16x16x32_bf16 v[10:13], v[154:157], v[130:133], v[10:13]
	v_mfma_f32_16x16x32_bf16 v[14:17], v[158:161], v[130:133], v[14:17]
	v_mfma_f32_16x16x32_bf16 v[26:29], v[154:157], v[134:137], v[26:29]
	v_mfma_f32_16x16x32_bf16 v[30:33], v[158:161], v[134:137], v[30:33]
	v_mfma_f32_16x16x32_bf16 v[34:37], v[146:149], v[138:141], v[34:37]
	v_mfma_f32_16x16x32_bf16 v[38:41], v[150:153], v[138:141], v[38:41]
	v_mfma_f32_16x16x32_bf16 v[42:45], v[154:157], v[138:141], v[42:45]
	v_mfma_f32_16x16x32_bf16 v[46:49], v[158:161], v[138:141], v[46:49]
	v_mfma_f32_16x16x32_bf16 v[50:53], v[146:149], v[142:145], v[50:53]
	v_mfma_f32_16x16x32_bf16 v[54:57], v[150:153], v[142:145], v[54:57]
	v_mfma_f32_16x16x32_bf16 v[58:61], v[154:157], v[142:145], v[58:61]
	v_mfma_f32_16x16x32_bf16 v[62:65], v[158:161], v[142:145], v[62:65]
	global_load_dwordx4 v[130:133], v194, s[20:21] offset:384
	global_load_dwordx4 v[146:149], v198, s[22:23] offset:384
	global_load_dwordx4 v[134:137], v195, s[20:21] offset:384
	global_load_dwordx4 v[150:153], v199, s[22:23] offset:384
	global_load_dwordx4 v[138:141], v196, s[20:21] offset:384
	global_load_dwordx4 v[154:157], v200, s[22:23] offset:384
	global_load_dwordx4 v[142:145], v197, s[20:21] offset:384
	global_load_dwordx4 v[158:161], v201, s[22:23] offset:384
	s_waitcnt vmcnt(28)
	v_mfma_f32_16x16x32_bf16 v[2:5], v[178:181], v[162:165], v[2:5]
	v_mfma_f32_16x16x32_bf16 v[6:9], v[182:185], v[162:165], v[6:9]
	v_mfma_f32_16x16x32_bf16 v[18:21], v[178:181], v[166:169], v[18:21]
	v_mfma_f32_16x16x32_bf16 v[22:25], v[182:185], v[166:169], v[22:25]
	s_waitcnt vmcnt(24)
	v_mfma_f32_16x16x32_bf16 v[10:13], v[186:189], v[162:165], v[10:13]
	v_mfma_f32_16x16x32_bf16 v[14:17], v[190:193], v[162:165], v[14:17]
	v_mfma_f32_16x16x32_bf16 v[26:29], v[186:189], v[166:169], v[26:29]
	v_mfma_f32_16x16x32_bf16 v[30:33], v[190:193], v[166:169], v[30:33]
	v_mfma_f32_16x16x32_bf16 v[34:37], v[178:181], v[170:173], v[34:37]
	v_mfma_f32_16x16x32_bf16 v[38:41], v[182:185], v[170:173], v[38:41]
	v_mfma_f32_16x16x32_bf16 v[42:45], v[186:189], v[170:173], v[42:45]
	v_mfma_f32_16x16x32_bf16 v[46:49], v[190:193], v[170:173], v[46:49]
	v_mfma_f32_16x16x32_bf16 v[50:53], v[178:181], v[174:177], v[50:53]
	v_mfma_f32_16x16x32_bf16 v[54:57], v[182:185], v[174:177], v[54:57]
	v_mfma_f32_16x16x32_bf16 v[58:61], v[186:189], v[174:177], v[58:61]
	v_mfma_f32_16x16x32_bf16 v[62:65], v[190:193], v[174:177], v[62:65]
	global_load_dwordx4 v[162:165], v194, s[20:21] offset:448
	global_load_dwordx4 v[178:181], v198, s[22:23] offset:448
	global_load_dwordx4 v[166:169], v195, s[20:21] offset:448
	global_load_dwordx4 v[182:185], v199, s[22:23] offset:448
	global_load_dwordx4 v[170:173], v196, s[20:21] offset:448
	global_load_dwordx4 v[186:189], v200, s[22:23] offset:448
	global_load_dwordx4 v[174:177], v197, s[20:21] offset:448
	global_load_dwordx4 v[190:193], v201, s[22:23] offset:448
	s_waitcnt vmcnt(28)
	v_mfma_f32_16x16x32_bf16 v[2:5], v[82:85], v[66:69], v[2:5]
	v_mfma_f32_16x16x32_bf16 v[6:9], v[86:89], v[66:69], v[6:9]
	v_mfma_f32_16x16x32_bf16 v[18:21], v[82:85], v[70:73], v[18:21]
	v_mfma_f32_16x16x32_bf16 v[22:25], v[86:89], v[70:73], v[22:25]
	s_waitcnt vmcnt(24)
	v_mfma_f32_16x16x32_bf16 v[10:13], v[90:93], v[66:69], v[10:13]
	v_mfma_f32_16x16x32_bf16 v[14:17], v[94:97], v[66:69], v[14:17]
	v_mfma_f32_16x16x32_bf16 v[26:29], v[90:93], v[70:73], v[26:29]
	v_mfma_f32_16x16x32_bf16 v[30:33], v[94:97], v[70:73], v[30:33]
	v_mfma_f32_16x16x32_bf16 v[34:37], v[82:85], v[74:77], v[34:37]
	v_mfma_f32_16x16x32_bf16 v[38:41], v[86:89], v[74:77], v[38:41]
	v_mfma_f32_16x16x32_bf16 v[42:45], v[90:93], v[74:77], v[42:45]
	v_mfma_f32_16x16x32_bf16 v[46:49], v[94:97], v[74:77], v[46:49]
	v_mfma_f32_16x16x32_bf16 v[50:53], v[82:85], v[78:81], v[50:53]
	v_mfma_f32_16x16x32_bf16 v[54:57], v[86:89], v[78:81], v[54:57]
	v_mfma_f32_16x16x32_bf16 v[58:61], v[90:93], v[78:81], v[58:61]
	v_mfma_f32_16x16x32_bf16 v[62:65], v[94:97], v[78:81], v[62:65]
	s_waitcnt vmcnt(20)
	v_mfma_f32_16x16x32_bf16 v[2:5], v[114:117], v[98:101], v[2:5]
	v_mfma_f32_16x16x32_bf16 v[6:9], v[118:121], v[98:101], v[6:9]
	v_mfma_f32_16x16x32_bf16 v[18:21], v[114:117], v[102:105], v[18:21]
	v_mfma_f32_16x16x32_bf16 v[22:25], v[118:121], v[102:105], v[22:25]
	s_waitcnt vmcnt(16)
	v_mfma_f32_16x16x32_bf16 v[10:13], v[122:125], v[98:101], v[10:13]
	v_mfma_f32_16x16x32_bf16 v[14:17], v[126:129], v[98:101], v[14:17]
	v_mfma_f32_16x16x32_bf16 v[26:29], v[122:125], v[102:105], v[26:29]
	v_mfma_f32_16x16x32_bf16 v[30:33], v[126:129], v[102:105], v[30:33]
	v_mfma_f32_16x16x32_bf16 v[34:37], v[114:117], v[106:109], v[34:37]
	v_mfma_f32_16x16x32_bf16 v[38:41], v[118:121], v[106:109], v[38:41]
	v_mfma_f32_16x16x32_bf16 v[42:45], v[122:125], v[106:109], v[42:45]
	v_mfma_f32_16x16x32_bf16 v[46:49], v[126:129], v[106:109], v[46:49]
	v_mfma_f32_16x16x32_bf16 v[50:53], v[114:117], v[110:113], v[50:53]
	v_mfma_f32_16x16x32_bf16 v[54:57], v[118:121], v[110:113], v[54:57]
	v_mfma_f32_16x16x32_bf16 v[58:61], v[122:125], v[110:113], v[58:61]
	v_mfma_f32_16x16x32_bf16 v[62:65], v[126:129], v[110:113], v[62:65]
	s_waitcnt vmcnt(12)
	v_mfma_f32_16x16x32_bf16 v[2:5], v[146:149], v[130:133], v[2:5]
	v_mfma_f32_16x16x32_bf16 v[6:9], v[150:153], v[130:133], v[6:9]
	v_mfma_f32_16x16x32_bf16 v[18:21], v[146:149], v[134:137], v[18:21]
	v_mfma_f32_16x16x32_bf16 v[22:25], v[150:153], v[134:137], v[22:25]
	s_waitcnt vmcnt(8)
	v_mfma_f32_16x16x32_bf16 v[10:13], v[154:157], v[130:133], v[10:13]
	v_mfma_f32_16x16x32_bf16 v[14:17], v[158:161], v[130:133], v[14:17]
	v_mfma_f32_16x16x32_bf16 v[26:29], v[154:157], v[134:137], v[26:29]
	v_mfma_f32_16x16x32_bf16 v[30:33], v[158:161], v[134:137], v[30:33]
	v_mfma_f32_16x16x32_bf16 v[34:37], v[146:149], v[138:141], v[34:37]
	v_mfma_f32_16x16x32_bf16 v[38:41], v[150:153], v[138:141], v[38:41]
	v_mfma_f32_16x16x32_bf16 v[42:45], v[154:157], v[138:141], v[42:45]
	v_mfma_f32_16x16x32_bf16 v[46:49], v[158:161], v[138:141], v[46:49]
	v_mfma_f32_16x16x32_bf16 v[50:53], v[146:149], v[142:145], v[50:53]
	v_mfma_f32_16x16x32_bf16 v[54:57], v[150:153], v[142:145], v[54:57]
	v_mfma_f32_16x16x32_bf16 v[58:61], v[154:157], v[142:145], v[58:61]
	v_mfma_f32_16x16x32_bf16 v[62:65], v[158:161], v[142:145], v[62:65]
	s_waitcnt vmcnt(4)
	v_mfma_f32_16x16x32_bf16 v[2:5], v[178:181], v[162:165], v[2:5]
	v_mfma_f32_16x16x32_bf16 v[6:9], v[182:185], v[162:165], v[6:9]
	v_mfma_f32_16x16x32_bf16 v[18:21], v[178:181], v[166:169], v[18:21]
	v_mfma_f32_16x16x32_bf16 v[22:25], v[182:185], v[166:169], v[22:25]
	s_waitcnt vmcnt(0)
	v_mfma_f32_16x16x32_bf16 v[10:13], v[186:189], v[162:165], v[10:13]
	v_mfma_f32_16x16x32_bf16 v[14:17], v[190:193], v[162:165], v[14:17]
	v_mfma_f32_16x16x32_bf16 v[26:29], v[186:189], v[166:169], v[26:29]
	v_mfma_f32_16x16x32_bf16 v[30:33], v[190:193], v[166:169], v[30:33]
	v_mfma_f32_16x16x32_bf16 v[34:37], v[178:181], v[170:173], v[34:37]
	v_mfma_f32_16x16x32_bf16 v[38:41], v[182:185], v[170:173], v[38:41]
	v_mfma_f32_16x16x32_bf16 v[42:45], v[186:189], v[170:173], v[42:45]
	v_mfma_f32_16x16x32_bf16 v[46:49], v[190:193], v[170:173], v[46:49]
	v_mfma_f32_16x16x32_bf16 v[50:53], v[178:181], v[174:177], v[50:53]
	v_mfma_f32_16x16x32_bf16 v[54:57], v[182:185], v[174:177], v[54:57]
	v_mfma_f32_16x16x32_bf16 v[58:61], v[186:189], v[174:177], v[58:61]
	v_mfma_f32_16x16x32_bf16 v[62:65], v[190:193], v[174:177], v[62:65]
	s_nop 7
	ds_write_b128 v206, v[2:5] offset:0
	ds_write_b128 v206, v[6:9] offset:1024
	ds_write_b128 v206, v[10:13] offset:2048
	ds_write_b128 v206, v[14:17] offset:3072
	ds_write_b128 v206, v[18:21] offset:4096
	ds_write_b128 v206, v[22:25] offset:5120
	ds_write_b128 v206, v[26:29] offset:6144
	ds_write_b128 v206, v[30:33] offset:7168
	ds_write_b128 v206, v[34:37] offset:8192
	ds_write_b128 v206, v[38:41] offset:9216
	ds_write_b128 v206, v[42:45] offset:10240
	ds_write_b128 v206, v[46:49] offset:11264
	ds_write_b128 v206, v[50:53] offset:12288
	ds_write_b128 v206, v[54:57] offset:13312
	ds_write_b128 v206, v[58:61] offset:14336
	ds_write_b128 v206, v[62:65] offset:15360
	s_waitcnt lgkmcnt(0)
	s_barrier
	ds_read_b128 v[2:5], v207 offset:0
	ds_read_b128 v[6:9], v207 offset:16384
	ds_read_b128 v[10:13], v207 offset:32768
	ds_read_b128 v[14:17], v207 offset:49152
	ds_read_b128 v[18:21], v207 offset:1024
	ds_read_b128 v[22:25], v207 offset:17408
	ds_read_b128 v[26:29], v207 offset:33792
	ds_read_b128 v[30:33], v207 offset:50176
	ds_read_b128 v[34:37], v207 offset:2048
	ds_read_b128 v[38:41], v207 offset:18432
	ds_read_b128 v[42:45], v207 offset:34816
	ds_read_b128 v[46:49], v207 offset:51200
	ds_read_b128 v[50:53], v207 offset:3072
	ds_read_b128 v[54:57], v207 offset:19456
	ds_read_b128 v[58:61], v207 offset:35840
	ds_read_b128 v[62:65], v207 offset:52224
	s_waitcnt lgkmcnt(12)
	v_add_f32_e32 v2, v2, v6
	v_add_f32_e32 v3, v3, v7
	v_add_f32_e32 v4, v4, v8
	v_add_f32_e32 v5, v5, v9
	v_add_f32_e32 v10, v10, v14
	v_add_f32_e32 v11, v11, v15
	v_add_f32_e32 v12, v12, v16
	v_add_f32_e32 v13, v13, v17
	v_add_f32_e32 v2, v2, v10
	v_add_f32_e32 v3, v3, v11
	v_add_f32_e32 v4, v4, v12
	v_add_f32_e32 v5, v5, v13
	s_waitcnt lgkmcnt(8)
	v_add_f32_e32 v18, v18, v22
	v_add_f32_e32 v19, v19, v23
	v_add_f32_e32 v20, v20, v24
	v_add_f32_e32 v21, v21, v25
	v_add_f32_e32 v26, v26, v30
	v_add_f32_e32 v27, v27, v31
	v_add_f32_e32 v28, v28, v32
	v_add_f32_e32 v29, v29, v33
	v_add_f32_e32 v18, v18, v26
	v_add_f32_e32 v19, v19, v27
	v_add_f32_e32 v20, v20, v28
	v_add_f32_e32 v21, v21, v29
	s_waitcnt lgkmcnt(4)
	v_add_f32_e32 v34, v34, v38
	v_add_f32_e32 v35, v35, v39
	v_add_f32_e32 v36, v36, v40
	v_add_f32_e32 v37, v37, v41
	v_add_f32_e32 v42, v42, v46
	v_add_f32_e32 v43, v43, v47
	v_add_f32_e32 v44, v44, v48
	v_add_f32_e32 v45, v45, v49
	v_add_f32_e32 v34, v34, v42
	v_add_f32_e32 v35, v35, v43
	v_add_f32_e32 v36, v36, v44
	v_add_f32_e32 v37, v37, v45
	s_waitcnt lgkmcnt(0)
	v_add_f32_e32 v50, v50, v54
	v_add_f32_e32 v51, v51, v55
	v_add_f32_e32 v52, v52, v56
	v_add_f32_e32 v53, v53, v57
	v_add_f32_e32 v58, v58, v62
	v_add_f32_e32 v59, v59, v63
	v_add_f32_e32 v60, v60, v64
	v_add_f32_e32 v61, v61, v65
	v_add_f32_e32 v50, v50, v58
	v_add_f32_e32 v51, v51, v59
	v_add_f32_e32 v52, v52, v60
	v_add_f32_e32 v53, v53, v61
	v_max_f32_e32 v2, 0, v2
	v_max_f32_e32 v3, 0, v3
	v_max_f32_e32 v4, 0, v4
	v_max_f32_e32 v5, 0, v5
	v_mul_f32_e32 v2, v2, v2
	v_mul_f32_e32 v3, v3, v3
	v_mul_f32_e32 v4, v4, v4
	v_mul_f32_e32 v5, v5, v5
	v_cvt_pk_bf16_f32 v210, v2, v3
	v_cvt_pk_bf16_f32 v211, v4, v5
	global_store_dwordx2 v209, v[210:211], s[24:25] offset:0
	v_max_f32_e32 v18, 0, v18
	v_max_f32_e32 v19, 0, v19
	v_max_f32_e32 v20, 0, v20
	v_max_f32_e32 v21, 0, v21
	v_mul_f32_e32 v18, v18, v18
	v_mul_f32_e32 v19, v19, v19
	v_mul_f32_e32 v20, v20, v20
	v_mul_f32_e32 v21, v21, v21
	v_cvt_pk_bf16_f32 v212, v18, v19
	v_cvt_pk_bf16_f32 v213, v20, v21
	global_store_dwordx2 v209, v[212:213], s[24:25] offset:32
	v_max_f32_e32 v34, 0, v34
	v_max_f32_e32 v35, 0, v35
	v_max_f32_e32 v36, 0, v36
	v_max_f32_e32 v37, 0, v37
	v_mul_f32_e32 v34, v34, v34
	v_mul_f32_e32 v35, v35, v35
	v_mul_f32_e32 v36, v36, v36
	v_mul_f32_e32 v37, v37, v37
	v_cvt_pk_bf16_f32 v214, v34, v35
	v_cvt_pk_bf16_f32 v215, v36, v37
	global_store_dwordx2 v209, v[214:215], s[24:25] offset:64
	v_max_f32_e32 v50, 0, v50
	v_max_f32_e32 v51, 0, v51
	v_max_f32_e32 v52, 0, v52
	v_max_f32_e32 v53, 0, v53
	v_mul_f32_e32 v50, v50, v50
	v_mul_f32_e32 v51, v51, v51
	v_mul_f32_e32 v52, v52, v52
	v_mul_f32_e32 v53, v53, v53
	v_cvt_pk_bf16_f32 v216, v50, v51
	v_cvt_pk_bf16_f32 v217, v52, v53
	global_store_dwordx2 v209, v[216:217], s[24:25] offset:96
	s_barrier
	s_add_i32 s12, s12, s3
	s_cmpk_lt_u32 s12, 0x100
	s_cbranch_scc1 .Lsmp5_unit
.Lsmp5_done:
	s_cmpk_gt_i32 s2, 0x3ff
	v_readfirstlane_b32 s5, v0
	s_cbranch_scc1 .LBB5_16
	v_lshlrev_b32_e32 v2, 4, v0
	v_add_u32_e32 v3, 0x2000, v2
	v_ashrrev_i32_e32 v1, 31, v3
	v_lshrrev_b32_e32 v1, 22, v1
	v_add_u32_e32 v1, v3, v1
	v_ashrrev_i32_e32 v1, 10, v1
	v_mul_i32_i24_e32 v4, 0x400, v1
	v_sub_u32_e32 v3, v3, v4
	v_lshrrev_b32_e32 v4, 4, v3
	v_bitop3_b32 v3, v4, v3, 32 bitop3:0x6c
	v_ashrrev_i32_e32 v4, 31, v3
	v_lshrrev_b32_e32 v4, 26, v4
	v_add_u32_e32 v4, v3, v4
	v_lshlrev_b32_e32 v5, 3, v1
	v_ashrrev_i32_e32 v10, 6, v4
	v_and_b32_e32 v5, -16, v5
	v_add_u32_e32 v5, v10, v5
	v_and_b32_e32 v6, 3, v10
	s_mov_b32 s4, 0x1fffe0
	v_lshrrev_b32_e32 v7, 2, v5
	v_lshlrev_b32_e32 v8, 1, v5
	v_and_b32_e32 v4, 0xc0, v4
	v_and_or_b32 v6, v5, s4, v6
	v_and_b32_e32 v7, 4, v7
	v_and_b32_e32 v8, 24, v8
	v_sub_u32_e32 v3, v3, v4
	v_mov_b32_e32 v4, 1
	v_or3_b32 v6, v6, v7, v8
	v_lshlrev_b32_e32 v7, 5, v1
	v_ashrrev_i16_sdwa v3, v4, sext(v3) dst_sel:DWORD dst_unused:UNUSED_PAD src0_sel:DWORD src1_sel:BYTE_0
	v_and_b32_e32 v7, 32, v7
	v_bfe_i32 v11, v3, 0, 16
	v_add_lshl_u32 v3, v7, v11, 1
	v_lshl_add_u32 v128, v6, 11, v3
	v_lshl_add_u32 v130, v5, 11, v3
	v_bfe_i32 v3, v0, 27, 1
	v_lshrrev_b32_e32 v3, 22, v3
	v_add_u32_e32 v3, v2, v3
	s_load_dwordx2 s[0:1], s[0:1], 0xd8
	v_and_b32_e32 v3, 0xfffffc00, v3
	v_sub_u32_e32 v2, v2, v3
	v_lshrrev_b32_e32 v3, 4, v2
	v_ashrrev_i32_e32 v5, 31, v0
	v_bitop3_b32 v2, v3, v2, 32 bitop3:0x6c
	v_lshrrev_b32_e32 v5, 26, v5
	v_ashrrev_i32_e32 v3, 31, v2
	v_add_u32_e32 v5, v0, v5
	s_waitcnt lgkmcnt(0)
	s_add_u32 s28, s0, 0x3100000
	v_lshrrev_b32_e32 v3, 26, v3
	v_ashrrev_i32_e32 v13, 6, v5
	s_addc_u32 s29, s1, 0
	v_add_u32_e32 v3, v2, v3
	v_lshlrev_b32_e32 v5, 3, v13
	s_add_u32 s30, s0, 0x900000
	v_ashrrev_i32_e32 v12, 6, v3
	v_and_b32_e32 v5, -16, v5
	s_addc_u32 s31, s1, 0
	v_add_u32_e32 v5, v12, v5
	v_and_b32_e32 v6, 3, v12
	s_ashr_i32 s34, s2, 31
	v_and_or_b32 v6, v5, s4, v6
	s_lshr_b32 s4, s34, 29
	s_add_i32 s4, s2, s4
	s_ashr_i32 s6, s5, 6
	s_ashr_i32 s7, s4, 3
	s_and_b32 s4, s4, -8
	s_ashr_i32 s10, s5, 8
	s_lshl_b32 s33, s6, 10
	s_sub_i32 s4, s2, s4
	s_cmp_lt_i32 s4, 0
	s_movk_i32 s35, 0x81
	s_cselect_b32 s8, s35, 0x80
	s_mul_i32 s4, s4, s8
	s_add_i32 s4, s4, s7
	s_ashr_i32 s7, s4, 31
	s_lshr_b32 s7, s7, 25
	s_add_i32 s7, s4, s7
	v_lshrrev_b32_e32 v7, 2, v5
	v_lshlrev_b32_e32 v8, 1, v5
	v_and_b32_e32 v3, 0xc0, v3
	s_ashr_i32 s8, s7, 7
	v_and_b32_e32 v7, 4, v7
	v_and_b32_e32 v8, 24, v8
	v_sub_u32_e32 v2, v2, v3
	s_lshl_b32 s11, s8, 3
	v_or3_b32 v6, v6, v7, v8
	v_lshlrev_b32_e32 v7, 5, v13
	v_ashrrev_i16_sdwa v2, v4, sext(v2) dst_sel:DWORD dst_unused:UNUSED_PAD src0_sel:DWORD src1_sel:BYTE_0
	s_sub_i32 s8, 0x40, s11
	v_and_b32_e32 v7, 32, v7
	v_bfe_i32 v14, v2, 0, 16
	s_min_u32 s12, s8, 8
	s_and_b32 s7, s7, 0xffffff80
	v_add_lshl_u32 v2, v7, v14, 1
	s_sub_i32 s7, s4, s7
	v_cvt_f32_ubyte0_e32 v4, s12
	v_lshl_add_u32 v132, v6, 11, v2
	v_cvt_f32_i32_e32 v3, s7
	v_rcp_iflag_f32_e32 v6, v4
	v_lshl_add_u32 v134, v5, 11, v2
	s_ashr_i32 s4, s7, 30
	s_or_b32 s4, s4, 1
	v_mul_f32_e32 v2, v3, v6
	v_trunc_f32_e32 v2, v2
	v_fma_f32 v3, -v2, v4, v3
	v_cvt_i32_f32_e32 v2, v2
	v_cmp_ge_f32_e64 s[8:9], |v3|, v4
	s_and_b64 s[8:9], s[8:9], exec
	s_cselect_b32 s4, s4, 0
	v_readfirstlane_b32 s8, v2
	s_add_i32 s4, s8, s4
	s_mul_i32 s8, s4, s12
	s_sub_i32 s7, s7, s8
	s_sext_i32_i8 s7, s7
	s_add_i32 s20, s11, s7
	s_ashr_i32 s21, s20, 31
	s_bfe_i64 s[12:13], s[4:5], 0x80000
	s_lshl_b64 s[8:9], s[20:21], 19
	s_lshl_b64 s[12:13], s[12:13], 19
	s_add_u32 s24, s30, s12
	s_addc_u32 s25, s31, s13
	s_add_i32 s21, s33, 0
	s_add_i32 m0, s21, 0x10000
	v_mov_b32_e32 v133, 0
	global_load_lds_dwordx4 v132, s[24:25]
	s_add_i32 m0, s21, 0x12000
	s_add_u32 s12, s24, 0x40000
	global_load_lds_dwordx4 v128, s[24:25]
	s_addc_u32 s13, s25, 0
	s_add_i32 m0, s21, 0x14000
	v_mov_b32_e32 v129, v133
	global_load_lds_dwordx4 v132, s[12:13]
	s_add_i32 m0, s21, 0x16000
	s_add_u32 s22, s28, s8
	s_addc_u32 s23, s29, s9
	s_add_i32 s36, s21, 0x2000
	global_load_lds_dwordx4 v128, s[12:13]
	s_mov_b32 m0, s21
	s_add_u32 s8, s22, 0x40000
	global_load_lds_dwordx4 v134, s[22:23]
	s_mov_b32 m0, s36
	s_addc_u32 s9, s23, 0
	s_add_i32 s37, s21, 0x4000
	global_load_lds_dwordx4 v130, s[22:23]
	s_mov_b32 m0, s37
	s_add_i32 s38, s21, 0x6000
	global_load_lds_dwordx4 v134, s[8:9]
	s_mov_b32 m0, s38
	v_mov_b32_e32 v135, v133
	global_load_lds_dwordx4 v130, s[8:9]
	v_mov_b32_e32 v131, v133
	s_cmp_eq_u32 s10, 1
	s_mov_b32 s7, 0
	v_lshl_add_u64 v[8:9], s[24:25], 0, v[132:133]
	v_lshl_add_u64 v[6:7], s[24:25], 0, v[128:129]
	v_lshl_add_u64 v[2:3], s[22:23], 0, v[134:135]
	s_cselect_b64 s[8:9], -1, 0
	s_cmp_lg_u32 s10, 1
	v_lshl_add_u64 v[4:5], s[22:23], 0, v[130:131]
	s_cbranch_scc1 .LBB5_3
	s_barrier
.LBB5_3:
	s_lshl_b32 s39, s10, 6
	s_lshl_b32 s14, s10, 13
	s_lshl_b32 s6, s6, 5
	s_mov_b64 s[10:11], 0x80
	s_and_b32 s6, s6, 0x60
	s_add_i32 m0, s21, 0x18000
	v_lshl_add_u64 v[8:9], v[8:9], 0, s[10:11]
	s_lshl_b32 s15, s6, 7
	s_waitcnt vmcnt(2)
	s_barrier
	global_load_lds_dwordx4 v[8:9], off
	v_lshl_add_u64 v[6:7], v[6:7], 0, s[10:11]
	s_add_i32 m0, s21, 0x1a000
	s_add_i32 s40, s21, 0x8000
	s_add_i32 s41, s21, 0xa000
	global_load_lds_dwordx4 v[6:7], off
	v_lshl_add_u64 v[2:3], v[2:3], 0, s[10:11]
	s_mov_b32 m0, s40
	s_add_u32 s12, s24, 0x40080
	global_load_lds_dwordx4 v[2:3], off
	v_lshl_add_u64 v[2:3], v[4:5], 0, s[10:11]
	s_mov_b32 m0, s41
	s_addc_u32 s13, s25, 0
	global_load_lds_dwordx4 v[2:3], off
	s_add_i32 m0, s21, 0x1c000
	v_lshl_add_u64 v[2:3], s[12:13], 0, v[132:133]
	global_load_lds_dwordx4 v[2:3], off
	v_lshl_add_u64 v[2:3], s[12:13], 0, v[128:129]
	s_add_i32 m0, s21, 0x1e000
	s_cmpk_lt_u32 s5, 0x100
	global_load_lds_dwordx4 v[2:3], off
	v_and_b32_e32 v2, 15, v0
	v_and_b32_e32 v3, 48, v0
	v_lshlrev_b32_e32 v0, 2, v0
	v_lshl_or_b32 v4, v2, 6, v3
	v_and_b32_e32 v0, 32, v0
	v_bitop3_b32 v5, v4, s14, v0 bitop3:0xde
	v_bitop3_b32 v148, s15, v4, v0 bitop3:0xf6
	v_lshl_or_b32 v2, v2, 13, v3
	v_mov_b32_e32 v3, v133
	v_lshlrev_b32_e32 v0, 14, v13
	v_lshl_add_u64 v[2:3], s[0:1], 0, v[2:3]
	s_mov_b64 s[0:1], 0x7400000
	v_and_b32_e32 v0, 0xffff8000, v0
	v_lshl_add_u64 v[136:137], v[2:3], 0, s[0:1]
	v_lshl_add_u32 v0, v12, 11, v0
	v_and_b32_e32 v2, 1, v13
	v_lshl_or_b32 v0, v2, 6, v0
	v_lshl_add_u32 v138, v14, 1, v0
	v_lshlrev_b32_e32 v0, 14, v1
	v_and_b32_e32 v0, 0xffff8000, v0
	s_waitcnt vmcnt(6)
	v_lshl_add_u32 v0, v10, 11, v0
	v_and_b32_e32 v1, 1, v1
	s_sext_i32_i8 s53, s4
	s_cselect_b64 s[4:5], -1, 0
	v_lshl_or_b32 v0, v1, 6, v0
	s_add_i32 s43, 0, 0x10000
	s_add_i32 s44, 0, 0x14000
	s_ashr_i32 s42, s3, 31
	v_mov_b32_e32 v139, v133
	v_lshl_add_u32 v140, v11, 1, v0
	v_mov_b32_e32 v141, v133
	v_mov_b64_e32 v[142:143], 0x400
	v_mov_b64_e32 v[144:145], 0x3ff
	v_add_u32_e32 v149, s43, v148
	v_add_u32_e32 v150, s44, v148
	v_add_u32_e32 v151, 0, v5
	s_and_b64 s[0:1], exec, s[4:5]
	s_mov_b32 s45, 0x20000
	s_mov_b32 s46, 0x40000
	s_mov_b32 s47, 0x60000
	s_mov_b32 s48, 0x100000
	s_mov_b32 s49, 0x120000
	s_mov_b32 s50, 0x140000
	s_mov_b32 s51, 0x160000
	s_mov_b32 s52, s7
	s_barrier
	s_branch .LBB5_6

.LBB5_6:
	s_add_i32 s52, s52, 1
	s_mul_i32 s4, s52, s42
	s_mul_hi_u32 s5, s52, s3
	s_add_i32 s5, s5, s4
	s_mul_i32 s4, s52, s3
	s_add_u32 s4, s4, s2
	s_addc_u32 s5, s5, s34
	v_cmp_gt_i64_e32 vcc, s[4:5], v[144:145]
	s_cbranch_vccnz .LBB5_8
	s_ashr_i32 s12, s4, 31
	s_lshr_b32 s12, s12, 29
	s_add_i32 s12, s4, s12
	s_ashr_i32 s13, s12, 3
	s_and_b32 s12, s12, -8
	s_sub_i32 s12, s4, s12
	s_cmp_lt_i32 s12, 0
	s_cselect_b32 s14, s35, 0x80
	s_mul_i32 s12, s12, s14
	s_add_i32 s12, s12, s13
	s_ashr_i32 s13, s12, 31
	s_lshr_b32 s13, s13, 25
	s_add_i32 s13, s12, s13
	s_ashr_i32 s14, s13, 7
	s_lshl_b32 s14, s14, 3
	s_sub_i32 s15, 0x40, s14
	s_min_i32 s15, s15, 8
	s_abs_i32 s16, s15
	v_cvt_f32_u32_e32 v0, s16
	s_sub_i32 s18, 0, s16
	s_and_b32 s13, s13, 0xffffff80
	s_sub_i32 s13, s12, s13
	v_rcp_iflag_f32_e32 v0, v0
	s_abs_i32 s12, s13
	s_xor_b32 s17, s13, s15
	s_ashr_i32 s17, s17, 31
	v_mul_f32_e32 v0, 0x4f7ffffe, v0
	v_cvt_u32_f32_e32 v0, v0
	s_nop 0
	v_readfirstlane_b32 s19, v0
	s_mul_i32 s18, s18, s19
	s_mul_hi_u32 s18, s19, s18
	s_add_i32 s19, s19, s18
	s_mul_hi_u32 s18, s12, s19
	s_mul_i32 s19, s18, s16
	s_sub_i32 s12, s12, s19
	s_add_i32 s26, s18, 1
	s_sub_i32 s19, s12, s16
	s_cmp_ge_u32 s12, s16
	s_cselect_b32 s18, s26, s18
	s_cselect_b32 s12, s19, s12
	s_add_i32 s19, s18, 1
	s_cmp_ge_u32 s12, s16
	s_cselect_b32 s12, s19, s18
	s_xor_b32 s12, s12, s17
	s_sub_i32 s12, s12, s17
	s_mul_i32 s15, s12, s15
	s_sub_i32 s13, s13, s15
	s_add_i32 s14, s14, s13

_Z10fwd_kernelILi7ELi8EEv4Args:
	s_load_dword s3, s[0:1], 0xe8
	s_load_dwordx4 s[4:7], s[0:1], 0xd0
	s_load_dwordx2 s[8:9], s[0:1], 0xb8
	s_load_dwordx2 s[10:11], s[0:1], 0xa0
	s_waitcnt lgkmcnt(0)
	s_cmp_lg_u32 s3, 0x100
	s_cbranch_scc1 .Lrows7_orig
	s_add_u32 s10, s10, 0x1000
	s_addc_u32 s11, s11, 0
	v_readfirstlane_b32 s16, v0
	s_lshr_b32 s16, s16, 6
	s_lshl_b32 s18, s2, 3
	s_add_u32 s16, s16, s18
	s_mov_b32 s17, 0x3a800000
	v_mov_b32_e32 v3, 0x358637bd
	v_and_b32_e32 v10, 63, v0
	v_lshlrev_b32_e32 v1, 4, v10
	v_lshlrev_b32_e32 v2, 3, v10
	v_xor_b32_e32 v4, 1, v10
	v_xor_b32_e32 v5, 2, v10
	v_xor_b32_e32 v6, 4, v10
	v_xor_b32_e32 v7, 8, v10
	v_xor_b32_e32 v8, 16, v10
	v_xor_b32_e32 v9, 32, v10
	v_lshlrev_b32_e32 v4, 2, v4
	v_lshlrev_b32_e32 v5, 2, v5
	v_lshlrev_b32_e32 v6, 2, v6
	v_lshlrev_b32_e32 v7, 2, v7
	v_lshlrev_b32_e32 v8, 2, v8
	v_lshlrev_b32_e32 v9, 2, v9
	global_load_dwordx4 v[20:23], v1, s[8:9] offset:0
	global_load_dwordx4 v[24:27], v1, s[8:9] offset:1024
	global_load_dwordx4 v[28:31], v1, s[8:9] offset:2048
	global_load_dwordx4 v[32:35], v1, s[8:9] offset:3072
	global_load_dwordx4 v[36:39], v1, s[10:11] offset:0
	global_load_dwordx4 v[40:43], v1, s[10:11] offset:1024
	global_load_dwordx4 v[44:47], v1, s[10:11] offset:2048
	global_load_dwordx4 v[48:51], v1, s[10:11] offset:3072
	s_add_u32 s53, s16, 0x0
	s_lshl_b32 s18, s53, 12
	s_lshl_b32 s19, s53, 11
	s_add_u32 s20, s4, s18
	s_addc_u32 s21, s5, 0
	s_add_u32 s22, s6, s19
	s_addc_u32 s23, s7, 0
	s_add_u32 s22, s22, 0x5200000
	s_addc_u32 s23, s23, 0
	s_add_u32 s24, s4, s18
	s_addc_u32 s25, s5, 0
	s_add_u32 s26, s6, s19
	s_addc_u32 s27, s7, 0
	s_add_u32 s26, s26, 0x3100000
	s_addc_u32 s27, s27, 0
	global_load_dwordx2 v[66:67], v2, s[22:23] offset:0
	global_load_dwordx2 v[70:71], v2, s[22:23] offset:512
	global_load_dwordx2 v[74:75], v2, s[22:23] offset:1024
	global_load_dwordx2 v[78:79], v2, s[22:23] offset:1536
	global_load_dwordx4 v[80:83], v1, s[20:21] offset:0
	global_load_dwordx4 v[84:87], v1, s[20:21] offset:1024
	global_load_dwordx4 v[88:91], v1, s[20:21] offset:2048
	global_load_dwordx4 v[92:95], v1, s[20:21] offset:3072
	s_add_u32 s53, s16, 0x800
	s_lshl_b32 s18, s53, 12
	s_lshl_b32 s19, s53, 11
	s_add_u32 s28, s4, s18
	s_addc_u32 s29, s5, 0
	s_add_u32 s30, s6, s19
	s_addc_u32 s31, s7, 0
	s_add_u32 s30, s30, 0x5200000
	s_addc_u32 s31, s31, 0
	s_add_u32 s32, s4, s18
	s_addc_u32 s33, s5, 0
	s_add_u32 s34, s6, s19
	s_addc_u32 s35, s7, 0
	s_add_u32 s34, s34, 0x3100000
	s_addc_u32 s35, s35, 0
	global_load_dwordx2 v[98:99], v2, s[30:31] offset:0
	global_load_dwordx2 v[102:103], v2, s[30:31] offset:512
	global_load_dwordx2 v[106:107], v2, s[30:31] offset:1024
	global_load_dwordx2 v[110:111], v2, s[30:31] offset:1536
	global_load_dwordx4 v[112:115], v1, s[28:29] offset:0
	global_load_dwordx4 v[116:119], v1, s[28:29] offset:1024
	global_load_dwordx4 v[120:123], v1, s[28:29] offset:2048
	global_load_dwordx4 v[124:127], v1, s[28:29] offset:3072
	s_add_u32 s53, s16, 0x1000
	s_lshl_b32 s18, s53, 12
	s_lshl_b32 s19, s53, 11
	s_add_u32 s36, s4, s18
	s_addc_u32 s37, s5, 0
	s_add_u32 s38, s6, s19
	s_addc_u32 s39, s7, 0
	s_add_u32 s38, s38, 0x5200000
	s_addc_u32 s39, s39, 0
	s_add_u32 s40, s4, s18
	s_addc_u32 s41, s5, 0
	s_add_u32 s42, s6, s19
	s_addc_u32 s43, s7, 0
	s_add_u32 s42, s42, 0x3100000
	s_addc_u32 s43, s43, 0
	global_load_dwordx2 v[130:131], v2, s[38:39] offset:0
	global_load_dwordx2 v[134:135], v2, s[38:39] offset:512
	global_load_dwordx2 v[138:139], v2, s[38:39] offset:1024
	global_load_dwordx2 v[142:143], v2, s[38:39] offset:1536
	global_load_dwordx4 v[144:147], v1, s[36:37] offset:0
	global_load_dwordx4 v[148:151], v1, s[36:37] offset:1024
	global_load_dwordx4 v[152:155], v1, s[36:37] offset:2048
	global_load_dwordx4 v[156:159], v1, s[36:37] offset:3072
	s_add_u32 s53, s16, 0x1800
	s_lshl_b32 s18, s53, 12
	s_lshl_b32 s19, s53, 11
	s_add_u32 s44, s4, s18
	s_addc_u32 s45, s5, 0
	s_add_u32 s46, s6, s19
	s_addc_u32 s47, s7, 0
	s_add_u32 s46, s46, 0x5200000
	s_addc_u32 s47, s47, 0
	s_add_u32 s48, s4, s18
	s_addc_u32 s49, s5, 0
	s_add_u32 s50, s6, s19
	s_addc_u32 s51, s7, 0
	s_add_u32 s50, s50, 0x3100000
	s_addc_u32 s51, s51, 0
	global_load_dwordx2 v[162:163], v2, s[46:47] offset:0
	global_load_dwordx2 v[166:167], v2, s[46:47] offset:512
	global_load_dwordx2 v[170:171], v2, s[46:47] offset:1024
	global_load_dwordx2 v[174:175], v2, s[46:47] offset:1536
	global_load_dwordx4 v[176:179], v1, s[44:45] offset:0
	global_load_dwordx4 v[180:183], v1, s[44:45] offset:1024
	global_load_dwordx4 v[184:187], v1, s[44:45] offset:2048
	global_load_dwordx4 v[188:191], v1, s[44:45] offset:3072
	s_waitcnt vmcnt(16)
	v_lshlrev_b32_e32 v64, 16, v66
	v_and_b32_e32 v65, 0xffff0000, v66
	v_lshlrev_b32_e32 v66, 16, v67
	v_and_b32_e32 v67, 0xffff0000, v67
	v_lshlrev_b32_e32 v68, 16, v70
	v_and_b32_e32 v69, 0xffff0000, v70
	v_lshlrev_b32_e32 v70, 16, v71
	v_and_b32_e32 v71, 0xffff0000, v71
	v_lshlrev_b32_e32 v72, 16, v74
	v_and_b32_e32 v73, 0xffff0000, v74
	v_lshlrev_b32_e32 v74, 16, v75
	v_and_b32_e32 v75, 0xffff0000, v75
	v_lshlrev_b32_e32 v76, 16, v78
	v_and_b32_e32 v77, 0xffff0000, v78
	v_lshlrev_b32_e32 v78, 16, v79
	v_and_b32_e32 v79, 0xffff0000, v79
	v_lshlrev_b32_e32 v96, 16, v98
	v_and_b32_e32 v97, 0xffff0000, v98
	v_lshlrev_b32_e32 v98, 16, v99
	v_and_b32_e32 v99, 0xffff0000, v99
	v_lshlrev_b32_e32 v100, 16, v102
	v_and_b32_e32 v101, 0xffff0000, v102
	v_lshlrev_b32_e32 v102, 16, v103
	v_and_b32_e32 v103, 0xffff0000, v103
	v_lshlrev_b32_e32 v104, 16, v106
	v_and_b32_e32 v105, 0xffff0000, v106
	v_lshlrev_b32_e32 v106, 16, v107
	v_and_b32_e32 v107, 0xffff0000, v107
	v_lshlrev_b32_e32 v108, 16, v110
	v_and_b32_e32 v109, 0xffff0000, v110
	v_lshlrev_b32_e32 v110, 16, v111
	v_and_b32_e32 v111, 0xffff0000, v111
	v_mul_f32_e32 v10, v64, v64
	v_fmac_f32_e32 v10, v65, v65
	v_fmac_f32_e32 v10, v66, v66
	v_fmac_f32_e32 v10, v67, v67
	v_fmac_f32_e32 v10, v68, v68
	v_fmac_f32_e32 v10, v69, v69
	v_fmac_f32_e32 v10, v70, v70
	v_fmac_f32_e32 v10, v71, v71
	v_fmac_f32_e32 v10, v72, v72
	v_fmac_f32_e32 v10, v73, v73
	v_fmac_f32_e32 v10, v74, v74
	v_fmac_f32_e32 v10, v75, v75
	v_fmac_f32_e32 v10, v76, v76
	v_fmac_f32_e32 v10, v77, v77
	v_fmac_f32_e32 v10, v78, v78
	v_fmac_f32_e32 v10, v79, v79
	v_mul_f32_e32 v11, v96, v96
	v_fmac_f32_e32 v11, v97, v97
	v_fmac_f32_e32 v11, v98, v98
	v_fmac_f32_e32 v11, v99, v99
	v_fmac_f32_e32 v11, v100, v100
	v_fmac_f32_e32 v11, v101, v101
	v_fmac_f32_e32 v11, v102, v102
	v_fmac_f32_e32 v11, v103, v103
	v_fmac_f32_e32 v11, v104, v104
	v_fmac_f32_e32 v11, v105, v105
	v_fmac_f32_e32 v11, v106, v106
	v_fmac_f32_e32 v11, v107, v107
	v_fmac_f32_e32 v11, v108, v108
	v_fmac_f32_e32 v11, v109, v109
	v_fmac_f32_e32 v11, v110, v110
	v_fmac_f32_e32 v11, v111, v111
	ds_bpermute_b32 v12, v4, v10
	ds_bpermute_b32 v13, v4, v11
	s_waitcnt lgkmcnt(0)
	v_add_f32_e32 v10, v10, v12
	v_add_f32_e32 v11, v11, v13
	ds_bpermute_b32 v12, v5, v10
	ds_bpermute_b32 v13, v5, v11
	s_waitcnt lgkmcnt(0)
	v_add_f32_e32 v10, v10, v12
	v_add_f32_e32 v11, v11, v13
	ds_bpermute_b32 v12, v6, v10
	ds_bpermute_b32 v13, v6, v11
	s_waitcnt lgkmcnt(0)
	v_add_f32_e32 v10, v10, v12
	v_add_f32_e32 v11, v11, v13
	ds_bpermute_b32 v12, v7, v10
	ds_bpermute_b32 v13, v7, v11
	s_waitcnt lgkmcnt(0)
	v_add_f32_e32 v10, v10, v12
	v_add_f32_e32 v11, v11, v13
	ds_bpermute_b32 v12, v8, v10
	ds_bpermute_b32 v13, v8, v11
	s_waitcnt lgkmcnt(0)
	v_add_f32_e32 v10, v10, v12
	v_add_f32_e32 v11, v11, v13
	ds_bpermute_b32 v12, v9, v10
	ds_bpermute_b32 v13, v9, v11
	s_waitcnt lgkmcnt(0)
	v_add_f32_e32 v10, v10, v12
	v_add_f32_e32 v11, v11, v13
	v_fma_f32 v14, v10, s17, v3
	v_fma_f32 v15, v11, s17, v3
	v_rsq_f32_e32 v14, v14
	v_rsq_f32_e32 v15, v15
	s_nop 0
	v_mul_f32_e32 v64, v64, v14
	v_mul_f32_e32 v65, v65, v14
	v_mul_f32_e32 v66, v66, v14
	v_mul_f32_e32 v67, v67, v14
	v_mul_f32_e32 v68, v68, v14
	v_mul_f32_e32 v69, v69, v14
	v_mul_f32_e32 v70, v70, v14
	v_mul_f32_e32 v71, v71, v14
	v_mul_f32_e32 v72, v72, v14
	v_mul_f32_e32 v73, v73, v14
	v_mul_f32_e32 v74, v74, v14
	v_mul_f32_e32 v75, v75, v14
	v_mul_f32_e32 v76, v76, v14
	v_mul_f32_e32 v77, v77, v14
	v_mul_f32_e32 v78, v78, v14
	v_mul_f32_e32 v79, v79, v14
	v_fmac_f32_e32 v80, v64, v20
	v_fmac_f32_e32 v81, v65, v21
	v_fmac_f32_e32 v82, v66, v22
	v_fmac_f32_e32 v83, v67, v23
	v_fmac_f32_e32 v84, v68, v24
	v_fmac_f32_e32 v85, v69, v25
	v_fmac_f32_e32 v86, v70, v26
	v_fmac_f32_e32 v87, v71, v27
	v_fmac_f32_e32 v88, v72, v28
	v_fmac_f32_e32 v89, v73, v29
	v_fmac_f32_e32 v90, v74, v30
	v_fmac_f32_e32 v91, v75, v31
	v_fmac_f32_e32 v92, v76, v32
	v_fmac_f32_e32 v93, v77, v33
	v_fmac_f32_e32 v94, v78, v34
	v_fmac_f32_e32 v95, v79, v35
	global_store_dwordx4 v1, v[80:83], s[24:25] offset:0
	global_store_dwordx4 v1, v[84:87], s[24:25] offset:1024
	global_store_dwordx4 v1, v[88:91], s[24:25] offset:2048
	global_store_dwordx4 v1, v[92:95], s[24:25] offset:3072
	v_mul_f32_e32 v96, v96, v15
	v_mul_f32_e32 v97, v97, v15
	v_mul_f32_e32 v98, v98, v15
	v_mul_f32_e32 v99, v99, v15
	v_mul_f32_e32 v100, v100, v15
	v_mul_f32_e32 v101, v101, v15
	v_mul_f32_e32 v102, v102, v15
	v_mul_f32_e32 v103, v103, v15
	v_mul_f32_e32 v104, v104, v15
	v_mul_f32_e32 v105, v105, v15
	v_mul_f32_e32 v106, v106, v15
	v_mul_f32_e32 v107, v107, v15
	v_mul_f32_e32 v108, v108, v15
	v_mul_f32_e32 v109, v109, v15
	v_mul_f32_e32 v110, v110, v15
	v_mul_f32_e32 v111, v111, v15
	v_fmac_f32_e32 v112, v96, v20
	v_fmac_f32_e32 v113, v97, v21
	v_fmac_f32_e32 v114, v98, v22
	v_fmac_f32_e32 v115, v99, v23
	v_fmac_f32_e32 v116, v100, v24
	v_fmac_f32_e32 v117, v101, v25
	v_fmac_f32_e32 v118, v102, v26
	v_fmac_f32_e32 v119, v103, v27
	v_fmac_f32_e32 v120, v104, v28
	v_fmac_f32_e32 v121, v105, v29
	v_fmac_f32_e32 v122, v106, v30
	v_fmac_f32_e32 v123, v107, v31
	v_fmac_f32_e32 v124, v108, v32
	v_fmac_f32_e32 v125, v109, v33
	v_fmac_f32_e32 v126, v110, v34
	v_fmac_f32_e32 v127, v111, v35
	global_store_dwordx4 v1, v[112:115], s[32:33] offset:0
	global_store_dwordx4 v1, v[116:119], s[32:33] offset:1024
	global_store_dwordx4 v1, v[120:123], s[32:33] offset:2048
	global_store_dwordx4 v1, v[124:127], s[32:33] offset:3072
	v_mul_f32_e32 v10, v80, v80
	v_fmac_f32_e32 v10, v81, v81
	v_fmac_f32_e32 v10, v82, v82
	v_fmac_f32_e32 v10, v83, v83
	v_fmac_f32_e32 v10, v84, v84
	v_fmac_f32_e32 v10, v85, v85
	v_fmac_f32_e32 v10, v86, v86
	v_fmac_f32_e32 v10, v87, v87
	v_fmac_f32_e32 v10, v88, v88
	v_fmac_f32_e32 v10, v89, v89
	v_fmac_f32_e32 v10, v90, v90
	v_fmac_f32_e32 v10, v91, v91
	v_fmac_f32_e32 v10, v92, v92
	v_fmac_f32_e32 v10, v93, v93
	v_fmac_f32_e32 v10, v94, v94
	v_fmac_f32_e32 v10, v95, v95
	v_mul_f32_e32 v11, v112, v112
	v_fmac_f32_e32 v11, v113, v113
	v_fmac_f32_e32 v11, v114, v114
	v_fmac_f32_e32 v11, v115, v115
	v_fmac_f32_e32 v11, v116, v116
	v_fmac_f32_e32 v11, v117, v117
	v_fmac_f32_e32 v11, v118, v118
	v_fmac_f32_e32 v11, v119, v119
	v_fmac_f32_e32 v11, v120, v120
	v_fmac_f32_e32 v11, v121, v121
	v_fmac_f32_e32 v11, v122, v122
	v_fmac_f32_e32 v11, v123, v123
	v_fmac_f32_e32 v11, v124, v124
	v_fmac_f32_e32 v11, v125, v125
	v_fmac_f32_e32 v11, v126, v126
	v_fmac_f32_e32 v11, v127, v127
	ds_bpermute_b32 v12, v4, v10
	ds_bpermute_b32 v13, v4, v11
	s_waitcnt lgkmcnt(0)
	v_add_f32_e32 v10, v10, v12
	v_add_f32_e32 v11, v11, v13
	ds_bpermute_b32 v12, v5, v10
	ds_bpermute_b32 v13, v5, v11
	s_waitcnt lgkmcnt(0)
	v_add_f32_e32 v10, v10, v12
	v_add_f32_e32 v11, v11, v13
	ds_bpermute_b32 v12, v6, v10
	ds_bpermute_b32 v13, v6, v11
	s_waitcnt lgkmcnt(0)
	v_add_f32_e32 v10, v10, v12
	v_add_f32_e32 v11, v11, v13
	ds_bpermute_b32 v12, v7, v10
	ds_bpermute_b32 v13, v7, v11
	s_waitcnt lgkmcnt(0)
	v_add_f32_e32 v10, v10, v12
	v_add_f32_e32 v11, v11, v13
	ds_bpermute_b32 v12, v8, v10
	ds_bpermute_b32 v13, v8, v11
	s_waitcnt lgkmcnt(0)
	v_add_f32_e32 v10, v10, v12
	v_add_f32_e32 v11, v11, v13
	ds_bpermute_b32 v12, v9, v10
	ds_bpermute_b32 v13, v9, v11
	s_waitcnt lgkmcnt(0)
	v_add_f32_e32 v10, v10, v12
	v_add_f32_e32 v11, v11, v13
	v_fma_f32 v14, v10, s17, v3
	v_fma_f32 v15, v11, s17, v3
	v_rsq_f32_e32 v14, v14
	v_rsq_f32_e32 v15, v15
	s_nop 0
	v_mul_f32_e32 v64, v80, v14
	v_mul_f32_e32 v65, v81, v14
	v_mul_f32_e32 v66, v82, v14
	v_mul_f32_e32 v67, v83, v14
	v_mul_f32_e32 v68, v84, v14
	v_mul_f32_e32 v69, v85, v14
	v_mul_f32_e32 v70, v86, v14
	v_mul_f32_e32 v71, v87, v14
	v_mul_f32_e32 v72, v88, v14
	v_mul_f32_e32 v73, v89, v14
	v_mul_f32_e32 v74, v90, v14
	v_mul_f32_e32 v75, v91, v14
	v_mul_f32_e32 v76, v92, v14
	v_mul_f32_e32 v77, v93, v14
	v_mul_f32_e32 v78, v94, v14
	v_mul_f32_e32 v79, v95, v14
	v_mul_f32_e32 v64, v64, v36
	v_mul_f32_e32 v65, v65, v37
	v_mul_f32_e32 v66, v66, v38
	v_mul_f32_e32 v67, v67, v39
	v_mul_f32_e32 v68, v68, v40
	v_mul_f32_e32 v69, v69, v41
	v_mul_f32_e32 v70, v70, v42
	v_mul_f32_e32 v71, v71, v43
	v_mul_f32_e32 v72, v72, v44
	v_mul_f32_e32 v73, v73, v45
	v_mul_f32_e32 v74, v74, v46
	v_mul_f32_e32 v75, v75, v47
	v_mul_f32_e32 v76, v76, v48
	v_mul_f32_e32 v77, v77, v49
	v_mul_f32_e32 v78, v78, v50
	v_mul_f32_e32 v79, v79, v51
	v_cvt_pk_bf16_f32 v64, v64, v65
	v_cvt_pk_bf16_f32 v65, v66, v67
	v_cvt_pk_bf16_f32 v68, v68, v69
	v_cvt_pk_bf16_f32 v69, v70, v71
	v_cvt_pk_bf16_f32 v72, v72, v73
	v_cvt_pk_bf16_f32 v73, v74, v75
	v_cvt_pk_bf16_f32 v76, v76, v77
	v_cvt_pk_bf16_f32 v77, v78, v79
	global_store_dwordx2 v2, v[64:65], s[26:27] offset:0
	global_store_dwordx2 v2, v[68:69], s[26:27] offset:512
	global_store_dwordx2 v2, v[72:73], s[26:27] offset:1024
	global_store_dwordx2 v2, v[76:77], s[26:27] offset:1536
	v_mul_f32_e32 v96, v112, v15
	v_mul_f32_e32 v97, v113, v15
	v_mul_f32_e32 v98, v114, v15
	v_mul_f32_e32 v99, v115, v15
	v_mul_f32_e32 v100, v116, v15
	v_mul_f32_e32 v101, v117, v15
	v_mul_f32_e32 v102, v118, v15
	v_mul_f32_e32 v103, v119, v15
	v_mul_f32_e32 v104, v120, v15
	v_mul_f32_e32 v105, v121, v15
	v_mul_f32_e32 v106, v122, v15
	v_mul_f32_e32 v107, v123, v15
	v_mul_f32_e32 v108, v124, v15
	v_mul_f32_e32 v109, v125, v15
	v_mul_f32_e32 v110, v126, v15
	v_mul_f32_e32 v111, v127, v15
	v_mul_f32_e32 v96, v96, v36
	v_mul_f32_e32 v97, v97, v37
	v_mul_f32_e32 v98, v98, v38
	v_mul_f32_e32 v99, v99, v39
	v_mul_f32_e32 v100, v100, v40
	v_mul_f32_e32 v101, v101, v41
	v_mul_f32_e32 v102, v102, v42
	v_mul_f32_e32 v103, v103, v43
	v_mul_f32_e32 v104, v104, v44
	v_mul_f32_e32 v105, v105, v45
	v_mul_f32_e32 v106, v106, v46
	v_mul_f32_e32 v107, v107, v47
	v_mul_f32_e32 v108, v108, v48
	v_mul_f32_e32 v109, v109, v49
	v_mul_f32_e32 v110, v110, v50
	v_mul_f32_e32 v111, v111, v51
	v_cvt_pk_bf16_f32 v96, v96, v97
	v_cvt_pk_bf16_f32 v97, v98, v99
	v_cvt_pk_bf16_f32 v100, v100, v101
	v_cvt_pk_bf16_f32 v101, v102, v103
	v_cvt_pk_bf16_f32 v104, v104, v105
	v_cvt_pk_bf16_f32 v105, v106, v107
	v_cvt_pk_bf16_f32 v108, v108, v109
	v_cvt_pk_bf16_f32 v109, v110, v111
	global_store_dwordx2 v2, v[96:97], s[34:35] offset:0
	global_store_dwordx2 v2, v[100:101], s[34:35] offset:512
	global_store_dwordx2 v2, v[104:105], s[34:35] offset:1024
	global_store_dwordx2 v2, v[108:109], s[34:35] offset:1536
	s_add_u32 s53, s16, 0x2000
	s_lshl_b32 s18, s53, 12
	s_lshl_b32 s19, s53, 11
	s_add_u32 s20, s4, s18
	s_addc_u32 s21, s5, 0
	s_add_u32 s22, s6, s19
	s_addc_u32 s23, s7, 0
	s_add_u32 s22, s22, 0x5200000
	s_addc_u32 s23, s23, 0
	s_add_u32 s24, s4, s18
	s_addc_u32 s25, s5, 0
	s_add_u32 s26, s6, s19
	s_addc_u32 s27, s7, 0
	s_add_u32 s26, s26, 0x3100000
	s_addc_u32 s27, s27, 0
	global_load_dwordx2 v[66:67], v2, s[22:23] offset:0
	global_load_dwordx2 v[70:71], v2, s[22:23] offset:512
	global_load_dwordx2 v[74:75], v2, s[22:23] offset:1024
	global_load_dwordx2 v[78:79], v2, s[22:23] offset:1536
	global_load_dwordx4 v[80:83], v1, s[20:21] offset:0
	global_load_dwordx4 v[84:87], v1, s[20:21] offset:1024
	global_load_dwordx4 v[88:91], v1, s[20:21] offset:2048
	global_load_dwordx4 v[92:95], v1, s[20:21] offset:3072
	s_add_u32 s53, s16, 0x2800
	s_lshl_b32 s18, s53, 12
	s_lshl_b32 s19, s53, 11
	s_add_u32 s28, s4, s18
	s_addc_u32 s29, s5, 0
	s_add_u32 s30, s6, s19
	s_addc_u32 s31, s7, 0
	s_add_u32 s30, s30, 0x5200000
	s_addc_u32 s31, s31, 0
	s_add_u32 s32, s4, s18
	s_addc_u32 s33, s5, 0
	s_add_u32 s34, s6, s19
	s_addc_u32 s35, s7, 0
	s_add_u32 s34, s34, 0x3100000
	s_addc_u32 s35, s35, 0
	global_load_dwordx2 v[98:99], v2, s[30:31] offset:0
	global_load_dwordx2 v[102:103], v2, s[30:31] offset:512
	global_load_dwordx2 v[106:107], v2, s[30:31] offset:1024
	global_load_dwordx2 v[110:111], v2, s[30:31] offset:1536
	global_load_dwordx4 v[112:115], v1, s[28:29] offset:0
	global_load_dwordx4 v[116:119], v1, s[28:29] offset:1024
	global_load_dwordx4 v[120:123], v1, s[28:29] offset:2048
	global_load_dwordx4 v[124:127], v1, s[28:29] offset:3072
	s_waitcnt vmcnt(32)
	v_lshlrev_b32_e32 v128, 16, v130
	v_and_b32_e32 v129, 0xffff0000, v130
	v_lshlrev_b32_e32 v130, 16, v131
	v_and_b32_e32 v131, 0xffff0000, v131
	v_lshlrev_b32_e32 v132, 16, v134
	v_and_b32_e32 v133, 0xffff0000, v134
	v_lshlrev_b32_e32 v134, 16, v135
	v_and_b32_e32 v135, 0xffff0000, v135
	v_lshlrev_b32_e32 v136, 16, v138
	v_and_b32_e32 v137, 0xffff0000, v138
	v_lshlrev_b32_e32 v138, 16, v139
	v_and_b32_e32 v139, 0xffff0000, v139
	v_lshlrev_b32_e32 v140, 16, v142
	v_and_b32_e32 v141, 0xffff0000, v142
	v_lshlrev_b32_e32 v142, 16, v143
	v_and_b32_e32 v143, 0xffff0000, v143
	v_lshlrev_b32_e32 v160, 16, v162
	v_and_b32_e32 v161, 0xffff0000, v162
	v_lshlrev_b32_e32 v162, 16, v163
	v_and_b32_e32 v163, 0xffff0000, v163
	v_lshlrev_b32_e32 v164, 16, v166
	v_and_b32_e32 v165, 0xffff0000, v166
	v_lshlrev_b32_e32 v166, 16, v167
	v_and_b32_e32 v167, 0xffff0000, v167
	v_lshlrev_b32_e32 v168, 16, v170
	v_and_b32_e32 v169, 0xffff0000, v170
	v_lshlrev_b32_e32 v170, 16, v171
	v_and_b32_e32 v171, 0xffff0000, v171
	v_lshlrev_b32_e32 v172, 16, v174
	v_and_b32_e32 v173, 0xffff0000, v174
	v_lshlrev_b32_e32 v174, 16, v175
	v_and_b32_e32 v175, 0xffff0000, v175
	v_mul_f32_e32 v10, v128, v128
	v_fmac_f32_e32 v10, v129, v129
	v_fmac_f32_e32 v10, v130, v130
	v_fmac_f32_e32 v10, v131, v131
	v_fmac_f32_e32 v10, v132, v132
	v_fmac_f32_e32 v10, v133, v133
	v_fmac_f32_e32 v10, v134, v134
	v_fmac_f32_e32 v10, v135, v135
	v_fmac_f32_e32 v10, v136, v136
	v_fmac_f32_e32 v10, v137, v137
	v_fmac_f32_e32 v10, v138, v138
	v_fmac_f32_e32 v10, v139, v139
	v_fmac_f32_e32 v10, v140, v140
	v_fmac_f32_e32 v10, v141, v141
	v_fmac_f32_e32 v10, v142, v142
	v_fmac_f32_e32 v10, v143, v143
	v_mul_f32_e32 v11, v160, v160
	v_fmac_f32_e32 v11, v161, v161
	v_fmac_f32_e32 v11, v162, v162
	v_fmac_f32_e32 v11, v163, v163
	v_fmac_f32_e32 v11, v164, v164
	v_fmac_f32_e32 v11, v165, v165
	v_fmac_f32_e32 v11, v166, v166
	v_fmac_f32_e32 v11, v167, v167
	v_fmac_f32_e32 v11, v168, v168
	v_fmac_f32_e32 v11, v169, v169
	v_fmac_f32_e32 v11, v170, v170
	v_fmac_f32_e32 v11, v171, v171
	v_fmac_f32_e32 v11, v172, v172
	v_fmac_f32_e32 v11, v173, v173
	v_fmac_f32_e32 v11, v174, v174
	v_fmac_f32_e32 v11, v175, v175
	ds_bpermute_b32 v12, v4, v10
	ds_bpermute_b32 v13, v4, v11
	s_waitcnt lgkmcnt(0)
	v_add_f32_e32 v10, v10, v12
	v_add_f32_e32 v11, v11, v13
	ds_bpermute_b32 v12, v5, v10
	ds_bpermute_b32 v13, v5, v11
	s_waitcnt lgkmcnt(0)
	v_add_f32_e32 v10, v10, v12
	v_add_f32_e32 v11, v11, v13
	ds_bpermute_b32 v12, v6, v10
	ds_bpermute_b32 v13, v6, v11
	s_waitcnt lgkmcnt(0)
	v_add_f32_e32 v10, v10, v12
	v_add_f32_e32 v11, v11, v13
	ds_bpermute_b32 v12, v7, v10
	ds_bpermute_b32 v13, v7, v11
	s_waitcnt lgkmcnt(0)
	v_add_f32_e32 v10, v10, v12
	v_add_f32_e32 v11, v11, v13
	ds_bpermute_b32 v12, v8, v10
	ds_bpermute_b32 v13, v8, v11
	s_waitcnt lgkmcnt(0)
	v_add_f32_e32 v10, v10, v12
	v_add_f32_e32 v11, v11, v13
	ds_bpermute_b32 v12, v9, v10
	ds_bpermute_b32 v13, v9, v11
	s_waitcnt lgkmcnt(0)
	v_add_f32_e32 v10, v10, v12
	v_add_f32_e32 v11, v11, v13
	v_fma_f32 v14, v10, s17, v3
	v_fma_f32 v15, v11, s17, v3
	v_rsq_f32_e32 v14, v14
	v_rsq_f32_e32 v15, v15
	s_nop 0
	v_mul_f32_e32 v128, v128, v14
	v_mul_f32_e32 v129, v129, v14
	v_mul_f32_e32 v130, v130, v14
	v_mul_f32_e32 v131, v131, v14
	v_mul_f32_e32 v132, v132, v14
	v_mul_f32_e32 v133, v133, v14
	v_mul_f32_e32 v134, v134, v14
	v_mul_f32_e32 v135, v135, v14
	v_mul_f32_e32 v136, v136, v14
	v_mul_f32_e32 v137, v137, v14
	v_mul_f32_e32 v138, v138, v14
	v_mul_f32_e32 v139, v139, v14
	v_mul_f32_e32 v140, v140, v14
	v_mul_f32_e32 v141, v141, v14
	v_mul_f32_e32 v142, v142, v14
	v_mul_f32_e32 v143, v143, v14
	v_fmac_f32_e32 v144, v128, v20
	v_fmac_f32_e32 v145, v129, v21
	v_fmac_f32_e32 v146, v130, v22
	v_fmac_f32_e32 v147, v131, v23
	v_fmac_f32_e32 v148, v132, v24
	v_fmac_f32_e32 v149, v133, v25
	v_fmac_f32_e32 v150, v134, v26
	v_fmac_f32_e32 v151, v135, v27
	v_fmac_f32_e32 v152, v136, v28
	v_fmac_f32_e32 v153, v137, v29
	v_fmac_f32_e32 v154, v138, v30
	v_fmac_f32_e32 v155, v139, v31
	v_fmac_f32_e32 v156, v140, v32
	v_fmac_f32_e32 v157, v141, v33
	v_fmac_f32_e32 v158, v142, v34
	v_fmac_f32_e32 v159, v143, v35
	global_store_dwordx4 v1, v[144:147], s[40:41] offset:0
	global_store_dwordx4 v1, v[148:151], s[40:41] offset:1024
	global_store_dwordx4 v1, v[152:155], s[40:41] offset:2048
	global_store_dwordx4 v1, v[156:159], s[40:41] offset:3072
	v_mul_f32_e32 v160, v160, v15
	v_mul_f32_e32 v161, v161, v15
	v_mul_f32_e32 v162, v162, v15
	v_mul_f32_e32 v163, v163, v15
	v_mul_f32_e32 v164, v164, v15
	v_mul_f32_e32 v165, v165, v15
	v_mul_f32_e32 v166, v166, v15
	v_mul_f32_e32 v167, v167, v15
	v_mul_f32_e32 v168, v168, v15
	v_mul_f32_e32 v169, v169, v15
	v_mul_f32_e32 v170, v170, v15
	v_mul_f32_e32 v171, v171, v15
	v_mul_f32_e32 v172, v172, v15
	v_mul_f32_e32 v173, v173, v15
	v_mul_f32_e32 v174, v174, v15
	v_mul_f32_e32 v175, v175, v15
	v_fmac_f32_e32 v176, v160, v20
	v_fmac_f32_e32 v177, v161, v21
	v_fmac_f32_e32 v178, v162, v22
	v_fmac_f32_e32 v179, v163, v23
	v_fmac_f32_e32 v180, v164, v24
	v_fmac_f32_e32 v181, v165, v25
	v_fmac_f32_e32 v182, v166, v26
	v_fmac_f32_e32 v183, v167, v27
	v_fmac_f32_e32 v184, v168, v28
	v_fmac_f32_e32 v185, v169, v29
	v_fmac_f32_e32 v186, v170, v30
	v_fmac_f32_e32 v187, v171, v31
	v_fmac_f32_e32 v188, v172, v32
	v_fmac_f32_e32 v189, v173, v33
	v_fmac_f32_e32 v190, v174, v34
	v_fmac_f32_e32 v191, v175, v35
	global_store_dwordx4 v1, v[176:179], s[48:49] offset:0
	global_store_dwordx4 v1, v[180:183], s[48:49] offset:1024
	global_store_dwordx4 v1, v[184:187], s[48:49] offset:2048
	global_store_dwordx4 v1, v[188:191], s[48:49] offset:3072
	v_mul_f32_e32 v10, v144, v144
	v_fmac_f32_e32 v10, v145, v145
	v_fmac_f32_e32 v10, v146, v146
	v_fmac_f32_e32 v10, v147, v147
	v_fmac_f32_e32 v10, v148, v148
	v_fmac_f32_e32 v10, v149, v149
	v_fmac_f32_e32 v10, v150, v150
	v_fmac_f32_e32 v10, v151, v151
	v_fmac_f32_e32 v10, v152, v152
	v_fmac_f32_e32 v10, v153, v153
	v_fmac_f32_e32 v10, v154, v154
	v_fmac_f32_e32 v10, v155, v155
	v_fmac_f32_e32 v10, v156, v156
	v_fmac_f32_e32 v10, v157, v157
	v_fmac_f32_e32 v10, v158, v158
	v_fmac_f32_e32 v10, v159, v159
	v_mul_f32_e32 v11, v176, v176
	v_fmac_f32_e32 v11, v177, v177
	v_fmac_f32_e32 v11, v178, v178
	v_fmac_f32_e32 v11, v179, v179
	v_fmac_f32_e32 v11, v180, v180
	v_fmac_f32_e32 v11, v181, v181
	v_fmac_f32_e32 v11, v182, v182
	v_fmac_f32_e32 v11, v183, v183
	v_fmac_f32_e32 v11, v184, v184
	v_fmac_f32_e32 v11, v185, v185
	v_fmac_f32_e32 v11, v186, v186
	v_fmac_f32_e32 v11, v187, v187
	v_fmac_f32_e32 v11, v188, v188
	v_fmac_f32_e32 v11, v189, v189
	v_fmac_f32_e32 v11, v190, v190
	v_fmac_f32_e32 v11, v191, v191
	ds_bpermute_b32 v12, v4, v10
	ds_bpermute_b32 v13, v4, v11
	s_waitcnt lgkmcnt(0)
	v_add_f32_e32 v10, v10, v12
	v_add_f32_e32 v11, v11, v13
	ds_bpermute_b32 v12, v5, v10
	ds_bpermute_b32 v13, v5, v11
	s_waitcnt lgkmcnt(0)
	v_add_f32_e32 v10, v10, v12
	v_add_f32_e32 v11, v11, v13
	ds_bpermute_b32 v12, v6, v10
	ds_bpermute_b32 v13, v6, v11
	s_waitcnt lgkmcnt(0)
	v_add_f32_e32 v10, v10, v12
	v_add_f32_e32 v11, v11, v13
	ds_bpermute_b32 v12, v7, v10
	ds_bpermute_b32 v13, v7, v11
	s_waitcnt lgkmcnt(0)
	v_add_f32_e32 v10, v10, v12
	v_add_f32_e32 v11, v11, v13
	ds_bpermute_b32 v12, v8, v10
	ds_bpermute_b32 v13, v8, v11
	s_waitcnt lgkmcnt(0)
	v_add_f32_e32 v10, v10, v12
	v_add_f32_e32 v11, v11, v13
	ds_bpermute_b32 v12, v9, v10
	ds_bpermute_b32 v13, v9, v11
	s_waitcnt lgkmcnt(0)
	v_add_f32_e32 v10, v10, v12
	v_add_f32_e32 v11, v11, v13
	v_fma_f32 v14, v10, s17, v3
	v_fma_f32 v15, v11, s17, v3
	v_rsq_f32_e32 v14, v14
	v_rsq_f32_e32 v15, v15
	s_nop 0
	v_mul_f32_e32 v128, v144, v14
	v_mul_f32_e32 v129, v145, v14
	v_mul_f32_e32 v130, v146, v14
	v_mul_f32_e32 v131, v147, v14
	v_mul_f32_e32 v132, v148, v14
	v_mul_f32_e32 v133, v149, v14
	v_mul_f32_e32 v134, v150, v14
	v_mul_f32_e32 v135, v151, v14
	v_mul_f32_e32 v136, v152, v14
	v_mul_f32_e32 v137, v153, v14
	v_mul_f32_e32 v138, v154, v14
	v_mul_f32_e32 v139, v155, v14
	v_mul_f32_e32 v140, v156, v14
	v_mul_f32_e32 v141, v157, v14
	v_mul_f32_e32 v142, v158, v14
	v_mul_f32_e32 v143, v159, v14
	v_mul_f32_e32 v128, v128, v36
	v_mul_f32_e32 v129, v129, v37
	v_mul_f32_e32 v130, v130, v38
	v_mul_f32_e32 v131, v131, v39
	v_mul_f32_e32 v132, v132, v40
	v_mul_f32_e32 v133, v133, v41
	v_mul_f32_e32 v134, v134, v42
	v_mul_f32_e32 v135, v135, v43
	v_mul_f32_e32 v136, v136, v44
	v_mul_f32_e32 v137, v137, v45
	v_mul_f32_e32 v138, v138, v46
	v_mul_f32_e32 v139, v139, v47
	v_mul_f32_e32 v140, v140, v48
	v_mul_f32_e32 v141, v141, v49
	v_mul_f32_e32 v142, v142, v50
	v_mul_f32_e32 v143, v143, v51
	v_cvt_pk_bf16_f32 v128, v128, v129
	v_cvt_pk_bf16_f32 v129, v130, v131
	v_cvt_pk_bf16_f32 v132, v132, v133
	v_cvt_pk_bf16_f32 v133, v134, v135
	v_cvt_pk_bf16_f32 v136, v136, v137
	v_cvt_pk_bf16_f32 v137, v138, v139
	v_cvt_pk_bf16_f32 v140, v140, v141
	v_cvt_pk_bf16_f32 v141, v142, v143
	global_store_dwordx2 v2, v[128:129], s[42:43] offset:0
	global_store_dwordx2 v2, v[132:133], s[42:43] offset:512
	global_store_dwordx2 v2, v[136:137], s[42:43] offset:1024
	global_store_dwordx2 v2, v[140:141], s[42:43] offset:1536
	v_mul_f32_e32 v160, v176, v15
	v_mul_f32_e32 v161, v177, v15
	v_mul_f32_e32 v162, v178, v15
	v_mul_f32_e32 v163, v179, v15
	v_mul_f32_e32 v164, v180, v15
	v_mul_f32_e32 v165, v181, v15
	v_mul_f32_e32 v166, v182, v15
	v_mul_f32_e32 v167, v183, v15
	v_mul_f32_e32 v168, v184, v15
	v_mul_f32_e32 v169, v185, v15
	v_mul_f32_e32 v170, v186, v15
	v_mul_f32_e32 v171, v187, v15
	v_mul_f32_e32 v172, v188, v15
	v_mul_f32_e32 v173, v189, v15
	v_mul_f32_e32 v174, v190, v15
	v_mul_f32_e32 v175, v191, v15
	v_mul_f32_e32 v160, v160, v36
	v_mul_f32_e32 v161, v161, v37
	v_mul_f32_e32 v162, v162, v38
	v_mul_f32_e32 v163, v163, v39
	v_mul_f32_e32 v164, v164, v40
	v_mul_f32_e32 v165, v165, v41
	v_mul_f32_e32 v166, v166, v42
	v_mul_f32_e32 v167, v167, v43
	v_mul_f32_e32 v168, v168, v44
	v_mul_f32_e32 v169, v169, v45
	v_mul_f32_e32 v170, v170, v46
	v_mul_f32_e32 v171, v171, v47
	v_mul_f32_e32 v172, v172, v48
	v_mul_f32_e32 v173, v173, v49
	v_mul_f32_e32 v174, v174, v50
	v_mul_f32_e32 v175, v175, v51
	v_cvt_pk_bf16_f32 v160, v160, v161
	v_cvt_pk_bf16_f32 v161, v162, v163
	v_cvt_pk_bf16_f32 v164, v164, v165
	v_cvt_pk_bf16_f32 v165, v166, v167
	v_cvt_pk_bf16_f32 v168, v168, v169
	v_cvt_pk_bf16_f32 v169, v170, v171
	v_cvt_pk_bf16_f32 v172, v172, v173
	v_cvt_pk_bf16_f32 v173, v174, v175
	global_store_dwordx2 v2, v[160:161], s[50:51] offset:0
	global_store_dwordx2 v2, v[164:165], s[50:51] offset:512
	global_store_dwordx2 v2, v[168:169], s[50:51] offset:1024
	global_store_dwordx2 v2, v[172:173], s[50:51] offset:1536
	s_add_u32 s53, s16, 0x3000
	s_lshl_b32 s18, s53, 12
	s_lshl_b32 s19, s53, 11
	s_add_u32 s36, s4, s18
	s_addc_u32 s37, s5, 0
	s_add_u32 s38, s6, s19
	s_addc_u32 s39, s7, 0
	s_add_u32 s38, s38, 0x5200000
	s_addc_u32 s39, s39, 0
	s_add_u32 s40, s4, s18
	s_addc_u32 s41, s5, 0
	s_add_u32 s42, s6, s19
	s_addc_u32 s43, s7, 0
	s_add_u32 s42, s42, 0x3100000
	s_addc_u32 s43, s43, 0
	global_load_dwordx2 v[130:131], v2, s[38:39] offset:0
	global_load_dwordx2 v[134:135], v2, s[38:39] offset:512
	global_load_dwordx2 v[138:139], v2, s[38:39] offset:1024
	global_load_dwordx2 v[142:143], v2, s[38:39] offset:1536
	global_load_dwordx4 v[144:147], v1, s[36:37] offset:0
	global_load_dwordx4 v[148:151], v1, s[36:37] offset:1024
	global_load_dwordx4 v[152:155], v1, s[36:37] offset:2048
	global_load_dwordx4 v[156:159], v1, s[36:37] offset:3072
	s_add_u32 s53, s16, 0x3800
	s_lshl_b32 s18, s53, 12
	s_lshl_b32 s19, s53, 11
	s_add_u32 s44, s4, s18
	s_addc_u32 s45, s5, 0
	s_add_u32 s46, s6, s19
	s_addc_u32 s47, s7, 0
	s_add_u32 s46, s46, 0x5200000
	s_addc_u32 s47, s47, 0
	s_add_u32 s48, s4, s18
	s_addc_u32 s49, s5, 0
	s_add_u32 s50, s6, s19
	s_addc_u32 s51, s7, 0
	s_add_u32 s50, s50, 0x3100000
	s_addc_u32 s51, s51, 0
	global_load_dwordx2 v[162:163], v2, s[46:47] offset:0
	global_load_dwordx2 v[166:167], v2, s[46:47] offset:512
	global_load_dwordx2 v[170:171], v2, s[46:47] offset:1024
	global_load_dwordx2 v[174:175], v2, s[46:47] offset:1536
	global_load_dwordx4 v[176:179], v1, s[44:45] offset:0
	global_load_dwordx4 v[180:183], v1, s[44:45] offset:1024
	global_load_dwordx4 v[184:187], v1, s[44:45] offset:2048
	global_load_dwordx4 v[188:191], v1, s[44:45] offset:3072
	s_waitcnt vmcnt(32)
	v_lshlrev_b32_e32 v64, 16, v66
	v_and_b32_e32 v65, 0xffff0000, v66
	v_lshlrev_b32_e32 v66, 16, v67
	v_and_b32_e32 v67, 0xffff0000, v67
	v_lshlrev_b32_e32 v68, 16, v70
	v_and_b32_e32 v69, 0xffff0000, v70
	v_lshlrev_b32_e32 v70, 16, v71
	v_and_b32_e32 v71, 0xffff0000, v71
	v_lshlrev_b32_e32 v72, 16, v74
	v_and_b32_e32 v73, 0xffff0000, v74
	v_lshlrev_b32_e32 v74, 16, v75
	v_and_b32_e32 v75, 0xffff0000, v75
	v_lshlrev_b32_e32 v76, 16, v78
	v_and_b32_e32 v77, 0xffff0000, v78
	v_lshlrev_b32_e32 v78, 16, v79
	v_and_b32_e32 v79, 0xffff0000, v79
	v_lshlrev_b32_e32 v96, 16, v98
	v_and_b32_e32 v97, 0xffff0000, v98
	v_lshlrev_b32_e32 v98, 16, v99
	v_and_b32_e32 v99, 0xffff0000, v99
	v_lshlrev_b32_e32 v100, 16, v102
	v_and_b32_e32 v101, 0xffff0000, v102
	v_lshlrev_b32_e32 v102, 16, v103
	v_and_b32_e32 v103, 0xffff0000, v103
	v_lshlrev_b32_e32 v104, 16, v106
	v_and_b32_e32 v105, 0xffff0000, v106
	v_lshlrev_b32_e32 v106, 16, v107
	v_and_b32_e32 v107, 0xffff0000, v107
	v_lshlrev_b32_e32 v108, 16, v110
	v_and_b32_e32 v109, 0xffff0000, v110
	v_lshlrev_b32_e32 v110, 16, v111
	v_and_b32_e32 v111, 0xffff0000, v111
	v_mul_f32_e32 v10, v64, v64
	v_fmac_f32_e32 v10, v65, v65
	v_fmac_f32_e32 v10, v66, v66
	v_fmac_f32_e32 v10, v67, v67
	v_fmac_f32_e32 v10, v68, v68
	v_fmac_f32_e32 v10, v69, v69
	v_fmac_f32_e32 v10, v70, v70
	v_fmac_f32_e32 v10, v71, v71
	v_fmac_f32_e32 v10, v72, v72
	v_fmac_f32_e32 v10, v73, v73
	v_fmac_f32_e32 v10, v74, v74
	v_fmac_f32_e32 v10, v75, v75
	v_fmac_f32_e32 v10, v76, v76
	v_fmac_f32_e32 v10, v77, v77
	v_fmac_f32_e32 v10, v78, v78
	v_fmac_f32_e32 v10, v79, v79
	v_mul_f32_e32 v11, v96, v96
	v_fmac_f32_e32 v11, v97, v97
	v_fmac_f32_e32 v11, v98, v98
	v_fmac_f32_e32 v11, v99, v99
	v_fmac_f32_e32 v11, v100, v100
	v_fmac_f32_e32 v11, v101, v101
	v_fmac_f32_e32 v11, v102, v102
	v_fmac_f32_e32 v11, v103, v103
	v_fmac_f32_e32 v11, v104, v104
	v_fmac_f32_e32 v11, v105, v105
	v_fmac_f32_e32 v11, v106, v106
	v_fmac_f32_e32 v11, v107, v107
	v_fmac_f32_e32 v11, v108, v108
	v_fmac_f32_e32 v11, v109, v109
	v_fmac_f32_e32 v11, v110, v110
	v_fmac_f32_e32 v11, v111, v111
	ds_bpermute_b32 v12, v4, v10
	ds_bpermute_b32 v13, v4, v11
	s_waitcnt lgkmcnt(0)
	v_add_f32_e32 v10, v10, v12
	v_add_f32_e32 v11, v11, v13
	ds_bpermute_b32 v12, v5, v10
	ds_bpermute_b32 v13, v5, v11
	s_waitcnt lgkmcnt(0)
	v_add_f32_e32 v10, v10, v12
	v_add_f32_e32 v11, v11, v13
	ds_bpermute_b32 v12, v6, v10
	ds_bpermute_b32 v13, v6, v11
	s_waitcnt lgkmcnt(0)
	v_add_f32_e32 v10, v10, v12
	v_add_f32_e32 v11, v11, v13
	ds_bpermute_b32 v12, v7, v10
	ds_bpermute_b32 v13, v7, v11
	s_waitcnt lgkmcnt(0)
	v_add_f32_e32 v10, v10, v12
	v_add_f32_e32 v11, v11, v13
	ds_bpermute_b32 v12, v8, v10
	ds_bpermute_b32 v13, v8, v11
	s_waitcnt lgkmcnt(0)
	v_add_f32_e32 v10, v10, v12
	v_add_f32_e32 v11, v11, v13
	ds_bpermute_b32 v12, v9, v10
	ds_bpermute_b32 v13, v9, v11
	s_waitcnt lgkmcnt(0)
	v_add_f32_e32 v10, v10, v12
	v_add_f32_e32 v11, v11, v13
	v_fma_f32 v14, v10, s17, v3
	v_fma_f32 v15, v11, s17, v3
	v_rsq_f32_e32 v14, v14
	v_rsq_f32_e32 v15, v15
	s_nop 0
	v_mul_f32_e32 v64, v64, v14
	v_mul_f32_e32 v65, v65, v14
	v_mul_f32_e32 v66, v66, v14
	v_mul_f32_e32 v67, v67, v14
	v_mul_f32_e32 v68, v68, v14
	v_mul_f32_e32 v69, v69, v14
	v_mul_f32_e32 v70, v70, v14
	v_mul_f32_e32 v71, v71, v14
	v_mul_f32_e32 v72, v72, v14
	v_mul_f32_e32 v73, v73, v14
	v_mul_f32_e32 v74, v74, v14
	v_mul_f32_e32 v75, v75, v14
	v_mul_f32_e32 v76, v76, v14
	v_mul_f32_e32 v77, v77, v14
	v_mul_f32_e32 v78, v78, v14
	v_mul_f32_e32 v79, v79, v14
	v_fmac_f32_e32 v80, v64, v20
	v_fmac_f32_e32 v81, v65, v21
	v_fmac_f32_e32 v82, v66, v22
	v_fmac_f32_e32 v83, v67, v23
	v_fmac_f32_e32 v84, v68, v24
	v_fmac_f32_e32 v85, v69, v25
	v_fmac_f32_e32 v86, v70, v26
	v_fmac_f32_e32 v87, v71, v27
	v_fmac_f32_e32 v88, v72, v28
	v_fmac_f32_e32 v89, v73, v29
	v_fmac_f32_e32 v90, v74, v30
	v_fmac_f32_e32 v91, v75, v31
	v_fmac_f32_e32 v92, v76, v32
	v_fmac_f32_e32 v93, v77, v33
	v_fmac_f32_e32 v94, v78, v34
	v_fmac_f32_e32 v95, v79, v35
	global_store_dwordx4 v1, v[80:83], s[24:25] offset:0
	global_store_dwordx4 v1, v[84:87], s[24:25] offset:1024
	global_store_dwordx4 v1, v[88:91], s[24:25] offset:2048
	global_store_dwordx4 v1, v[92:95], s[24:25] offset:3072
	v_mul_f32_e32 v96, v96, v15
	v_mul_f32_e32 v97, v97, v15
	v_mul_f32_e32 v98, v98, v15
	v_mul_f32_e32 v99, v99, v15
	v_mul_f32_e32 v100, v100, v15
	v_mul_f32_e32 v101, v101, v15
	v_mul_f32_e32 v102, v102, v15
	v_mul_f32_e32 v103, v103, v15
	v_mul_f32_e32 v104, v104, v15
	v_mul_f32_e32 v105, v105, v15
	v_mul_f32_e32 v106, v106, v15
	v_mul_f32_e32 v107, v107, v15
	v_mul_f32_e32 v108, v108, v15
	v_mul_f32_e32 v109, v109, v15
	v_mul_f32_e32 v110, v110, v15
	v_mul_f32_e32 v111, v111, v15
	v_fmac_f32_e32 v112, v96, v20
	v_fmac_f32_e32 v113, v97, v21
	v_fmac_f32_e32 v114, v98, v22
	v_fmac_f32_e32 v115, v99, v23
	v_fmac_f32_e32 v116, v100, v24
	v_fmac_f32_e32 v117, v101, v25
	v_fmac_f32_e32 v118, v102, v26
	v_fmac_f32_e32 v119, v103, v27
	v_fmac_f32_e32 v120, v104, v28
	v_fmac_f32_e32 v121, v105, v29
	v_fmac_f32_e32 v122, v106, v30
	v_fmac_f32_e32 v123, v107, v31
	v_fmac_f32_e32 v124, v108, v32
	v_fmac_f32_e32 v125, v109, v33
	v_fmac_f32_e32 v126, v110, v34
	v_fmac_f32_e32 v127, v111, v35
	global_store_dwordx4 v1, v[112:115], s[32:33] offset:0
	global_store_dwordx4 v1, v[116:119], s[32:33] offset:1024
	global_store_dwordx4 v1, v[120:123], s[32:33] offset:2048
	global_store_dwordx4 v1, v[124:127], s[32:33] offset:3072
	v_mul_f32_e32 v10, v80, v80
	v_fmac_f32_e32 v10, v81, v81
	v_fmac_f32_e32 v10, v82, v82
	v_fmac_f32_e32 v10, v83, v83
	v_fmac_f32_e32 v10, v84, v84
	v_fmac_f32_e32 v10, v85, v85
	v_fmac_f32_e32 v10, v86, v86
	v_fmac_f32_e32 v10, v87, v87
	v_fmac_f32_e32 v10, v88, v88
	v_fmac_f32_e32 v10, v89, v89
	v_fmac_f32_e32 v10, v90, v90
	v_fmac_f32_e32 v10, v91, v91
	v_fmac_f32_e32 v10, v92, v92
	v_fmac_f32_e32 v10, v93, v93
	v_fmac_f32_e32 v10, v94, v94
	v_fmac_f32_e32 v10, v95, v95
	v_mul_f32_e32 v11, v112, v112
	v_fmac_f32_e32 v11, v113, v113
	v_fmac_f32_e32 v11, v114, v114
	v_fmac_f32_e32 v11, v115, v115
	v_fmac_f32_e32 v11, v116, v116
	v_fmac_f32_e32 v11, v117, v117
	v_fmac_f32_e32 v11, v118, v118
	v_fmac_f32_e32 v11, v119, v119
	v_fmac_f32_e32 v11, v120, v120
	v_fmac_f32_e32 v11, v121, v121
	v_fmac_f32_e32 v11, v122, v122
	v_fmac_f32_e32 v11, v123, v123
	v_fmac_f32_e32 v11, v124, v124
	v_fmac_f32_e32 v11, v125, v125
	v_fmac_f32_e32 v11, v126, v126
	v_fmac_f32_e32 v11, v127, v127
	ds_bpermute_b32 v12, v4, v10
	ds_bpermute_b32 v13, v4, v11
	s_waitcnt lgkmcnt(0)
	v_add_f32_e32 v10, v10, v12
	v_add_f32_e32 v11, v11, v13
	ds_bpermute_b32 v12, v5, v10
	ds_bpermute_b32 v13, v5, v11
	s_waitcnt lgkmcnt(0)
	v_add_f32_e32 v10, v10, v12
	v_add_f32_e32 v11, v11, v13
	ds_bpermute_b32 v12, v6, v10
	ds_bpermute_b32 v13, v6, v11
	s_waitcnt lgkmcnt(0)
	v_add_f32_e32 v10, v10, v12
	v_add_f32_e32 v11, v11, v13
	ds_bpermute_b32 v12, v7, v10
	ds_bpermute_b32 v13, v7, v11
	s_waitcnt lgkmcnt(0)
	v_add_f32_e32 v10, v10, v12
	v_add_f32_e32 v11, v11, v13
	ds_bpermute_b32 v12, v8, v10
	ds_bpermute_b32 v13, v8, v11
	s_waitcnt lgkmcnt(0)
	v_add_f32_e32 v10, v10, v12
	v_add_f32_e32 v11, v11, v13
	ds_bpermute_b32 v12, v9, v10
	ds_bpermute_b32 v13, v9, v11
	s_waitcnt lgkmcnt(0)
	v_add_f32_e32 v10, v10, v12
	v_add_f32_e32 v11, v11, v13
	v_fma_f32 v14, v10, s17, v3
	v_fma_f32 v15, v11, s17, v3
	v_rsq_f32_e32 v14, v14
	v_rsq_f32_e32 v15, v15
	s_nop 0
	v_mul_f32_e32 v64, v80, v14
	v_mul_f32_e32 v65, v81, v14
	v_mul_f32_e32 v66, v82, v14
	v_mul_f32_e32 v67, v83, v14
	v_mul_f32_e32 v68, v84, v14
	v_mul_f32_e32 v69, v85, v14
	v_mul_f32_e32 v70, v86, v14
	v_mul_f32_e32 v71, v87, v14
	v_mul_f32_e32 v72, v88, v14
	v_mul_f32_e32 v73, v89, v14
	v_mul_f32_e32 v74, v90, v14
	v_mul_f32_e32 v75, v91, v14
	v_mul_f32_e32 v76, v92, v14
	v_mul_f32_e32 v77, v93, v14
	v_mul_f32_e32 v78, v94, v14
	v_mul_f32_e32 v79, v95, v14
	v_mul_f32_e32 v64, v64, v36
	v_mul_f32_e32 v65, v65, v37
	v_mul_f32_e32 v66, v66, v38
	v_mul_f32_e32 v67, v67, v39
	v_mul_f32_e32 v68, v68, v40
	v_mul_f32_e32 v69, v69, v41
	v_mul_f32_e32 v70, v70, v42
	v_mul_f32_e32 v71, v71, v43
	v_mul_f32_e32 v72, v72, v44
	v_mul_f32_e32 v73, v73, v45
	v_mul_f32_e32 v74, v74, v46
	v_mul_f32_e32 v75, v75, v47
	v_mul_f32_e32 v76, v76, v48
	v_mul_f32_e32 v77, v77, v49
	v_mul_f32_e32 v78, v78, v50
	v_mul_f32_e32 v79, v79, v51
	v_cvt_pk_bf16_f32 v64, v64, v65
	v_cvt_pk_bf16_f32 v65, v66, v67
	v_cvt_pk_bf16_f32 v68, v68, v69
	v_cvt_pk_bf16_f32 v69, v70, v71
	v_cvt_pk_bf16_f32 v72, v72, v73
	v_cvt_pk_bf16_f32 v73, v74, v75
	v_cvt_pk_bf16_f32 v76, v76, v77
	v_cvt_pk_bf16_f32 v77, v78, v79
	global_store_dwordx2 v2, v[64:65], s[26:27] offset:0
	global_store_dwordx2 v2, v[68:69], s[26:27] offset:512
	global_store_dwordx2 v2, v[72:73], s[26:27] offset:1024
	global_store_dwordx2 v2, v[76:77], s[26:27] offset:1536
	v_mul_f32_e32 v96, v112, v15
	v_mul_f32_e32 v97, v113, v15
	v_mul_f32_e32 v98, v114, v15
	v_mul_f32_e32 v99, v115, v15
	v_mul_f32_e32 v100, v116, v15
	v_mul_f32_e32 v101, v117, v15
	v_mul_f32_e32 v102, v118, v15
	v_mul_f32_e32 v103, v119, v15
	v_mul_f32_e32 v104, v120, v15
	v_mul_f32_e32 v105, v121, v15
	v_mul_f32_e32 v106, v122, v15
	v_mul_f32_e32 v107, v123, v15
	v_mul_f32_e32 v108, v124, v15
	v_mul_f32_e32 v109, v125, v15
	v_mul_f32_e32 v110, v126, v15
	v_mul_f32_e32 v111, v127, v15
	v_mul_f32_e32 v96, v96, v36
	v_mul_f32_e32 v97, v97, v37
	v_mul_f32_e32 v98, v98, v38
	v_mul_f32_e32 v99, v99, v39
	v_mul_f32_e32 v100, v100, v40
	v_mul_f32_e32 v101, v101, v41
	v_mul_f32_e32 v102, v102, v42
	v_mul_f32_e32 v103, v103, v43
	v_mul_f32_e32 v104, v104, v44
	v_mul_f32_e32 v105, v105, v45
	v_mul_f32_e32 v106, v106, v46
	v_mul_f32_e32 v107, v107, v47
	v_mul_f32_e32 v108, v108, v48
	v_mul_f32_e32 v109, v109, v49
	v_mul_f32_e32 v110, v110, v50
	v_mul_f32_e32 v111, v111, v51
	v_cvt_pk_bf16_f32 v96, v96, v97
	v_cvt_pk_bf16_f32 v97, v98, v99
	v_cvt_pk_bf16_f32 v100, v100, v101
	v_cvt_pk_bf16_f32 v101, v102, v103
	v_cvt_pk_bf16_f32 v104, v104, v105
	v_cvt_pk_bf16_f32 v105, v106, v107
	v_cvt_pk_bf16_f32 v108, v108, v109
	v_cvt_pk_bf16_f32 v109, v110, v111
	global_store_dwordx2 v2, v[96:97], s[34:35] offset:0
	global_store_dwordx2 v2, v[100:101], s[34:35] offset:512
	global_store_dwordx2 v2, v[104:105], s[34:35] offset:1024
	global_store_dwordx2 v2, v[108:109], s[34:35] offset:1536
	s_waitcnt vmcnt(16)
	v_lshlrev_b32_e32 v128, 16, v130
	v_and_b32_e32 v129, 0xffff0000, v130
	v_lshlrev_b32_e32 v130, 16, v131
	v_and_b32_e32 v131, 0xffff0000, v131
	v_lshlrev_b32_e32 v132, 16, v134
	v_and_b32_e32 v133, 0xffff0000, v134
	v_lshlrev_b32_e32 v134, 16, v135
	v_and_b32_e32 v135, 0xffff0000, v135
	v_lshlrev_b32_e32 v136, 16, v138
	v_and_b32_e32 v137, 0xffff0000, v138
	v_lshlrev_b32_e32 v138, 16, v139
	v_and_b32_e32 v139, 0xffff0000, v139
	v_lshlrev_b32_e32 v140, 16, v142
	v_and_b32_e32 v141, 0xffff0000, v142
	v_lshlrev_b32_e32 v142, 16, v143
	v_and_b32_e32 v143, 0xffff0000, v143
	v_lshlrev_b32_e32 v160, 16, v162
	v_and_b32_e32 v161, 0xffff0000, v162
	v_lshlrev_b32_e32 v162, 16, v163
	v_and_b32_e32 v163, 0xffff0000, v163
	v_lshlrev_b32_e32 v164, 16, v166
	v_and_b32_e32 v165, 0xffff0000, v166
	v_lshlrev_b32_e32 v166, 16, v167
	v_and_b32_e32 v167, 0xffff0000, v167
	v_lshlrev_b32_e32 v168, 16, v170
	v_and_b32_e32 v169, 0xffff0000, v170
	v_lshlrev_b32_e32 v170, 16, v171
	v_and_b32_e32 v171, 0xffff0000, v171
	v_lshlrev_b32_e32 v172, 16, v174
	v_and_b32_e32 v173, 0xffff0000, v174
	v_lshlrev_b32_e32 v174, 16, v175
	v_and_b32_e32 v175, 0xffff0000, v175
	v_mul_f32_e32 v10, v128, v128
	v_fmac_f32_e32 v10, v129, v129
	v_fmac_f32_e32 v10, v130, v130
	v_fmac_f32_e32 v10, v131, v131
	v_fmac_f32_e32 v10, v132, v132
	v_fmac_f32_e32 v10, v133, v133
	v_fmac_f32_e32 v10, v134, v134
	v_fmac_f32_e32 v10, v135, v135
	v_fmac_f32_e32 v10, v136, v136
	v_fmac_f32_e32 v10, v137, v137
	v_fmac_f32_e32 v10, v138, v138
	v_fmac_f32_e32 v10, v139, v139
	v_fmac_f32_e32 v10, v140, v140
	v_fmac_f32_e32 v10, v141, v141
	v_fmac_f32_e32 v10, v142, v142
	v_fmac_f32_e32 v10, v143, v143
	v_mul_f32_e32 v11, v160, v160
	v_fmac_f32_e32 v11, v161, v161
	v_fmac_f32_e32 v11, v162, v162
	v_fmac_f32_e32 v11, v163, v163
	v_fmac_f32_e32 v11, v164, v164
	v_fmac_f32_e32 v11, v165, v165
	v_fmac_f32_e32 v11, v166, v166
	v_fmac_f32_e32 v11, v167, v167
	v_fmac_f32_e32 v11, v168, v168
	v_fmac_f32_e32 v11, v169, v169
	v_fmac_f32_e32 v11, v170, v170
	v_fmac_f32_e32 v11, v171, v171
	v_fmac_f32_e32 v11, v172, v172
	v_fmac_f32_e32 v11, v173, v173
	v_fmac_f32_e32 v11, v174, v174
	v_fmac_f32_e32 v11, v175, v175
	ds_bpermute_b32 v12, v4, v10
	ds_bpermute_b32 v13, v4, v11
	s_waitcnt lgkmcnt(0)
	v_add_f32_e32 v10, v10, v12
	v_add_f32_e32 v11, v11, v13
	ds_bpermute_b32 v12, v5, v10
	ds_bpermute_b32 v13, v5, v11
	s_waitcnt lgkmcnt(0)
	v_add_f32_e32 v10, v10, v12
	v_add_f32_e32 v11, v11, v13
	ds_bpermute_b32 v12, v6, v10
	ds_bpermute_b32 v13, v6, v11
	s_waitcnt lgkmcnt(0)
	v_add_f32_e32 v10, v10, v12
	v_add_f32_e32 v11, v11, v13
	ds_bpermute_b32 v12, v7, v10
	ds_bpermute_b32 v13, v7, v11
	s_waitcnt lgkmcnt(0)
	v_add_f32_e32 v10, v10, v12
	v_add_f32_e32 v11, v11, v13
	ds_bpermute_b32 v12, v8, v10
	ds_bpermute_b32 v13, v8, v11
	s_waitcnt lgkmcnt(0)
	v_add_f32_e32 v10, v10, v12
	v_add_f32_e32 v11, v11, v13
	ds_bpermute_b32 v12, v9, v10
	ds_bpermute_b32 v13, v9, v11
	s_waitcnt lgkmcnt(0)
	v_add_f32_e32 v10, v10, v12
	v_add_f32_e32 v11, v11, v13
	v_fma_f32 v14, v10, s17, v3
	v_fma_f32 v15, v11, s17, v3
	v_rsq_f32_e32 v14, v14
	v_rsq_f32_e32 v15, v15
	s_nop 0
	v_mul_f32_e32 v128, v128, v14
	v_mul_f32_e32 v129, v129, v14
	v_mul_f32_e32 v130, v130, v14
	v_mul_f32_e32 v131, v131, v14
	v_mul_f32_e32 v132, v132, v14
	v_mul_f32_e32 v133, v133, v14
	v_mul_f32_e32 v134, v134, v14
	v_mul_f32_e32 v135, v135, v14
	v_mul_f32_e32 v136, v136, v14
	v_mul_f32_e32 v137, v137, v14
	v_mul_f32_e32 v138, v138, v14
	v_mul_f32_e32 v139, v139, v14
	v_mul_f32_e32 v140, v140, v14
	v_mul_f32_e32 v141, v141, v14
	v_mul_f32_e32 v142, v142, v14
	v_mul_f32_e32 v143, v143, v14
	v_fmac_f32_e32 v144, v128, v20
	v_fmac_f32_e32 v145, v129, v21
	v_fmac_f32_e32 v146, v130, v22
	v_fmac_f32_e32 v147, v131, v23
	v_fmac_f32_e32 v148, v132, v24
	v_fmac_f32_e32 v149, v133, v25
	v_fmac_f32_e32 v150, v134, v26
	v_fmac_f32_e32 v151, v135, v27
	v_fmac_f32_e32 v152, v136, v28
	v_fmac_f32_e32 v153, v137, v29
	v_fmac_f32_e32 v154, v138, v30
	v_fmac_f32_e32 v155, v139, v31
	v_fmac_f32_e32 v156, v140, v32
	v_fmac_f32_e32 v157, v141, v33
	v_fmac_f32_e32 v158, v142, v34
	v_fmac_f32_e32 v159, v143, v35
	global_store_dwordx4 v1, v[144:147], s[40:41] offset:0
	global_store_dwordx4 v1, v[148:151], s[40:41] offset:1024
	global_store_dwordx4 v1, v[152:155], s[40:41] offset:2048
	global_store_dwordx4 v1, v[156:159], s[40:41] offset:3072
	v_mul_f32_e32 v160, v160, v15
	v_mul_f32_e32 v161, v161, v15
	v_mul_f32_e32 v162, v162, v15
	v_mul_f32_e32 v163, v163, v15
	v_mul_f32_e32 v164, v164, v15
	v_mul_f32_e32 v165, v165, v15
	v_mul_f32_e32 v166, v166, v15
	v_mul_f32_e32 v167, v167, v15
	v_mul_f32_e32 v168, v168, v15
	v_mul_f32_e32 v169, v169, v15
	v_mul_f32_e32 v170, v170, v15
	v_mul_f32_e32 v171, v171, v15
	v_mul_f32_e32 v172, v172, v15
	v_mul_f32_e32 v173, v173, v15
	v_mul_f32_e32 v174, v174, v15
	v_mul_f32_e32 v175, v175, v15
	v_fmac_f32_e32 v176, v160, v20
	v_fmac_f32_e32 v177, v161, v21
	v_fmac_f32_e32 v178, v162, v22
	v_fmac_f32_e32 v179, v163, v23
	v_fmac_f32_e32 v180, v164, v24
	v_fmac_f32_e32 v181, v165, v25
	v_fmac_f32_e32 v182, v166, v26
	v_fmac_f32_e32 v183, v167, v27
	v_fmac_f32_e32 v184, v168, v28
	v_fmac_f32_e32 v185, v169, v29
	v_fmac_f32_e32 v186, v170, v30
	v_fmac_f32_e32 v187, v171, v31
	v_fmac_f32_e32 v188, v172, v32
	v_fmac_f32_e32 v189, v173, v33
	v_fmac_f32_e32 v190, v174, v34
	v_fmac_f32_e32 v191, v175, v35
	global_store_dwordx4 v1, v[176:179], s[48:49] offset:0
	global_store_dwordx4 v1, v[180:183], s[48:49] offset:1024
	global_store_dwordx4 v1, v[184:187], s[48:49] offset:2048
	global_store_dwordx4 v1, v[188:191], s[48:49] offset:3072
	v_mul_f32_e32 v10, v144, v144
	v_fmac_f32_e32 v10, v145, v145
	v_fmac_f32_e32 v10, v146, v146
	v_fmac_f32_e32 v10, v147, v147
	v_fmac_f32_e32 v10, v148, v148
	v_fmac_f32_e32 v10, v149, v149
	v_fmac_f32_e32 v10, v150, v150
	v_fmac_f32_e32 v10, v151, v151
	v_fmac_f32_e32 v10, v152, v152
	v_fmac_f32_e32 v10, v153, v153
	v_fmac_f32_e32 v10, v154, v154
	v_fmac_f32_e32 v10, v155, v155
	v_fmac_f32_e32 v10, v156, v156
	v_fmac_f32_e32 v10, v157, v157
	v_fmac_f32_e32 v10, v158, v158
	v_fmac_f32_e32 v10, v159, v159
	v_mul_f32_e32 v11, v176, v176
	v_fmac_f32_e32 v11, v177, v177
	v_fmac_f32_e32 v11, v178, v178
	v_fmac_f32_e32 v11, v179, v179
	v_fmac_f32_e32 v11, v180, v180
	v_fmac_f32_e32 v11, v181, v181
	v_fmac_f32_e32 v11, v182, v182
	v_fmac_f32_e32 v11, v183, v183
	v_fmac_f32_e32 v11, v184, v184
	v_fmac_f32_e32 v11, v185, v185
	v_fmac_f32_e32 v11, v186, v186
	v_fmac_f32_e32 v11, v187, v187
	v_fmac_f32_e32 v11, v188, v188
	v_fmac_f32_e32 v11, v189, v189
	v_fmac_f32_e32 v11, v190, v190
	v_fmac_f32_e32 v11, v191, v191
	ds_bpermute_b32 v12, v4, v10
	ds_bpermute_b32 v13, v4, v11
	s_waitcnt lgkmcnt(0)
	v_add_f32_e32 v10, v10, v12
	v_add_f32_e32 v11, v11, v13
	ds_bpermute_b32 v12, v5, v10
	ds_bpermute_b32 v13, v5, v11
	s_waitcnt lgkmcnt(0)
	v_add_f32_e32 v10, v10, v12
	v_add_f32_e32 v11, v11, v13
	ds_bpermute_b32 v12, v6, v10
	ds_bpermute_b32 v13, v6, v11
	s_waitcnt lgkmcnt(0)
	v_add_f32_e32 v10, v10, v12
	v_add_f32_e32 v11, v11, v13
	ds_bpermute_b32 v12, v7, v10
	ds_bpermute_b32 v13, v7, v11
	s_waitcnt lgkmcnt(0)
	v_add_f32_e32 v10, v10, v12
	v_add_f32_e32 v11, v11, v13
	ds_bpermute_b32 v12, v8, v10
	ds_bpermute_b32 v13, v8, v11
	s_waitcnt lgkmcnt(0)
	v_add_f32_e32 v10, v10, v12
	v_add_f32_e32 v11, v11, v13
	ds_bpermute_b32 v12, v9, v10
	ds_bpermute_b32 v13, v9, v11
	s_waitcnt lgkmcnt(0)
	v_add_f32_e32 v10, v10, v12
	v_add_f32_e32 v11, v11, v13
	v_fma_f32 v14, v10, s17, v3
	v_fma_f32 v15, v11, s17, v3
	v_rsq_f32_e32 v14, v14
	v_rsq_f32_e32 v15, v15
	s_nop 0
	v_mul_f32_e32 v128, v144, v14
	v_mul_f32_e32 v129, v145, v14
	v_mul_f32_e32 v130, v146, v14
	v_mul_f32_e32 v131, v147, v14
	v_mul_f32_e32 v132, v148, v14
	v_mul_f32_e32 v133, v149, v14
	v_mul_f32_e32 v134, v150, v14
	v_mul_f32_e32 v135, v151, v14
	v_mul_f32_e32 v136, v152, v14
	v_mul_f32_e32 v137, v153, v14
	v_mul_f32_e32 v138, v154, v14
	v_mul_f32_e32 v139, v155, v14
	v_mul_f32_e32 v140, v156, v14
	v_mul_f32_e32 v141, v157, v14
	v_mul_f32_e32 v142, v158, v14
	v_mul_f32_e32 v143, v159, v14
	v_mul_f32_e32 v128, v128, v36
	v_mul_f32_e32 v129, v129, v37
	v_mul_f32_e32 v130, v130, v38
	v_mul_f32_e32 v131, v131, v39
	v_mul_f32_e32 v132, v132, v40
	v_mul_f32_e32 v133, v133, v41
	v_mul_f32_e32 v134, v134, v42
	v_mul_f32_e32 v135, v135, v43
	v_mul_f32_e32 v136, v136, v44
	v_mul_f32_e32 v137, v137, v45
	v_mul_f32_e32 v138, v138, v46
	v_mul_f32_e32 v139, v139, v47
	v_mul_f32_e32 v140, v140, v48
	v_mul_f32_e32 v141, v141, v49
	v_mul_f32_e32 v142, v142, v50
	v_mul_f32_e32 v143, v143, v51
	v_cvt_pk_bf16_f32 v128, v128, v129
	v_cvt_pk_bf16_f32 v129, v130, v131
	v_cvt_pk_bf16_f32 v132, v132, v133
	v_cvt_pk_bf16_f32 v133, v134, v135
	v_cvt_pk_bf16_f32 v136, v136, v137
	v_cvt_pk_bf16_f32 v137, v138, v139
	v_cvt_pk_bf16_f32 v140, v140, v141
	v_cvt_pk_bf16_f32 v141, v142, v143
	global_store_dwordx2 v2, v[128:129], s[42:43] offset:0
	global_store_dwordx2 v2, v[132:133], s[42:43] offset:512
	global_store_dwordx2 v2, v[136:137], s[42:43] offset:1024
	global_store_dwordx2 v2, v[140:141], s[42:43] offset:1536
	v_mul_f32_e32 v160, v176, v15
	v_mul_f32_e32 v161, v177, v15
	v_mul_f32_e32 v162, v178, v15
	v_mul_f32_e32 v163, v179, v15
	v_mul_f32_e32 v164, v180, v15
	v_mul_f32_e32 v165, v181, v15
	v_mul_f32_e32 v166, v182, v15
	v_mul_f32_e32 v167, v183, v15
	v_mul_f32_e32 v168, v184, v15
	v_mul_f32_e32 v169, v185, v15
	v_mul_f32_e32 v170, v186, v15
	v_mul_f32_e32 v171, v187, v15
	v_mul_f32_e32 v172, v188, v15
	v_mul_f32_e32 v173, v189, v15
	v_mul_f32_e32 v174, v190, v15
	v_mul_f32_e32 v175, v191, v15
	v_mul_f32_e32 v160, v160, v36
	v_mul_f32_e32 v161, v161, v37
	v_mul_f32_e32 v162, v162, v38
	v_mul_f32_e32 v163, v163, v39
	v_mul_f32_e32 v164, v164, v40
	v_mul_f32_e32 v165, v165, v41
	v_mul_f32_e32 v166, v166, v42
	v_mul_f32_e32 v167, v167, v43
	v_mul_f32_e32 v168, v168, v44
	v_mul_f32_e32 v169, v169, v45
	v_mul_f32_e32 v170, v170, v46
	v_mul_f32_e32 v171, v171, v47
	v_mul_f32_e32 v172, v172, v48
	v_mul_f32_e32 v173, v173, v49
	v_mul_f32_e32 v174, v174, v50
	v_mul_f32_e32 v175, v175, v51
	v_cvt_pk_bf16_f32 v160, v160, v161
	v_cvt_pk_bf16_f32 v161, v162, v163
	v_cvt_pk_bf16_f32 v164, v164, v165
	v_cvt_pk_bf16_f32 v165, v166, v167
	v_cvt_pk_bf16_f32 v168, v168, v169
	v_cvt_pk_bf16_f32 v169, v170, v171
	v_cvt_pk_bf16_f32 v172, v172, v173
	v_cvt_pk_bf16_f32 v173, v174, v175
	global_store_dwordx2 v2, v[160:161], s[50:51] offset:0
	global_store_dwordx2 v2, v[164:165], s[50:51] offset:512
	global_store_dwordx2 v2, v[168:169], s[50:51] offset:1024
	global_store_dwordx2 v2, v[172:173], s[50:51] offset:1536
	s_and_b32 s18, s16, 3
	s_cmp_lg_u32 s18, 0
	s_cbranch_scc1 .Lrows7_end
	s_lshr_b32 s54, s16, 2
	s_add_u32 s53, s54, 0x4000
	s_lshl_b32 s18, s53, 12
	s_lshl_b32 s19, s53, 11
	s_add_u32 s20, s4, s18
	s_addc_u32 s21, s5, 0
	s_add_u32 s24, s4, s18
	s_addc_u32 s25, s5, 0
	s_add_u32 s26, s6, s19
	s_addc_u32 s27, s7, 0
	s_add_u32 s26, s26, 0x3100000
	s_addc_u32 s27, s27, 0
	s_lshl_b32 s18, s54, 12
	s_add_u32 s22, s6, s18
	s_addc_u32 s23, s7, 0
	s_add_u32 s22, s22, 0x100000
	s_addc_u32 s23, s23, 0
	global_load_dwordx4 v[64:67], v1, s[22:23] offset:0
	global_load_dwordx4 v[68:71], v1, s[22:23] offset:1024
	global_load_dwordx4 v[72:75], v1, s[22:23] offset:2048
	global_load_dwordx4 v[76:79], v1, s[22:23] offset:3072
	s_add_u32 s22, s22, 0x200000
	s_addc_u32 s23, s23, 0
	global_load_dwordx4 v[80:83], v1, s[22:23] offset:0
	global_load_dwordx4 v[84:87], v1, s[22:23] offset:1024
	global_load_dwordx4 v[88:91], v1, s[22:23] offset:2048
	global_load_dwordx4 v[92:95], v1, s[22:23] offset:3072
	s_add_u32 s22, s22, 0x200000
	s_addc_u32 s23, s23, 0
	global_load_dwordx4 v[96:99], v1, s[22:23] offset:0
	global_load_dwordx4 v[100:103], v1, s[22:23] offset:1024
	global_load_dwordx4 v[104:107], v1, s[22:23] offset:2048
	global_load_dwordx4 v[108:111], v1, s[22:23] offset:3072
	s_add_u32 s22, s22, 0x200000
	s_addc_u32 s23, s23, 0
	global_load_dwordx4 v[112:115], v1, s[22:23] offset:0
	global_load_dwordx4 v[116:119], v1, s[22:23] offset:1024
	global_load_dwordx4 v[120:123], v1, s[22:23] offset:2048
	global_load_dwordx4 v[124:127], v1, s[22:23] offset:3072
	s_add_u32 s22, s22, 0x200000
	s_addc_u32 s23, s23, 0
	global_load_dwordx4 v[128:131], v1, s[22:23] offset:0
	global_load_dwordx4 v[132:135], v1, s[22:23] offset:1024
	global_load_dwordx4 v[136:139], v1, s[22:23] offset:2048
	global_load_dwordx4 v[140:143], v1, s[22:23] offset:3072
	s_add_u32 s22, s22, 0x200000
	s_addc_u32 s23, s23, 0
	global_load_dwordx4 v[144:147], v1, s[22:23] offset:0
	global_load_dwordx4 v[148:151], v1, s[22:23] offset:1024
	global_load_dwordx4 v[152:155], v1, s[22:23] offset:2048
	global_load_dwordx4 v[156:159], v1, s[22:23] offset:3072
	s_add_u32 s22, s22, 0x200000
	s_addc_u32 s23, s23, 0
	global_load_dwordx4 v[160:163], v1, s[22:23] offset:0
	global_load_dwordx4 v[164:167], v1, s[22:23] offset:1024
	global_load_dwordx4 v[168:171], v1, s[22:23] offset:2048
	global_load_dwordx4 v[172:175], v1, s[22:23] offset:3072
	s_add_u32 s22, s22, 0x200000
	s_addc_u32 s23, s23, 0
	global_load_dwordx4 v[176:179], v1, s[22:23] offset:0
	global_load_dwordx4 v[180:183], v1, s[22:23] offset:1024
	global_load_dwordx4 v[184:187], v1, s[22:23] offset:2048
	global_load_dwordx4 v[188:191], v1, s[22:23] offset:3072
	global_load_dwordx4 v[192:195], v1, s[20:21] offset:0
	global_load_dwordx4 v[196:199], v1, s[20:21] offset:1024
	global_load_dwordx4 v[200:203], v1, s[20:21] offset:2048
	global_load_dwordx4 v[204:207], v1, s[20:21] offset:3072
	s_waitcnt vmcnt(0)
	v_add_f32_e32 v64, v64, v80
	v_add_f32_e32 v65, v65, v81
	v_add_f32_e32 v66, v66, v82
	v_add_f32_e32 v67, v67, v83
	v_add_f32_e32 v68, v68, v84
	v_add_f32_e32 v69, v69, v85
	v_add_f32_e32 v70, v70, v86
	v_add_f32_e32 v71, v71, v87
	v_add_f32_e32 v72, v72, v88
	v_add_f32_e32 v73, v73, v89
	v_add_f32_e32 v74, v74, v90
	v_add_f32_e32 v75, v75, v91
	v_add_f32_e32 v76, v76, v92
	v_add_f32_e32 v77, v77, v93
	v_add_f32_e32 v78, v78, v94
	v_add_f32_e32 v79, v79, v95
	v_add_f32_e32 v96, v96, v112
	v_add_f32_e32 v97, v97, v113
	v_add_f32_e32 v98, v98, v114
	v_add_f32_e32 v99, v99, v115
	v_add_f32_e32 v100, v100, v116
	v_add_f32_e32 v101, v101, v117
	v_add_f32_e32 v102, v102, v118
	v_add_f32_e32 v103, v103, v119
	v_add_f32_e32 v104, v104, v120
	v_add_f32_e32 v105, v105, v121
	v_add_f32_e32 v106, v106, v122
	v_add_f32_e32 v107, v107, v123
	v_add_f32_e32 v108, v108, v124
	v_add_f32_e32 v109, v109, v125
	v_add_f32_e32 v110, v110, v126
	v_add_f32_e32 v111, v111, v127
	v_add_f32_e32 v128, v128, v144
	v_add_f32_e32 v129, v129, v145
	v_add_f32_e32 v130, v130, v146
	v_add_f32_e32 v131, v131, v147
	v_add_f32_e32 v132, v132, v148
	v_add_f32_e32 v133, v133, v149
	v_add_f32_e32 v134, v134, v150
	v_add_f32_e32 v135, v135, v151
	v_add_f32_e32 v136, v136, v152
	v_add_f32_e32 v137, v137, v153
	v_add_f32_e32 v138, v138, v154
	v_add_f32_e32 v139, v139, v155
	v_add_f32_e32 v140, v140, v156
	v_add_f32_e32 v141, v141, v157
	v_add_f32_e32 v142, v142, v158
	v_add_f32_e32 v143, v143, v159
	v_add_f32_e32 v160, v160, v176
	v_add_f32_e32 v161, v161, v177
	v_add_f32_e32 v162, v162, v178
	v_add_f32_e32 v163, v163, v179
	v_add_f32_e32 v164, v164, v180
	v_add_f32_e32 v165, v165, v181
	v_add_f32_e32 v166, v166, v182
	v_add_f32_e32 v167, v167, v183
	v_add_f32_e32 v168, v168, v184
	v_add_f32_e32 v169, v169, v185
	v_add_f32_e32 v170, v170, v186
	v_add_f32_e32 v171, v171, v187
	v_add_f32_e32 v172, v172, v188
	v_add_f32_e32 v173, v173, v189
	v_add_f32_e32 v174, v174, v190
	v_add_f32_e32 v175, v175, v191
	v_add_f32_e32 v64, v64, v96
	v_add_f32_e32 v65, v65, v97
	v_add_f32_e32 v66, v66, v98
	v_add_f32_e32 v67, v67, v99
	v_add_f32_e32 v68, v68, v100
	v_add_f32_e32 v69, v69, v101
	v_add_f32_e32 v70, v70, v102
	v_add_f32_e32 v71, v71, v103
	v_add_f32_e32 v72, v72, v104
	v_add_f32_e32 v73, v73, v105
	v_add_f32_e32 v74, v74, v106
	v_add_f32_e32 v75, v75, v107
	v_add_f32_e32 v76, v76, v108
	v_add_f32_e32 v77, v77, v109
	v_add_f32_e32 v78, v78, v110
	v_add_f32_e32 v79, v79, v111
	v_add_f32_e32 v128, v128, v160
	v_add_f32_e32 v129, v129, v161
	v_add_f32_e32 v130, v130, v162
	v_add_f32_e32 v131, v131, v163
	v_add_f32_e32 v132, v132, v164
	v_add_f32_e32 v133, v133, v165
	v_add_f32_e32 v134, v134, v166
	v_add_f32_e32 v135, v135, v167
	v_add_f32_e32 v136, v136, v168
	v_add_f32_e32 v137, v137, v169
	v_add_f32_e32 v138, v138, v170
	v_add_f32_e32 v139, v139, v171
	v_add_f32_e32 v140, v140, v172
	v_add_f32_e32 v141, v141, v173
	v_add_f32_e32 v142, v142, v174
	v_add_f32_e32 v143, v143, v175
	v_add_f32_e32 v64, v64, v128
	v_add_f32_e32 v65, v65, v129
	v_add_f32_e32 v66, v66, v130
	v_add_f32_e32 v67, v67, v131
	v_add_f32_e32 v68, v68, v132
	v_add_f32_e32 v69, v69, v133
	v_add_f32_e32 v70, v70, v134
	v_add_f32_e32 v71, v71, v135
	v_add_f32_e32 v72, v72, v136
	v_add_f32_e32 v73, v73, v137
	v_add_f32_e32 v74, v74, v138
	v_add_f32_e32 v75, v75, v139
	v_add_f32_e32 v76, v76, v140
	v_add_f32_e32 v77, v77, v141
	v_add_f32_e32 v78, v78, v142
	v_add_f32_e32 v79, v79, v143
	v_mul_f32_e32 v10, v64, v64
	v_fmac_f32_e32 v10, v65, v65
	v_fmac_f32_e32 v10, v66, v66
	v_fmac_f32_e32 v10, v67, v67
	v_fmac_f32_e32 v10, v68, v68
	v_fmac_f32_e32 v10, v69, v69
	v_fmac_f32_e32 v10, v70, v70
	v_fmac_f32_e32 v10, v71, v71
	v_fmac_f32_e32 v10, v72, v72
	v_fmac_f32_e32 v10, v73, v73
	v_fmac_f32_e32 v10, v74, v74
	v_fmac_f32_e32 v10, v75, v75
	v_fmac_f32_e32 v10, v76, v76
	v_fmac_f32_e32 v10, v77, v77
	v_fmac_f32_e32 v10, v78, v78
	v_fmac_f32_e32 v10, v79, v79
	ds_bpermute_b32 v12, v4, v10
	s_waitcnt lgkmcnt(0)
	v_add_f32_e32 v10, v10, v12
	ds_bpermute_b32 v12, v5, v10
	s_waitcnt lgkmcnt(0)
	v_add_f32_e32 v10, v10, v12
	ds_bpermute_b32 v12, v6, v10
	s_waitcnt lgkmcnt(0)
	v_add_f32_e32 v10, v10, v12
	ds_bpermute_b32 v12, v7, v10
	s_waitcnt lgkmcnt(0)
	v_add_f32_e32 v10, v10, v12
	ds_bpermute_b32 v12, v8, v10
	s_waitcnt lgkmcnt(0)
	v_add_f32_e32 v10, v10, v12
	ds_bpermute_b32 v12, v9, v10
	s_waitcnt lgkmcnt(0)
	v_add_f32_e32 v10, v10, v12
	v_fma_f32 v14, v10, s17, v3
	v_rsq_f32_e32 v14, v14
	s_nop 0
	v_mul_f32_e32 v64, v64, v14
	v_mul_f32_e32 v65, v65, v14
	v_mul_f32_e32 v66, v66, v14
	v_mul_f32_e32 v67, v67, v14
	v_mul_f32_e32 v68, v68, v14
	v_mul_f32_e32 v69, v69, v14
	v_mul_f32_e32 v70, v70, v14
	v_mul_f32_e32 v71, v71, v14
	v_mul_f32_e32 v72, v72, v14
	v_mul_f32_e32 v73, v73, v14
	v_mul_f32_e32 v74, v74, v14
	v_mul_f32_e32 v75, v75, v14
	v_mul_f32_e32 v76, v76, v14
	v_mul_f32_e32 v77, v77, v14
	v_mul_f32_e32 v78, v78, v14
	v_mul_f32_e32 v79, v79, v14
	v_fmac_f32_e32 v192, v64, v20
	v_fmac_f32_e32 v193, v65, v21
	v_fmac_f32_e32 v194, v66, v22
	v_fmac_f32_e32 v195, v67, v23
	v_fmac_f32_e32 v196, v68, v24
	v_fmac_f32_e32 v197, v69, v25
	v_fmac_f32_e32 v198, v70, v26
	v_fmac_f32_e32 v199, v71, v27
	v_fmac_f32_e32 v200, v72, v28
	v_fmac_f32_e32 v201, v73, v29
	v_fmac_f32_e32 v202, v74, v30
	v_fmac_f32_e32 v203, v75, v31
	v_fmac_f32_e32 v204, v76, v32
	v_fmac_f32_e32 v205, v77, v33
	v_fmac_f32_e32 v206, v78, v34
	v_fmac_f32_e32 v207, v79, v35
	global_store_dwordx4 v1, v[192:195], s[24:25] offset:0
	global_store_dwordx4 v1, v[196:199], s[24:25] offset:1024
	global_store_dwordx4 v1, v[200:203], s[24:25] offset:2048
	global_store_dwordx4 v1, v[204:207], s[24:25] offset:3072
	v_mul_f32_e32 v10, v192, v192
	v_fmac_f32_e32 v10, v193, v193
	v_fmac_f32_e32 v10, v194, v194
	v_fmac_f32_e32 v10, v195, v195
	v_fmac_f32_e32 v10, v196, v196
	v_fmac_f32_e32 v10, v197, v197
	v_fmac_f32_e32 v10, v198, v198
	v_fmac_f32_e32 v10, v199, v199
	v_fmac_f32_e32 v10, v200, v200
	v_fmac_f32_e32 v10, v201, v201
	v_fmac_f32_e32 v10, v202, v202
	v_fmac_f32_e32 v10, v203, v203
	v_fmac_f32_e32 v10, v204, v204
	v_fmac_f32_e32 v10, v205, v205
	v_fmac_f32_e32 v10, v206, v206
	v_fmac_f32_e32 v10, v207, v207
	ds_bpermute_b32 v12, v4, v10
	s_waitcnt lgkmcnt(0)
	v_add_f32_e32 v10, v10, v12
	ds_bpermute_b32 v12, v5, v10
	s_waitcnt lgkmcnt(0)
	v_add_f32_e32 v10, v10, v12
	ds_bpermute_b32 v12, v6, v10
	s_waitcnt lgkmcnt(0)
	v_add_f32_e32 v10, v10, v12
	ds_bpermute_b32 v12, v7, v10
	s_waitcnt lgkmcnt(0)
	v_add_f32_e32 v10, v10, v12
	ds_bpermute_b32 v12, v8, v10
	s_waitcnt lgkmcnt(0)
	v_add_f32_e32 v10, v10, v12
	ds_bpermute_b32 v12, v9, v10
	s_waitcnt lgkmcnt(0)
	v_add_f32_e32 v10, v10, v12
	v_fma_f32 v14, v10, s17, v3
	v_rsq_f32_e32 v14, v14
	s_nop 0
	v_mul_f32_e32 v64, v192, v14
	v_mul_f32_e32 v65, v193, v14
	v_mul_f32_e32 v66, v194, v14
	v_mul_f32_e32 v67, v195, v14
	v_mul_f32_e32 v68, v196, v14
	v_mul_f32_e32 v69, v197, v14
	v_mul_f32_e32 v70, v198, v14
	v_mul_f32_e32 v71, v199, v14
	v_mul_f32_e32 v72, v200, v14
	v_mul_f32_e32 v73, v201, v14
	v_mul_f32_e32 v74, v202, v14
	v_mul_f32_e32 v75, v203, v14
	v_mul_f32_e32 v76, v204, v14
	v_mul_f32_e32 v77, v205, v14
	v_mul_f32_e32 v78, v206, v14
	v_mul_f32_e32 v79, v207, v14
	v_mul_f32_e32 v64, v64, v36
	v_mul_f32_e32 v65, v65, v37
	v_mul_f32_e32 v66, v66, v38
	v_mul_f32_e32 v67, v67, v39
	v_mul_f32_e32 v68, v68, v40
	v_mul_f32_e32 v69, v69, v41
	v_mul_f32_e32 v70, v70, v42
	v_mul_f32_e32 v71, v71, v43
	v_mul_f32_e32 v72, v72, v44
	v_mul_f32_e32 v73, v73, v45
	v_mul_f32_e32 v74, v74, v46
	v_mul_f32_e32 v75, v75, v47
	v_mul_f32_e32 v76, v76, v48
	v_mul_f32_e32 v77, v77, v49
	v_mul_f32_e32 v78, v78, v50
	v_mul_f32_e32 v79, v79, v51
	v_cvt_pk_bf16_f32 v64, v64, v65
	v_cvt_pk_bf16_f32 v65, v66, v67
	v_cvt_pk_bf16_f32 v68, v68, v69
	v_cvt_pk_bf16_f32 v69, v70, v71
	v_cvt_pk_bf16_f32 v72, v72, v73
	v_cvt_pk_bf16_f32 v73, v74, v75
	v_cvt_pk_bf16_f32 v76, v76, v77
	v_cvt_pk_bf16_f32 v77, v78, v79
	global_store_dwordx2 v2, v[64:65], s[26:27] offset:0
	global_store_dwordx2 v2, v[68:69], s[26:27] offset:512
	global_store_dwordx2 v2, v[72:73], s[26:27] offset:1024
	global_store_dwordx2 v2, v[76:77], s[26:27] offset:1536

.Lrows7_orig:
	s_load_dword s3, s[0:1], 0xe8
	s_mov_b32 s5, s2
	s_waitcnt lgkmcnt(0)
	s_mov_b32 s5, s3
	v_readfirstlane_b32 s4, v0
	s_ashr_i32 s4, s4, 6
	s_lshl_b32 s2, s2, 3
	s_add_i32 s2, s2, s4
	s_cmpk_gt_i32 s2, 0x41ff
	s_cbranch_scc1 .LBB7_79
	s_load_dwordx2 s[4:5], s[0:1], 0xa0
	s_load_dwordx2 s[6:7], s[0:1], 0xb8
	v_and_b32_e32 v112, 63, v0
	v_lshlrev_b32_e32 v32, 4, v112
	v_or_b32_e32 v34, 0x400, v32
	s_waitcnt lgkmcnt(0)
	s_add_u32 s4, s4, 0x1000
	s_addc_u32 s5, s5, 0
	global_load_dwordx4 v[0:3], v32, s[4:5]
	global_load_dwordx4 v[4:7], v32, s[6:7]
	global_load_dwordx4 v[8:11], v32, s[6:7] offset:1024
	v_or_b32_e32 v36, 0x800, v32
	global_load_dwordx4 v[12:15], v34, s[4:5]
	global_load_dwordx4 v[16:19], v32, s[6:7] offset:2048
	global_load_dwordx4 v[20:23], v32, s[6:7] offset:3072
	v_or_b32_e32 v38, 0xc00, v32
	global_load_dwordx4 v[24:27], v36, s[4:5]
	global_load_dwordx4 v[28:31], v38, s[4:5]
	v_mbcnt_lo_u32_b32 v40, -1, 0
	v_mbcnt_hi_u32_b32 v40, -1, v40
	v_and_b32_e32 v41, 64, v40
	v_add_u32_e32 v41, 64, v41
	v_xor_b32_e32 v42, 1, v40
	s_load_dwordx4 s[4:7], s[0:1], 0xd0
	v_cmp_lt_i32_e32 vcc, v42, v41
	s_mul_i32 s35, s3, 24
	v_mov_b32_e32 v33, 0
	v_cndmask_b32_e32 v42, v40, v42, vcc
	v_lshlrev_b32_e32 v113, 2, v42
	v_xor_b32_e32 v42, 2, v40
	v_cmp_lt_i32_e32 vcc, v42, v41
	s_waitcnt lgkmcnt(0)
	s_add_u32 s30, s6, 0x5200000
	s_addc_u32 s31, s7, 0
	v_cndmask_b32_e32 v42, v40, v42, vcc
	v_lshlrev_b32_e32 v178, 2, v42
	v_xor_b32_e32 v42, 4, v40
	s_lshl_b32 s33, s3, 3
	v_cmp_lt_i32_e32 vcc, v42, v41
	s_add_u32 s0, s6, 0x100000
	s_addc_u32 s1, s7, 0
	v_cndmask_b32_e32 v42, v40, v42, vcc
	s_lshl_b32 s8, s3, 5
	s_lshl_b32 s34, s3, 4
	v_lshlrev_b32_e32 v179, 2, v42
	v_xor_b32_e32 v42, 8, v40
	s_ashr_i32 s3, s2, 31
	v_cmp_lt_i32_e32 vcc, v42, v41
	s_lshl_b64 s[12:13], s[2:3], 12
	v_lshl_add_u64 v[122:123], s[4:5], 0, v[32:33]
	v_cndmask_b32_e32 v42, v40, v42, vcc
	s_add_u32 s4, s4, s12
	v_lshlrev_b32_e32 v180, 2, v42
	v_xor_b32_e32 v42, 16, v40
	s_addc_u32 s5, s5, s13
	v_mov_b32_e32 v35, v33
	v_mov_b32_e32 v37, v33
	v_mov_b32_e32 v39, v33
	v_lshl_add_u64 v[114:115], s[0:1], 0, v[32:33]
	v_cmp_lt_i32_e32 vcc, v42, v41
	v_lshl_add_u64 v[32:33], s[4:5], 0, v[32:33]
	s_mov_b64 s[4:5], 0xc00
	s_ashr_i32 s9, s8, 31
	v_cndmask_b32_e32 v42, v40, v42, vcc
	v_lshl_add_u64 v[116:117], s[0:1], 0, v[34:35]
	v_lshlrev_b32_e32 v34, 3, v112
	v_lshl_add_u64 v[126:127], v[32:33], 0, s[4:5]
	s_lshl_b64 s[4:5], s[8:9], 12
	s_lshl_b64 s[12:13], s[2:3], 11
	v_lshlrev_b32_e32 v181, 2, v42
	v_xor_b32_e32 v42, 32, v40
	v_lshl_add_u64 v[118:119], s[0:1], 0, v[36:37]
	v_lshl_add_u64 v[36:37], s[6:7], 0, v[34:35]
	s_add_u32 s6, s6, s12
	v_cmp_lt_i32_e32 vcc, v42, v41
	s_addc_u32 s7, s7, s13
	v_lshl_add_u64 v[120:121], s[0:1], 0, v[38:39]
	v_cndmask_b32_e32 v40, v40, v42, vcc
	s_mov_b64 s[0:1], 0x3100000
	v_lshl_add_u64 v[32:33], s[6:7], 0, v[34:35]
	s_mov_b32 s11, 0
	v_lshlrev_b32_e32 v182, 2, v40
	v_lshl_add_u64 v[124:125], v[36:37], 0, s[0:1]
	v_lshl_add_u64 v[128:129], v[32:33], 0, s[0:1]
	s_lshl_b64 s[6:7], s[8:9], 11
	s_mov_b32 s3, 0x800000
	v_mov_b32_e32 v183, 0x358637bd
	s_branch .LBB7_3

	.amdhsa_kernel _Z10fwd_kernelILi7ELi8EEv4Args
		.amdhsa_group_segment_fixed_size 0
		.amdhsa_private_segment_fixed_size 0
		.amdhsa_kernarg_size 488
		.amdhsa_user_sgpr_count 2
		.amdhsa_user_sgpr_dispatch_ptr 0
		.amdhsa_user_sgpr_queue_ptr 0
		.amdhsa_user_sgpr_kernarg_segment_ptr 1
		.amdhsa_user_sgpr_dispatch_id 0
		.amdhsa_user_sgpr_kernarg_preload_length 0
		.amdhsa_user_sgpr_kernarg_preload_offset 0
		.amdhsa_user_sgpr_private_segment_size 0
		.amdhsa_uses_dynamic_stack 0
		.amdhsa_enable_private_segment 0
		.amdhsa_system_sgpr_workgroup_id_x 1
		.amdhsa_system_sgpr_workgroup_id_y 0
		.amdhsa_system_sgpr_workgroup_id_z 0
		.amdhsa_system_sgpr_workgroup_info 0
		.amdhsa_system_vgpr_workitem_id 0
		.amdhsa_next_free_vgpr 208
		.amdhsa_next_free_sgpr 56
		.amdhsa_accum_offset 208
		.amdhsa_reserve_vcc 1
		.amdhsa_float_round_mode_32 0
		.amdhsa_float_round_mode_16_64 0
		.amdhsa_float_denorm_mode_32 3
		.amdhsa_float_denorm_mode_16_64 3
		.amdhsa_dx10_clamp 1
		.amdhsa_ieee_mode 1
		.amdhsa_fp16_overflow 0
		.amdhsa_tg_split 0
		.amdhsa_exception_fp_ieee_invalid_op 0
		.amdhsa_exception_fp_denorm_src 0
		.amdhsa_exception_fp_ieee_div_zero 0
		.amdhsa_exception_fp_ieee_overflow 0
		.amdhsa_exception_fp_ieee_underflow 0
		.amdhsa_exception_fp_ieee_inexact 0
		.amdhsa_exception_int_div_zero 0
	.end_amdhsa_kernel

_Z10fwd_kernelILi11ELi12EEv4Args:
	s_load_dword s3, s[0:1], 0xe8
	s_load_dwordx4 s[4:7], s[0:1], 0xd0
	s_load_dwordx2 s[8:9], s[0:1], 0xa8
	s_load_dwordx2 s[10:11], s[0:1], 0xb0
	s_waitcnt lgkmcnt(0)
	s_cmp_lg_u32 s3, 0x100
	s_cbranch_scc1 .Lrows11_orig
	s_add_u32 s8, s8, 0x1000
	s_addc_u32 s9, s9, 0
	s_add_u32 s10, s10, 0x1000
	s_addc_u32 s11, s11, 0
	v_readfirstlane_b32 s16, v0
	s_lshr_b32 s16, s16, 6
	s_lshl_b32 s18, s2, 3
	s_add_u32 s16, s16, s18
	s_mov_b32 s17, 0x3a800000
	v_mov_b32_e32 v3, 0x358637bd
	v_and_b32_e32 v10, 63, v0
	v_lshlrev_b32_e32 v1, 4, v10
	v_lshlrev_b32_e32 v2, 3, v10
	v_xor_b32_e32 v4, 1, v10
	v_xor_b32_e32 v5, 2, v10
	v_xor_b32_e32 v6, 4, v10
	v_xor_b32_e32 v7, 8, v10
	v_xor_b32_e32 v8, 16, v10
	v_xor_b32_e32 v9, 32, v10
	v_lshlrev_b32_e32 v4, 2, v4
	v_lshlrev_b32_e32 v5, 2, v5
	v_lshlrev_b32_e32 v6, 2, v6
	v_lshlrev_b32_e32 v7, 2, v7
	v_lshlrev_b32_e32 v8, 2, v8
	v_lshlrev_b32_e32 v9, 2, v9
	global_load_dwordx4 v[20:23], v1, s[8:9] offset:0
	global_load_dwordx4 v[24:27], v1, s[8:9] offset:1024
	global_load_dwordx4 v[28:31], v1, s[8:9] offset:2048
	global_load_dwordx4 v[32:35], v1, s[8:9] offset:3072
	global_load_dwordx4 v[36:39], v1, s[10:11] offset:0
	global_load_dwordx4 v[40:43], v1, s[10:11] offset:1024
	global_load_dwordx4 v[44:47], v1, s[10:11] offset:2048
	global_load_dwordx4 v[48:51], v1, s[10:11] offset:3072
	s_add_u32 s53, s16, 0x0
	s_lshl_b32 s18, s53, 12
	s_lshl_b32 s19, s53, 11
	s_add_u32 s20, s4, s18
	s_addc_u32 s21, s5, 0
	s_add_u32 s22, s6, s19
	s_addc_u32 s23, s7, 0
	s_add_u32 s22, s22, 0x5200000
	s_addc_u32 s23, s23, 0
	s_add_u32 s24, s4, s18
	s_addc_u32 s25, s5, 0
	s_add_u32 s26, s6, s19
	s_addc_u32 s27, s7, 0
	s_add_u32 s26, s26, 0x3100000
	s_addc_u32 s27, s27, 0
	global_load_dwordx2 v[66:67], v2, s[22:23] offset:0
	global_load_dwordx2 v[70:71], v2, s[22:23] offset:512
	global_load_dwordx2 v[74:75], v2, s[22:23] offset:1024
	global_load_dwordx2 v[78:79], v2, s[22:23] offset:1536
	global_load_dwordx4 v[80:83], v1, s[20:21] offset:0
	global_load_dwordx4 v[84:87], v1, s[20:21] offset:1024
	global_load_dwordx4 v[88:91], v1, s[20:21] offset:2048
	global_load_dwordx4 v[92:95], v1, s[20:21] offset:3072
	s_add_u32 s53, s16, 0x800
	s_lshl_b32 s18, s53, 12
	s_lshl_b32 s19, s53, 11
	s_add_u32 s28, s4, s18
	s_addc_u32 s29, s5, 0
	s_add_u32 s30, s6, s19
	s_addc_u32 s31, s7, 0
	s_add_u32 s30, s30, 0x5200000
	s_addc_u32 s31, s31, 0
	s_add_u32 s32, s4, s18
	s_addc_u32 s33, s5, 0
	s_add_u32 s34, s6, s19
	s_addc_u32 s35, s7, 0
	s_add_u32 s34, s34, 0x3100000
	s_addc_u32 s35, s35, 0
	global_load_dwordx2 v[98:99], v2, s[30:31] offset:0
	global_load_dwordx2 v[102:103], v2, s[30:31] offset:512
	global_load_dwordx2 v[106:107], v2, s[30:31] offset:1024
	global_load_dwordx2 v[110:111], v2, s[30:31] offset:1536
	global_load_dwordx4 v[112:115], v1, s[28:29] offset:0
	global_load_dwordx4 v[116:119], v1, s[28:29] offset:1024
	global_load_dwordx4 v[120:123], v1, s[28:29] offset:2048
	global_load_dwordx4 v[124:127], v1, s[28:29] offset:3072
	s_add_u32 s53, s16, 0x1000
	s_lshl_b32 s18, s53, 12
	s_lshl_b32 s19, s53, 11
	s_add_u32 s36, s4, s18
	s_addc_u32 s37, s5, 0
	s_add_u32 s38, s6, s19
	s_addc_u32 s39, s7, 0
	s_add_u32 s38, s38, 0x5200000
	s_addc_u32 s39, s39, 0
	s_add_u32 s40, s4, s18
	s_addc_u32 s41, s5, 0
	s_add_u32 s42, s6, s19
	s_addc_u32 s43, s7, 0
	s_add_u32 s42, s42, 0x3100000
	s_addc_u32 s43, s43, 0
	global_load_dwordx2 v[130:131], v2, s[38:39] offset:0
	global_load_dwordx2 v[134:135], v2, s[38:39] offset:512
	global_load_dwordx2 v[138:139], v2, s[38:39] offset:1024
	global_load_dwordx2 v[142:143], v2, s[38:39] offset:1536
	global_load_dwordx4 v[144:147], v1, s[36:37] offset:0
	global_load_dwordx4 v[148:151], v1, s[36:37] offset:1024
	global_load_dwordx4 v[152:155], v1, s[36:37] offset:2048
	global_load_dwordx4 v[156:159], v1, s[36:37] offset:3072
	s_add_u32 s53, s16, 0x1800
	s_lshl_b32 s18, s53, 12
	s_lshl_b32 s19, s53, 11
	s_add_u32 s44, s4, s18
	s_addc_u32 s45, s5, 0
	s_add_u32 s46, s6, s19
	s_addc_u32 s47, s7, 0
	s_add_u32 s46, s46, 0x5200000
	s_addc_u32 s47, s47, 0
	s_add_u32 s48, s4, s18
	s_addc_u32 s49, s5, 0
	s_add_u32 s50, s6, s19
	s_addc_u32 s51, s7, 0
	s_add_u32 s50, s50, 0x3100000
	s_addc_u32 s51, s51, 0
	global_load_dwordx2 v[162:163], v2, s[46:47] offset:0
	global_load_dwordx2 v[166:167], v2, s[46:47] offset:512
	global_load_dwordx2 v[170:171], v2, s[46:47] offset:1024
	global_load_dwordx2 v[174:175], v2, s[46:47] offset:1536
	global_load_dwordx4 v[176:179], v1, s[44:45] offset:0
	global_load_dwordx4 v[180:183], v1, s[44:45] offset:1024
	global_load_dwordx4 v[184:187], v1, s[44:45] offset:2048
	global_load_dwordx4 v[188:191], v1, s[44:45] offset:3072
	s_waitcnt vmcnt(16)
	v_lshlrev_b32_e32 v64, 16, v66
	v_and_b32_e32 v65, 0xffff0000, v66
	v_lshlrev_b32_e32 v66, 16, v67
	v_and_b32_e32 v67, 0xffff0000, v67
	v_lshlrev_b32_e32 v68, 16, v70
	v_and_b32_e32 v69, 0xffff0000, v70
	v_lshlrev_b32_e32 v70, 16, v71
	v_and_b32_e32 v71, 0xffff0000, v71
	v_lshlrev_b32_e32 v72, 16, v74
	v_and_b32_e32 v73, 0xffff0000, v74
	v_lshlrev_b32_e32 v74, 16, v75
	v_and_b32_e32 v75, 0xffff0000, v75
	v_lshlrev_b32_e32 v76, 16, v78
	v_and_b32_e32 v77, 0xffff0000, v78
	v_lshlrev_b32_e32 v78, 16, v79
	v_and_b32_e32 v79, 0xffff0000, v79
	v_lshlrev_b32_e32 v96, 16, v98
	v_and_b32_e32 v97, 0xffff0000, v98
	v_lshlrev_b32_e32 v98, 16, v99
	v_and_b32_e32 v99, 0xffff0000, v99
	v_lshlrev_b32_e32 v100, 16, v102
	v_and_b32_e32 v101, 0xffff0000, v102
	v_lshlrev_b32_e32 v102, 16, v103
	v_and_b32_e32 v103, 0xffff0000, v103
	v_lshlrev_b32_e32 v104, 16, v106
	v_and_b32_e32 v105, 0xffff0000, v106
	v_lshlrev_b32_e32 v106, 16, v107
	v_and_b32_e32 v107, 0xffff0000, v107
	v_lshlrev_b32_e32 v108, 16, v110
	v_and_b32_e32 v109, 0xffff0000, v110
	v_lshlrev_b32_e32 v110, 16, v111
	v_and_b32_e32 v111, 0xffff0000, v111
	v_mul_f32_e32 v10, v64, v64
	v_fmac_f32_e32 v10, v65, v65
	v_fmac_f32_e32 v10, v66, v66
	v_fmac_f32_e32 v10, v67, v67
	v_fmac_f32_e32 v10, v68, v68
	v_fmac_f32_e32 v10, v69, v69
	v_fmac_f32_e32 v10, v70, v70
	v_fmac_f32_e32 v10, v71, v71
	v_fmac_f32_e32 v10, v72, v72
	v_fmac_f32_e32 v10, v73, v73
	v_fmac_f32_e32 v10, v74, v74
	v_fmac_f32_e32 v10, v75, v75
	v_fmac_f32_e32 v10, v76, v76
	v_fmac_f32_e32 v10, v77, v77
	v_fmac_f32_e32 v10, v78, v78
	v_fmac_f32_e32 v10, v79, v79
	v_mul_f32_e32 v11, v96, v96
	v_fmac_f32_e32 v11, v97, v97
	v_fmac_f32_e32 v11, v98, v98
	v_fmac_f32_e32 v11, v99, v99
	v_fmac_f32_e32 v11, v100, v100
	v_fmac_f32_e32 v11, v101, v101
	v_fmac_f32_e32 v11, v102, v102
	v_fmac_f32_e32 v11, v103, v103
	v_fmac_f32_e32 v11, v104, v104
	v_fmac_f32_e32 v11, v105, v105
	v_fmac_f32_e32 v11, v106, v106
	v_fmac_f32_e32 v11, v107, v107
	v_fmac_f32_e32 v11, v108, v108
	v_fmac_f32_e32 v11, v109, v109
	v_fmac_f32_e32 v11, v110, v110
	v_fmac_f32_e32 v11, v111, v111
	ds_bpermute_b32 v12, v4, v10
	ds_bpermute_b32 v13, v4, v11
	s_waitcnt lgkmcnt(0)
	v_add_f32_e32 v10, v10, v12
	v_add_f32_e32 v11, v11, v13
	ds_bpermute_b32 v12, v5, v10
	ds_bpermute_b32 v13, v5, v11
	s_waitcnt lgkmcnt(0)
	v_add_f32_e32 v10, v10, v12
	v_add_f32_e32 v11, v11, v13
	ds_bpermute_b32 v12, v6, v10
	ds_bpermute_b32 v13, v6, v11
	s_waitcnt lgkmcnt(0)
	v_add_f32_e32 v10, v10, v12
	v_add_f32_e32 v11, v11, v13
	ds_bpermute_b32 v12, v7, v10
	ds_bpermute_b32 v13, v7, v11
	s_waitcnt lgkmcnt(0)
	v_add_f32_e32 v10, v10, v12
	v_add_f32_e32 v11, v11, v13
	ds_bpermute_b32 v12, v8, v10
	ds_bpermute_b32 v13, v8, v11
	s_waitcnt lgkmcnt(0)
	v_add_f32_e32 v10, v10, v12
	v_add_f32_e32 v11, v11, v13
	ds_bpermute_b32 v12, v9, v10
	ds_bpermute_b32 v13, v9, v11
	s_waitcnt lgkmcnt(0)
	v_add_f32_e32 v10, v10, v12
	v_add_f32_e32 v11, v11, v13
	v_fma_f32 v14, v10, s17, v3
	v_fma_f32 v15, v11, s17, v3
	v_rsq_f32_e32 v14, v14
	v_rsq_f32_e32 v15, v15
	s_nop 0
	v_mul_f32_e32 v64, v64, v14
	v_mul_f32_e32 v65, v65, v14
	v_mul_f32_e32 v66, v66, v14
	v_mul_f32_e32 v67, v67, v14
	v_mul_f32_e32 v68, v68, v14
	v_mul_f32_e32 v69, v69, v14
	v_mul_f32_e32 v70, v70, v14
	v_mul_f32_e32 v71, v71, v14
	v_mul_f32_e32 v72, v72, v14
	v_mul_f32_e32 v73, v73, v14
	v_mul_f32_e32 v74, v74, v14
	v_mul_f32_e32 v75, v75, v14
	v_mul_f32_e32 v76, v76, v14
	v_mul_f32_e32 v77, v77, v14
	v_mul_f32_e32 v78, v78, v14
	v_mul_f32_e32 v79, v79, v14
	v_fmac_f32_e32 v80, v64, v20
	v_fmac_f32_e32 v81, v65, v21
	v_fmac_f32_e32 v82, v66, v22
	v_fmac_f32_e32 v83, v67, v23
	v_fmac_f32_e32 v84, v68, v24
	v_fmac_f32_e32 v85, v69, v25
	v_fmac_f32_e32 v86, v70, v26
	v_fmac_f32_e32 v87, v71, v27
	v_fmac_f32_e32 v88, v72, v28
	v_fmac_f32_e32 v89, v73, v29
	v_fmac_f32_e32 v90, v74, v30
	v_fmac_f32_e32 v91, v75, v31
	v_fmac_f32_e32 v92, v76, v32
	v_fmac_f32_e32 v93, v77, v33
	v_fmac_f32_e32 v94, v78, v34
	v_fmac_f32_e32 v95, v79, v35
	global_store_dwordx4 v1, v[80:83], s[24:25] offset:0
	global_store_dwordx4 v1, v[84:87], s[24:25] offset:1024
	global_store_dwordx4 v1, v[88:91], s[24:25] offset:2048
	global_store_dwordx4 v1, v[92:95], s[24:25] offset:3072
	v_mul_f32_e32 v96, v96, v15
	v_mul_f32_e32 v97, v97, v15
	v_mul_f32_e32 v98, v98, v15
	v_mul_f32_e32 v99, v99, v15
	v_mul_f32_e32 v100, v100, v15
	v_mul_f32_e32 v101, v101, v15
	v_mul_f32_e32 v102, v102, v15
	v_mul_f32_e32 v103, v103, v15
	v_mul_f32_e32 v104, v104, v15
	v_mul_f32_e32 v105, v105, v15
	v_mul_f32_e32 v106, v106, v15
	v_mul_f32_e32 v107, v107, v15
	v_mul_f32_e32 v108, v108, v15
	v_mul_f32_e32 v109, v109, v15
	v_mul_f32_e32 v110, v110, v15
	v_mul_f32_e32 v111, v111, v15
	v_fmac_f32_e32 v112, v96, v20
	v_fmac_f32_e32 v113, v97, v21
	v_fmac_f32_e32 v114, v98, v22
	v_fmac_f32_e32 v115, v99, v23
	v_fmac_f32_e32 v116, v100, v24
	v_fmac_f32_e32 v117, v101, v25
	v_fmac_f32_e32 v118, v102, v26
	v_fmac_f32_e32 v119, v103, v27
	v_fmac_f32_e32 v120, v104, v28
	v_fmac_f32_e32 v121, v105, v29
	v_fmac_f32_e32 v122, v106, v30
	v_fmac_f32_e32 v123, v107, v31
	v_fmac_f32_e32 v124, v108, v32
	v_fmac_f32_e32 v125, v109, v33
	v_fmac_f32_e32 v126, v110, v34
	v_fmac_f32_e32 v127, v111, v35
	global_store_dwordx4 v1, v[112:115], s[32:33] offset:0
	global_store_dwordx4 v1, v[116:119], s[32:33] offset:1024
	global_store_dwordx4 v1, v[120:123], s[32:33] offset:2048
	global_store_dwordx4 v1, v[124:127], s[32:33] offset:3072
	v_mul_f32_e32 v10, v80, v80
	v_fmac_f32_e32 v10, v81, v81
	v_fmac_f32_e32 v10, v82, v82
	v_fmac_f32_e32 v10, v83, v83
	v_fmac_f32_e32 v10, v84, v84
	v_fmac_f32_e32 v10, v85, v85
	v_fmac_f32_e32 v10, v86, v86
	v_fmac_f32_e32 v10, v87, v87
	v_fmac_f32_e32 v10, v88, v88
	v_fmac_f32_e32 v10, v89, v89
	v_fmac_f32_e32 v10, v90, v90
	v_fmac_f32_e32 v10, v91, v91
	v_fmac_f32_e32 v10, v92, v92
	v_fmac_f32_e32 v10, v93, v93
	v_fmac_f32_e32 v10, v94, v94
	v_fmac_f32_e32 v10, v95, v95
	v_mul_f32_e32 v11, v112, v112
	v_fmac_f32_e32 v11, v113, v113
	v_fmac_f32_e32 v11, v114, v114
	v_fmac_f32_e32 v11, v115, v115
	v_fmac_f32_e32 v11, v116, v116
	v_fmac_f32_e32 v11, v117, v117
	v_fmac_f32_e32 v11, v118, v118
	v_fmac_f32_e32 v11, v119, v119
	v_fmac_f32_e32 v11, v120, v120
	v_fmac_f32_e32 v11, v121, v121
	v_fmac_f32_e32 v11, v122, v122
	v_fmac_f32_e32 v11, v123, v123
	v_fmac_f32_e32 v11, v124, v124
	v_fmac_f32_e32 v11, v125, v125
	v_fmac_f32_e32 v11, v126, v126
	v_fmac_f32_e32 v11, v127, v127
	ds_bpermute_b32 v12, v4, v10
	ds_bpermute_b32 v13, v4, v11
	s_waitcnt lgkmcnt(0)
	v_add_f32_e32 v10, v10, v12
	v_add_f32_e32 v11, v11, v13
	ds_bpermute_b32 v12, v5, v10
	ds_bpermute_b32 v13, v5, v11
	s_waitcnt lgkmcnt(0)
	v_add_f32_e32 v10, v10, v12
	v_add_f32_e32 v11, v11, v13
	ds_bpermute_b32 v12, v6, v10
	ds_bpermute_b32 v13, v6, v11
	s_waitcnt lgkmcnt(0)
	v_add_f32_e32 v10, v10, v12
	v_add_f32_e32 v11, v11, v13
	ds_bpermute_b32 v12, v7, v10
	ds_bpermute_b32 v13, v7, v11
	s_waitcnt lgkmcnt(0)
	v_add_f32_e32 v10, v10, v12
	v_add_f32_e32 v11, v11, v13
	ds_bpermute_b32 v12, v8, v10
	ds_bpermute_b32 v13, v8, v11
	s_waitcnt lgkmcnt(0)
	v_add_f32_e32 v10, v10, v12
	v_add_f32_e32 v11, v11, v13
	ds_bpermute_b32 v12, v9, v10
	ds_bpermute_b32 v13, v9, v11
	s_waitcnt lgkmcnt(0)
	v_add_f32_e32 v10, v10, v12
	v_add_f32_e32 v11, v11, v13
	v_fma_f32 v14, v10, s17, v3
	v_fma_f32 v15, v11, s17, v3
	v_rsq_f32_e32 v14, v14
	v_rsq_f32_e32 v15, v15
	s_nop 0
	v_mul_f32_e32 v64, v80, v14
	v_mul_f32_e32 v65, v81, v14
	v_mul_f32_e32 v66, v82, v14
	v_mul_f32_e32 v67, v83, v14
	v_mul_f32_e32 v68, v84, v14
	v_mul_f32_e32 v69, v85, v14
	v_mul_f32_e32 v70, v86, v14
	v_mul_f32_e32 v71, v87, v14
	v_mul_f32_e32 v72, v88, v14
	v_mul_f32_e32 v73, v89, v14
	v_mul_f32_e32 v74, v90, v14
	v_mul_f32_e32 v75, v91, v14
	v_mul_f32_e32 v76, v92, v14
	v_mul_f32_e32 v77, v93, v14
	v_mul_f32_e32 v78, v94, v14
	v_mul_f32_e32 v79, v95, v14
	v_mul_f32_e32 v64, v64, v36
	v_mul_f32_e32 v65, v65, v37
	v_mul_f32_e32 v66, v66, v38
	v_mul_f32_e32 v67, v67, v39
	v_mul_f32_e32 v68, v68, v40
	v_mul_f32_e32 v69, v69, v41
	v_mul_f32_e32 v70, v70, v42
	v_mul_f32_e32 v71, v71, v43
	v_mul_f32_e32 v72, v72, v44
	v_mul_f32_e32 v73, v73, v45
	v_mul_f32_e32 v74, v74, v46
	v_mul_f32_e32 v75, v75, v47
	v_mul_f32_e32 v76, v76, v48
	v_mul_f32_e32 v77, v77, v49
	v_mul_f32_e32 v78, v78, v50
	v_mul_f32_e32 v79, v79, v51
	v_cvt_pk_bf16_f32 v64, v64, v65
	v_cvt_pk_bf16_f32 v65, v66, v67
	v_cvt_pk_bf16_f32 v68, v68, v69
	v_cvt_pk_bf16_f32 v69, v70, v71
	v_cvt_pk_bf16_f32 v72, v72, v73
	v_cvt_pk_bf16_f32 v73, v74, v75
	v_cvt_pk_bf16_f32 v76, v76, v77
	v_cvt_pk_bf16_f32 v77, v78, v79
	global_store_dwordx2 v2, v[64:65], s[26:27] offset:0
	global_store_dwordx2 v2, v[68:69], s[26:27] offset:512
	global_store_dwordx2 v2, v[72:73], s[26:27] offset:1024
	global_store_dwordx2 v2, v[76:77], s[26:27] offset:1536
	v_mul_f32_e32 v96, v112, v15
	v_mul_f32_e32 v97, v113, v15
	v_mul_f32_e32 v98, v114, v15
	v_mul_f32_e32 v99, v115, v15
	v_mul_f32_e32 v100, v116, v15
	v_mul_f32_e32 v101, v117, v15
	v_mul_f32_e32 v102, v118, v15
	v_mul_f32_e32 v103, v119, v15
	v_mul_f32_e32 v104, v120, v15
	v_mul_f32_e32 v105, v121, v15
	v_mul_f32_e32 v106, v122, v15
	v_mul_f32_e32 v107, v123, v15
	v_mul_f32_e32 v108, v124, v15
	v_mul_f32_e32 v109, v125, v15
	v_mul_f32_e32 v110, v126, v15
	v_mul_f32_e32 v111, v127, v15
	v_mul_f32_e32 v96, v96, v36
	v_mul_f32_e32 v97, v97, v37
	v_mul_f32_e32 v98, v98, v38
	v_mul_f32_e32 v99, v99, v39
	v_mul_f32_e32 v100, v100, v40
	v_mul_f32_e32 v101, v101, v41
	v_mul_f32_e32 v102, v102, v42
	v_mul_f32_e32 v103, v103, v43
	v_mul_f32_e32 v104, v104, v44
	v_mul_f32_e32 v105, v105, v45
	v_mul_f32_e32 v106, v106, v46
	v_mul_f32_e32 v107, v107, v47
	v_mul_f32_e32 v108, v108, v48
	v_mul_f32_e32 v109, v109, v49
	v_mul_f32_e32 v110, v110, v50
	v_mul_f32_e32 v111, v111, v51
	v_cvt_pk_bf16_f32 v96, v96, v97
	v_cvt_pk_bf16_f32 v97, v98, v99
	v_cvt_pk_bf16_f32 v100, v100, v101
	v_cvt_pk_bf16_f32 v101, v102, v103
	v_cvt_pk_bf16_f32 v104, v104, v105
	v_cvt_pk_bf16_f32 v105, v106, v107
	v_cvt_pk_bf16_f32 v108, v108, v109
	v_cvt_pk_bf16_f32 v109, v110, v111
	global_store_dwordx2 v2, v[96:97], s[34:35] offset:0
	global_store_dwordx2 v2, v[100:101], s[34:35] offset:512
	global_store_dwordx2 v2, v[104:105], s[34:35] offset:1024
	global_store_dwordx2 v2, v[108:109], s[34:35] offset:1536
	s_add_u32 s53, s16, 0x2000
	s_lshl_b32 s18, s53, 12
	s_lshl_b32 s19, s53, 11
	s_add_u32 s20, s4, s18
	s_addc_u32 s21, s5, 0
	s_add_u32 s22, s6, s19
	s_addc_u32 s23, s7, 0
	s_add_u32 s22, s22, 0x5200000
	s_addc_u32 s23, s23, 0
	s_add_u32 s24, s4, s18
	s_addc_u32 s25, s5, 0
	s_add_u32 s26, s6, s19
	s_addc_u32 s27, s7, 0
	s_add_u32 s26, s26, 0x3100000
	s_addc_u32 s27, s27, 0
	global_load_dwordx2 v[66:67], v2, s[22:23] offset:0
	global_load_dwordx2 v[70:71], v2, s[22:23] offset:512
	global_load_dwordx2 v[74:75], v2, s[22:23] offset:1024
	global_load_dwordx2 v[78:79], v2, s[22:23] offset:1536
	global_load_dwordx4 v[80:83], v1, s[20:21] offset:0
	global_load_dwordx4 v[84:87], v1, s[20:21] offset:1024
	global_load_dwordx4 v[88:91], v1, s[20:21] offset:2048
	global_load_dwordx4 v[92:95], v1, s[20:21] offset:3072
	s_add_u32 s53, s16, 0x2800
	s_lshl_b32 s18, s53, 12
	s_lshl_b32 s19, s53, 11
	s_add_u32 s28, s4, s18
	s_addc_u32 s29, s5, 0
	s_add_u32 s30, s6, s19
	s_addc_u32 s31, s7, 0
	s_add_u32 s30, s30, 0x5200000
	s_addc_u32 s31, s31, 0
	s_add_u32 s32, s4, s18
	s_addc_u32 s33, s5, 0
	s_add_u32 s34, s6, s19
	s_addc_u32 s35, s7, 0
	s_add_u32 s34, s34, 0x3100000
	s_addc_u32 s35, s35, 0
	global_load_dwordx2 v[98:99], v2, s[30:31] offset:0
	global_load_dwordx2 v[102:103], v2, s[30:31] offset:512
	global_load_dwordx2 v[106:107], v2, s[30:31] offset:1024
	global_load_dwordx2 v[110:111], v2, s[30:31] offset:1536
	global_load_dwordx4 v[112:115], v1, s[28:29] offset:0
	global_load_dwordx4 v[116:119], v1, s[28:29] offset:1024
	global_load_dwordx4 v[120:123], v1, s[28:29] offset:2048
	global_load_dwordx4 v[124:127], v1, s[28:29] offset:3072
	s_waitcnt vmcnt(32)
	v_lshlrev_b32_e32 v128, 16, v130
	v_and_b32_e32 v129, 0xffff0000, v130
	v_lshlrev_b32_e32 v130, 16, v131
	v_and_b32_e32 v131, 0xffff0000, v131
	v_lshlrev_b32_e32 v132, 16, v134
	v_and_b32_e32 v133, 0xffff0000, v134
	v_lshlrev_b32_e32 v134, 16, v135
	v_and_b32_e32 v135, 0xffff0000, v135
	v_lshlrev_b32_e32 v136, 16, v138
	v_and_b32_e32 v137, 0xffff0000, v138
	v_lshlrev_b32_e32 v138, 16, v139
	v_and_b32_e32 v139, 0xffff0000, v139
	v_lshlrev_b32_e32 v140, 16, v142
	v_and_b32_e32 v141, 0xffff0000, v142
	v_lshlrev_b32_e32 v142, 16, v143
	v_and_b32_e32 v143, 0xffff0000, v143
	v_lshlrev_b32_e32 v160, 16, v162
	v_and_b32_e32 v161, 0xffff0000, v162
	v_lshlrev_b32_e32 v162, 16, v163
	v_and_b32_e32 v163, 0xffff0000, v163
	v_lshlrev_b32_e32 v164, 16, v166
	v_and_b32_e32 v165, 0xffff0000, v166
	v_lshlrev_b32_e32 v166, 16, v167
	v_and_b32_e32 v167, 0xffff0000, v167
	v_lshlrev_b32_e32 v168, 16, v170
	v_and_b32_e32 v169, 0xffff0000, v170
	v_lshlrev_b32_e32 v170, 16, v171
	v_and_b32_e32 v171, 0xffff0000, v171
	v_lshlrev_b32_e32 v172, 16, v174
	v_and_b32_e32 v173, 0xffff0000, v174
	v_lshlrev_b32_e32 v174, 16, v175
	v_and_b32_e32 v175, 0xffff0000, v175
	v_mul_f32_e32 v10, v128, v128
	v_fmac_f32_e32 v10, v129, v129
	v_fmac_f32_e32 v10, v130, v130
	v_fmac_f32_e32 v10, v131, v131
	v_fmac_f32_e32 v10, v132, v132
	v_fmac_f32_e32 v10, v133, v133
	v_fmac_f32_e32 v10, v134, v134
	v_fmac_f32_e32 v10, v135, v135
	v_fmac_f32_e32 v10, v136, v136
	v_fmac_f32_e32 v10, v137, v137
	v_fmac_f32_e32 v10, v138, v138
	v_fmac_f32_e32 v10, v139, v139
	v_fmac_f32_e32 v10, v140, v140
	v_fmac_f32_e32 v10, v141, v141
	v_fmac_f32_e32 v10, v142, v142
	v_fmac_f32_e32 v10, v143, v143
	v_mul_f32_e32 v11, v160, v160
	v_fmac_f32_e32 v11, v161, v161
	v_fmac_f32_e32 v11, v162, v162
	v_fmac_f32_e32 v11, v163, v163
	v_fmac_f32_e32 v11, v164, v164
	v_fmac_f32_e32 v11, v165, v165
	v_fmac_f32_e32 v11, v166, v166
	v_fmac_f32_e32 v11, v167, v167
	v_fmac_f32_e32 v11, v168, v168
	v_fmac_f32_e32 v11, v169, v169
	v_fmac_f32_e32 v11, v170, v170
	v_fmac_f32_e32 v11, v171, v171
	v_fmac_f32_e32 v11, v172, v172
	v_fmac_f32_e32 v11, v173, v173
	v_fmac_f32_e32 v11, v174, v174
	v_fmac_f32_e32 v11, v175, v175
	ds_bpermute_b32 v12, v4, v10
	ds_bpermute_b32 v13, v4, v11
	s_waitcnt lgkmcnt(0)
	v_add_f32_e32 v10, v10, v12
	v_add_f32_e32 v11, v11, v13
	ds_bpermute_b32 v12, v5, v10
	ds_bpermute_b32 v13, v5, v11
	s_waitcnt lgkmcnt(0)
	v_add_f32_e32 v10, v10, v12
	v_add_f32_e32 v11, v11, v13
	ds_bpermute_b32 v12, v6, v10
	ds_bpermute_b32 v13, v6, v11
	s_waitcnt lgkmcnt(0)
	v_add_f32_e32 v10, v10, v12
	v_add_f32_e32 v11, v11, v13
	ds_bpermute_b32 v12, v7, v10
	ds_bpermute_b32 v13, v7, v11
	s_waitcnt lgkmcnt(0)
	v_add_f32_e32 v10, v10, v12
	v_add_f32_e32 v11, v11, v13
	ds_bpermute_b32 v12, v8, v10
	ds_bpermute_b32 v13, v8, v11
	s_waitcnt lgkmcnt(0)
	v_add_f32_e32 v10, v10, v12
	v_add_f32_e32 v11, v11, v13
	ds_bpermute_b32 v12, v9, v10
	ds_bpermute_b32 v13, v9, v11
	s_waitcnt lgkmcnt(0)
	v_add_f32_e32 v10, v10, v12
	v_add_f32_e32 v11, v11, v13
	v_fma_f32 v14, v10, s17, v3
	v_fma_f32 v15, v11, s17, v3
	v_rsq_f32_e32 v14, v14
	v_rsq_f32_e32 v15, v15
	s_nop 0
	v_mul_f32_e32 v128, v128, v14
	v_mul_f32_e32 v129, v129, v14
	v_mul_f32_e32 v130, v130, v14
	v_mul_f32_e32 v131, v131, v14
	v_mul_f32_e32 v132, v132, v14
	v_mul_f32_e32 v133, v133, v14
	v_mul_f32_e32 v134, v134, v14
	v_mul_f32_e32 v135, v135, v14
	v_mul_f32_e32 v136, v136, v14
	v_mul_f32_e32 v137, v137, v14
	v_mul_f32_e32 v138, v138, v14
	v_mul_f32_e32 v139, v139, v14
	v_mul_f32_e32 v140, v140, v14
	v_mul_f32_e32 v141, v141, v14
	v_mul_f32_e32 v142, v142, v14
	v_mul_f32_e32 v143, v143, v14
	v_fmac_f32_e32 v144, v128, v20
	v_fmac_f32_e32 v145, v129, v21
	v_fmac_f32_e32 v146, v130, v22
	v_fmac_f32_e32 v147, v131, v23
	v_fmac_f32_e32 v148, v132, v24
	v_fmac_f32_e32 v149, v133, v25
	v_fmac_f32_e32 v150, v134, v26
	v_fmac_f32_e32 v151, v135, v27
	v_fmac_f32_e32 v152, v136, v28
	v_fmac_f32_e32 v153, v137, v29
	v_fmac_f32_e32 v154, v138, v30
	v_fmac_f32_e32 v155, v139, v31
	v_fmac_f32_e32 v156, v140, v32
	v_fmac_f32_e32 v157, v141, v33
	v_fmac_f32_e32 v158, v142, v34
	v_fmac_f32_e32 v159, v143, v35
	global_store_dwordx4 v1, v[144:147], s[40:41] offset:0
	global_store_dwordx4 v1, v[148:151], s[40:41] offset:1024
	global_store_dwordx4 v1, v[152:155], s[40:41] offset:2048
	global_store_dwordx4 v1, v[156:159], s[40:41] offset:3072
	v_mul_f32_e32 v160, v160, v15
	v_mul_f32_e32 v161, v161, v15
	v_mul_f32_e32 v162, v162, v15
	v_mul_f32_e32 v163, v163, v15
	v_mul_f32_e32 v164, v164, v15
	v_mul_f32_e32 v165, v165, v15
	v_mul_f32_e32 v166, v166, v15
	v_mul_f32_e32 v167, v167, v15
	v_mul_f32_e32 v168, v168, v15
	v_mul_f32_e32 v169, v169, v15
	v_mul_f32_e32 v170, v170, v15
	v_mul_f32_e32 v171, v171, v15
	v_mul_f32_e32 v172, v172, v15
	v_mul_f32_e32 v173, v173, v15
	v_mul_f32_e32 v174, v174, v15
	v_mul_f32_e32 v175, v175, v15
	v_fmac_f32_e32 v176, v160, v20
	v_fmac_f32_e32 v177, v161, v21
	v_fmac_f32_e32 v178, v162, v22
	v_fmac_f32_e32 v179, v163, v23
	v_fmac_f32_e32 v180, v164, v24
	v_fmac_f32_e32 v181, v165, v25
	v_fmac_f32_e32 v182, v166, v26
	v_fmac_f32_e32 v183, v167, v27
	v_fmac_f32_e32 v184, v168, v28
	v_fmac_f32_e32 v185, v169, v29
	v_fmac_f32_e32 v186, v170, v30
	v_fmac_f32_e32 v187, v171, v31
	v_fmac_f32_e32 v188, v172, v32
	v_fmac_f32_e32 v189, v173, v33
	v_fmac_f32_e32 v190, v174, v34
	v_fmac_f32_e32 v191, v175, v35
	global_store_dwordx4 v1, v[176:179], s[48:49] offset:0
	global_store_dwordx4 v1, v[180:183], s[48:49] offset:1024
	global_store_dwordx4 v1, v[184:187], s[48:49] offset:2048
	global_store_dwordx4 v1, v[188:191], s[48:49] offset:3072
	v_mul_f32_e32 v10, v144, v144
	v_fmac_f32_e32 v10, v145, v145
	v_fmac_f32_e32 v10, v146, v146
	v_fmac_f32_e32 v10, v147, v147
	v_fmac_f32_e32 v10, v148, v148
	v_fmac_f32_e32 v10, v149, v149
	v_fmac_f32_e32 v10, v150, v150
	v_fmac_f32_e32 v10, v151, v151
	v_fmac_f32_e32 v10, v152, v152
	v_fmac_f32_e32 v10, v153, v153
	v_fmac_f32_e32 v10, v154, v154
	v_fmac_f32_e32 v10, v155, v155
	v_fmac_f32_e32 v10, v156, v156
	v_fmac_f32_e32 v10, v157, v157
	v_fmac_f32_e32 v10, v158, v158
	v_fmac_f32_e32 v10, v159, v159
	v_mul_f32_e32 v11, v176, v176
	v_fmac_f32_e32 v11, v177, v177
	v_fmac_f32_e32 v11, v178, v178
	v_fmac_f32_e32 v11, v179, v179
	v_fmac_f32_e32 v11, v180, v180
	v_fmac_f32_e32 v11, v181, v181
	v_fmac_f32_e32 v11, v182, v182
	v_fmac_f32_e32 v11, v183, v183
	v_fmac_f32_e32 v11, v184, v184
	v_fmac_f32_e32 v11, v185, v185
	v_fmac_f32_e32 v11, v186, v186
	v_fmac_f32_e32 v11, v187, v187
	v_fmac_f32_e32 v11, v188, v188
	v_fmac_f32_e32 v11, v189, v189
	v_fmac_f32_e32 v11, v190, v190
	v_fmac_f32_e32 v11, v191, v191
	ds_bpermute_b32 v12, v4, v10
	ds_bpermute_b32 v13, v4, v11
	s_waitcnt lgkmcnt(0)
	v_add_f32_e32 v10, v10, v12
	v_add_f32_e32 v11, v11, v13
	ds_bpermute_b32 v12, v5, v10
	ds_bpermute_b32 v13, v5, v11
	s_waitcnt lgkmcnt(0)
	v_add_f32_e32 v10, v10, v12
	v_add_f32_e32 v11, v11, v13
	ds_bpermute_b32 v12, v6, v10
	ds_bpermute_b32 v13, v6, v11
	s_waitcnt lgkmcnt(0)
	v_add_f32_e32 v10, v10, v12
	v_add_f32_e32 v11, v11, v13
	ds_bpermute_b32 v12, v7, v10
	ds_bpermute_b32 v13, v7, v11
	s_waitcnt lgkmcnt(0)
	v_add_f32_e32 v10, v10, v12
	v_add_f32_e32 v11, v11, v13
	ds_bpermute_b32 v12, v8, v10
	ds_bpermute_b32 v13, v8, v11
	s_waitcnt lgkmcnt(0)
	v_add_f32_e32 v10, v10, v12
	v_add_f32_e32 v11, v11, v13
	ds_bpermute_b32 v12, v9, v10
	ds_bpermute_b32 v13, v9, v11
	s_waitcnt lgkmcnt(0)
	v_add_f32_e32 v10, v10, v12
	v_add_f32_e32 v11, v11, v13
	v_fma_f32 v14, v10, s17, v3
	v_fma_f32 v15, v11, s17, v3
	v_rsq_f32_e32 v14, v14
	v_rsq_f32_e32 v15, v15
	s_nop 0
	v_mul_f32_e32 v128, v144, v14
	v_mul_f32_e32 v129, v145, v14
	v_mul_f32_e32 v130, v146, v14
	v_mul_f32_e32 v131, v147, v14
	v_mul_f32_e32 v132, v148, v14
	v_mul_f32_e32 v133, v149, v14
	v_mul_f32_e32 v134, v150, v14
	v_mul_f32_e32 v135, v151, v14
	v_mul_f32_e32 v136, v152, v14
	v_mul_f32_e32 v137, v153, v14
	v_mul_f32_e32 v138, v154, v14
	v_mul_f32_e32 v139, v155, v14
	v_mul_f32_e32 v140, v156, v14
	v_mul_f32_e32 v141, v157, v14
	v_mul_f32_e32 v142, v158, v14
	v_mul_f32_e32 v143, v159, v14
	v_mul_f32_e32 v128, v128, v36
	v_mul_f32_e32 v129, v129, v37
	v_mul_f32_e32 v130, v130, v38
	v_mul_f32_e32 v131, v131, v39
	v_mul_f32_e32 v132, v132, v40
	v_mul_f32_e32 v133, v133, v41
	v_mul_f32_e32 v134, v134, v42
	v_mul_f32_e32 v135, v135, v43
	v_mul_f32_e32 v136, v136, v44
	v_mul_f32_e32 v137, v137, v45
	v_mul_f32_e32 v138, v138, v46
	v_mul_f32_e32 v139, v139, v47
	v_mul_f32_e32 v140, v140, v48
	v_mul_f32_e32 v141, v141, v49
	v_mul_f32_e32 v142, v142, v50
	v_mul_f32_e32 v143, v143, v51
	v_cvt_pk_bf16_f32 v128, v128, v129
	v_cvt_pk_bf16_f32 v129, v130, v131
	v_cvt_pk_bf16_f32 v132, v132, v133
	v_cvt_pk_bf16_f32 v133, v134, v135
	v_cvt_pk_bf16_f32 v136, v136, v137
	v_cvt_pk_bf16_f32 v137, v138, v139
	v_cvt_pk_bf16_f32 v140, v140, v141
	v_cvt_pk_bf16_f32 v141, v142, v143
	global_store_dwordx2 v2, v[128:129], s[42:43] offset:0
	global_store_dwordx2 v2, v[132:133], s[42:43] offset:512
	global_store_dwordx2 v2, v[136:137], s[42:43] offset:1024
	global_store_dwordx2 v2, v[140:141], s[42:43] offset:1536
	v_mul_f32_e32 v160, v176, v15
	v_mul_f32_e32 v161, v177, v15
	v_mul_f32_e32 v162, v178, v15
	v_mul_f32_e32 v163, v179, v15
	v_mul_f32_e32 v164, v180, v15
	v_mul_f32_e32 v165, v181, v15
	v_mul_f32_e32 v166, v182, v15
	v_mul_f32_e32 v167, v183, v15
	v_mul_f32_e32 v168, v184, v15
	v_mul_f32_e32 v169, v185, v15
	v_mul_f32_e32 v170, v186, v15
	v_mul_f32_e32 v171, v187, v15
	v_mul_f32_e32 v172, v188, v15
	v_mul_f32_e32 v173, v189, v15
	v_mul_f32_e32 v174, v190, v15
	v_mul_f32_e32 v175, v191, v15
	v_mul_f32_e32 v160, v160, v36
	v_mul_f32_e32 v161, v161, v37
	v_mul_f32_e32 v162, v162, v38
	v_mul_f32_e32 v163, v163, v39
	v_mul_f32_e32 v164, v164, v40
	v_mul_f32_e32 v165, v165, v41
	v_mul_f32_e32 v166, v166, v42
	v_mul_f32_e32 v167, v167, v43
	v_mul_f32_e32 v168, v168, v44
	v_mul_f32_e32 v169, v169, v45
	v_mul_f32_e32 v170, v170, v46
	v_mul_f32_e32 v171, v171, v47
	v_mul_f32_e32 v172, v172, v48
	v_mul_f32_e32 v173, v173, v49
	v_mul_f32_e32 v174, v174, v50
	v_mul_f32_e32 v175, v175, v51
	v_cvt_pk_bf16_f32 v160, v160, v161
	v_cvt_pk_bf16_f32 v161, v162, v163
	v_cvt_pk_bf16_f32 v164, v164, v165
	v_cvt_pk_bf16_f32 v165, v166, v167
	v_cvt_pk_bf16_f32 v168, v168, v169
	v_cvt_pk_bf16_f32 v169, v170, v171
	v_cvt_pk_bf16_f32 v172, v172, v173
	v_cvt_pk_bf16_f32 v173, v174, v175
	global_store_dwordx2 v2, v[160:161], s[50:51] offset:0
	global_store_dwordx2 v2, v[164:165], s[50:51] offset:512
	global_store_dwordx2 v2, v[168:169], s[50:51] offset:1024
	global_store_dwordx2 v2, v[172:173], s[50:51] offset:1536
	s_add_u32 s53, s16, 0x3000
	s_lshl_b32 s18, s53, 12
	s_lshl_b32 s19, s53, 11
	s_add_u32 s36, s4, s18
	s_addc_u32 s37, s5, 0
	s_add_u32 s38, s6, s19
	s_addc_u32 s39, s7, 0
	s_add_u32 s38, s38, 0x5200000
	s_addc_u32 s39, s39, 0
	s_add_u32 s40, s4, s18
	s_addc_u32 s41, s5, 0
	s_add_u32 s42, s6, s19
	s_addc_u32 s43, s7, 0
	s_add_u32 s42, s42, 0x3100000
	s_addc_u32 s43, s43, 0
	global_load_dwordx2 v[130:131], v2, s[38:39] offset:0
	global_load_dwordx2 v[134:135], v2, s[38:39] offset:512
	global_load_dwordx2 v[138:139], v2, s[38:39] offset:1024
	global_load_dwordx2 v[142:143], v2, s[38:39] offset:1536
	global_load_dwordx4 v[144:147], v1, s[36:37] offset:0
	global_load_dwordx4 v[148:151], v1, s[36:37] offset:1024
	global_load_dwordx4 v[152:155], v1, s[36:37] offset:2048
	global_load_dwordx4 v[156:159], v1, s[36:37] offset:3072
	s_add_u32 s53, s16, 0x3800
	s_lshl_b32 s18, s53, 12
	s_lshl_b32 s19, s53, 11
	s_add_u32 s44, s4, s18
	s_addc_u32 s45, s5, 0
	s_add_u32 s46, s6, s19
	s_addc_u32 s47, s7, 0
	s_add_u32 s46, s46, 0x5200000
	s_addc_u32 s47, s47, 0
	s_add_u32 s48, s4, s18
	s_addc_u32 s49, s5, 0
	s_add_u32 s50, s6, s19
	s_addc_u32 s51, s7, 0
	s_add_u32 s50, s50, 0x3100000
	s_addc_u32 s51, s51, 0
	global_load_dwordx2 v[162:163], v2, s[46:47] offset:0
	global_load_dwordx2 v[166:167], v2, s[46:47] offset:512
	global_load_dwordx2 v[170:171], v2, s[46:47] offset:1024
	global_load_dwordx2 v[174:175], v2, s[46:47] offset:1536
	global_load_dwordx4 v[176:179], v1, s[44:45] offset:0
	global_load_dwordx4 v[180:183], v1, s[44:45] offset:1024
	global_load_dwordx4 v[184:187], v1, s[44:45] offset:2048
	global_load_dwordx4 v[188:191], v1, s[44:45] offset:3072
	s_waitcnt vmcnt(32)
	v_lshlrev_b32_e32 v64, 16, v66
	v_and_b32_e32 v65, 0xffff0000, v66
	v_lshlrev_b32_e32 v66, 16, v67
	v_and_b32_e32 v67, 0xffff0000, v67
	v_lshlrev_b32_e32 v68, 16, v70
	v_and_b32_e32 v69, 0xffff0000, v70
	v_lshlrev_b32_e32 v70, 16, v71
	v_and_b32_e32 v71, 0xffff0000, v71
	v_lshlrev_b32_e32 v72, 16, v74
	v_and_b32_e32 v73, 0xffff0000, v74
	v_lshlrev_b32_e32 v74, 16, v75
	v_and_b32_e32 v75, 0xffff0000, v75
	v_lshlrev_b32_e32 v76, 16, v78
	v_and_b32_e32 v77, 0xffff0000, v78
	v_lshlrev_b32_e32 v78, 16, v79
	v_and_b32_e32 v79, 0xffff0000, v79
	v_lshlrev_b32_e32 v96, 16, v98
	v_and_b32_e32 v97, 0xffff0000, v98
	v_lshlrev_b32_e32 v98, 16, v99
	v_and_b32_e32 v99, 0xffff0000, v99
	v_lshlrev_b32_e32 v100, 16, v102
	v_and_b32_e32 v101, 0xffff0000, v102
	v_lshlrev_b32_e32 v102, 16, v103
	v_and_b32_e32 v103, 0xffff0000, v103
	v_lshlrev_b32_e32 v104, 16, v106
	v_and_b32_e32 v105, 0xffff0000, v106
	v_lshlrev_b32_e32 v106, 16, v107
	v_and_b32_e32 v107, 0xffff0000, v107
	v_lshlrev_b32_e32 v108, 16, v110
	v_and_b32_e32 v109, 0xffff0000, v110
	v_lshlrev_b32_e32 v110, 16, v111
	v_and_b32_e32 v111, 0xffff0000, v111
	v_mul_f32_e32 v10, v64, v64
	v_fmac_f32_e32 v10, v65, v65
	v_fmac_f32_e32 v10, v66, v66
	v_fmac_f32_e32 v10, v67, v67
	v_fmac_f32_e32 v10, v68, v68
	v_fmac_f32_e32 v10, v69, v69
	v_fmac_f32_e32 v10, v70, v70
	v_fmac_f32_e32 v10, v71, v71
	v_fmac_f32_e32 v10, v72, v72
	v_fmac_f32_e32 v10, v73, v73
	v_fmac_f32_e32 v10, v74, v74
	v_fmac_f32_e32 v10, v75, v75
	v_fmac_f32_e32 v10, v76, v76
	v_fmac_f32_e32 v10, v77, v77
	v_fmac_f32_e32 v10, v78, v78
	v_fmac_f32_e32 v10, v79, v79
	v_mul_f32_e32 v11, v96, v96
	v_fmac_f32_e32 v11, v97, v97
	v_fmac_f32_e32 v11, v98, v98
	v_fmac_f32_e32 v11, v99, v99
	v_fmac_f32_e32 v11, v100, v100
	v_fmac_f32_e32 v11, v101, v101
	v_fmac_f32_e32 v11, v102, v102
	v_fmac_f32_e32 v11, v103, v103
	v_fmac_f32_e32 v11, v104, v104
	v_fmac_f32_e32 v11, v105, v105
	v_fmac_f32_e32 v11, v106, v106
	v_fmac_f32_e32 v11, v107, v107
	v_fmac_f32_e32 v11, v108, v108
	v_fmac_f32_e32 v11, v109, v109
	v_fmac_f32_e32 v11, v110, v110
	v_fmac_f32_e32 v11, v111, v111
	ds_bpermute_b32 v12, v4, v10
	ds_bpermute_b32 v13, v4, v11
	s_waitcnt lgkmcnt(0)
	v_add_f32_e32 v10, v10, v12
	v_add_f32_e32 v11, v11, v13
	ds_bpermute_b32 v12, v5, v10
	ds_bpermute_b32 v13, v5, v11
	s_waitcnt lgkmcnt(0)
	v_add_f32_e32 v10, v10, v12
	v_add_f32_e32 v11, v11, v13
	ds_bpermute_b32 v12, v6, v10
	ds_bpermute_b32 v13, v6, v11
	s_waitcnt lgkmcnt(0)
	v_add_f32_e32 v10, v10, v12
	v_add_f32_e32 v11, v11, v13
	ds_bpermute_b32 v12, v7, v10
	ds_bpermute_b32 v13, v7, v11
	s_waitcnt lgkmcnt(0)
	v_add_f32_e32 v10, v10, v12
	v_add_f32_e32 v11, v11, v13
	ds_bpermute_b32 v12, v8, v10
	ds_bpermute_b32 v13, v8, v11
	s_waitcnt lgkmcnt(0)
	v_add_f32_e32 v10, v10, v12
	v_add_f32_e32 v11, v11, v13
	ds_bpermute_b32 v12, v9, v10
	ds_bpermute_b32 v13, v9, v11
	s_waitcnt lgkmcnt(0)
	v_add_f32_e32 v10, v10, v12
	v_add_f32_e32 v11, v11, v13
	v_fma_f32 v14, v10, s17, v3
	v_fma_f32 v15, v11, s17, v3
	v_rsq_f32_e32 v14, v14
	v_rsq_f32_e32 v15, v15
	s_nop 0
	v_mul_f32_e32 v64, v64, v14
	v_mul_f32_e32 v65, v65, v14
	v_mul_f32_e32 v66, v66, v14
	v_mul_f32_e32 v67, v67, v14
	v_mul_f32_e32 v68, v68, v14
	v_mul_f32_e32 v69, v69, v14
	v_mul_f32_e32 v70, v70, v14
	v_mul_f32_e32 v71, v71, v14
	v_mul_f32_e32 v72, v72, v14
	v_mul_f32_e32 v73, v73, v14
	v_mul_f32_e32 v74, v74, v14
	v_mul_f32_e32 v75, v75, v14
	v_mul_f32_e32 v76, v76, v14
	v_mul_f32_e32 v77, v77, v14
	v_mul_f32_e32 v78, v78, v14
	v_mul_f32_e32 v79, v79, v14
	v_fmac_f32_e32 v80, v64, v20
	v_fmac_f32_e32 v81, v65, v21
	v_fmac_f32_e32 v82, v66, v22
	v_fmac_f32_e32 v83, v67, v23
	v_fmac_f32_e32 v84, v68, v24
	v_fmac_f32_e32 v85, v69, v25
	v_fmac_f32_e32 v86, v70, v26
	v_fmac_f32_e32 v87, v71, v27
	v_fmac_f32_e32 v88, v72, v28
	v_fmac_f32_e32 v89, v73, v29
	v_fmac_f32_e32 v90, v74, v30
	v_fmac_f32_e32 v91, v75, v31
	v_fmac_f32_e32 v92, v76, v32
	v_fmac_f32_e32 v93, v77, v33
	v_fmac_f32_e32 v94, v78, v34
	v_fmac_f32_e32 v95, v79, v35
	global_store_dwordx4 v1, v[80:83], s[24:25] offset:0
	global_store_dwordx4 v1, v[84:87], s[24:25] offset:1024
	global_store_dwordx4 v1, v[88:91], s[24:25] offset:2048
	global_store_dwordx4 v1, v[92:95], s[24:25] offset:3072
	v_mul_f32_e32 v96, v96, v15
	v_mul_f32_e32 v97, v97, v15
	v_mul_f32_e32 v98, v98, v15
	v_mul_f32_e32 v99, v99, v15
	v_mul_f32_e32 v100, v100, v15
	v_mul_f32_e32 v101, v101, v15
	v_mul_f32_e32 v102, v102, v15
	v_mul_f32_e32 v103, v103, v15
	v_mul_f32_e32 v104, v104, v15
	v_mul_f32_e32 v105, v105, v15
	v_mul_f32_e32 v106, v106, v15
	v_mul_f32_e32 v107, v107, v15
	v_mul_f32_e32 v108, v108, v15
	v_mul_f32_e32 v109, v109, v15
	v_mul_f32_e32 v110, v110, v15
	v_mul_f32_e32 v111, v111, v15
	v_fmac_f32_e32 v112, v96, v20
	v_fmac_f32_e32 v113, v97, v21
	v_fmac_f32_e32 v114, v98, v22
	v_fmac_f32_e32 v115, v99, v23
	v_fmac_f32_e32 v116, v100, v24
	v_fmac_f32_e32 v117, v101, v25
	v_fmac_f32_e32 v118, v102, v26
	v_fmac_f32_e32 v119, v103, v27
	v_fmac_f32_e32 v120, v104, v28
	v_fmac_f32_e32 v121, v105, v29
	v_fmac_f32_e32 v122, v106, v30
	v_fmac_f32_e32 v123, v107, v31
	v_fmac_f32_e32 v124, v108, v32
	v_fmac_f32_e32 v125, v109, v33
	v_fmac_f32_e32 v126, v110, v34
	v_fmac_f32_e32 v127, v111, v35
	global_store_dwordx4 v1, v[112:115], s[32:33] offset:0
	global_store_dwordx4 v1, v[116:119], s[32:33] offset:1024
	global_store_dwordx4 v1, v[120:123], s[32:33] offset:2048
	global_store_dwordx4 v1, v[124:127], s[32:33] offset:3072
	v_mul_f32_e32 v10, v80, v80
	v_fmac_f32_e32 v10, v81, v81
	v_fmac_f32_e32 v10, v82, v82
	v_fmac_f32_e32 v10, v83, v83
	v_fmac_f32_e32 v10, v84, v84
	v_fmac_f32_e32 v10, v85, v85
	v_fmac_f32_e32 v10, v86, v86
	v_fmac_f32_e32 v10, v87, v87
	v_fmac_f32_e32 v10, v88, v88
	v_fmac_f32_e32 v10, v89, v89
	v_fmac_f32_e32 v10, v90, v90
	v_fmac_f32_e32 v10, v91, v91
	v_fmac_f32_e32 v10, v92, v92
	v_fmac_f32_e32 v10, v93, v93
	v_fmac_f32_e32 v10, v94, v94
	v_fmac_f32_e32 v10, v95, v95
	v_mul_f32_e32 v11, v112, v112
	v_fmac_f32_e32 v11, v113, v113
	v_fmac_f32_e32 v11, v114, v114
	v_fmac_f32_e32 v11, v115, v115
	v_fmac_f32_e32 v11, v116, v116
	v_fmac_f32_e32 v11, v117, v117
	v_fmac_f32_e32 v11, v118, v118
	v_fmac_f32_e32 v11, v119, v119
	v_fmac_f32_e32 v11, v120, v120
	v_fmac_f32_e32 v11, v121, v121
	v_fmac_f32_e32 v11, v122, v122
	v_fmac_f32_e32 v11, v123, v123
	v_fmac_f32_e32 v11, v124, v124
	v_fmac_f32_e32 v11, v125, v125
	v_fmac_f32_e32 v11, v126, v126
	v_fmac_f32_e32 v11, v127, v127
	ds_bpermute_b32 v12, v4, v10
	ds_bpermute_b32 v13, v4, v11
	s_waitcnt lgkmcnt(0)
	v_add_f32_e32 v10, v10, v12
	v_add_f32_e32 v11, v11, v13
	ds_bpermute_b32 v12, v5, v10
	ds_bpermute_b32 v13, v5, v11
	s_waitcnt lgkmcnt(0)
	v_add_f32_e32 v10, v10, v12
	v_add_f32_e32 v11, v11, v13
	ds_bpermute_b32 v12, v6, v10
	ds_bpermute_b32 v13, v6, v11
	s_waitcnt lgkmcnt(0)
	v_add_f32_e32 v10, v10, v12
	v_add_f32_e32 v11, v11, v13
	ds_bpermute_b32 v12, v7, v10
	ds_bpermute_b32 v13, v7, v11
	s_waitcnt lgkmcnt(0)
	v_add_f32_e32 v10, v10, v12
	v_add_f32_e32 v11, v11, v13
	ds_bpermute_b32 v12, v8, v10
	ds_bpermute_b32 v13, v8, v11
	s_waitcnt lgkmcnt(0)
	v_add_f32_e32 v10, v10, v12
	v_add_f32_e32 v11, v11, v13
	ds_bpermute_b32 v12, v9, v10
	ds_bpermute_b32 v13, v9, v11
	s_waitcnt lgkmcnt(0)
	v_add_f32_e32 v10, v10, v12
	v_add_f32_e32 v11, v11, v13
	v_fma_f32 v14, v10, s17, v3
	v_fma_f32 v15, v11, s17, v3
	v_rsq_f32_e32 v14, v14
	v_rsq_f32_e32 v15, v15
	s_nop 0
	v_mul_f32_e32 v64, v80, v14
	v_mul_f32_e32 v65, v81, v14
	v_mul_f32_e32 v66, v82, v14
	v_mul_f32_e32 v67, v83, v14
	v_mul_f32_e32 v68, v84, v14
	v_mul_f32_e32 v69, v85, v14
	v_mul_f32_e32 v70, v86, v14
	v_mul_f32_e32 v71, v87, v14
	v_mul_f32_e32 v72, v88, v14
	v_mul_f32_e32 v73, v89, v14
	v_mul_f32_e32 v74, v90, v14
	v_mul_f32_e32 v75, v91, v14
	v_mul_f32_e32 v76, v92, v14
	v_mul_f32_e32 v77, v93, v14
	v_mul_f32_e32 v78, v94, v14
	v_mul_f32_e32 v79, v95, v14
	v_mul_f32_e32 v64, v64, v36
	v_mul_f32_e32 v65, v65, v37
	v_mul_f32_e32 v66, v66, v38
	v_mul_f32_e32 v67, v67, v39
	v_mul_f32_e32 v68, v68, v40
	v_mul_f32_e32 v69, v69, v41
	v_mul_f32_e32 v70, v70, v42
	v_mul_f32_e32 v71, v71, v43
	v_mul_f32_e32 v72, v72, v44
	v_mul_f32_e32 v73, v73, v45
	v_mul_f32_e32 v74, v74, v46
	v_mul_f32_e32 v75, v75, v47
	v_mul_f32_e32 v76, v76, v48
	v_mul_f32_e32 v77, v77, v49
	v_mul_f32_e32 v78, v78, v50
	v_mul_f32_e32 v79, v79, v51
	v_cvt_pk_bf16_f32 v64, v64, v65
	v_cvt_pk_bf16_f32 v65, v66, v67
	v_cvt_pk_bf16_f32 v68, v68, v69
	v_cvt_pk_bf16_f32 v69, v70, v71
	v_cvt_pk_bf16_f32 v72, v72, v73
	v_cvt_pk_bf16_f32 v73, v74, v75
	v_cvt_pk_bf16_f32 v76, v76, v77
	v_cvt_pk_bf16_f32 v77, v78, v79
	global_store_dwordx2 v2, v[64:65], s[26:27] offset:0
	global_store_dwordx2 v2, v[68:69], s[26:27] offset:512
	global_store_dwordx2 v2, v[72:73], s[26:27] offset:1024
	global_store_dwordx2 v2, v[76:77], s[26:27] offset:1536
	v_mul_f32_e32 v96, v112, v15
	v_mul_f32_e32 v97, v113, v15
	v_mul_f32_e32 v98, v114, v15
	v_mul_f32_e32 v99, v115, v15
	v_mul_f32_e32 v100, v116, v15
	v_mul_f32_e32 v101, v117, v15
	v_mul_f32_e32 v102, v118, v15
	v_mul_f32_e32 v103, v119, v15
	v_mul_f32_e32 v104, v120, v15
	v_mul_f32_e32 v105, v121, v15
	v_mul_f32_e32 v106, v122, v15
	v_mul_f32_e32 v107, v123, v15
	v_mul_f32_e32 v108, v124, v15
	v_mul_f32_e32 v109, v125, v15
	v_mul_f32_e32 v110, v126, v15
	v_mul_f32_e32 v111, v127, v15
	v_mul_f32_e32 v96, v96, v36
	v_mul_f32_e32 v97, v97, v37
	v_mul_f32_e32 v98, v98, v38
	v_mul_f32_e32 v99, v99, v39
	v_mul_f32_e32 v100, v100, v40
	v_mul_f32_e32 v101, v101, v41
	v_mul_f32_e32 v102, v102, v42
	v_mul_f32_e32 v103, v103, v43
	v_mul_f32_e32 v104, v104, v44
	v_mul_f32_e32 v105, v105, v45
	v_mul_f32_e32 v106, v106, v46
	v_mul_f32_e32 v107, v107, v47
	v_mul_f32_e32 v108, v108, v48
	v_mul_f32_e32 v109, v109, v49
	v_mul_f32_e32 v110, v110, v50
	v_mul_f32_e32 v111, v111, v51
	v_cvt_pk_bf16_f32 v96, v96, v97
	v_cvt_pk_bf16_f32 v97, v98, v99
	v_cvt_pk_bf16_f32 v100, v100, v101
	v_cvt_pk_bf16_f32 v101, v102, v103
	v_cvt_pk_bf16_f32 v104, v104, v105
	v_cvt_pk_bf16_f32 v105, v106, v107
	v_cvt_pk_bf16_f32 v108, v108, v109
	v_cvt_pk_bf16_f32 v109, v110, v111
	global_store_dwordx2 v2, v[96:97], s[34:35] offset:0
	global_store_dwordx2 v2, v[100:101], s[34:35] offset:512
	global_store_dwordx2 v2, v[104:105], s[34:35] offset:1024
	global_store_dwordx2 v2, v[108:109], s[34:35] offset:1536
	s_waitcnt vmcnt(16)
	v_lshlrev_b32_e32 v128, 16, v130
	v_and_b32_e32 v129, 0xffff0000, v130
	v_lshlrev_b32_e32 v130, 16, v131
	v_and_b32_e32 v131, 0xffff0000, v131
	v_lshlrev_b32_e32 v132, 16, v134
	v_and_b32_e32 v133, 0xffff0000, v134
	v_lshlrev_b32_e32 v134, 16, v135
	v_and_b32_e32 v135, 0xffff0000, v135
	v_lshlrev_b32_e32 v136, 16, v138
	v_and_b32_e32 v137, 0xffff0000, v138
	v_lshlrev_b32_e32 v138, 16, v139
	v_and_b32_e32 v139, 0xffff0000, v139
	v_lshlrev_b32_e32 v140, 16, v142
	v_and_b32_e32 v141, 0xffff0000, v142
	v_lshlrev_b32_e32 v142, 16, v143
	v_and_b32_e32 v143, 0xffff0000, v143
	v_lshlrev_b32_e32 v160, 16, v162
	v_and_b32_e32 v161, 0xffff0000, v162
	v_lshlrev_b32_e32 v162, 16, v163
	v_and_b32_e32 v163, 0xffff0000, v163
	v_lshlrev_b32_e32 v164, 16, v166
	v_and_b32_e32 v165, 0xffff0000, v166
	v_lshlrev_b32_e32 v166, 16, v167
	v_and_b32_e32 v167, 0xffff0000, v167
	v_lshlrev_b32_e32 v168, 16, v170
	v_and_b32_e32 v169, 0xffff0000, v170
	v_lshlrev_b32_e32 v170, 16, v171
	v_and_b32_e32 v171, 0xffff0000, v171
	v_lshlrev_b32_e32 v172, 16, v174
	v_and_b32_e32 v173, 0xffff0000, v174
	v_lshlrev_b32_e32 v174, 16, v175
	v_and_b32_e32 v175, 0xffff0000, v175
	v_mul_f32_e32 v10, v128, v128
	v_fmac_f32_e32 v10, v129, v129
	v_fmac_f32_e32 v10, v130, v130
	v_fmac_f32_e32 v10, v131, v131
	v_fmac_f32_e32 v10, v132, v132
	v_fmac_f32_e32 v10, v133, v133
	v_fmac_f32_e32 v10, v134, v134
	v_fmac_f32_e32 v10, v135, v135
	v_fmac_f32_e32 v10, v136, v136
	v_fmac_f32_e32 v10, v137, v137
	v_fmac_f32_e32 v10, v138, v138
	v_fmac_f32_e32 v10, v139, v139
	v_fmac_f32_e32 v10, v140, v140
	v_fmac_f32_e32 v10, v141, v141
	v_fmac_f32_e32 v10, v142, v142
	v_fmac_f32_e32 v10, v143, v143
	v_mul_f32_e32 v11, v160, v160
	v_fmac_f32_e32 v11, v161, v161
	v_fmac_f32_e32 v11, v162, v162
	v_fmac_f32_e32 v11, v163, v163
	v_fmac_f32_e32 v11, v164, v164
	v_fmac_f32_e32 v11, v165, v165
	v_fmac_f32_e32 v11, v166, v166
	v_fmac_f32_e32 v11, v167, v167
	v_fmac_f32_e32 v11, v168, v168
	v_fmac_f32_e32 v11, v169, v169
	v_fmac_f32_e32 v11, v170, v170
	v_fmac_f32_e32 v11, v171, v171
	v_fmac_f32_e32 v11, v172, v172
	v_fmac_f32_e32 v11, v173, v173
	v_fmac_f32_e32 v11, v174, v174
	v_fmac_f32_e32 v11, v175, v175
	ds_bpermute_b32 v12, v4, v10
	ds_bpermute_b32 v13, v4, v11
	s_waitcnt lgkmcnt(0)
	v_add_f32_e32 v10, v10, v12
	v_add_f32_e32 v11, v11, v13
	ds_bpermute_b32 v12, v5, v10
	ds_bpermute_b32 v13, v5, v11
	s_waitcnt lgkmcnt(0)
	v_add_f32_e32 v10, v10, v12
	v_add_f32_e32 v11, v11, v13
	ds_bpermute_b32 v12, v6, v10
	ds_bpermute_b32 v13, v6, v11
	s_waitcnt lgkmcnt(0)
	v_add_f32_e32 v10, v10, v12
	v_add_f32_e32 v11, v11, v13
	ds_bpermute_b32 v12, v7, v10
	ds_bpermute_b32 v13, v7, v11
	s_waitcnt lgkmcnt(0)
	v_add_f32_e32 v10, v10, v12
	v_add_f32_e32 v11, v11, v13
	ds_bpermute_b32 v12, v8, v10
	ds_bpermute_b32 v13, v8, v11
	s_waitcnt lgkmcnt(0)
	v_add_f32_e32 v10, v10, v12
	v_add_f32_e32 v11, v11, v13
	ds_bpermute_b32 v12, v9, v10
	ds_bpermute_b32 v13, v9, v11
	s_waitcnt lgkmcnt(0)
	v_add_f32_e32 v10, v10, v12
	v_add_f32_e32 v11, v11, v13
	v_fma_f32 v14, v10, s17, v3
	v_fma_f32 v15, v11, s17, v3
	v_rsq_f32_e32 v14, v14
	v_rsq_f32_e32 v15, v15
	s_nop 0
	v_mul_f32_e32 v128, v128, v14
	v_mul_f32_e32 v129, v129, v14
	v_mul_f32_e32 v130, v130, v14
	v_mul_f32_e32 v131, v131, v14
	v_mul_f32_e32 v132, v132, v14
	v_mul_f32_e32 v133, v133, v14
	v_mul_f32_e32 v134, v134, v14
	v_mul_f32_e32 v135, v135, v14
	v_mul_f32_e32 v136, v136, v14
	v_mul_f32_e32 v137, v137, v14
	v_mul_f32_e32 v138, v138, v14
	v_mul_f32_e32 v139, v139, v14
	v_mul_f32_e32 v140, v140, v14
	v_mul_f32_e32 v141, v141, v14
	v_mul_f32_e32 v142, v142, v14
	v_mul_f32_e32 v143, v143, v14
	v_fmac_f32_e32 v144, v128, v20
	v_fmac_f32_e32 v145, v129, v21
	v_fmac_f32_e32 v146, v130, v22
	v_fmac_f32_e32 v147, v131, v23
	v_fmac_f32_e32 v148, v132, v24
	v_fmac_f32_e32 v149, v133, v25
	v_fmac_f32_e32 v150, v134, v26
	v_fmac_f32_e32 v151, v135, v27
	v_fmac_f32_e32 v152, v136, v28
	v_fmac_f32_e32 v153, v137, v29
	v_fmac_f32_e32 v154, v138, v30
	v_fmac_f32_e32 v155, v139, v31
	v_fmac_f32_e32 v156, v140, v32
	v_fmac_f32_e32 v157, v141, v33
	v_fmac_f32_e32 v158, v142, v34
	v_fmac_f32_e32 v159, v143, v35
	global_store_dwordx4 v1, v[144:147], s[40:41] offset:0
	global_store_dwordx4 v1, v[148:151], s[40:41] offset:1024
	global_store_dwordx4 v1, v[152:155], s[40:41] offset:2048
	global_store_dwordx4 v1, v[156:159], s[40:41] offset:3072
	v_mul_f32_e32 v160, v160, v15
	v_mul_f32_e32 v161, v161, v15
	v_mul_f32_e32 v162, v162, v15
	v_mul_f32_e32 v163, v163, v15
	v_mul_f32_e32 v164, v164, v15
	v_mul_f32_e32 v165, v165, v15
	v_mul_f32_e32 v166, v166, v15
	v_mul_f32_e32 v167, v167, v15
	v_mul_f32_e32 v168, v168, v15
	v_mul_f32_e32 v169, v169, v15
	v_mul_f32_e32 v170, v170, v15
	v_mul_f32_e32 v171, v171, v15
	v_mul_f32_e32 v172, v172, v15
	v_mul_f32_e32 v173, v173, v15
	v_mul_f32_e32 v174, v174, v15
	v_mul_f32_e32 v175, v175, v15
	v_fmac_f32_e32 v176, v160, v20
	v_fmac_f32_e32 v177, v161, v21
	v_fmac_f32_e32 v178, v162, v22
	v_fmac_f32_e32 v179, v163, v23
	v_fmac_f32_e32 v180, v164, v24
	v_fmac_f32_e32 v181, v165, v25
	v_fmac_f32_e32 v182, v166, v26
	v_fmac_f32_e32 v183, v167, v27
	v_fmac_f32_e32 v184, v168, v28
	v_fmac_f32_e32 v185, v169, v29
	v_fmac_f32_e32 v186, v170, v30
	v_fmac_f32_e32 v187, v171, v31
	v_fmac_f32_e32 v188, v172, v32
	v_fmac_f32_e32 v189, v173, v33
	v_fmac_f32_e32 v190, v174, v34
	v_fmac_f32_e32 v191, v175, v35
	global_store_dwordx4 v1, v[176:179], s[48:49] offset:0
	global_store_dwordx4 v1, v[180:183], s[48:49] offset:1024
	global_store_dwordx4 v1, v[184:187], s[48:49] offset:2048
	global_store_dwordx4 v1, v[188:191], s[48:49] offset:3072
	v_mul_f32_e32 v10, v144, v144
	v_fmac_f32_e32 v10, v145, v145
	v_fmac_f32_e32 v10, v146, v146
	v_fmac_f32_e32 v10, v147, v147
	v_fmac_f32_e32 v10, v148, v148
	v_fmac_f32_e32 v10, v149, v149
	v_fmac_f32_e32 v10, v150, v150
	v_fmac_f32_e32 v10, v151, v151
	v_fmac_f32_e32 v10, v152, v152
	v_fmac_f32_e32 v10, v153, v153
	v_fmac_f32_e32 v10, v154, v154
	v_fmac_f32_e32 v10, v155, v155
	v_fmac_f32_e32 v10, v156, v156
	v_fmac_f32_e32 v10, v157, v157
	v_fmac_f32_e32 v10, v158, v158
	v_fmac_f32_e32 v10, v159, v159
	v_mul_f32_e32 v11, v176, v176
	v_fmac_f32_e32 v11, v177, v177
	v_fmac_f32_e32 v11, v178, v178
	v_fmac_f32_e32 v11, v179, v179
	v_fmac_f32_e32 v11, v180, v180
	v_fmac_f32_e32 v11, v181, v181
	v_fmac_f32_e32 v11, v182, v182
	v_fmac_f32_e32 v11, v183, v183
	v_fmac_f32_e32 v11, v184, v184
	v_fmac_f32_e32 v11, v185, v185
	v_fmac_f32_e32 v11, v186, v186
	v_fmac_f32_e32 v11, v187, v187
	v_fmac_f32_e32 v11, v188, v188
	v_fmac_f32_e32 v11, v189, v189
	v_fmac_f32_e32 v11, v190, v190
	v_fmac_f32_e32 v11, v191, v191
	ds_bpermute_b32 v12, v4, v10
	ds_bpermute_b32 v13, v4, v11
	s_waitcnt lgkmcnt(0)
	v_add_f32_e32 v10, v10, v12
	v_add_f32_e32 v11, v11, v13
	ds_bpermute_b32 v12, v5, v10
	ds_bpermute_b32 v13, v5, v11
	s_waitcnt lgkmcnt(0)
	v_add_f32_e32 v10, v10, v12
	v_add_f32_e32 v11, v11, v13
	ds_bpermute_b32 v12, v6, v10
	ds_bpermute_b32 v13, v6, v11
	s_waitcnt lgkmcnt(0)
	v_add_f32_e32 v10, v10, v12
	v_add_f32_e32 v11, v11, v13
	ds_bpermute_b32 v12, v7, v10
	ds_bpermute_b32 v13, v7, v11
	s_waitcnt lgkmcnt(0)
	v_add_f32_e32 v10, v10, v12
	v_add_f32_e32 v11, v11, v13
	ds_bpermute_b32 v12, v8, v10
	ds_bpermute_b32 v13, v8, v11
	s_waitcnt lgkmcnt(0)
	v_add_f32_e32 v10, v10, v12
	v_add_f32_e32 v11, v11, v13
	ds_bpermute_b32 v12, v9, v10
	ds_bpermute_b32 v13, v9, v11
	s_waitcnt lgkmcnt(0)
	v_add_f32_e32 v10, v10, v12
	v_add_f32_e32 v11, v11, v13
	v_fma_f32 v14, v10, s17, v3
	v_fma_f32 v15, v11, s17, v3
	v_rsq_f32_e32 v14, v14
	v_rsq_f32_e32 v15, v15
	s_nop 0
	v_mul_f32_e32 v128, v144, v14
	v_mul_f32_e32 v129, v145, v14
	v_mul_f32_e32 v130, v146, v14
	v_mul_f32_e32 v131, v147, v14
	v_mul_f32_e32 v132, v148, v14
	v_mul_f32_e32 v133, v149, v14
	v_mul_f32_e32 v134, v150, v14
	v_mul_f32_e32 v135, v151, v14
	v_mul_f32_e32 v136, v152, v14
	v_mul_f32_e32 v137, v153, v14
	v_mul_f32_e32 v138, v154, v14
	v_mul_f32_e32 v139, v155, v14
	v_mul_f32_e32 v140, v156, v14
	v_mul_f32_e32 v141, v157, v14
	v_mul_f32_e32 v142, v158, v14
	v_mul_f32_e32 v143, v159, v14
	v_mul_f32_e32 v128, v128, v36
	v_mul_f32_e32 v129, v129, v37
	v_mul_f32_e32 v130, v130, v38
	v_mul_f32_e32 v131, v131, v39
	v_mul_f32_e32 v132, v132, v40
	v_mul_f32_e32 v133, v133, v41
	v_mul_f32_e32 v134, v134, v42
	v_mul_f32_e32 v135, v135, v43
	v_mul_f32_e32 v136, v136, v44
	v_mul_f32_e32 v137, v137, v45
	v_mul_f32_e32 v138, v138, v46
	v_mul_f32_e32 v139, v139, v47
	v_mul_f32_e32 v140, v140, v48
	v_mul_f32_e32 v141, v141, v49
	v_mul_f32_e32 v142, v142, v50
	v_mul_f32_e32 v143, v143, v51
	v_cvt_pk_bf16_f32 v128, v128, v129
	v_cvt_pk_bf16_f32 v129, v130, v131
	v_cvt_pk_bf16_f32 v132, v132, v133
	v_cvt_pk_bf16_f32 v133, v134, v135
	v_cvt_pk_bf16_f32 v136, v136, v137
	v_cvt_pk_bf16_f32 v137, v138, v139
	v_cvt_pk_bf16_f32 v140, v140, v141
	v_cvt_pk_bf16_f32 v141, v142, v143
	global_store_dwordx2 v2, v[128:129], s[42:43] offset:0
	global_store_dwordx2 v2, v[132:133], s[42:43] offset:512
	global_store_dwordx2 v2, v[136:137], s[42:43] offset:1024
	global_store_dwordx2 v2, v[140:141], s[42:43] offset:1536
	v_mul_f32_e32 v160, v176, v15
	v_mul_f32_e32 v161, v177, v15
	v_mul_f32_e32 v162, v178, v15
	v_mul_f32_e32 v163, v179, v15
	v_mul_f32_e32 v164, v180, v15
	v_mul_f32_e32 v165, v181, v15
	v_mul_f32_e32 v166, v182, v15
	v_mul_f32_e32 v167, v183, v15
	v_mul_f32_e32 v168, v184, v15
	v_mul_f32_e32 v169, v185, v15
	v_mul_f32_e32 v170, v186, v15
	v_mul_f32_e32 v171, v187, v15
	v_mul_f32_e32 v172, v188, v15
	v_mul_f32_e32 v173, v189, v15
	v_mul_f32_e32 v174, v190, v15
	v_mul_f32_e32 v175, v191, v15
	v_mul_f32_e32 v160, v160, v36
	v_mul_f32_e32 v161, v161, v37
	v_mul_f32_e32 v162, v162, v38
	v_mul_f32_e32 v163, v163, v39
	v_mul_f32_e32 v164, v164, v40
	v_mul_f32_e32 v165, v165, v41
	v_mul_f32_e32 v166, v166, v42
	v_mul_f32_e32 v167, v167, v43
	v_mul_f32_e32 v168, v168, v44
	v_mul_f32_e32 v169, v169, v45
	v_mul_f32_e32 v170, v170, v46
	v_mul_f32_e32 v171, v171, v47
	v_mul_f32_e32 v172, v172, v48
	v_mul_f32_e32 v173, v173, v49
	v_mul_f32_e32 v174, v174, v50
	v_mul_f32_e32 v175, v175, v51
	v_cvt_pk_bf16_f32 v160, v160, v161
	v_cvt_pk_bf16_f32 v161, v162, v163
	v_cvt_pk_bf16_f32 v164, v164, v165
	v_cvt_pk_bf16_f32 v165, v166, v167
	v_cvt_pk_bf16_f32 v168, v168, v169
	v_cvt_pk_bf16_f32 v169, v170, v171
	v_cvt_pk_bf16_f32 v172, v172, v173
	v_cvt_pk_bf16_f32 v173, v174, v175
	global_store_dwordx2 v2, v[160:161], s[50:51] offset:0
	global_store_dwordx2 v2, v[164:165], s[50:51] offset:512
	global_store_dwordx2 v2, v[168:169], s[50:51] offset:1024
	global_store_dwordx2 v2, v[172:173], s[50:51] offset:1536
	s_and_b32 s18, s16, 3
	s_cmp_lg_u32 s18, 0
	s_cbranch_scc1 .Lrows11_end
	s_lshr_b32 s54, s16, 2
	s_add_u32 s53, s54, 0x4000
	s_lshl_b32 s18, s53, 12
	s_lshl_b32 s19, s53, 11
	s_add_u32 s20, s4, s18
	s_addc_u32 s21, s5, 0
	s_add_u32 s24, s4, s18
	s_addc_u32 s25, s5, 0
	s_add_u32 s26, s6, s19
	s_addc_u32 s27, s7, 0
	s_add_u32 s26, s26, 0x3100000
	s_addc_u32 s27, s27, 0
	s_lshl_b32 s18, s54, 12
	s_add_u32 s22, s6, s18
	s_addc_u32 s23, s7, 0
	s_add_u32 s22, s22, 0x7400000
	s_addc_u32 s23, s23, 0
	global_load_dwordx4 v[64:67], v1, s[22:23] offset:0
	global_load_dwordx4 v[68:71], v1, s[22:23] offset:1024
	global_load_dwordx4 v[72:75], v1, s[22:23] offset:2048
	global_load_dwordx4 v[76:79], v1, s[22:23] offset:3072
	s_add_u32 s22, s22, 0x200000
	s_addc_u32 s23, s23, 0
	global_load_dwordx4 v[80:83], v1, s[22:23] offset:0
	global_load_dwordx4 v[84:87], v1, s[22:23] offset:1024
	global_load_dwordx4 v[88:91], v1, s[22:23] offset:2048
	global_load_dwordx4 v[92:95], v1, s[22:23] offset:3072
	global_load_dwordx4 v[192:195], v1, s[20:21] offset:0
	global_load_dwordx4 v[196:199], v1, s[20:21] offset:1024
	global_load_dwordx4 v[200:203], v1, s[20:21] offset:2048
	global_load_dwordx4 v[204:207], v1, s[20:21] offset:3072
	s_waitcnt vmcnt(0)
	v_add_f32_e32 v64, v64, v80
	v_add_f32_e32 v65, v65, v81
	v_add_f32_e32 v66, v66, v82
	v_add_f32_e32 v67, v67, v83
	v_add_f32_e32 v68, v68, v84
	v_add_f32_e32 v69, v69, v85
	v_add_f32_e32 v70, v70, v86
	v_add_f32_e32 v71, v71, v87
	v_add_f32_e32 v72, v72, v88
	v_add_f32_e32 v73, v73, v89
	v_add_f32_e32 v74, v74, v90
	v_add_f32_e32 v75, v75, v91
	v_add_f32_e32 v76, v76, v92
	v_add_f32_e32 v77, v77, v93
	v_add_f32_e32 v78, v78, v94
	v_add_f32_e32 v79, v79, v95
	v_mul_f32_e32 v10, v64, v64
	v_fmac_f32_e32 v10, v65, v65
	v_fmac_f32_e32 v10, v66, v66
	v_fmac_f32_e32 v10, v67, v67
	v_fmac_f32_e32 v10, v68, v68
	v_fmac_f32_e32 v10, v69, v69
	v_fmac_f32_e32 v10, v70, v70
	v_fmac_f32_e32 v10, v71, v71
	v_fmac_f32_e32 v10, v72, v72
	v_fmac_f32_e32 v10, v73, v73
	v_fmac_f32_e32 v10, v74, v74
	v_fmac_f32_e32 v10, v75, v75
	v_fmac_f32_e32 v10, v76, v76
	v_fmac_f32_e32 v10, v77, v77
	v_fmac_f32_e32 v10, v78, v78
	v_fmac_f32_e32 v10, v79, v79
	ds_bpermute_b32 v12, v4, v10
	s_waitcnt lgkmcnt(0)
	v_add_f32_e32 v10, v10, v12
	ds_bpermute_b32 v12, v5, v10
	s_waitcnt lgkmcnt(0)
	v_add_f32_e32 v10, v10, v12
	ds_bpermute_b32 v12, v6, v10
	s_waitcnt lgkmcnt(0)
	v_add_f32_e32 v10, v10, v12
	ds_bpermute_b32 v12, v7, v10
	s_waitcnt lgkmcnt(0)
	v_add_f32_e32 v10, v10, v12
	ds_bpermute_b32 v12, v8, v10
	s_waitcnt lgkmcnt(0)
	v_add_f32_e32 v10, v10, v12
	ds_bpermute_b32 v12, v9, v10
	s_waitcnt lgkmcnt(0)
	v_add_f32_e32 v10, v10, v12
	v_fma_f32 v14, v10, s17, v3
	v_rsq_f32_e32 v14, v14
	s_nop 0
	v_mul_f32_e32 v64, v64, v14
	v_mul_f32_e32 v65, v65, v14
	v_mul_f32_e32 v66, v66, v14
	v_mul_f32_e32 v67, v67, v14
	v_mul_f32_e32 v68, v68, v14
	v_mul_f32_e32 v69, v69, v14
	v_mul_f32_e32 v70, v70, v14
	v_mul_f32_e32 v71, v71, v14
	v_mul_f32_e32 v72, v72, v14
	v_mul_f32_e32 v73, v73, v14
	v_mul_f32_e32 v74, v74, v14
	v_mul_f32_e32 v75, v75, v14
	v_mul_f32_e32 v76, v76, v14
	v_mul_f32_e32 v77, v77, v14
	v_mul_f32_e32 v78, v78, v14
	v_mul_f32_e32 v79, v79, v14
	v_fmac_f32_e32 v192, v64, v20
	v_fmac_f32_e32 v193, v65, v21
	v_fmac_f32_e32 v194, v66, v22
	v_fmac_f32_e32 v195, v67, v23
	v_fmac_f32_e32 v196, v68, v24
	v_fmac_f32_e32 v197, v69, v25
	v_fmac_f32_e32 v198, v70, v26
	v_fmac_f32_e32 v199, v71, v27
	v_fmac_f32_e32 v200, v72, v28
	v_fmac_f32_e32 v201, v73, v29
	v_fmac_f32_e32 v202, v74, v30
	v_fmac_f32_e32 v203, v75, v31
	v_fmac_f32_e32 v204, v76, v32
	v_fmac_f32_e32 v205, v77, v33
	v_fmac_f32_e32 v206, v78, v34
	v_fmac_f32_e32 v207, v79, v35
	global_store_dwordx4 v1, v[192:195], s[24:25] offset:0
	global_store_dwordx4 v1, v[196:199], s[24:25] offset:1024
	global_store_dwordx4 v1, v[200:203], s[24:25] offset:2048
	global_store_dwordx4 v1, v[204:207], s[24:25] offset:3072
	v_mul_f32_e32 v10, v192, v192
	v_fmac_f32_e32 v10, v193, v193
	v_fmac_f32_e32 v10, v194, v194
	v_fmac_f32_e32 v10, v195, v195
	v_fmac_f32_e32 v10, v196, v196
	v_fmac_f32_e32 v10, v197, v197
	v_fmac_f32_e32 v10, v198, v198
	v_fmac_f32_e32 v10, v199, v199
	v_fmac_f32_e32 v10, v200, v200
	v_fmac_f32_e32 v10, v201, v201
	v_fmac_f32_e32 v10, v202, v202
	v_fmac_f32_e32 v10, v203, v203
	v_fmac_f32_e32 v10, v204, v204
	v_fmac_f32_e32 v10, v205, v205
	v_fmac_f32_e32 v10, v206, v206
	v_fmac_f32_e32 v10, v207, v207
	ds_bpermute_b32 v12, v4, v10
	s_waitcnt lgkmcnt(0)
	v_add_f32_e32 v10, v10, v12
	ds_bpermute_b32 v12, v5, v10
	s_waitcnt lgkmcnt(0)
	v_add_f32_e32 v10, v10, v12
	ds_bpermute_b32 v12, v6, v10
	s_waitcnt lgkmcnt(0)
	v_add_f32_e32 v10, v10, v12
	ds_bpermute_b32 v12, v7, v10
	s_waitcnt lgkmcnt(0)
	v_add_f32_e32 v10, v10, v12
	ds_bpermute_b32 v12, v8, v10
	s_waitcnt lgkmcnt(0)
	v_add_f32_e32 v10, v10, v12
	ds_bpermute_b32 v12, v9, v10
	s_waitcnt lgkmcnt(0)
	v_add_f32_e32 v10, v10, v12
	v_fma_f32 v14, v10, s17, v3
	v_rsq_f32_e32 v14, v14
	s_nop 0
	v_mul_f32_e32 v64, v192, v14
	v_mul_f32_e32 v65, v193, v14
	v_mul_f32_e32 v66, v194, v14
	v_mul_f32_e32 v67, v195, v14
	v_mul_f32_e32 v68, v196, v14
	v_mul_f32_e32 v69, v197, v14
	v_mul_f32_e32 v70, v198, v14
	v_mul_f32_e32 v71, v199, v14
	v_mul_f32_e32 v72, v200, v14
	v_mul_f32_e32 v73, v201, v14
	v_mul_f32_e32 v74, v202, v14
	v_mul_f32_e32 v75, v203, v14
	v_mul_f32_e32 v76, v204, v14
	v_mul_f32_e32 v77, v205, v14
	v_mul_f32_e32 v78, v206, v14
	v_mul_f32_e32 v79, v207, v14
	v_mul_f32_e32 v64, v64, v36
	v_mul_f32_e32 v65, v65, v37
	v_mul_f32_e32 v66, v66, v38
	v_mul_f32_e32 v67, v67, v39
	v_mul_f32_e32 v68, v68, v40
	v_mul_f32_e32 v69, v69, v41
	v_mul_f32_e32 v70, v70, v42
	v_mul_f32_e32 v71, v71, v43
	v_mul_f32_e32 v72, v72, v44
	v_mul_f32_e32 v73, v73, v45
	v_mul_f32_e32 v74, v74, v46
	v_mul_f32_e32 v75, v75, v47
	v_mul_f32_e32 v76, v76, v48
	v_mul_f32_e32 v77, v77, v49
	v_mul_f32_e32 v78, v78, v50
	v_mul_f32_e32 v79, v79, v51
	v_cvt_pk_bf16_f32 v64, v64, v65
	v_cvt_pk_bf16_f32 v65, v66, v67
	v_cvt_pk_bf16_f32 v68, v68, v69
	v_cvt_pk_bf16_f32 v69, v70, v71
	v_cvt_pk_bf16_f32 v72, v72, v73
	v_cvt_pk_bf16_f32 v73, v74, v75
	v_cvt_pk_bf16_f32 v76, v76, v77
	v_cvt_pk_bf16_f32 v77, v78, v79
	global_store_dwordx2 v2, v[64:65], s[26:27] offset:0
	global_store_dwordx2 v2, v[68:69], s[26:27] offset:512
	global_store_dwordx2 v2, v[72:73], s[26:27] offset:1024
	global_store_dwordx2 v2, v[76:77], s[26:27] offset:1536

.Lrows11_orig:
	s_load_dword s3, s[0:1], 0xe8
	s_mov_b32 s5, s2
	s_waitcnt lgkmcnt(0)
	s_mov_b32 s5, s3
	v_readfirstlane_b32 s4, v0
	s_ashr_i32 s4, s4, 6
	s_lshl_b32 s2, s2, 3
	s_add_i32 s2, s2, s4
	s_cmpk_gt_i32 s2, 0x41ff
	s_cbranch_scc1 .LBB11_79
	s_load_dwordx4 s[8:11], s[0:1], 0xa8
	s_load_dwordx4 s[4:7], s[0:1], 0xd0
	v_and_b32_e32 v112, 63, v0
	v_lshlrev_b32_e32 v32, 4, v112
	v_or_b32_e32 v34, 0x400, v32
	s_waitcnt lgkmcnt(0)
	s_add_u32 s0, s8, 0x1000
	s_addc_u32 s1, s9, 0
	s_add_u32 s8, s10, 0x1000
	v_or_b32_e32 v36, 0x800, v32
	v_or_b32_e32 v38, 0xc00, v32
	s_addc_u32 s9, s11, 0
	global_load_dwordx4 v[0:3], v32, s[0:1]
	global_load_dwordx4 v[4:7], v32, s[8:9]
	global_load_dwordx4 v[8:11], v34, s[0:1]
	global_load_dwordx4 v[12:15], v34, s[8:9]
	global_load_dwordx4 v[16:19], v36, s[0:1]
	global_load_dwordx4 v[20:23], v36, s[8:9]
	global_load_dwordx4 v[24:27], v38, s[0:1]
	global_load_dwordx4 v[28:31], v38, s[8:9]
	v_mbcnt_lo_u32_b32 v40, -1, 0
	v_mbcnt_hi_u32_b32 v40, -1, v40
	v_and_b32_e32 v41, 64, v40
	v_add_u32_e32 v41, 64, v41
	v_xor_b32_e32 v42, 1, v40
	v_cmp_lt_i32_e32 vcc, v42, v41
	s_add_u32 s30, s6, 0x5200000
	s_addc_u32 s31, s7, 0
	v_cndmask_b32_e32 v42, v40, v42, vcc
	v_lshlrev_b32_e32 v113, 2, v42
	v_xor_b32_e32 v42, 2, v40
	v_cmp_lt_i32_e32 vcc, v42, v41
	s_lshl_b32 s33, s3, 3
	s_add_u32 s0, s6, 0x7400000
	v_cndmask_b32_e32 v42, v40, v42, vcc
	v_lshlrev_b32_e32 v178, 2, v42
	v_xor_b32_e32 v42, 4, v40
	v_cmp_lt_i32_e32 vcc, v42, v41
	s_addc_u32 s1, s7, 0
	s_lshl_b32 s8, s3, 5
	v_cndmask_b32_e32 v42, v40, v42, vcc
	v_lshlrev_b32_e32 v179, 2, v42
	v_xor_b32_e32 v42, 8, v40
	s_lshl_b32 s34, s3, 4
	s_mul_i32 s35, s3, 24
	s_ashr_i32 s3, s2, 31
	v_mov_b32_e32 v33, 0
	v_cmp_lt_i32_e32 vcc, v42, v41
	s_lshl_b64 s[12:13], s[2:3], 12
	v_lshl_add_u64 v[122:123], s[4:5], 0, v[32:33]
	v_cndmask_b32_e32 v42, v40, v42, vcc
	s_add_u32 s4, s4, s12
	v_lshlrev_b32_e32 v180, 2, v42
	v_xor_b32_e32 v42, 16, v40
	s_addc_u32 s5, s5, s13
	v_mov_b32_e32 v35, v33
	v_mov_b32_e32 v37, v33
	v_mov_b32_e32 v39, v33
	v_lshl_add_u64 v[114:115], s[0:1], 0, v[32:33]
	v_cmp_lt_i32_e32 vcc, v42, v41
	v_lshl_add_u64 v[32:33], s[4:5], 0, v[32:33]
	s_mov_b64 s[4:5], 0xc00
	s_ashr_i32 s9, s8, 31
	v_cndmask_b32_e32 v42, v40, v42, vcc
	v_lshl_add_u64 v[116:117], s[0:1], 0, v[34:35]
	v_lshlrev_b32_e32 v34, 3, v112
	v_lshl_add_u64 v[126:127], v[32:33], 0, s[4:5]
	s_lshl_b64 s[4:5], s[8:9], 12
	s_lshl_b64 s[12:13], s[2:3], 11
	v_lshlrev_b32_e32 v181, 2, v42
	v_xor_b32_e32 v42, 32, v40
	v_lshl_add_u64 v[118:119], s[0:1], 0, v[36:37]
	v_lshl_add_u64 v[36:37], s[6:7], 0, v[34:35]
	s_add_u32 s6, s6, s12
	v_cmp_lt_i32_e32 vcc, v42, v41
	s_addc_u32 s7, s7, s13
	v_lshl_add_u64 v[120:121], s[0:1], 0, v[38:39]
	v_cndmask_b32_e32 v40, v40, v42, vcc
	s_mov_b64 s[0:1], 0x3100000
	v_lshl_add_u64 v[32:33], s[6:7], 0, v[34:35]
	s_mov_b32 s11, 0
	v_lshlrev_b32_e32 v182, 2, v40
	v_lshl_add_u64 v[124:125], v[36:37], 0, s[0:1]
	v_lshl_add_u64 v[128:129], v[32:33], 0, s[0:1]
	s_lshl_b64 s[6:7], s[8:9], 11
	v_mov_b32_e32 v183, 0x358637bd
	s_mov_b32 s3, 0x800000
	s_branch .LBB11_3

	.amdhsa_kernel _Z10fwd_kernelILi11ELi12EEv4Args
		.amdhsa_group_segment_fixed_size 0
		.amdhsa_private_segment_fixed_size 0
		.amdhsa_kernarg_size 488
		.amdhsa_user_sgpr_count 2
		.amdhsa_user_sgpr_dispatch_ptr 0
		.amdhsa_user_sgpr_queue_ptr 0
		.amdhsa_user_sgpr_kernarg_segment_ptr 1
		.amdhsa_user_sgpr_dispatch_id 0
		.amdhsa_user_sgpr_kernarg_preload_length 0
		.amdhsa_user_sgpr_kernarg_preload_offset 0
		.amdhsa_user_sgpr_private_segment_size 0
		.amdhsa_uses_dynamic_stack 0
		.amdhsa_enable_private_segment 0
		.amdhsa_system_sgpr_workgroup_id_x 1
		.amdhsa_system_sgpr_workgroup_id_y 0
		.amdhsa_system_sgpr_workgroup_id_z 0
		.amdhsa_system_sgpr_workgroup_info 0
		.amdhsa_system_vgpr_workitem_id 0
		.amdhsa_next_free_vgpr 208
		.amdhsa_next_free_sgpr 56
		.amdhsa_accum_offset 208
		.amdhsa_reserve_vcc 1
		.amdhsa_float_round_mode_32 0
		.amdhsa_float_round_mode_16_64 0
		.amdhsa_float_denorm_mode_32 3
		.amdhsa_float_denorm_mode_16_64 3
		.amdhsa_dx10_clamp 1
		.amdhsa_ieee_mode 1
		.amdhsa_fp16_overflow 0
		.amdhsa_tg_split 0
		.amdhsa_exception_fp_ieee_invalid_op 0
		.amdhsa_exception_fp_denorm_src 0
		.amdhsa_exception_fp_ieee_div_zero 0
		.amdhsa_exception_fp_ieee_overflow 0
		.amdhsa_exception_fp_ieee_underflow 0
		.amdhsa_exception_fp_ieee_inexact 0
		.amdhsa_exception_int_div_zero 0
	.end_amdhsa_kernel

_Z10fwd_kernelILi12ELi13EEv4Args:
	s_load_dword s3, s[0:1], 0xe8
	v_mov_b32_e32 v1, v0
	s_waitcnt lgkmcnt(0)
	s_load_dwordx2 s[16:17], s[0:1], 0xd8
	v_readfirstlane_b32 s4, v0
	s_lshr_b32 s4, s4, 6
	s_and_b32 s5, s4, 3
	s_lshr_b32 s6, s4, 2
	s_mov_b32 s12, s2
	s_cmpk_gt_u32 s12, 0xff
	s_cbranch_scc1 .Lsmp12_done
	v_and_b32_e32 v202, 15, v0
	v_bfe_u32 v203, v0, 4, 2
	v_and_b32_e32 v205, 63, v0
	v_lshlrev_b32_e32 v204, 11, v202
	v_lshl_add_u32 v204, v203, 4, v204
	s_lshl_b32 s7, s5, 9
	v_add_u32_e32 v204, s7, v204
	s_lshl_b32 s7, s4, 14
	v_lshl_add_u32 v206, v205, 4, s7
	s_lshl_b32 s7, s6, 16
	s_lshl_b32 s8, s5, 12
	s_add_u32 s7, s7, s8
	v_lshl_add_u32 v207, v205, 4, s7
	s_waitcnt lgkmcnt(0)
	v_lshlrev_b32_e32 v208, 13, v202
	v_lshl_add_u32 v208, v203, 3, v208
	s_lshl_b32 s7, s5, 17
	v_add_u32_e32 v208, s7, v208
.Lsmp12_unit:
	s_add_u32 s20, s16, 0x5100000
	s_addc_u32 s21, s17, 0
	s_add_u32 s22, s16, 0x2100000
	s_addc_u32 s23, s17, 0
	s_add_u32 s24, s16, 0xf400000
	s_addc_u32 s25, s17, 0
	s_and_b32 s28, s12, 7
	s_lshr_b32 s29, s12, 3
	s_lshl_b32 s29, s29, 1
	s_add_u32 s29, s29, s6
	s_lshr_b32 s30, s29, 3
	s_lshl_b32 s28, s28, 3
	s_add_u32 s30, s30, s28
	s_and_b32 s31, s29, 7
	s_lshl_b32 s33, s31, 17
	s_lshl_b32 s34, s30, 17
	v_add_u32_e32 v194, s33, v204
	v_add_u32_e32 v198, s34, v204
	v_add_u32_e32 v195, s33, v204
	v_add_u32_e32 v199, s34, v204
	v_add_u32_e32 v196, s33, v204
	v_add_u32_e32 v200, s34, v204
	v_add_u32_e32 v197, s33, v204
	v_add_u32_e32 v201, s34, v204
	v_add_u32_e32 v195, 0x8000, v195
	v_add_u32_e32 v199, 0x8000, v199
	v_add_u32_e32 v196, 0x10000, v196
	v_add_u32_e32 v200, 0x10000, v200
	v_add_u32_e32 v197, 0x18000, v197
	v_add_u32_e32 v201, 0x18000, v201
	s_lshl_b32 s33, s31, 19
	s_lshl_b32 s34, s30, 7
	s_add_u32 s33, s33, s34
	v_add_u32_e32 v209, s33, v208
	global_load_dwordx4 v[66:69], v194, s[20:21] offset:0
	global_load_dwordx4 v[82:85], v198, s[22:23] offset:0
	global_load_dwordx4 v[70:73], v195, s[20:21] offset:0
	global_load_dwordx4 v[86:89], v199, s[22:23] offset:0
	global_load_dwordx4 v[74:77], v196, s[20:21] offset:0
	global_load_dwordx4 v[90:93], v200, s[22:23] offset:0
	global_load_dwordx4 v[78:81], v197, s[20:21] offset:0
	global_load_dwordx4 v[94:97], v201, s[22:23] offset:0
	global_load_dwordx4 v[98:101], v194, s[20:21] offset:64
	global_load_dwordx4 v[114:117], v198, s[22:23] offset:64
	global_load_dwordx4 v[102:105], v195, s[20:21] offset:64
	global_load_dwordx4 v[118:121], v199, s[22:23] offset:64
	global_load_dwordx4 v[106:109], v196, s[20:21] offset:64
	global_load_dwordx4 v[122:125], v200, s[22:23] offset:64
	global_load_dwordx4 v[110:113], v197, s[20:21] offset:64
	global_load_dwordx4 v[126:129], v201, s[22:23] offset:64
	global_load_dwordx4 v[130:133], v194, s[20:21] offset:128
	global_load_dwordx4 v[146:149], v198, s[22:23] offset:128
	global_load_dwordx4 v[134:137], v195, s[20:21] offset:128
	global_load_dwordx4 v[150:153], v199, s[22:23] offset:128
	global_load_dwordx4 v[138:141], v196, s[20:21] offset:128
	global_load_dwordx4 v[154:157], v200, s[22:23] offset:128
	global_load_dwordx4 v[142:145], v197, s[20:21] offset:128
	global_load_dwordx4 v[158:161], v201, s[22:23] offset:128
	global_load_dwordx4 v[162:165], v194, s[20:21] offset:192
	global_load_dwordx4 v[178:181], v198, s[22:23] offset:192
	global_load_dwordx4 v[166:169], v195, s[20:21] offset:192
	global_load_dwordx4 v[182:185], v199, s[22:23] offset:192
	global_load_dwordx4 v[170:173], v196, s[20:21] offset:192
	global_load_dwordx4 v[186:189], v200, s[22:23] offset:192
	global_load_dwordx4 v[174:177], v197, s[20:21] offset:192
	global_load_dwordx4 v[190:193], v201, s[22:23] offset:192
	s_waitcnt vmcnt(28)
	v_mfma_f32_16x16x32_bf16 v[2:5], v[82:85], v[66:69], 0
	v_mfma_f32_16x16x32_bf16 v[6:9], v[86:89], v[66:69], 0
	v_mfma_f32_16x16x32_bf16 v[18:21], v[82:85], v[70:73], 0
	v_mfma_f32_16x16x32_bf16 v[22:25], v[86:89], v[70:73], 0
	s_waitcnt vmcnt(24)
	v_mfma_f32_16x16x32_bf16 v[10:13], v[90:93], v[66:69], 0
	v_mfma_f32_16x16x32_bf16 v[14:17], v[94:97], v[66:69], 0
	v_mfma_f32_16x16x32_bf16 v[26:29], v[90:93], v[70:73], 0
	v_mfma_f32_16x16x32_bf16 v[30:33], v[94:97], v[70:73], 0
	v_mfma_f32_16x16x32_bf16 v[34:37], v[82:85], v[74:77], 0
	v_mfma_f32_16x16x32_bf16 v[38:41], v[86:89], v[74:77], 0
	v_mfma_f32_16x16x32_bf16 v[42:45], v[90:93], v[74:77], 0
	v_mfma_f32_16x16x32_bf16 v[46:49], v[94:97], v[74:77], 0
	v_mfma_f32_16x16x32_bf16 v[50:53], v[82:85], v[78:81], 0
	v_mfma_f32_16x16x32_bf16 v[54:57], v[86:89], v[78:81], 0
	v_mfma_f32_16x16x32_bf16 v[58:61], v[90:93], v[78:81], 0
	v_mfma_f32_16x16x32_bf16 v[62:65], v[94:97], v[78:81], 0
	global_load_dwordx4 v[66:69], v194, s[20:21] offset:256
	global_load_dwordx4 v[82:85], v198, s[22:23] offset:256
	global_load_dwordx4 v[70:73], v195, s[20:21] offset:256
	global_load_dwordx4 v[86:89], v199, s[22:23] offset:256
	global_load_dwordx4 v[74:77], v196, s[20:21] offset:256
	global_load_dwordx4 v[90:93], v200, s[22:23] offset:256
	global_load_dwordx4 v[78:81], v197, s[20:21] offset:256
	global_load_dwordx4 v[94:97], v201, s[22:23] offset:256
	s_waitcnt vmcnt(28)
	v_mfma_f32_16x16x32_bf16 v[2:5], v[114:117], v[98:101], v[2:5]
	v_mfma_f32_16x16x32_bf16 v[6:9], v[118:121], v[98:101], v[6:9]
	v_mfma_f32_16x16x32_bf16 v[18:21], v[114:117], v[102:105], v[18:21]
	v_mfma_f32_16x16x32_bf16 v[22:25], v[118:121], v[102:105], v[22:25]
	s_waitcnt vmcnt(24)
	v_mfma_f32_16x16x32_bf16 v[10:13], v[122:125], v[98:101], v[10:13]
	v_mfma_f32_16x16x32_bf16 v[14:17], v[126:129], v[98:101], v[14:17]
	v_mfma_f32_16x16x32_bf16 v[26:29], v[122:125], v[102:105], v[26:29]
	v_mfma_f32_16x16x32_bf16 v[30:33], v[126:129], v[102:105], v[30:33]
	v_mfma_f32_16x16x32_bf16 v[34:37], v[114:117], v[106:109], v[34:37]
	v_mfma_f32_16x16x32_bf16 v[38:41], v[118:121], v[106:109], v[38:41]
	v_mfma_f32_16x16x32_bf16 v[42:45], v[122:125], v[106:109], v[42:45]
	v_mfma_f32_16x16x32_bf16 v[46:49], v[126:129], v[106:109], v[46:49]
	v_mfma_f32_16x16x32_bf16 v[50:53], v[114:117], v[110:113], v[50:53]
	v_mfma_f32_16x16x32_bf16 v[54:57], v[118:121], v[110:113], v[54:57]
	v_mfma_f32_16x16x32_bf16 v[58:61], v[122:125], v[110:113], v[58:61]
	v_mfma_f32_16x16x32_bf16 v[62:65], v[126:129], v[110:113], v[62:65]
	global_load_dwordx4 v[98:101], v194, s[20:21] offset:320
	global_load_dwordx4 v[114:117], v198, s[22:23] offset:320
	global_load_dwordx4 v[102:105], v195, s[20:21] offset:320
	global_load_dwordx4 v[118:121], v199, s[22:23] offset:320
	global_load_dwordx4 v[106:109], v196, s[20:21] offset:320
	global_load_dwordx4 v[122:125], v200, s[22:23] offset:320
	global_load_dwordx4 v[110:113], v197, s[20:21] offset:320
	global_load_dwordx4 v[126:129], v201, s[22:23] offset:320
	s_waitcnt vmcnt(28)
	v_mfma_f32_16x16x32_bf16 v[2:5], v[146:149], v[130:133], v[2:5]
	v_mfma_f32_16x16x32_bf16 v[6:9], v[150:153], v[130:133], v[6:9]
	v_mfma_f32_16x16x32_bf16 v[18:21], v[146:149], v[134:137], v[18:21]
	v_mfma_f32_16x16x32_bf16 v[22:25], v[150:153], v[134:137], v[22:25]
	s_waitcnt vmcnt(24)
	v_mfma_f32_16x16x32_bf16 v[10:13], v[154:157], v[130:133], v[10:13]
	v_mfma_f32_16x16x32_bf16 v[14:17], v[158:161], v[130:133], v[14:17]
	v_mfma_f32_16x16x32_bf16 v[26:29], v[154:157], v[134:137], v[26:29]
	v_mfma_f32_16x16x32_bf16 v[30:33], v[158:161], v[134:137], v[30:33]
	v_mfma_f32_16x16x32_bf16 v[34:37], v[146:149], v[138:141], v[34:37]
	v_mfma_f32_16x16x32_bf16 v[38:41], v[150:153], v[138:141], v[38:41]
	v_mfma_f32_16x16x32_bf16 v[42:45], v[154:157], v[138:141], v[42:45]
	v_mfma_f32_16x16x32_bf16 v[46:49], v[158:161], v[138:141], v[46:49]
	v_mfma_f32_16x16x32_bf16 v[50:53], v[146:149], v[142:145], v[50:53]
	v_mfma_f32_16x16x32_bf16 v[54:57], v[150:153], v[142:145], v[54:57]
	v_mfma_f32_16x16x32_bf16 v[58:61], v[154:157], v[142:145], v[58:61]
	v_mfma_f32_16x16x32_bf16 v[62:65], v[158:161], v[142:145], v[62:65]
	global_load_dwordx4 v[130:133], v194, s[20:21] offset:384
	global_load_dwordx4 v[146:149], v198, s[22:23] offset:384
	global_load_dwordx4 v[134:137], v195, s[20:21] offset:384
	global_load_dwordx4 v[150:153], v199, s[22:23] offset:384
	global_load_dwordx4 v[138:141], v196, s[20:21] offset:384
	global_load_dwordx4 v[154:157], v200, s[22:23] offset:384
	global_load_dwordx4 v[142:145], v197, s[20:21] offset:384
	global_load_dwordx4 v[158:161], v201, s[22:23] offset:384
	s_waitcnt vmcnt(28)
	v_mfma_f32_16x16x32_bf16 v[2:5], v[178:181], v[162:165], v[2:5]
	v_mfma_f32_16x16x32_bf16 v[6:9], v[182:185], v[162:165], v[6:9]
	v_mfma_f32_16x16x32_bf16 v[18:21], v[178:181], v[166:169], v[18:21]
	v_mfma_f32_16x16x32_bf16 v[22:25], v[182:185], v[166:169], v[22:25]
	s_waitcnt vmcnt(24)
	v_mfma_f32_16x16x32_bf16 v[10:13], v[186:189], v[162:165], v[10:13]
	v_mfma_f32_16x16x32_bf16 v[14:17], v[190:193], v[162:165], v[14:17]
	v_mfma_f32_16x16x32_bf16 v[26:29], v[186:189], v[166:169], v[26:29]
	v_mfma_f32_16x16x32_bf16 v[30:33], v[190:193], v[166:169], v[30:33]
	v_mfma_f32_16x16x32_bf16 v[34:37], v[178:181], v[170:173], v[34:37]
	v_mfma_f32_16x16x32_bf16 v[38:41], v[182:185], v[170:173], v[38:41]
	v_mfma_f32_16x16x32_bf16 v[42:45], v[186:189], v[170:173], v[42:45]
	v_mfma_f32_16x16x32_bf16 v[46:49], v[190:193], v[170:173], v[46:49]
	v_mfma_f32_16x16x32_bf16 v[50:53], v[178:181], v[174:177], v[50:53]
	v_mfma_f32_16x16x32_bf16 v[54:57], v[182:185], v[174:177], v[54:57]
	v_mfma_f32_16x16x32_bf16 v[58:61], v[186:189], v[174:177], v[58:61]
	v_mfma_f32_16x16x32_bf16 v[62:65], v[190:193], v[174:177], v[62:65]
	global_load_dwordx4 v[162:165], v194, s[20:21] offset:448
	global_load_dwordx4 v[178:181], v198, s[22:23] offset:448
	global_load_dwordx4 v[166:169], v195, s[20:21] offset:448
	global_load_dwordx4 v[182:185], v199, s[22:23] offset:448
	global_load_dwordx4 v[170:173], v196, s[20:21] offset:448
	global_load_dwordx4 v[186:189], v200, s[22:23] offset:448
	global_load_dwordx4 v[174:177], v197, s[20:21] offset:448
	global_load_dwordx4 v[190:193], v201, s[22:23] offset:448
	s_waitcnt vmcnt(28)
	v_mfma_f32_16x16x32_bf16 v[2:5], v[82:85], v[66:69], v[2:5]
	v_mfma_f32_16x16x32_bf16 v[6:9], v[86:89], v[66:69], v[6:9]
	v_mfma_f32_16x16x32_bf16 v[18:21], v[82:85], v[70:73], v[18:21]
	v_mfma_f32_16x16x32_bf16 v[22:25], v[86:89], v[70:73], v[22:25]
	s_waitcnt vmcnt(24)
	v_mfma_f32_16x16x32_bf16 v[10:13], v[90:93], v[66:69], v[10:13]
	v_mfma_f32_16x16x32_bf16 v[14:17], v[94:97], v[66:69], v[14:17]
	v_mfma_f32_16x16x32_bf16 v[26:29], v[90:93], v[70:73], v[26:29]
	v_mfma_f32_16x16x32_bf16 v[30:33], v[94:97], v[70:73], v[30:33]
	v_mfma_f32_16x16x32_bf16 v[34:37], v[82:85], v[74:77], v[34:37]
	v_mfma_f32_16x16x32_bf16 v[38:41], v[86:89], v[74:77], v[38:41]
	v_mfma_f32_16x16x32_bf16 v[42:45], v[90:93], v[74:77], v[42:45]
	v_mfma_f32_16x16x32_bf16 v[46:49], v[94:97], v[74:77], v[46:49]
	v_mfma_f32_16x16x32_bf16 v[50:53], v[82:85], v[78:81], v[50:53]
	v_mfma_f32_16x16x32_bf16 v[54:57], v[86:89], v[78:81], v[54:57]
	v_mfma_f32_16x16x32_bf16 v[58:61], v[90:93], v[78:81], v[58:61]
	v_mfma_f32_16x16x32_bf16 v[62:65], v[94:97], v[78:81], v[62:65]
	s_waitcnt vmcnt(20)
	v_mfma_f32_16x16x32_bf16 v[2:5], v[114:117], v[98:101], v[2:5]
	v_mfma_f32_16x16x32_bf16 v[6:9], v[118:121], v[98:101], v[6:9]
	v_mfma_f32_16x16x32_bf16 v[18:21], v[114:117], v[102:105], v[18:21]
	v_mfma_f32_16x16x32_bf16 v[22:25], v[118:121], v[102:105], v[22:25]
	s_waitcnt vmcnt(16)
	v_mfma_f32_16x16x32_bf16 v[10:13], v[122:125], v[98:101], v[10:13]
	v_mfma_f32_16x16x32_bf16 v[14:17], v[126:129], v[98:101], v[14:17]
	v_mfma_f32_16x16x32_bf16 v[26:29], v[122:125], v[102:105], v[26:29]
	v_mfma_f32_16x16x32_bf16 v[30:33], v[126:129], v[102:105], v[30:33]
	v_mfma_f32_16x16x32_bf16 v[34:37], v[114:117], v[106:109], v[34:37]
	v_mfma_f32_16x16x32_bf16 v[38:41], v[118:121], v[106:109], v[38:41]
	v_mfma_f32_16x16x32_bf16 v[42:45], v[122:125], v[106:109], v[42:45]
	v_mfma_f32_16x16x32_bf16 v[46:49], v[126:129], v[106:109], v[46:49]
	v_mfma_f32_16x16x32_bf16 v[50:53], v[114:117], v[110:113], v[50:53]
	v_mfma_f32_16x16x32_bf16 v[54:57], v[118:121], v[110:113], v[54:57]
	v_mfma_f32_16x16x32_bf16 v[58:61], v[122:125], v[110:113], v[58:61]
	v_mfma_f32_16x16x32_bf16 v[62:65], v[126:129], v[110:113], v[62:65]
	s_waitcnt vmcnt(12)
	v_mfma_f32_16x16x32_bf16 v[2:5], v[146:149], v[130:133], v[2:5]
	v_mfma_f32_16x16x32_bf16 v[6:9], v[150:153], v[130:133], v[6:9]
	v_mfma_f32_16x16x32_bf16 v[18:21], v[146:149], v[134:137], v[18:21]
	v_mfma_f32_16x16x32_bf16 v[22:25], v[150:153], v[134:137], v[22:25]
	s_waitcnt vmcnt(8)
	v_mfma_f32_16x16x32_bf16 v[10:13], v[154:157], v[130:133], v[10:13]
	v_mfma_f32_16x16x32_bf16 v[14:17], v[158:161], v[130:133], v[14:17]
	v_mfma_f32_16x16x32_bf16 v[26:29], v[154:157], v[134:137], v[26:29]
	v_mfma_f32_16x16x32_bf16 v[30:33], v[158:161], v[134:137], v[30:33]
	v_mfma_f32_16x16x32_bf16 v[34:37], v[146:149], v[138:141], v[34:37]
	v_mfma_f32_16x16x32_bf16 v[38:41], v[150:153], v[138:141], v[38:41]
	v_mfma_f32_16x16x32_bf16 v[42:45], v[154:157], v[138:141], v[42:45]
	v_mfma_f32_16x16x32_bf16 v[46:49], v[158:161], v[138:141], v[46:49]
	v_mfma_f32_16x16x32_bf16 v[50:53], v[146:149], v[142:145], v[50:53]
	v_mfma_f32_16x16x32_bf16 v[54:57], v[150:153], v[142:145], v[54:57]
	v_mfma_f32_16x16x32_bf16 v[58:61], v[154:157], v[142:145], v[58:61]
	v_mfma_f32_16x16x32_bf16 v[62:65], v[158:161], v[142:145], v[62:65]
	s_waitcnt vmcnt(4)
	v_mfma_f32_16x16x32_bf16 v[2:5], v[178:181], v[162:165], v[2:5]
	v_mfma_f32_16x16x32_bf16 v[6:9], v[182:185], v[162:165], v[6:9]
	v_mfma_f32_16x16x32_bf16 v[18:21], v[178:181], v[166:169], v[18:21]
	v_mfma_f32_16x16x32_bf16 v[22:25], v[182:185], v[166:169], v[22:25]
	s_waitcnt vmcnt(0)
	v_mfma_f32_16x16x32_bf16 v[10:13], v[186:189], v[162:165], v[10:13]
	v_mfma_f32_16x16x32_bf16 v[14:17], v[190:193], v[162:165], v[14:17]
	v_mfma_f32_16x16x32_bf16 v[26:29], v[186:189], v[166:169], v[26:29]
	v_mfma_f32_16x16x32_bf16 v[30:33], v[190:193], v[166:169], v[30:33]
	v_mfma_f32_16x16x32_bf16 v[34:37], v[178:181], v[170:173], v[34:37]
	v_mfma_f32_16x16x32_bf16 v[38:41], v[182:185], v[170:173], v[38:41]
	v_mfma_f32_16x16x32_bf16 v[42:45], v[186:189], v[170:173], v[42:45]
	v_mfma_f32_16x16x32_bf16 v[46:49], v[190:193], v[170:173], v[46:49]
	v_mfma_f32_16x16x32_bf16 v[50:53], v[178:181], v[174:177], v[50:53]
	v_mfma_f32_16x16x32_bf16 v[54:57], v[182:185], v[174:177], v[54:57]
	v_mfma_f32_16x16x32_bf16 v[58:61], v[186:189], v[174:177], v[58:61]
	v_mfma_f32_16x16x32_bf16 v[62:65], v[190:193], v[174:177], v[62:65]
	s_nop 7
	ds_write_b128 v206, v[2:5] offset:0
	ds_write_b128 v206, v[6:9] offset:1024
	ds_write_b128 v206, v[10:13] offset:2048
	ds_write_b128 v206, v[14:17] offset:3072
	ds_write_b128 v206, v[18:21] offset:4096
	ds_write_b128 v206, v[22:25] offset:5120
	ds_write_b128 v206, v[26:29] offset:6144
	ds_write_b128 v206, v[30:33] offset:7168
	ds_write_b128 v206, v[34:37] offset:8192
	ds_write_b128 v206, v[38:41] offset:9216
	ds_write_b128 v206, v[42:45] offset:10240
	ds_write_b128 v206, v[46:49] offset:11264
	ds_write_b128 v206, v[50:53] offset:12288
	ds_write_b128 v206, v[54:57] offset:13312
	ds_write_b128 v206, v[58:61] offset:14336
	ds_write_b128 v206, v[62:65] offset:15360
	s_waitcnt lgkmcnt(0)
	s_barrier
	ds_read_b128 v[2:5], v207 offset:0
	ds_read_b128 v[6:9], v207 offset:16384
	ds_read_b128 v[10:13], v207 offset:32768
	ds_read_b128 v[14:17], v207 offset:49152
	ds_read_b128 v[18:21], v207 offset:1024
	ds_read_b128 v[22:25], v207 offset:17408
	ds_read_b128 v[26:29], v207 offset:33792
	ds_read_b128 v[30:33], v207 offset:50176
	ds_read_b128 v[34:37], v207 offset:2048
	ds_read_b128 v[38:41], v207 offset:18432
	ds_read_b128 v[42:45], v207 offset:34816
	ds_read_b128 v[46:49], v207 offset:51200
	ds_read_b128 v[50:53], v207 offset:3072
	ds_read_b128 v[54:57], v207 offset:19456
	ds_read_b128 v[58:61], v207 offset:35840
	ds_read_b128 v[62:65], v207 offset:52224
	s_waitcnt lgkmcnt(12)
	v_add_f32_e32 v2, v2, v6
	v_add_f32_e32 v3, v3, v7
	v_add_f32_e32 v4, v4, v8
	v_add_f32_e32 v5, v5, v9
	v_add_f32_e32 v10, v10, v14
	v_add_f32_e32 v11, v11, v15
	v_add_f32_e32 v12, v12, v16
	v_add_f32_e32 v13, v13, v17
	v_add_f32_e32 v2, v2, v10
	v_add_f32_e32 v3, v3, v11
	v_add_f32_e32 v4, v4, v12
	v_add_f32_e32 v5, v5, v13
	s_waitcnt lgkmcnt(8)
	v_add_f32_e32 v18, v18, v22
	v_add_f32_e32 v19, v19, v23
	v_add_f32_e32 v20, v20, v24
	v_add_f32_e32 v21, v21, v25
	v_add_f32_e32 v26, v26, v30
	v_add_f32_e32 v27, v27, v31
	v_add_f32_e32 v28, v28, v32
	v_add_f32_e32 v29, v29, v33
	v_add_f32_e32 v18, v18, v26
	v_add_f32_e32 v19, v19, v27
	v_add_f32_e32 v20, v20, v28
	v_add_f32_e32 v21, v21, v29
	s_waitcnt lgkmcnt(4)
	v_add_f32_e32 v34, v34, v38
	v_add_f32_e32 v35, v35, v39
	v_add_f32_e32 v36, v36, v40
	v_add_f32_e32 v37, v37, v41
	v_add_f32_e32 v42, v42, v46
	v_add_f32_e32 v43, v43, v47
	v_add_f32_e32 v44, v44, v48
	v_add_f32_e32 v45, v45, v49
	v_add_f32_e32 v34, v34, v42
	v_add_f32_e32 v35, v35, v43
	v_add_f32_e32 v36, v36, v44
	v_add_f32_e32 v37, v37, v45
	s_waitcnt lgkmcnt(0)
	v_add_f32_e32 v50, v50, v54
	v_add_f32_e32 v51, v51, v55
	v_add_f32_e32 v52, v52, v56
	v_add_f32_e32 v53, v53, v57
	v_add_f32_e32 v58, v58, v62
	v_add_f32_e32 v59, v59, v63
	v_add_f32_e32 v60, v60, v64
	v_add_f32_e32 v61, v61, v65
	v_add_f32_e32 v50, v50, v58
	v_add_f32_e32 v51, v51, v59
	v_add_f32_e32 v52, v52, v60
	v_add_f32_e32 v53, v53, v61
	v_max_f32_e32 v2, 0, v2
	v_max_f32_e32 v3, 0, v3
	v_max_f32_e32 v4, 0, v4
	v_max_f32_e32 v5, 0, v5
	v_mul_f32_e32 v2, v2, v2
	v_mul_f32_e32 v3, v3, v3
	v_mul_f32_e32 v4, v4, v4
	v_mul_f32_e32 v5, v5, v5
	v_cvt_pk_bf16_f32 v210, v2, v3
	v_cvt_pk_bf16_f32 v211, v4, v5
	global_store_dwordx2 v209, v[210:211], s[24:25] offset:0
	v_max_f32_e32 v18, 0, v18
	v_max_f32_e32 v19, 0, v19
	v_max_f32_e32 v20, 0, v20
	v_max_f32_e32 v21, 0, v21
	v_mul_f32_e32 v18, v18, v18
	v_mul_f32_e32 v19, v19, v19
	v_mul_f32_e32 v20, v20, v20
	v_mul_f32_e32 v21, v21, v21
	v_cvt_pk_bf16_f32 v212, v18, v19
	v_cvt_pk_bf16_f32 v213, v20, v21
	global_store_dwordx2 v209, v[212:213], s[24:25] offset:32
	v_max_f32_e32 v34, 0, v34
	v_max_f32_e32 v35, 0, v35
	v_max_f32_e32 v36, 0, v36
	v_max_f32_e32 v37, 0, v37
	v_mul_f32_e32 v34, v34, v34
	v_mul_f32_e32 v35, v35, v35
	v_mul_f32_e32 v36, v36, v36
	v_mul_f32_e32 v37, v37, v37
	v_cvt_pk_bf16_f32 v214, v34, v35
	v_cvt_pk_bf16_f32 v215, v36, v37
	global_store_dwordx2 v209, v[214:215], s[24:25] offset:64
	v_max_f32_e32 v50, 0, v50
	v_max_f32_e32 v51, 0, v51
	v_max_f32_e32 v52, 0, v52
	v_max_f32_e32 v53, 0, v53
	v_mul_f32_e32 v50, v50, v50
	v_mul_f32_e32 v51, v51, v51
	v_mul_f32_e32 v52, v52, v52
	v_mul_f32_e32 v53, v53, v53
	v_cvt_pk_bf16_f32 v216, v50, v51
	v_cvt_pk_bf16_f32 v217, v52, v53
	global_store_dwordx2 v209, v[216:217], s[24:25] offset:96
	s_barrier
	s_add_i32 s12, s12, s3
	s_cmpk_lt_u32 s12, 0x100
	s_cbranch_scc1 .Lsmp12_unit
.Lsmp12_done:
	s_cmpk_gt_i32 s2, 0x3ff
	v_readfirstlane_b32 s11, v0
	s_cbranch_scc1 .LBB12_16
	v_lshlrev_b32_e32 v2, 4, v0
	v_add_u32_e32 v3, 0x2000, v2
	v_ashrrev_i32_e32 v1, 31, v3
	v_lshrrev_b32_e32 v1, 22, v1
	v_add_u32_e32 v1, v3, v1
	v_ashrrev_i32_e32 v1, 10, v1
	v_mul_i32_i24_e32 v4, 0x400, v1
	v_sub_u32_e32 v3, v3, v4
	v_lshrrev_b32_e32 v4, 4, v3
	v_bitop3_b32 v3, v4, v3, 32 bitop3:0x6c
	v_ashrrev_i32_e32 v4, 31, v3
	v_lshrrev_b32_e32 v4, 26, v4
	v_add_u32_e32 v4, v3, v4
	v_lshlrev_b32_e32 v5, 3, v1
	v_ashrrev_i32_e32 v10, 6, v4
	v_and_b32_e32 v5, -16, v5
	v_add_u32_e32 v5, v10, v5
	v_and_b32_e32 v6, 3, v10
	s_mov_b32 s5, 0x1fffe0
	v_lshrrev_b32_e32 v7, 2, v5
	v_lshlrev_b32_e32 v8, 1, v5
	v_and_b32_e32 v4, 0xc0, v4
	v_and_or_b32 v6, v5, s5, v6
	v_and_b32_e32 v7, 4, v7
	v_and_b32_e32 v8, 24, v8
	v_sub_u32_e32 v3, v3, v4
	v_mov_b32_e32 v4, 1
	v_or3_b32 v6, v6, v7, v8
	v_lshlrev_b32_e32 v7, 5, v1
	v_ashrrev_i16_sdwa v3, v4, sext(v3) dst_sel:DWORD dst_unused:UNUSED_PAD src0_sel:DWORD src1_sel:BYTE_0
	v_and_b32_e32 v7, 32, v7
	v_bfe_i32 v11, v3, 0, 16
	v_add_lshl_u32 v3, v7, v11, 1
	v_lshl_add_u32 v128, v6, 11, v3
	v_lshl_add_u32 v130, v5, 11, v3
	v_bfe_i32 v3, v0, 27, 1
	v_lshrrev_b32_e32 v3, 22, v3
	v_add_u32_e32 v3, v2, v3
	s_load_dwordx2 s[0:1], s[0:1], 0xd8
	v_and_b32_e32 v3, 0xfffffc00, v3
	v_sub_u32_e32 v2, v2, v3
	v_lshrrev_b32_e32 v3, 4, v2
	v_ashrrev_i32_e32 v5, 31, v0
	v_bitop3_b32 v2, v3, v2, 32 bitop3:0x6c
	v_lshrrev_b32_e32 v5, 26, v5
	v_ashrrev_i32_e32 v3, 31, v2
	v_add_u32_e32 v5, v0, v5
	s_waitcnt lgkmcnt(0)
	s_add_u32 s28, s0, 0x3100000
	v_lshrrev_b32_e32 v3, 26, v3
	v_ashrrev_i32_e32 v13, 6, v5
	s_addc_u32 s29, s1, 0
	v_add_u32_e32 v3, v2, v3
	v_lshlrev_b32_e32 v5, 3, v13
	s_add_u32 s30, s0, 0x2100000
	v_ashrrev_i32_e32 v12, 6, v3
	v_and_b32_e32 v5, -16, v5
	s_addc_u32 s31, s1, 0
	v_add_u32_e32 v5, v12, v5
	v_and_b32_e32 v6, 3, v12
	s_ashr_i32 s34, s2, 31
	v_and_or_b32 v6, v5, s5, v6
	s_lshr_b32 s5, s34, 29
	s_add_i32 s5, s2, s5
	s_ashr_i32 s4, s11, 6
	s_ashr_i32 s6, s5, 3
	s_and_b32 s5, s5, -8
	s_ashr_i32 s8, s11, 8
	s_lshl_b32 s33, s4, 10
	s_sub_i32 s5, s2, s5
	s_cmp_lt_i32 s5, 0
	s_movk_i32 s35, 0x81
	s_cselect_b32 s7, s35, 0x80
	s_mul_i32 s5, s5, s7
	s_add_i32 s5, s5, s6
	s_ashr_i32 s6, s5, 31
	s_lshr_b32 s6, s6, 25
	s_add_i32 s6, s5, s6
	v_lshrrev_b32_e32 v7, 2, v5
	v_lshlrev_b32_e32 v8, 1, v5
	v_and_b32_e32 v3, 0xc0, v3
	s_ashr_i32 s7, s6, 7
	v_and_b32_e32 v7, 4, v7
	v_and_b32_e32 v8, 24, v8
	v_sub_u32_e32 v2, v2, v3
	s_lshl_b32 s9, s7, 3
	v_or3_b32 v6, v6, v7, v8
	v_lshlrev_b32_e32 v7, 5, v13
	v_ashrrev_i16_sdwa v2, v4, sext(v2) dst_sel:DWORD dst_unused:UNUSED_PAD src0_sel:DWORD src1_sel:BYTE_0
	s_sub_i32 s7, 0x40, s9
	v_and_b32_e32 v7, 32, v7
	v_bfe_i32 v14, v2, 0, 16
	s_min_u32 s12, s7, 8
	s_and_b32 s6, s6, 0xffffff80
	v_add_lshl_u32 v2, v7, v14, 1
	s_sub_i32 s5, s5, s6
	v_cvt_f32_ubyte0_e32 v4, s12
	v_lshl_add_u32 v132, v6, 11, v2
	v_cvt_f32_i32_e32 v3, s5
	v_rcp_iflag_f32_e32 v6, v4
	v_lshl_add_u32 v134, v5, 11, v2
	s_ashr_i32 s6, s5, 30
	s_or_b32 s10, s6, 1
	v_mul_f32_e32 v2, v3, v6
	v_trunc_f32_e32 v2, v2
	v_fma_f32 v3, -v2, v4, v3
	v_cvt_i32_f32_e32 v2, v2
	v_cmp_ge_f32_e64 s[6:7], |v3|, v4
	s_and_b64 s[6:7], s[6:7], exec
	s_cselect_b32 s6, s10, 0
	v_readfirstlane_b32 s7, v2
	s_add_i32 s10, s7, s6
	s_mul_i32 s6, s10, s12
	s_sub_i32 s5, s5, s6
	s_sext_i32_i8 s5, s5
	s_add_i32 s20, s9, s5
	s_ashr_i32 s21, s20, 31
	s_bfe_i64 s[12:13], s[10:11], 0x80000
	s_lshl_b64 s[6:7], s[20:21], 19
	s_lshl_b64 s[12:13], s[12:13], 19
	s_add_u32 s22, s30, s12
	s_addc_u32 s23, s31, s13
	s_add_i32 s36, s33, 0
	s_add_i32 m0, s36, 0x10000
	v_mov_b32_e32 v133, 0
	global_load_lds_dwordx4 v132, s[22:23]
	s_add_i32 m0, s36, 0x12000
	s_add_u32 s12, s22, 0x40000
	global_load_lds_dwordx4 v128, s[22:23]
	s_addc_u32 s13, s23, 0
	s_add_i32 m0, s36, 0x14000
	v_mov_b32_e32 v129, v133
	global_load_lds_dwordx4 v132, s[12:13]
	s_add_i32 m0, s36, 0x16000
	s_add_u32 s24, s28, s6
	s_addc_u32 s25, s29, s7
	s_add_i32 s37, s36, 0x2000
	global_load_lds_dwordx4 v128, s[12:13]
	s_mov_b32 m0, s36
	s_add_u32 s6, s24, 0x40000
	global_load_lds_dwordx4 v134, s[24:25]
	s_mov_b32 m0, s37
	s_addc_u32 s7, s25, 0
	s_add_i32 s38, s36, 0x4000
	global_load_lds_dwordx4 v130, s[24:25]
	s_mov_b32 m0, s38
	s_add_i32 s39, s36, 0x6000
	global_load_lds_dwordx4 v134, s[6:7]
	s_mov_b32 m0, s39
	v_mov_b32_e32 v135, v133
	global_load_lds_dwordx4 v130, s[6:7]
	v_mov_b32_e32 v131, v133
	s_cmp_eq_u32 s8, 1
	s_mov_b32 s5, 0
	v_lshl_add_u64 v[8:9], s[22:23], 0, v[132:133]
	v_lshl_add_u64 v[6:7], s[22:23], 0, v[128:129]
	v_lshl_add_u64 v[2:3], s[24:25], 0, v[134:135]
	s_cselect_b64 s[6:7], -1, 0
	s_cmp_lg_u32 s8, 1
	v_lshl_add_u64 v[4:5], s[24:25], 0, v[130:131]
	s_cbranch_scc1 .LBB12_3
	s_barrier
.LBB12_3:
	s_lshl_b32 s40, s8, 6
	s_lshl_b32 s14, s8, 13
	s_lshl_b32 s4, s4, 5
	s_mov_b64 s[8:9], 0x80
	s_and_b32 s4, s4, 0x60
	s_add_i32 m0, s36, 0x18000
	v_lshl_add_u64 v[8:9], v[8:9], 0, s[8:9]
	s_lshl_b32 s15, s4, 7
	s_waitcnt vmcnt(2)
	s_barrier
	global_load_lds_dwordx4 v[8:9], off
	v_lshl_add_u64 v[6:7], v[6:7], 0, s[8:9]
	s_add_i32 m0, s36, 0x1a000
	s_add_i32 s41, s36, 0x8000
	s_add_i32 s42, s36, 0xa000
	global_load_lds_dwordx4 v[6:7], off
	v_lshl_add_u64 v[2:3], v[2:3], 0, s[8:9]
	s_mov_b32 m0, s41
	s_add_u32 s12, s22, 0x40080
	global_load_lds_dwordx4 v[2:3], off
	v_lshl_add_u64 v[2:3], v[4:5], 0, s[8:9]
	s_mov_b32 m0, s42
	s_addc_u32 s13, s23, 0
	global_load_lds_dwordx4 v[2:3], off
	s_add_i32 m0, s36, 0x1c000
	v_lshl_add_u64 v[2:3], s[12:13], 0, v[132:133]
	global_load_lds_dwordx4 v[2:3], off
	v_lshl_add_u64 v[2:3], s[12:13], 0, v[128:129]
	s_add_i32 m0, s36, 0x1e000
	s_cmpk_lt_u32 s11, 0x100
	global_load_lds_dwordx4 v[2:3], off
	v_and_b32_e32 v2, 15, v0
	v_and_b32_e32 v3, 48, v0
	v_lshlrev_b32_e32 v0, 2, v0
	v_lshl_or_b32 v4, v2, 6, v3
	v_and_b32_e32 v0, 32, v0
	v_bitop3_b32 v5, v4, s14, v0 bitop3:0xde
	v_bitop3_b32 v148, s15, v4, v0 bitop3:0xf6
	v_lshlrev_b32_e32 v0, 14, v1
	v_and_b32_e32 v0, 0xffff8000, v0
	v_lshl_add_u32 v0, v10, 11, v0
	v_and_b32_e32 v1, 1, v1
	v_lshl_or_b32 v0, v1, 6, v0
	v_lshl_add_u32 v138, v11, 1, v0
	v_lshlrev_b32_e32 v0, 14, v13
	v_and_b32_e32 v0, 0xffff8000, v0
	s_waitcnt vmcnt(6)
	v_lshl_or_b32 v2, v2, 13, v3
	v_mov_b32_e32 v3, v133
	v_lshl_add_u32 v0, v12, 11, v0
	v_and_b32_e32 v1, 1, v13
	s_sext_i32_i8 s21, s10
	s_cselect_b64 s[10:11], -1, 0
	v_lshl_add_u64 v[2:3], s[0:1], 0, v[2:3]
	s_mov_b64 s[0:1], 0x7400000
	v_lshl_or_b32 v0, v1, 6, v0
	s_add_i32 s44, 0, 0x10000
	s_add_i32 s45, 0, 0x14000
	v_lshl_add_u64 v[136:137], v[2:3], 0, s[0:1]
	s_ashr_i32 s43, s3, 31
	v_mov_b32_e32 v139, v133
	v_lshl_add_u32 v140, v14, 1, v0
	v_mov_b32_e32 v141, v133
	v_mov_b64_e32 v[142:143], 0x400
	v_mov_b64_e32 v[144:145], 0x3ff
	v_add_u32_e32 v149, s44, v148
	v_add_u32_e32 v150, s45, v148
	v_add_u32_e32 v151, 0, v5
	s_mov_b32 s46, 0x20000
	s_mov_b32 s47, 0x40000
	s_mov_b32 s48, 0x60000
	s_mov_b32 s49, 0x100000
	s_mov_b32 s50, 0x120000
	s_mov_b32 s51, 0x140000
	s_mov_b32 s52, 0x160000
	s_mov_b32 s53, s5
	s_barrier
	s_branch .LBB12_6

.LBB12_6:
	s_add_i32 s53, s53, 1
	s_mul_i32 s0, s53, s43
	s_mul_hi_u32 s1, s53, s3
	s_add_i32 s1, s1, s0
	s_mul_i32 s0, s53, s3
	s_add_u32 s0, s0, s2
	s_addc_u32 s1, s1, s34
	v_cmp_gt_i64_e32 vcc, s[0:1], v[144:145]
	s_cbranch_vccnz .LBB12_8
	s_ashr_i32 s12, s0, 31
	s_lshr_b32 s12, s12, 29
	s_add_i32 s12, s0, s12
	s_ashr_i32 s13, s12, 3
	s_and_b32 s12, s12, -8
	s_sub_i32 s12, s0, s12
	s_cmp_lt_i32 s12, 0
	s_cselect_b32 s14, s35, 0x80
	s_mul_i32 s12, s12, s14
	s_add_i32 s12, s12, s13
	s_ashr_i32 s13, s12, 31
	s_lshr_b32 s13, s13, 25
	s_add_i32 s13, s12, s13
	s_ashr_i32 s14, s13, 7
	s_lshl_b32 s14, s14, 3
	s_sub_i32 s15, 0x40, s14
	s_min_i32 s15, s15, 8
	s_abs_i32 s16, s15
	v_cvt_f32_u32_e32 v0, s16
	s_sub_i32 s18, 0, s16
	s_and_b32 s13, s13, 0xffffff80
	s_sub_i32 s13, s12, s13
	v_rcp_iflag_f32_e32 v0, v0
	s_abs_i32 s12, s13
	s_xor_b32 s17, s13, s15
	s_ashr_i32 s17, s17, 31
	v_mul_f32_e32 v0, 0x4f7ffffe, v0
	v_cvt_u32_f32_e32 v0, v0
	s_nop 0
	v_readfirstlane_b32 s19, v0
	s_mul_i32 s18, s18, s19
	s_mul_hi_u32 s18, s19, s18
	s_add_i32 s19, s19, s18
	s_mul_hi_u32 s18, s12, s19
	s_mul_i32 s19, s18, s16
	s_sub_i32 s12, s12, s19
	s_add_i32 s26, s18, 1
	s_sub_i32 s19, s12, s16
	s_cmp_ge_u32 s12, s16
	s_cselect_b32 s18, s26, s18
	s_cselect_b32 s12, s19, s12
	s_add_i32 s19, s18, 1
	s_cmp_ge_u32 s12, s16
	s_cselect_b32 s12, s19, s18
	s_xor_b32 s12, s12, s17
	s_sub_i32 s12, s12, s17
	s_mul_i32 s15, s12, s15
	s_sub_i32 s13, s13, s15
	s_add_i32 s14, s14, s13

_Z10fwd_kernelILi14ELi15EEv4Args:
	s_load_dword s3, s[0:1], 0xe8
	s_load_dwordx4 s[4:7], s[0:1], 0xd0
	s_load_dwordx2 s[8:9], s[0:1], 0xb8
	s_waitcnt lgkmcnt(0)
	s_cmp_lg_u32 s3, 0x100
	s_cbranch_scc1 .Lrows14_orig
	s_add_u32 s8, s8, 0x1000
	s_addc_u32 s9, s9, 0
	v_readfirstlane_b32 s16, v0
	s_lshr_b32 s16, s16, 6
	s_lshl_b32 s18, s2, 3
	s_add_u32 s16, s16, s18
	s_mov_b32 s17, 0x3a800000
	v_mov_b32_e32 v3, 0x358637bd
	v_and_b32_e32 v10, 63, v0
	v_lshlrev_b32_e32 v1, 4, v10
	v_lshlrev_b32_e32 v2, 3, v10
	v_xor_b32_e32 v4, 1, v10
	v_xor_b32_e32 v5, 2, v10
	v_xor_b32_e32 v6, 4, v10
	v_xor_b32_e32 v7, 8, v10
	v_xor_b32_e32 v8, 16, v10
	v_xor_b32_e32 v9, 32, v10
	v_lshlrev_b32_e32 v4, 2, v4
	v_lshlrev_b32_e32 v5, 2, v5
	v_lshlrev_b32_e32 v6, 2, v6
	v_lshlrev_b32_e32 v7, 2, v7
	v_lshlrev_b32_e32 v8, 2, v8
	v_lshlrev_b32_e32 v9, 2, v9
	global_load_dwordx4 v[20:23], v1, s[8:9] offset:0
	global_load_dwordx4 v[24:27], v1, s[8:9] offset:1024
	global_load_dwordx4 v[28:31], v1, s[8:9] offset:2048
	global_load_dwordx4 v[32:35], v1, s[8:9] offset:3072
	s_add_u32 s53, s16, 0x0
	s_lshl_b32 s18, s53, 12
	s_lshl_b32 s19, s53, 11
	s_add_u32 s20, s4, s18
	s_addc_u32 s21, s5, 0
	s_add_u32 s22, s6, s19
	s_addc_u32 s23, s7, 0
	s_add_u32 s22, s22, 0x5200000
	s_addc_u32 s23, s23, 0
	s_add_u32 s24, s4, s18
	s_addc_u32 s25, s5, 0
	global_load_dwordx2 v[66:67], v2, s[22:23] offset:0
	global_load_dwordx2 v[70:71], v2, s[22:23] offset:512
	global_load_dwordx2 v[74:75], v2, s[22:23] offset:1024
	global_load_dwordx2 v[78:79], v2, s[22:23] offset:1536
	global_load_dwordx4 v[80:83], v1, s[20:21] offset:0
	global_load_dwordx4 v[84:87], v1, s[20:21] offset:1024
	global_load_dwordx4 v[88:91], v1, s[20:21] offset:2048
	global_load_dwordx4 v[92:95], v1, s[20:21] offset:3072
	s_add_u32 s53, s16, 0x800
	s_lshl_b32 s18, s53, 12
	s_lshl_b32 s19, s53, 11
	s_add_u32 s28, s4, s18
	s_addc_u32 s29, s5, 0
	s_add_u32 s30, s6, s19
	s_addc_u32 s31, s7, 0
	s_add_u32 s30, s30, 0x5200000
	s_addc_u32 s31, s31, 0
	s_add_u32 s32, s4, s18
	s_addc_u32 s33, s5, 0
	global_load_dwordx2 v[98:99], v2, s[30:31] offset:0
	global_load_dwordx2 v[102:103], v2, s[30:31] offset:512
	global_load_dwordx2 v[106:107], v2, s[30:31] offset:1024
	global_load_dwordx2 v[110:111], v2, s[30:31] offset:1536
	global_load_dwordx4 v[112:115], v1, s[28:29] offset:0
	global_load_dwordx4 v[116:119], v1, s[28:29] offset:1024
	global_load_dwordx4 v[120:123], v1, s[28:29] offset:2048
	global_load_dwordx4 v[124:127], v1, s[28:29] offset:3072
	s_add_u32 s53, s16, 0x1000
	s_lshl_b32 s18, s53, 12
	s_lshl_b32 s19, s53, 11
	s_add_u32 s36, s4, s18
	s_addc_u32 s37, s5, 0
	s_add_u32 s38, s6, s19
	s_addc_u32 s39, s7, 0
	s_add_u32 s38, s38, 0x5200000
	s_addc_u32 s39, s39, 0
	s_add_u32 s40, s4, s18
	s_addc_u32 s41, s5, 0
	global_load_dwordx2 v[130:131], v2, s[38:39] offset:0
	global_load_dwordx2 v[134:135], v2, s[38:39] offset:512
	global_load_dwordx2 v[138:139], v2, s[38:39] offset:1024
	global_load_dwordx2 v[142:143], v2, s[38:39] offset:1536
	global_load_dwordx4 v[144:147], v1, s[36:37] offset:0
	global_load_dwordx4 v[148:151], v1, s[36:37] offset:1024
	global_load_dwordx4 v[152:155], v1, s[36:37] offset:2048
	global_load_dwordx4 v[156:159], v1, s[36:37] offset:3072
	s_add_u32 s53, s16, 0x1800
	s_lshl_b32 s18, s53, 12
	s_lshl_b32 s19, s53, 11
	s_add_u32 s44, s4, s18
	s_addc_u32 s45, s5, 0
	s_add_u32 s46, s6, s19
	s_addc_u32 s47, s7, 0
	s_add_u32 s46, s46, 0x5200000
	s_addc_u32 s47, s47, 0
	s_add_u32 s48, s4, s18
	s_addc_u32 s49, s5, 0
	global_load_dwordx2 v[162:163], v2, s[46:47] offset:0
	global_load_dwordx2 v[166:167], v2, s[46:47] offset:512
	global_load_dwordx2 v[170:171], v2, s[46:47] offset:1024
	global_load_dwordx2 v[174:175], v2, s[46:47] offset:1536
	global_load_dwordx4 v[176:179], v1, s[44:45] offset:0
	global_load_dwordx4 v[180:183], v1, s[44:45] offset:1024
	global_load_dwordx4 v[184:187], v1, s[44:45] offset:2048
	global_load_dwordx4 v[188:191], v1, s[44:45] offset:3072
	s_waitcnt vmcnt(16)
	v_lshlrev_b32_e32 v64, 16, v66
	v_and_b32_e32 v65, 0xffff0000, v66
	v_lshlrev_b32_e32 v66, 16, v67
	v_and_b32_e32 v67, 0xffff0000, v67
	v_lshlrev_b32_e32 v68, 16, v70
	v_and_b32_e32 v69, 0xffff0000, v70
	v_lshlrev_b32_e32 v70, 16, v71
	v_and_b32_e32 v71, 0xffff0000, v71
	v_lshlrev_b32_e32 v72, 16, v74
	v_and_b32_e32 v73, 0xffff0000, v74
	v_lshlrev_b32_e32 v74, 16, v75
	v_and_b32_e32 v75, 0xffff0000, v75
	v_lshlrev_b32_e32 v76, 16, v78
	v_and_b32_e32 v77, 0xffff0000, v78
	v_lshlrev_b32_e32 v78, 16, v79
	v_and_b32_e32 v79, 0xffff0000, v79
	v_lshlrev_b32_e32 v96, 16, v98
	v_and_b32_e32 v97, 0xffff0000, v98
	v_lshlrev_b32_e32 v98, 16, v99
	v_and_b32_e32 v99, 0xffff0000, v99
	v_lshlrev_b32_e32 v100, 16, v102
	v_and_b32_e32 v101, 0xffff0000, v102
	v_lshlrev_b32_e32 v102, 16, v103
	v_and_b32_e32 v103, 0xffff0000, v103
	v_lshlrev_b32_e32 v104, 16, v106
	v_and_b32_e32 v105, 0xffff0000, v106
	v_lshlrev_b32_e32 v106, 16, v107
	v_and_b32_e32 v107, 0xffff0000, v107
	v_lshlrev_b32_e32 v108, 16, v110
	v_and_b32_e32 v109, 0xffff0000, v110
	v_lshlrev_b32_e32 v110, 16, v111
	v_and_b32_e32 v111, 0xffff0000, v111
	v_mul_f32_e32 v10, v64, v64
	v_fmac_f32_e32 v10, v65, v65
	v_fmac_f32_e32 v10, v66, v66
	v_fmac_f32_e32 v10, v67, v67
	v_fmac_f32_e32 v10, v68, v68
	v_fmac_f32_e32 v10, v69, v69
	v_fmac_f32_e32 v10, v70, v70
	v_fmac_f32_e32 v10, v71, v71
	v_fmac_f32_e32 v10, v72, v72
	v_fmac_f32_e32 v10, v73, v73
	v_fmac_f32_e32 v10, v74, v74
	v_fmac_f32_e32 v10, v75, v75
	v_fmac_f32_e32 v10, v76, v76
	v_fmac_f32_e32 v10, v77, v77
	v_fmac_f32_e32 v10, v78, v78
	v_fmac_f32_e32 v10, v79, v79
	v_mul_f32_e32 v11, v96, v96
	v_fmac_f32_e32 v11, v97, v97
	v_fmac_f32_e32 v11, v98, v98
	v_fmac_f32_e32 v11, v99, v99
	v_fmac_f32_e32 v11, v100, v100
	v_fmac_f32_e32 v11, v101, v101
	v_fmac_f32_e32 v11, v102, v102
	v_fmac_f32_e32 v11, v103, v103
	v_fmac_f32_e32 v11, v104, v104
	v_fmac_f32_e32 v11, v105, v105
	v_fmac_f32_e32 v11, v106, v106
	v_fmac_f32_e32 v11, v107, v107
	v_fmac_f32_e32 v11, v108, v108
	v_fmac_f32_e32 v11, v109, v109
	v_fmac_f32_e32 v11, v110, v110
	v_fmac_f32_e32 v11, v111, v111
	ds_bpermute_b32 v12, v4, v10
	ds_bpermute_b32 v13, v4, v11
	s_waitcnt lgkmcnt(0)
	v_add_f32_e32 v10, v10, v12
	v_add_f32_e32 v11, v11, v13
	ds_bpermute_b32 v12, v5, v10
	ds_bpermute_b32 v13, v5, v11
	s_waitcnt lgkmcnt(0)
	v_add_f32_e32 v10, v10, v12
	v_add_f32_e32 v11, v11, v13
	ds_bpermute_b32 v12, v6, v10
	ds_bpermute_b32 v13, v6, v11
	s_waitcnt lgkmcnt(0)
	v_add_f32_e32 v10, v10, v12
	v_add_f32_e32 v11, v11, v13
	ds_bpermute_b32 v12, v7, v10
	ds_bpermute_b32 v13, v7, v11
	s_waitcnt lgkmcnt(0)
	v_add_f32_e32 v10, v10, v12
	v_add_f32_e32 v11, v11, v13
	ds_bpermute_b32 v12, v8, v10
	ds_bpermute_b32 v13, v8, v11
	s_waitcnt lgkmcnt(0)
	v_add_f32_e32 v10, v10, v12
	v_add_f32_e32 v11, v11, v13
	ds_bpermute_b32 v12, v9, v10
	ds_bpermute_b32 v13, v9, v11
	s_waitcnt lgkmcnt(0)
	v_add_f32_e32 v10, v10, v12
	v_add_f32_e32 v11, v11, v13
	v_fma_f32 v14, v10, s17, v3
	v_fma_f32 v15, v11, s17, v3
	v_rsq_f32_e32 v14, v14
	v_rsq_f32_e32 v15, v15
	s_nop 0
	v_mul_f32_e32 v64, v64, v14
	v_mul_f32_e32 v65, v65, v14
	v_mul_f32_e32 v66, v66, v14
	v_mul_f32_e32 v67, v67, v14
	v_mul_f32_e32 v68, v68, v14
	v_mul_f32_e32 v69, v69, v14
	v_mul_f32_e32 v70, v70, v14
	v_mul_f32_e32 v71, v71, v14
	v_mul_f32_e32 v72, v72, v14
	v_mul_f32_e32 v73, v73, v14
	v_mul_f32_e32 v74, v74, v14
	v_mul_f32_e32 v75, v75, v14
	v_mul_f32_e32 v76, v76, v14
	v_mul_f32_e32 v77, v77, v14
	v_mul_f32_e32 v78, v78, v14
	v_mul_f32_e32 v79, v79, v14
	v_fmac_f32_e32 v80, v64, v20
	v_fmac_f32_e32 v81, v65, v21
	v_fmac_f32_e32 v82, v66, v22
	v_fmac_f32_e32 v83, v67, v23
	v_fmac_f32_e32 v84, v68, v24
	v_fmac_f32_e32 v85, v69, v25
	v_fmac_f32_e32 v86, v70, v26
	v_fmac_f32_e32 v87, v71, v27
	v_fmac_f32_e32 v88, v72, v28
	v_fmac_f32_e32 v89, v73, v29
	v_fmac_f32_e32 v90, v74, v30
	v_fmac_f32_e32 v91, v75, v31
	v_fmac_f32_e32 v92, v76, v32
	v_fmac_f32_e32 v93, v77, v33
	v_fmac_f32_e32 v94, v78, v34
	v_fmac_f32_e32 v95, v79, v35
	global_store_dwordx4 v1, v[80:83], s[24:25] offset:0
	global_store_dwordx4 v1, v[84:87], s[24:25] offset:1024
	global_store_dwordx4 v1, v[88:91], s[24:25] offset:2048
	global_store_dwordx4 v1, v[92:95], s[24:25] offset:3072
	v_mul_f32_e32 v96, v96, v15
	v_mul_f32_e32 v97, v97, v15
	v_mul_f32_e32 v98, v98, v15
	v_mul_f32_e32 v99, v99, v15
	v_mul_f32_e32 v100, v100, v15
	v_mul_f32_e32 v101, v101, v15
	v_mul_f32_e32 v102, v102, v15
	v_mul_f32_e32 v103, v103, v15
	v_mul_f32_e32 v104, v104, v15
	v_mul_f32_e32 v105, v105, v15
	v_mul_f32_e32 v106, v106, v15
	v_mul_f32_e32 v107, v107, v15
	v_mul_f32_e32 v108, v108, v15
	v_mul_f32_e32 v109, v109, v15
	v_mul_f32_e32 v110, v110, v15
	v_mul_f32_e32 v111, v111, v15
	v_fmac_f32_e32 v112, v96, v20
	v_fmac_f32_e32 v113, v97, v21
	v_fmac_f32_e32 v114, v98, v22
	v_fmac_f32_e32 v115, v99, v23
	v_fmac_f32_e32 v116, v100, v24
	v_fmac_f32_e32 v117, v101, v25
	v_fmac_f32_e32 v118, v102, v26
	v_fmac_f32_e32 v119, v103, v27
	v_fmac_f32_e32 v120, v104, v28
	v_fmac_f32_e32 v121, v105, v29
	v_fmac_f32_e32 v122, v106, v30
	v_fmac_f32_e32 v123, v107, v31
	v_fmac_f32_e32 v124, v108, v32
	v_fmac_f32_e32 v125, v109, v33
	v_fmac_f32_e32 v126, v110, v34
	v_fmac_f32_e32 v127, v111, v35
	global_store_dwordx4 v1, v[112:115], s[32:33] offset:0
	global_store_dwordx4 v1, v[116:119], s[32:33] offset:1024
	global_store_dwordx4 v1, v[120:123], s[32:33] offset:2048
	global_store_dwordx4 v1, v[124:127], s[32:33] offset:3072
	s_add_u32 s53, s16, 0x2000
	s_lshl_b32 s18, s53, 12
	s_lshl_b32 s19, s53, 11
	s_add_u32 s20, s4, s18
	s_addc_u32 s21, s5, 0
	s_add_u32 s22, s6, s19
	s_addc_u32 s23, s7, 0
	s_add_u32 s22, s22, 0x5200000
	s_addc_u32 s23, s23, 0
	s_add_u32 s24, s4, s18
	s_addc_u32 s25, s5, 0
	global_load_dwordx2 v[66:67], v2, s[22:23] offset:0
	global_load_dwordx2 v[70:71], v2, s[22:23] offset:512
	global_load_dwordx2 v[74:75], v2, s[22:23] offset:1024
	global_load_dwordx2 v[78:79], v2, s[22:23] offset:1536
	global_load_dwordx4 v[80:83], v1, s[20:21] offset:0
	global_load_dwordx4 v[84:87], v1, s[20:21] offset:1024
	global_load_dwordx4 v[88:91], v1, s[20:21] offset:2048
	global_load_dwordx4 v[92:95], v1, s[20:21] offset:3072
	s_add_u32 s53, s16, 0x2800
	s_lshl_b32 s18, s53, 12
	s_lshl_b32 s19, s53, 11
	s_add_u32 s28, s4, s18
	s_addc_u32 s29, s5, 0
	s_add_u32 s30, s6, s19
	s_addc_u32 s31, s7, 0
	s_add_u32 s30, s30, 0x5200000
	s_addc_u32 s31, s31, 0
	s_add_u32 s32, s4, s18
	s_addc_u32 s33, s5, 0
	global_load_dwordx2 v[98:99], v2, s[30:31] offset:0
	global_load_dwordx2 v[102:103], v2, s[30:31] offset:512
	global_load_dwordx2 v[106:107], v2, s[30:31] offset:1024
	global_load_dwordx2 v[110:111], v2, s[30:31] offset:1536
	global_load_dwordx4 v[112:115], v1, s[28:29] offset:0
	global_load_dwordx4 v[116:119], v1, s[28:29] offset:1024
	global_load_dwordx4 v[120:123], v1, s[28:29] offset:2048
	global_load_dwordx4 v[124:127], v1, s[28:29] offset:3072
	s_waitcnt vmcnt(24)
	v_lshlrev_b32_e32 v128, 16, v130
	v_and_b32_e32 v129, 0xffff0000, v130
	v_lshlrev_b32_e32 v130, 16, v131
	v_and_b32_e32 v131, 0xffff0000, v131
	v_lshlrev_b32_e32 v132, 16, v134
	v_and_b32_e32 v133, 0xffff0000, v134
	v_lshlrev_b32_e32 v134, 16, v135
	v_and_b32_e32 v135, 0xffff0000, v135
	v_lshlrev_b32_e32 v136, 16, v138
	v_and_b32_e32 v137, 0xffff0000, v138
	v_lshlrev_b32_e32 v138, 16, v139
	v_and_b32_e32 v139, 0xffff0000, v139
	v_lshlrev_b32_e32 v140, 16, v142
	v_and_b32_e32 v141, 0xffff0000, v142
	v_lshlrev_b32_e32 v142, 16, v143
	v_and_b32_e32 v143, 0xffff0000, v143
	v_lshlrev_b32_e32 v160, 16, v162
	v_and_b32_e32 v161, 0xffff0000, v162
	v_lshlrev_b32_e32 v162, 16, v163
	v_and_b32_e32 v163, 0xffff0000, v163
	v_lshlrev_b32_e32 v164, 16, v166
	v_and_b32_e32 v165, 0xffff0000, v166
	v_lshlrev_b32_e32 v166, 16, v167
	v_and_b32_e32 v167, 0xffff0000, v167
	v_lshlrev_b32_e32 v168, 16, v170
	v_and_b32_e32 v169, 0xffff0000, v170
	v_lshlrev_b32_e32 v170, 16, v171
	v_and_b32_e32 v171, 0xffff0000, v171
	v_lshlrev_b32_e32 v172, 16, v174
	v_and_b32_e32 v173, 0xffff0000, v174
	v_lshlrev_b32_e32 v174, 16, v175
	v_and_b32_e32 v175, 0xffff0000, v175
	v_mul_f32_e32 v10, v128, v128
	v_fmac_f32_e32 v10, v129, v129
	v_fmac_f32_e32 v10, v130, v130
	v_fmac_f32_e32 v10, v131, v131
	v_fmac_f32_e32 v10, v132, v132
	v_fmac_f32_e32 v10, v133, v133
	v_fmac_f32_e32 v10, v134, v134
	v_fmac_f32_e32 v10, v135, v135
	v_fmac_f32_e32 v10, v136, v136
	v_fmac_f32_e32 v10, v137, v137
	v_fmac_f32_e32 v10, v138, v138
	v_fmac_f32_e32 v10, v139, v139
	v_fmac_f32_e32 v10, v140, v140
	v_fmac_f32_e32 v10, v141, v141
	v_fmac_f32_e32 v10, v142, v142
	v_fmac_f32_e32 v10, v143, v143
	v_mul_f32_e32 v11, v160, v160
	v_fmac_f32_e32 v11, v161, v161
	v_fmac_f32_e32 v11, v162, v162
	v_fmac_f32_e32 v11, v163, v163
	v_fmac_f32_e32 v11, v164, v164
	v_fmac_f32_e32 v11, v165, v165
	v_fmac_f32_e32 v11, v166, v166
	v_fmac_f32_e32 v11, v167, v167
	v_fmac_f32_e32 v11, v168, v168
	v_fmac_f32_e32 v11, v169, v169
	v_fmac_f32_e32 v11, v170, v170
	v_fmac_f32_e32 v11, v171, v171
	v_fmac_f32_e32 v11, v172, v172
	v_fmac_f32_e32 v11, v173, v173
	v_fmac_f32_e32 v11, v174, v174
	v_fmac_f32_e32 v11, v175, v175
	ds_bpermute_b32 v12, v4, v10
	ds_bpermute_b32 v13, v4, v11
	s_waitcnt lgkmcnt(0)
	v_add_f32_e32 v10, v10, v12
	v_add_f32_e32 v11, v11, v13
	ds_bpermute_b32 v12, v5, v10
	ds_bpermute_b32 v13, v5, v11
	s_waitcnt lgkmcnt(0)
	v_add_f32_e32 v10, v10, v12
	v_add_f32_e32 v11, v11, v13
	ds_bpermute_b32 v12, v6, v10
	ds_bpermute_b32 v13, v6, v11
	s_waitcnt lgkmcnt(0)
	v_add_f32_e32 v10, v10, v12
	v_add_f32_e32 v11, v11, v13
	ds_bpermute_b32 v12, v7, v10
	ds_bpermute_b32 v13, v7, v11
	s_waitcnt lgkmcnt(0)
	v_add_f32_e32 v10, v10, v12
	v_add_f32_e32 v11, v11, v13
	ds_bpermute_b32 v12, v8, v10
	ds_bpermute_b32 v13, v8, v11
	s_waitcnt lgkmcnt(0)
	v_add_f32_e32 v10, v10, v12
	v_add_f32_e32 v11, v11, v13
	ds_bpermute_b32 v12, v9, v10
	ds_bpermute_b32 v13, v9, v11
	s_waitcnt lgkmcnt(0)
	v_add_f32_e32 v10, v10, v12
	v_add_f32_e32 v11, v11, v13
	v_fma_f32 v14, v10, s17, v3
	v_fma_f32 v15, v11, s17, v3
	v_rsq_f32_e32 v14, v14
	v_rsq_f32_e32 v15, v15
	s_nop 0
	v_mul_f32_e32 v128, v128, v14
	v_mul_f32_e32 v129, v129, v14
	v_mul_f32_e32 v130, v130, v14
	v_mul_f32_e32 v131, v131, v14
	v_mul_f32_e32 v132, v132, v14
	v_mul_f32_e32 v133, v133, v14
	v_mul_f32_e32 v134, v134, v14
	v_mul_f32_e32 v135, v135, v14
	v_mul_f32_e32 v136, v136, v14
	v_mul_f32_e32 v137, v137, v14
	v_mul_f32_e32 v138, v138, v14
	v_mul_f32_e32 v139, v139, v14
	v_mul_f32_e32 v140, v140, v14
	v_mul_f32_e32 v141, v141, v14
	v_mul_f32_e32 v142, v142, v14
	v_mul_f32_e32 v143, v143, v14
	v_fmac_f32_e32 v144, v128, v20
	v_fmac_f32_e32 v145, v129, v21
	v_fmac_f32_e32 v146, v130, v22
	v_fmac_f32_e32 v147, v131, v23
	v_fmac_f32_e32 v148, v132, v24
	v_fmac_f32_e32 v149, v133, v25
	v_fmac_f32_e32 v150, v134, v26
	v_fmac_f32_e32 v151, v135, v27
	v_fmac_f32_e32 v152, v136, v28
	v_fmac_f32_e32 v153, v137, v29
	v_fmac_f32_e32 v154, v138, v30
	v_fmac_f32_e32 v155, v139, v31
	v_fmac_f32_e32 v156, v140, v32
	v_fmac_f32_e32 v157, v141, v33
	v_fmac_f32_e32 v158, v142, v34
	v_fmac_f32_e32 v159, v143, v35
	global_store_dwordx4 v1, v[144:147], s[40:41] offset:0
	global_store_dwordx4 v1, v[148:151], s[40:41] offset:1024
	global_store_dwordx4 v1, v[152:155], s[40:41] offset:2048
	global_store_dwordx4 v1, v[156:159], s[40:41] offset:3072
	v_mul_f32_e32 v160, v160, v15
	v_mul_f32_e32 v161, v161, v15
	v_mul_f32_e32 v162, v162, v15
	v_mul_f32_e32 v163, v163, v15
	v_mul_f32_e32 v164, v164, v15
	v_mul_f32_e32 v165, v165, v15
	v_mul_f32_e32 v166, v166, v15
	v_mul_f32_e32 v167, v167, v15
	v_mul_f32_e32 v168, v168, v15
	v_mul_f32_e32 v169, v169, v15
	v_mul_f32_e32 v170, v170, v15
	v_mul_f32_e32 v171, v171, v15
	v_mul_f32_e32 v172, v172, v15
	v_mul_f32_e32 v173, v173, v15
	v_mul_f32_e32 v174, v174, v15
	v_mul_f32_e32 v175, v175, v15
	v_fmac_f32_e32 v176, v160, v20
	v_fmac_f32_e32 v177, v161, v21
	v_fmac_f32_e32 v178, v162, v22
	v_fmac_f32_e32 v179, v163, v23
	v_fmac_f32_e32 v180, v164, v24
	v_fmac_f32_e32 v181, v165, v25
	v_fmac_f32_e32 v182, v166, v26
	v_fmac_f32_e32 v183, v167, v27
	v_fmac_f32_e32 v184, v168, v28
	v_fmac_f32_e32 v185, v169, v29
	v_fmac_f32_e32 v186, v170, v30
	v_fmac_f32_e32 v187, v171, v31
	v_fmac_f32_e32 v188, v172, v32
	v_fmac_f32_e32 v189, v173, v33
	v_fmac_f32_e32 v190, v174, v34
	v_fmac_f32_e32 v191, v175, v35
	global_store_dwordx4 v1, v[176:179], s[48:49] offset:0
	global_store_dwordx4 v1, v[180:183], s[48:49] offset:1024
	global_store_dwordx4 v1, v[184:187], s[48:49] offset:2048
	global_store_dwordx4 v1, v[188:191], s[48:49] offset:3072
	s_add_u32 s53, s16, 0x3000
	s_lshl_b32 s18, s53, 12
	s_lshl_b32 s19, s53, 11
	s_add_u32 s36, s4, s18
	s_addc_u32 s37, s5, 0
	s_add_u32 s38, s6, s19
	s_addc_u32 s39, s7, 0
	s_add_u32 s38, s38, 0x5200000
	s_addc_u32 s39, s39, 0
	s_add_u32 s40, s4, s18
	s_addc_u32 s41, s5, 0
	global_load_dwordx2 v[130:131], v2, s[38:39] offset:0
	global_load_dwordx2 v[134:135], v2, s[38:39] offset:512
	global_load_dwordx2 v[138:139], v2, s[38:39] offset:1024
	global_load_dwordx2 v[142:143], v2, s[38:39] offset:1536
	global_load_dwordx4 v[144:147], v1, s[36:37] offset:0
	global_load_dwordx4 v[148:151], v1, s[36:37] offset:1024
	global_load_dwordx4 v[152:155], v1, s[36:37] offset:2048
	global_load_dwordx4 v[156:159], v1, s[36:37] offset:3072
	s_add_u32 s53, s16, 0x3800
	s_lshl_b32 s18, s53, 12
	s_lshl_b32 s19, s53, 11
	s_add_u32 s44, s4, s18
	s_addc_u32 s45, s5, 0
	s_add_u32 s46, s6, s19
	s_addc_u32 s47, s7, 0
	s_add_u32 s46, s46, 0x5200000
	s_addc_u32 s47, s47, 0
	s_add_u32 s48, s4, s18
	s_addc_u32 s49, s5, 0
	global_load_dwordx2 v[162:163], v2, s[46:47] offset:0
	global_load_dwordx2 v[166:167], v2, s[46:47] offset:512
	global_load_dwordx2 v[170:171], v2, s[46:47] offset:1024
	global_load_dwordx2 v[174:175], v2, s[46:47] offset:1536
	global_load_dwordx4 v[176:179], v1, s[44:45] offset:0
	global_load_dwordx4 v[180:183], v1, s[44:45] offset:1024
	global_load_dwordx4 v[184:187], v1, s[44:45] offset:2048
	global_load_dwordx4 v[188:191], v1, s[44:45] offset:3072
	s_waitcnt vmcnt(24)
	v_lshlrev_b32_e32 v64, 16, v66
	v_and_b32_e32 v65, 0xffff0000, v66
	v_lshlrev_b32_e32 v66, 16, v67
	v_and_b32_e32 v67, 0xffff0000, v67
	v_lshlrev_b32_e32 v68, 16, v70
	v_and_b32_e32 v69, 0xffff0000, v70
	v_lshlrev_b32_e32 v70, 16, v71
	v_and_b32_e32 v71, 0xffff0000, v71
	v_lshlrev_b32_e32 v72, 16, v74
	v_and_b32_e32 v73, 0xffff0000, v74
	v_lshlrev_b32_e32 v74, 16, v75
	v_and_b32_e32 v75, 0xffff0000, v75
	v_lshlrev_b32_e32 v76, 16, v78
	v_and_b32_e32 v77, 0xffff0000, v78
	v_lshlrev_b32_e32 v78, 16, v79
	v_and_b32_e32 v79, 0xffff0000, v79
	v_lshlrev_b32_e32 v96, 16, v98
	v_and_b32_e32 v97, 0xffff0000, v98
	v_lshlrev_b32_e32 v98, 16, v99
	v_and_b32_e32 v99, 0xffff0000, v99
	v_lshlrev_b32_e32 v100, 16, v102
	v_and_b32_e32 v101, 0xffff0000, v102
	v_lshlrev_b32_e32 v102, 16, v103
	v_and_b32_e32 v103, 0xffff0000, v103
	v_lshlrev_b32_e32 v104, 16, v106
	v_and_b32_e32 v105, 0xffff0000, v106
	v_lshlrev_b32_e32 v106, 16, v107
	v_and_b32_e32 v107, 0xffff0000, v107
	v_lshlrev_b32_e32 v108, 16, v110
	v_and_b32_e32 v109, 0xffff0000, v110
	v_lshlrev_b32_e32 v110, 16, v111
	v_and_b32_e32 v111, 0xffff0000, v111
	v_mul_f32_e32 v10, v64, v64
	v_fmac_f32_e32 v10, v65, v65
	v_fmac_f32_e32 v10, v66, v66
	v_fmac_f32_e32 v10, v67, v67
	v_fmac_f32_e32 v10, v68, v68
	v_fmac_f32_e32 v10, v69, v69
	v_fmac_f32_e32 v10, v70, v70
	v_fmac_f32_e32 v10, v71, v71
	v_fmac_f32_e32 v10, v72, v72
	v_fmac_f32_e32 v10, v73, v73
	v_fmac_f32_e32 v10, v74, v74
	v_fmac_f32_e32 v10, v75, v75
	v_fmac_f32_e32 v10, v76, v76
	v_fmac_f32_e32 v10, v77, v77
	v_fmac_f32_e32 v10, v78, v78
	v_fmac_f32_e32 v10, v79, v79
	v_mul_f32_e32 v11, v96, v96
	v_fmac_f32_e32 v11, v97, v97
	v_fmac_f32_e32 v11, v98, v98
	v_fmac_f32_e32 v11, v99, v99
	v_fmac_f32_e32 v11, v100, v100
	v_fmac_f32_e32 v11, v101, v101
	v_fmac_f32_e32 v11, v102, v102
	v_fmac_f32_e32 v11, v103, v103
	v_fmac_f32_e32 v11, v104, v104
	v_fmac_f32_e32 v11, v105, v105
	v_fmac_f32_e32 v11, v106, v106
	v_fmac_f32_e32 v11, v107, v107
	v_fmac_f32_e32 v11, v108, v108
	v_fmac_f32_e32 v11, v109, v109
	v_fmac_f32_e32 v11, v110, v110
	v_fmac_f32_e32 v11, v111, v111
	ds_bpermute_b32 v12, v4, v10
	ds_bpermute_b32 v13, v4, v11
	s_waitcnt lgkmcnt(0)
	v_add_f32_e32 v10, v10, v12
	v_add_f32_e32 v11, v11, v13
	ds_bpermute_b32 v12, v5, v10
	ds_bpermute_b32 v13, v5, v11
	s_waitcnt lgkmcnt(0)
	v_add_f32_e32 v10, v10, v12
	v_add_f32_e32 v11, v11, v13
	ds_bpermute_b32 v12, v6, v10
	ds_bpermute_b32 v13, v6, v11
	s_waitcnt lgkmcnt(0)
	v_add_f32_e32 v10, v10, v12
	v_add_f32_e32 v11, v11, v13
	ds_bpermute_b32 v12, v7, v10
	ds_bpermute_b32 v13, v7, v11
	s_waitcnt lgkmcnt(0)
	v_add_f32_e32 v10, v10, v12
	v_add_f32_e32 v11, v11, v13
	ds_bpermute_b32 v12, v8, v10
	ds_bpermute_b32 v13, v8, v11
	s_waitcnt lgkmcnt(0)
	v_add_f32_e32 v10, v10, v12
	v_add_f32_e32 v11, v11, v13
	ds_bpermute_b32 v12, v9, v10
	ds_bpermute_b32 v13, v9, v11
	s_waitcnt lgkmcnt(0)
	v_add_f32_e32 v10, v10, v12
	v_add_f32_e32 v11, v11, v13
	v_fma_f32 v14, v10, s17, v3
	v_fma_f32 v15, v11, s17, v3
	v_rsq_f32_e32 v14, v14
	v_rsq_f32_e32 v15, v15
	s_nop 0
	v_mul_f32_e32 v64, v64, v14
	v_mul_f32_e32 v65, v65, v14
	v_mul_f32_e32 v66, v66, v14
	v_mul_f32_e32 v67, v67, v14
	v_mul_f32_e32 v68, v68, v14
	v_mul_f32_e32 v69, v69, v14
	v_mul_f32_e32 v70, v70, v14
	v_mul_f32_e32 v71, v71, v14
	v_mul_f32_e32 v72, v72, v14
	v_mul_f32_e32 v73, v73, v14
	v_mul_f32_e32 v74, v74, v14
	v_mul_f32_e32 v75, v75, v14
	v_mul_f32_e32 v76, v76, v14
	v_mul_f32_e32 v77, v77, v14
	v_mul_f32_e32 v78, v78, v14
	v_mul_f32_e32 v79, v79, v14
	v_fmac_f32_e32 v80, v64, v20
	v_fmac_f32_e32 v81, v65, v21
	v_fmac_f32_e32 v82, v66, v22
	v_fmac_f32_e32 v83, v67, v23
	v_fmac_f32_e32 v84, v68, v24
	v_fmac_f32_e32 v85, v69, v25
	v_fmac_f32_e32 v86, v70, v26
	v_fmac_f32_e32 v87, v71, v27
	v_fmac_f32_e32 v88, v72, v28
	v_fmac_f32_e32 v89, v73, v29
	v_fmac_f32_e32 v90, v74, v30
	v_fmac_f32_e32 v91, v75, v31
	v_fmac_f32_e32 v92, v76, v32
	v_fmac_f32_e32 v93, v77, v33
	v_fmac_f32_e32 v94, v78, v34
	v_fmac_f32_e32 v95, v79, v35
	global_store_dwordx4 v1, v[80:83], s[24:25] offset:0
	global_store_dwordx4 v1, v[84:87], s[24:25] offset:1024
	global_store_dwordx4 v1, v[88:91], s[24:25] offset:2048
	global_store_dwordx4 v1, v[92:95], s[24:25] offset:3072
	v_mul_f32_e32 v96, v96, v15
	v_mul_f32_e32 v97, v97, v15
	v_mul_f32_e32 v98, v98, v15
	v_mul_f32_e32 v99, v99, v15
	v_mul_f32_e32 v100, v100, v15
	v_mul_f32_e32 v101, v101, v15
	v_mul_f32_e32 v102, v102, v15
	v_mul_f32_e32 v103, v103, v15
	v_mul_f32_e32 v104, v104, v15
	v_mul_f32_e32 v105, v105, v15
	v_mul_f32_e32 v106, v106, v15
	v_mul_f32_e32 v107, v107, v15
	v_mul_f32_e32 v108, v108, v15
	v_mul_f32_e32 v109, v109, v15
	v_mul_f32_e32 v110, v110, v15
	v_mul_f32_e32 v111, v111, v15
	v_fmac_f32_e32 v112, v96, v20
	v_fmac_f32_e32 v113, v97, v21
	v_fmac_f32_e32 v114, v98, v22
	v_fmac_f32_e32 v115, v99, v23
	v_fmac_f32_e32 v116, v100, v24
	v_fmac_f32_e32 v117, v101, v25
	v_fmac_f32_e32 v118, v102, v26
	v_fmac_f32_e32 v119, v103, v27
	v_fmac_f32_e32 v120, v104, v28
	v_fmac_f32_e32 v121, v105, v29
	v_fmac_f32_e32 v122, v106, v30
	v_fmac_f32_e32 v123, v107, v31
	v_fmac_f32_e32 v124, v108, v32
	v_fmac_f32_e32 v125, v109, v33
	v_fmac_f32_e32 v126, v110, v34
	v_fmac_f32_e32 v127, v111, v35
	global_store_dwordx4 v1, v[112:115], s[32:33] offset:0
	global_store_dwordx4 v1, v[116:119], s[32:33] offset:1024
	global_store_dwordx4 v1, v[120:123], s[32:33] offset:2048
	global_store_dwordx4 v1, v[124:127], s[32:33] offset:3072
	s_waitcnt vmcnt(8)
	v_lshlrev_b32_e32 v128, 16, v130
	v_and_b32_e32 v129, 0xffff0000, v130
	v_lshlrev_b32_e32 v130, 16, v131
	v_and_b32_e32 v131, 0xffff0000, v131
	v_lshlrev_b32_e32 v132, 16, v134
	v_and_b32_e32 v133, 0xffff0000, v134
	v_lshlrev_b32_e32 v134, 16, v135
	v_and_b32_e32 v135, 0xffff0000, v135
	v_lshlrev_b32_e32 v136, 16, v138
	v_and_b32_e32 v137, 0xffff0000, v138
	v_lshlrev_b32_e32 v138, 16, v139
	v_and_b32_e32 v139, 0xffff0000, v139
	v_lshlrev_b32_e32 v140, 16, v142
	v_and_b32_e32 v141, 0xffff0000, v142
	v_lshlrev_b32_e32 v142, 16, v143
	v_and_b32_e32 v143, 0xffff0000, v143
	v_lshlrev_b32_e32 v160, 16, v162
	v_and_b32_e32 v161, 0xffff0000, v162
	v_lshlrev_b32_e32 v162, 16, v163
	v_and_b32_e32 v163, 0xffff0000, v163
	v_lshlrev_b32_e32 v164, 16, v166
	v_and_b32_e32 v165, 0xffff0000, v166
	v_lshlrev_b32_e32 v166, 16, v167
	v_and_b32_e32 v167, 0xffff0000, v167
	v_lshlrev_b32_e32 v168, 16, v170
	v_and_b32_e32 v169, 0xffff0000, v170
	v_lshlrev_b32_e32 v170, 16, v171
	v_and_b32_e32 v171, 0xffff0000, v171
	v_lshlrev_b32_e32 v172, 16, v174
	v_and_b32_e32 v173, 0xffff0000, v174
	v_lshlrev_b32_e32 v174, 16, v175
	v_and_b32_e32 v175, 0xffff0000, v175
	v_mul_f32_e32 v10, v128, v128
	v_fmac_f32_e32 v10, v129, v129
	v_fmac_f32_e32 v10, v130, v130
	v_fmac_f32_e32 v10, v131, v131
	v_fmac_f32_e32 v10, v132, v132
	v_fmac_f32_e32 v10, v133, v133
	v_fmac_f32_e32 v10, v134, v134
	v_fmac_f32_e32 v10, v135, v135
	v_fmac_f32_e32 v10, v136, v136
	v_fmac_f32_e32 v10, v137, v137
	v_fmac_f32_e32 v10, v138, v138
	v_fmac_f32_e32 v10, v139, v139
	v_fmac_f32_e32 v10, v140, v140
	v_fmac_f32_e32 v10, v141, v141
	v_fmac_f32_e32 v10, v142, v142
	v_fmac_f32_e32 v10, v143, v143
	v_mul_f32_e32 v11, v160, v160
	v_fmac_f32_e32 v11, v161, v161
	v_fmac_f32_e32 v11, v162, v162
	v_fmac_f32_e32 v11, v163, v163
	v_fmac_f32_e32 v11, v164, v164
	v_fmac_f32_e32 v11, v165, v165
	v_fmac_f32_e32 v11, v166, v166
	v_fmac_f32_e32 v11, v167, v167
	v_fmac_f32_e32 v11, v168, v168
	v_fmac_f32_e32 v11, v169, v169
	v_fmac_f32_e32 v11, v170, v170
	v_fmac_f32_e32 v11, v171, v171
	v_fmac_f32_e32 v11, v172, v172
	v_fmac_f32_e32 v11, v173, v173
	v_fmac_f32_e32 v11, v174, v174
	v_fmac_f32_e32 v11, v175, v175
	ds_bpermute_b32 v12, v4, v10
	ds_bpermute_b32 v13, v4, v11
	s_waitcnt lgkmcnt(0)
	v_add_f32_e32 v10, v10, v12
	v_add_f32_e32 v11, v11, v13
	ds_bpermute_b32 v12, v5, v10
	ds_bpermute_b32 v13, v5, v11
	s_waitcnt lgkmcnt(0)
	v_add_f32_e32 v10, v10, v12
	v_add_f32_e32 v11, v11, v13
	ds_bpermute_b32 v12, v6, v10
	ds_bpermute_b32 v13, v6, v11
	s_waitcnt lgkmcnt(0)
	v_add_f32_e32 v10, v10, v12
	v_add_f32_e32 v11, v11, v13
	ds_bpermute_b32 v12, v7, v10
	ds_bpermute_b32 v13, v7, v11
	s_waitcnt lgkmcnt(0)
	v_add_f32_e32 v10, v10, v12
	v_add_f32_e32 v11, v11, v13
	ds_bpermute_b32 v12, v8, v10
	ds_bpermute_b32 v13, v8, v11
	s_waitcnt lgkmcnt(0)
	v_add_f32_e32 v10, v10, v12
	v_add_f32_e32 v11, v11, v13
	ds_bpermute_b32 v12, v9, v10
	ds_bpermute_b32 v13, v9, v11
	s_waitcnt lgkmcnt(0)
	v_add_f32_e32 v10, v10, v12
	v_add_f32_e32 v11, v11, v13
	v_fma_f32 v14, v10, s17, v3
	v_fma_f32 v15, v11, s17, v3
	v_rsq_f32_e32 v14, v14
	v_rsq_f32_e32 v15, v15
	s_nop 0
	v_mul_f32_e32 v128, v128, v14
	v_mul_f32_e32 v129, v129, v14
	v_mul_f32_e32 v130, v130, v14
	v_mul_f32_e32 v131, v131, v14
	v_mul_f32_e32 v132, v132, v14
	v_mul_f32_e32 v133, v133, v14
	v_mul_f32_e32 v134, v134, v14
	v_mul_f32_e32 v135, v135, v14
	v_mul_f32_e32 v136, v136, v14
	v_mul_f32_e32 v137, v137, v14
	v_mul_f32_e32 v138, v138, v14
	v_mul_f32_e32 v139, v139, v14
	v_mul_f32_e32 v140, v140, v14
	v_mul_f32_e32 v141, v141, v14
	v_mul_f32_e32 v142, v142, v14
	v_mul_f32_e32 v143, v143, v14
	v_fmac_f32_e32 v144, v128, v20
	v_fmac_f32_e32 v145, v129, v21
	v_fmac_f32_e32 v146, v130, v22
	v_fmac_f32_e32 v147, v131, v23
	v_fmac_f32_e32 v148, v132, v24
	v_fmac_f32_e32 v149, v133, v25
	v_fmac_f32_e32 v150, v134, v26
	v_fmac_f32_e32 v151, v135, v27
	v_fmac_f32_e32 v152, v136, v28
	v_fmac_f32_e32 v153, v137, v29
	v_fmac_f32_e32 v154, v138, v30
	v_fmac_f32_e32 v155, v139, v31
	v_fmac_f32_e32 v156, v140, v32
	v_fmac_f32_e32 v157, v141, v33
	v_fmac_f32_e32 v158, v142, v34
	v_fmac_f32_e32 v159, v143, v35
	global_store_dwordx4 v1, v[144:147], s[40:41] offset:0
	global_store_dwordx4 v1, v[148:151], s[40:41] offset:1024
	global_store_dwordx4 v1, v[152:155], s[40:41] offset:2048
	global_store_dwordx4 v1, v[156:159], s[40:41] offset:3072
	v_mul_f32_e32 v160, v160, v15
	v_mul_f32_e32 v161, v161, v15
	v_mul_f32_e32 v162, v162, v15
	v_mul_f32_e32 v163, v163, v15
	v_mul_f32_e32 v164, v164, v15
	v_mul_f32_e32 v165, v165, v15
	v_mul_f32_e32 v166, v166, v15
	v_mul_f32_e32 v167, v167, v15
	v_mul_f32_e32 v168, v168, v15
	v_mul_f32_e32 v169, v169, v15
	v_mul_f32_e32 v170, v170, v15
	v_mul_f32_e32 v171, v171, v15
	v_mul_f32_e32 v172, v172, v15
	v_mul_f32_e32 v173, v173, v15
	v_mul_f32_e32 v174, v174, v15
	v_mul_f32_e32 v175, v175, v15
	v_fmac_f32_e32 v176, v160, v20
	v_fmac_f32_e32 v177, v161, v21
	v_fmac_f32_e32 v178, v162, v22
	v_fmac_f32_e32 v179, v163, v23
	v_fmac_f32_e32 v180, v164, v24
	v_fmac_f32_e32 v181, v165, v25
	v_fmac_f32_e32 v182, v166, v26
	v_fmac_f32_e32 v183, v167, v27
	v_fmac_f32_e32 v184, v168, v28
	v_fmac_f32_e32 v185, v169, v29
	v_fmac_f32_e32 v186, v170, v30
	v_fmac_f32_e32 v187, v171, v31
	v_fmac_f32_e32 v188, v172, v32
	v_fmac_f32_e32 v189, v173, v33
	v_fmac_f32_e32 v190, v174, v34
	v_fmac_f32_e32 v191, v175, v35
	global_store_dwordx4 v1, v[176:179], s[48:49] offset:0
	global_store_dwordx4 v1, v[180:183], s[48:49] offset:1024
	global_store_dwordx4 v1, v[184:187], s[48:49] offset:2048
	global_store_dwordx4 v1, v[188:191], s[48:49] offset:3072
	s_and_b32 s18, s16, 3
	s_cmp_lg_u32 s18, 0
	s_cbranch_scc1 .Lrows14_end
	s_lshr_b32 s54, s16, 2
	s_add_u32 s53, s54, 0x4000
	s_lshl_b32 s18, s53, 12
	s_lshl_b32 s19, s53, 11
	s_add_u32 s20, s4, s18
	s_addc_u32 s21, s5, 0
	s_add_u32 s24, s4, s18
	s_addc_u32 s25, s5, 0
	s_lshl_b32 s18, s54, 12
	s_add_u32 s22, s6, s18
	s_addc_u32 s23, s7, 0
	s_add_u32 s22, s22, 0x100000
	s_addc_u32 s23, s23, 0
	global_load_dwordx4 v[64:67], v1, s[22:23] offset:0
	global_load_dwordx4 v[68:71], v1, s[22:23] offset:1024
	global_load_dwordx4 v[72:75], v1, s[22:23] offset:2048
	global_load_dwordx4 v[76:79], v1, s[22:23] offset:3072
	s_add_u32 s22, s22, 0x200000
	s_addc_u32 s23, s23, 0
	global_load_dwordx4 v[80:83], v1, s[22:23] offset:0
	global_load_dwordx4 v[84:87], v1, s[22:23] offset:1024
	global_load_dwordx4 v[88:91], v1, s[22:23] offset:2048
	global_load_dwordx4 v[92:95], v1, s[22:23] offset:3072
	s_add_u32 s22, s22, 0x200000
	s_addc_u32 s23, s23, 0
	global_load_dwordx4 v[96:99], v1, s[22:23] offset:0
	global_load_dwordx4 v[100:103], v1, s[22:23] offset:1024
	global_load_dwordx4 v[104:107], v1, s[22:23] offset:2048
	global_load_dwordx4 v[108:111], v1, s[22:23] offset:3072
	s_add_u32 s22, s22, 0x200000
	s_addc_u32 s23, s23, 0
	global_load_dwordx4 v[112:115], v1, s[22:23] offset:0
	global_load_dwordx4 v[116:119], v1, s[22:23] offset:1024
	global_load_dwordx4 v[120:123], v1, s[22:23] offset:2048
	global_load_dwordx4 v[124:127], v1, s[22:23] offset:3072
	s_add_u32 s22, s22, 0x200000
	s_addc_u32 s23, s23, 0
	global_load_dwordx4 v[128:131], v1, s[22:23] offset:0
	global_load_dwordx4 v[132:135], v1, s[22:23] offset:1024
	global_load_dwordx4 v[136:139], v1, s[22:23] offset:2048
	global_load_dwordx4 v[140:143], v1, s[22:23] offset:3072
	s_add_u32 s22, s22, 0x200000
	s_addc_u32 s23, s23, 0
	global_load_dwordx4 v[144:147], v1, s[22:23] offset:0
	global_load_dwordx4 v[148:151], v1, s[22:23] offset:1024
	global_load_dwordx4 v[152:155], v1, s[22:23] offset:2048
	global_load_dwordx4 v[156:159], v1, s[22:23] offset:3072
	s_add_u32 s22, s22, 0x200000
	s_addc_u32 s23, s23, 0
	global_load_dwordx4 v[160:163], v1, s[22:23] offset:0
	global_load_dwordx4 v[164:167], v1, s[22:23] offset:1024
	global_load_dwordx4 v[168:171], v1, s[22:23] offset:2048
	global_load_dwordx4 v[172:175], v1, s[22:23] offset:3072
	s_add_u32 s22, s22, 0x200000
	s_addc_u32 s23, s23, 0
	global_load_dwordx4 v[176:179], v1, s[22:23] offset:0
	global_load_dwordx4 v[180:183], v1, s[22:23] offset:1024
	global_load_dwordx4 v[184:187], v1, s[22:23] offset:2048
	global_load_dwordx4 v[188:191], v1, s[22:23] offset:3072
	global_load_dwordx4 v[192:195], v1, s[20:21] offset:0
	global_load_dwordx4 v[196:199], v1, s[20:21] offset:1024
	global_load_dwordx4 v[200:203], v1, s[20:21] offset:2048
	global_load_dwordx4 v[204:207], v1, s[20:21] offset:3072
	s_waitcnt vmcnt(0)
	v_add_f32_e32 v64, v64, v80
	v_add_f32_e32 v65, v65, v81
	v_add_f32_e32 v66, v66, v82
	v_add_f32_e32 v67, v67, v83
	v_add_f32_e32 v68, v68, v84
	v_add_f32_e32 v69, v69, v85
	v_add_f32_e32 v70, v70, v86
	v_add_f32_e32 v71, v71, v87
	v_add_f32_e32 v72, v72, v88
	v_add_f32_e32 v73, v73, v89
	v_add_f32_e32 v74, v74, v90
	v_add_f32_e32 v75, v75, v91
	v_add_f32_e32 v76, v76, v92
	v_add_f32_e32 v77, v77, v93
	v_add_f32_e32 v78, v78, v94
	v_add_f32_e32 v79, v79, v95
	v_add_f32_e32 v96, v96, v112
	v_add_f32_e32 v97, v97, v113
	v_add_f32_e32 v98, v98, v114
	v_add_f32_e32 v99, v99, v115
	v_add_f32_e32 v100, v100, v116
	v_add_f32_e32 v101, v101, v117
	v_add_f32_e32 v102, v102, v118
	v_add_f32_e32 v103, v103, v119
	v_add_f32_e32 v104, v104, v120
	v_add_f32_e32 v105, v105, v121
	v_add_f32_e32 v106, v106, v122
	v_add_f32_e32 v107, v107, v123
	v_add_f32_e32 v108, v108, v124
	v_add_f32_e32 v109, v109, v125
	v_add_f32_e32 v110, v110, v126
	v_add_f32_e32 v111, v111, v127
	v_add_f32_e32 v128, v128, v144
	v_add_f32_e32 v129, v129, v145
	v_add_f32_e32 v130, v130, v146
	v_add_f32_e32 v131, v131, v147
	v_add_f32_e32 v132, v132, v148
	v_add_f32_e32 v133, v133, v149
	v_add_f32_e32 v134, v134, v150
	v_add_f32_e32 v135, v135, v151
	v_add_f32_e32 v136, v136, v152
	v_add_f32_e32 v137, v137, v153
	v_add_f32_e32 v138, v138, v154
	v_add_f32_e32 v139, v139, v155
	v_add_f32_e32 v140, v140, v156
	v_add_f32_e32 v141, v141, v157
	v_add_f32_e32 v142, v142, v158
	v_add_f32_e32 v143, v143, v159
	v_add_f32_e32 v160, v160, v176
	v_add_f32_e32 v161, v161, v177
	v_add_f32_e32 v162, v162, v178
	v_add_f32_e32 v163, v163, v179
	v_add_f32_e32 v164, v164, v180
	v_add_f32_e32 v165, v165, v181
	v_add_f32_e32 v166, v166, v182
	v_add_f32_e32 v167, v167, v183
	v_add_f32_e32 v168, v168, v184
	v_add_f32_e32 v169, v169, v185
	v_add_f32_e32 v170, v170, v186
	v_add_f32_e32 v171, v171, v187
	v_add_f32_e32 v172, v172, v188
	v_add_f32_e32 v173, v173, v189
	v_add_f32_e32 v174, v174, v190
	v_add_f32_e32 v175, v175, v191
	v_add_f32_e32 v64, v64, v96
	v_add_f32_e32 v65, v65, v97
	v_add_f32_e32 v66, v66, v98
	v_add_f32_e32 v67, v67, v99
	v_add_f32_e32 v68, v68, v100
	v_add_f32_e32 v69, v69, v101
	v_add_f32_e32 v70, v70, v102
	v_add_f32_e32 v71, v71, v103
	v_add_f32_e32 v72, v72, v104
	v_add_f32_e32 v73, v73, v105
	v_add_f32_e32 v74, v74, v106
	v_add_f32_e32 v75, v75, v107
	v_add_f32_e32 v76, v76, v108
	v_add_f32_e32 v77, v77, v109
	v_add_f32_e32 v78, v78, v110
	v_add_f32_e32 v79, v79, v111
	v_add_f32_e32 v128, v128, v160
	v_add_f32_e32 v129, v129, v161
	v_add_f32_e32 v130, v130, v162
	v_add_f32_e32 v131, v131, v163
	v_add_f32_e32 v132, v132, v164
	v_add_f32_e32 v133, v133, v165
	v_add_f32_e32 v134, v134, v166
	v_add_f32_e32 v135, v135, v167
	v_add_f32_e32 v136, v136, v168
	v_add_f32_e32 v137, v137, v169
	v_add_f32_e32 v138, v138, v170
	v_add_f32_e32 v139, v139, v171
	v_add_f32_e32 v140, v140, v172
	v_add_f32_e32 v141, v141, v173
	v_add_f32_e32 v142, v142, v174
	v_add_f32_e32 v143, v143, v175
	v_add_f32_e32 v64, v64, v128
	v_add_f32_e32 v65, v65, v129
	v_add_f32_e32 v66, v66, v130
	v_add_f32_e32 v67, v67, v131
	v_add_f32_e32 v68, v68, v132
	v_add_f32_e32 v69, v69, v133
	v_add_f32_e32 v70, v70, v134
	v_add_f32_e32 v71, v71, v135
	v_add_f32_e32 v72, v72, v136
	v_add_f32_e32 v73, v73, v137
	v_add_f32_e32 v74, v74, v138
	v_add_f32_e32 v75, v75, v139
	v_add_f32_e32 v76, v76, v140
	v_add_f32_e32 v77, v77, v141
	v_add_f32_e32 v78, v78, v142
	v_add_f32_e32 v79, v79, v143
	v_mul_f32_e32 v10, v64, v64
	v_fmac_f32_e32 v10, v65, v65
	v_fmac_f32_e32 v10, v66, v66
	v_fmac_f32_e32 v10, v67, v67
	v_fmac_f32_e32 v10, v68, v68
	v_fmac_f32_e32 v10, v69, v69
	v_fmac_f32_e32 v10, v70, v70
	v_fmac_f32_e32 v10, v71, v71
	v_fmac_f32_e32 v10, v72, v72
	v_fmac_f32_e32 v10, v73, v73
	v_fmac_f32_e32 v10, v74, v74
	v_fmac_f32_e32 v10, v75, v75
	v_fmac_f32_e32 v10, v76, v76
	v_fmac_f32_e32 v10, v77, v77
	v_fmac_f32_e32 v10, v78, v78
	v_fmac_f32_e32 v10, v79, v79
	ds_bpermute_b32 v12, v4, v10
	s_waitcnt lgkmcnt(0)
	v_add_f32_e32 v10, v10, v12
	ds_bpermute_b32 v12, v5, v10
	s_waitcnt lgkmcnt(0)
	v_add_f32_e32 v10, v10, v12
	ds_bpermute_b32 v12, v6, v10
	s_waitcnt lgkmcnt(0)
	v_add_f32_e32 v10, v10, v12
	ds_bpermute_b32 v12, v7, v10
	s_waitcnt lgkmcnt(0)
	v_add_f32_e32 v10, v10, v12
	ds_bpermute_b32 v12, v8, v10
	s_waitcnt lgkmcnt(0)
	v_add_f32_e32 v10, v10, v12
	ds_bpermute_b32 v12, v9, v10
	s_waitcnt lgkmcnt(0)
	v_add_f32_e32 v10, v10, v12
	v_fma_f32 v14, v10, s17, v3
	v_rsq_f32_e32 v14, v14
	s_nop 0
	v_mul_f32_e32 v64, v64, v14
	v_mul_f32_e32 v65, v65, v14
	v_mul_f32_e32 v66, v66, v14
	v_mul_f32_e32 v67, v67, v14
	v_mul_f32_e32 v68, v68, v14
	v_mul_f32_e32 v69, v69, v14
	v_mul_f32_e32 v70, v70, v14
	v_mul_f32_e32 v71, v71, v14
	v_mul_f32_e32 v72, v72, v14
	v_mul_f32_e32 v73, v73, v14
	v_mul_f32_e32 v74, v74, v14
	v_mul_f32_e32 v75, v75, v14
	v_mul_f32_e32 v76, v76, v14
	v_mul_f32_e32 v77, v77, v14
	v_mul_f32_e32 v78, v78, v14
	v_mul_f32_e32 v79, v79, v14
	v_fmac_f32_e32 v192, v64, v20
	v_fmac_f32_e32 v193, v65, v21
	v_fmac_f32_e32 v194, v66, v22
	v_fmac_f32_e32 v195, v67, v23
	v_fmac_f32_e32 v196, v68, v24
	v_fmac_f32_e32 v197, v69, v25
	v_fmac_f32_e32 v198, v70, v26
	v_fmac_f32_e32 v199, v71, v27
	v_fmac_f32_e32 v200, v72, v28
	v_fmac_f32_e32 v201, v73, v29
	v_fmac_f32_e32 v202, v74, v30
	v_fmac_f32_e32 v203, v75, v31
	v_fmac_f32_e32 v204, v76, v32
	v_fmac_f32_e32 v205, v77, v33
	v_fmac_f32_e32 v206, v78, v34
	v_fmac_f32_e32 v207, v79, v35
	global_store_dwordx4 v1, v[192:195], s[24:25] offset:0
	global_store_dwordx4 v1, v[196:199], s[24:25] offset:1024
	global_store_dwordx4 v1, v[200:203], s[24:25] offset:2048
	global_store_dwordx4 v1, v[204:207], s[24:25] offset:3072

.Lrows14_orig:
	s_load_dword s3, s[0:1], 0xe8
	s_mov_b32 s5, s2
	s_waitcnt lgkmcnt(0)
	s_mov_b32 s5, s3
	v_readfirstlane_b32 s4, v0
	s_ashr_i32 s4, s4, 6
	s_lshl_b32 s2, s2, 3
	s_add_i32 s2, s2, s4
	s_cmpk_gt_i32 s2, 0x41ff
	s_cbranch_scc1 .LBB14_79
	s_load_dwordx2 s[8:9], s[0:1], 0xb8
	s_load_dwordx4 s[4:7], s[0:1], 0xd0
	v_and_b32_e32 v96, 63, v0
	v_lshlrev_b32_e32 v16, 4, v96
	v_or_b32_e32 v18, 0x400, v16
	s_waitcnt lgkmcnt(0)
	s_add_u32 s0, s8, 0x1000
	s_addc_u32 s1, s9, 0
	v_or_b32_e32 v20, 0x800, v16
	global_load_dwordx4 v[0:3], v18, s[0:1]
	global_load_dwordx4 v[4:7], v20, s[0:1]
	v_or_b32_e32 v22, 0xc00, v16
	global_load_dwordx4 v[8:11], v16, s[0:1]
	global_load_dwordx4 v[12:15], v22, s[0:1]
	v_mbcnt_lo_u32_b32 v24, -1, 0
	v_mbcnt_hi_u32_b32 v24, -1, v24
	v_and_b32_e32 v25, 64, v24
	v_add_u32_e32 v25, 64, v25
	v_xor_b32_e32 v26, 1, v24
	v_cmp_lt_i32_e32 vcc, v26, v25
	s_add_u32 s30, s6, 0x5200000
	s_addc_u32 s31, s7, 0
	v_cndmask_b32_e32 v26, v24, v26, vcc
	v_lshlrev_b32_e32 v97, 2, v26
	v_xor_b32_e32 v26, 2, v24
	v_cmp_lt_i32_e32 vcc, v26, v25
	s_lshl_b32 s33, s3, 3
	v_mov_b32_e32 v17, 0
	v_cndmask_b32_e32 v26, v24, v26, vcc
	v_lshlrev_b32_e32 v160, 2, v26
	v_xor_b32_e32 v26, 4, v24
	v_cmp_lt_i32_e32 vcc, v26, v25
	s_add_u32 s0, s6, 0x100000
	v_mov_b32_e32 v19, v17
	v_cndmask_b32_e32 v26, v24, v26, vcc
	v_mov_b32_e32 v21, v17
	v_mov_b32_e32 v23, v17
	s_addc_u32 s1, s7, 0
	s_lshl_b32 s8, s3, 5
	s_lshl_b32 s34, s3, 4
	s_mul_i32 s35, s3, 24
	v_lshlrev_b32_e32 v161, 2, v26
	v_xor_b32_e32 v26, 8, v24
	s_ashr_i32 s3, s2, 31
	v_lshl_add_u64 v[98:99], s[0:1], 0, v[16:17]
	v_cmp_lt_i32_e32 vcc, v26, v25
	v_lshl_add_u64 v[100:101], s[0:1], 0, v[18:19]
	v_lshl_add_u64 v[102:103], s[0:1], 0, v[20:21]
	v_lshl_add_u64 v[104:105], s[0:1], 0, v[22:23]
	s_lshl_b64 s[0:1], s[2:3], 12
	v_cndmask_b32_e32 v26, v24, v26, vcc
	s_add_u32 s0, s4, s0
	v_lshlrev_b32_e32 v162, 2, v26
	v_xor_b32_e32 v26, 16, v24
	s_addc_u32 s1, s5, s1
	v_cmp_lt_i32_e32 vcc, v26, v25
	v_lshl_add_u64 v[18:19], s[0:1], 0, v[16:17]
	s_mov_b64 s[0:1], 0xc00
	s_ashr_i32 s9, s8, 31
	v_cndmask_b32_e32 v26, v24, v26, vcc
	v_lshl_add_u64 v[106:107], s[4:5], 0, v[16:17]
	v_lshl_add_u64 v[108:109], v[18:19], 0, s[0:1]
	s_lshl_b64 s[4:5], s[8:9], 12
	s_lshl_b64 s[0:1], s[2:3], 11
	v_lshlrev_b32_e32 v163, 2, v26
	v_xor_b32_e32 v26, 32, v24
	s_add_u32 s0, s6, s0
	v_cmp_lt_i32_e32 vcc, v26, v25
	v_lshlrev_b32_e32 v16, 3, v96
	s_addc_u32 s1, s7, s1
	v_cndmask_b32_e32 v24, v24, v26, vcc
	v_lshl_add_u64 v[16:17], s[0:1], 0, v[16:17]
	s_mov_b64 s[0:1], 0x5200600
	s_mov_b32 s11, 0
	v_lshlrev_b32_e32 v164, 2, v24
	v_lshl_add_u64 v[110:111], v[16:17], 0, s[0:1]
	s_lshl_b64 s[6:7], s[8:9], 11
	s_mov_b32 s3, 0x800000
	v_mov_b32_e32 v165, 0x358637bd
	s_branch .LBB14_3

	.amdhsa_kernel _Z10fwd_kernelILi14ELi15EEv4Args
		.amdhsa_group_segment_fixed_size 0
		.amdhsa_private_segment_fixed_size 0
		.amdhsa_kernarg_size 488
		.amdhsa_user_sgpr_count 2
		.amdhsa_user_sgpr_dispatch_ptr 0
		.amdhsa_user_sgpr_queue_ptr 0
		.amdhsa_user_sgpr_kernarg_segment_ptr 1
		.amdhsa_user_sgpr_dispatch_id 0
		.amdhsa_user_sgpr_kernarg_preload_length 0
		.amdhsa_user_sgpr_kernarg_preload_offset 0
		.amdhsa_user_sgpr_private_segment_size 0
		.amdhsa_uses_dynamic_stack 0
		.amdhsa_enable_private_segment 0
		.amdhsa_system_sgpr_workgroup_id_x 1
		.amdhsa_system_sgpr_workgroup_id_y 0
		.amdhsa_system_sgpr_workgroup_id_z 0
		.amdhsa_system_sgpr_workgroup_info 0
		.amdhsa_system_vgpr_workitem_id 0
		.amdhsa_next_free_vgpr 208
		.amdhsa_next_free_sgpr 56
		.amdhsa_accum_offset 208
		.amdhsa_reserve_vcc 1
		.amdhsa_float_round_mode_32 0
		.amdhsa_float_round_mode_16_64 0
		.amdhsa_float_denorm_mode_32 3
		.amdhsa_float_denorm_mode_16_64 3
		.amdhsa_dx10_clamp 1
		.amdhsa_ieee_mode 1
		.amdhsa_fp16_overflow 0
		.amdhsa_tg_split 0
		.amdhsa_exception_fp_ieee_invalid_op 0
		.amdhsa_exception_fp_denorm_src 0
		.amdhsa_exception_fp_ieee_div_zero 0
		.amdhsa_exception_fp_ieee_overflow 0
		.amdhsa_exception_fp_ieee_underflow 0
		.amdhsa_exception_fp_ieee_inexact 0
		.amdhsa_exception_int_div_zero 0
	.end_amdhsa_kernel

amdhsa.kernels:
  - .agpr_count:     0
    .args:
      - .offset:         0
        .size:           232
        .value_kind:     by_value
      - .offset:         232
        .size:           4
        .value_kind:     hidden_block_count_x
      - .offset:         236
        .size:           4
        .value_kind:     hidden_block_count_y
      - .offset:         240
        .size:           4
        .value_kind:     hidden_block_count_z
      - .offset:         244
        .size:           2
        .value_kind:     hidden_group_size_x
      - .offset:         246
        .size:           2
        .value_kind:     hidden_group_size_y
      - .offset:         248
        .size:           2
        .value_kind:     hidden_group_size_z
      - .offset:         250
        .size:           2
        .value_kind:     hidden_remainder_x
      - .offset:         252
        .size:           2
        .value_kind:     hidden_remainder_y
      - .offset:         254
        .size:           2
        .value_kind:     hidden_remainder_z
      - .offset:         272
        .size:           8
        .value_kind:     hidden_global_offset_x
      - .offset:         280
        .size:           8
        .value_kind:     hidden_global_offset_y
      - .offset:         288
        .size:           8
        .value_kind:     hidden_global_offset_z
      - .offset:         296
        .size:           2
        .value_kind:     hidden_grid_dims
      - .offset:         352
        .size:           4
        .value_kind:     hidden_dynamic_lds_size
    .group_segment_fixed_size: 0
    .kernarg_segment_align: 8
    .kernarg_segment_size: 488
    .language:       OpenCL C
    .language_version:
      - 2
      - 0
    .max_flat_workgroup_size: 512
    .name:           _Z10fwd_kernelILi0ELi1EEv4Args
    .private_segment_fixed_size: 0
    .sgpr_count:     106
    .sgpr_spill_count: 0
    .symbol:         _Z10fwd_kernelILi0ELi1EEv4Args.kd
    .uniform_work_group_size: 1
    .uses_dynamic_stack: false
    .vgpr_count:     224
    .vgpr_spill_count: 0
    .wavefront_size: 64
  - .agpr_count:     0
    .args:
      - .offset:         0
        .size:           232
        .value_kind:     by_value
      - .offset:         232
        .size:           4
        .value_kind:     hidden_block_count_x
      - .offset:         236
        .size:           4
        .value_kind:     hidden_block_count_y
      - .offset:         240
        .size:           4
        .value_kind:     hidden_block_count_z
      - .offset:         244
        .size:           2
        .value_kind:     hidden_group_size_x
      - .offset:         246
        .size:           2
        .value_kind:     hidden_group_size_y
      - .offset:         248
        .size:           2
        .value_kind:     hidden_group_size_z
      - .offset:         250
        .size:           2
        .value_kind:     hidden_remainder_x
      - .offset:         252
        .size:           2
        .value_kind:     hidden_remainder_y
      - .offset:         254
        .size:           2
        .value_kind:     hidden_remainder_z
      - .offset:         272
        .size:           8
        .value_kind:     hidden_global_offset_x
      - .offset:         280
        .size:           8
        .value_kind:     hidden_global_offset_y
      - .offset:         288
        .size:           8
        .value_kind:     hidden_global_offset_z
      - .offset:         296
        .size:           2
        .value_kind:     hidden_grid_dims
      - .offset:         352
        .size:           4
        .value_kind:     hidden_dynamic_lds_size
    .group_segment_fixed_size: 0
    .kernarg_segment_align: 8
    .kernarg_segment_size: 488
    .language:       OpenCL C
    .language_version:
      - 2
      - 0
    .max_flat_workgroup_size: 512
    .name:           _Z10fwd_kernelILi1ELi2EEv4Args
    .private_segment_fixed_size: 0
    .sgpr_count:     64
    .sgpr_spill_count: 0
    .symbol:         _Z10fwd_kernelILi1ELi2EEv4Args.kd
    .uniform_work_group_size: 1
    .uses_dynamic_stack: false
    .vgpr_count:     226
    .vgpr_spill_count: 0
    .wavefront_size: 64
  - .agpr_count:     0
    .args:
      - .offset:         0
        .size:           232
        .value_kind:     by_value
      - .offset:         232
        .size:           4
        .value_kind:     hidden_block_count_x
      - .offset:         236
        .size:           4
        .value_kind:     hidden_block_count_y
      - .offset:         240
        .size:           4
        .value_kind:     hidden_block_count_z
      - .offset:         244
        .size:           2
        .value_kind:     hidden_group_size_x
      - .offset:         246
        .size:           2
        .value_kind:     hidden_group_size_y
      - .offset:         248
        .size:           2
        .value_kind:     hidden_group_size_z
      - .offset:         250
        .size:           2
        .value_kind:     hidden_remainder_x
      - .offset:         252
        .size:           2
        .value_kind:     hidden_remainder_y
      - .offset:         254
        .size:           2
        .value_kind:     hidden_remainder_z
      - .offset:         272
        .size:           8
        .value_kind:     hidden_global_offset_x
      - .offset:         280
        .size:           8
        .value_kind:     hidden_global_offset_y
      - .offset:         288
        .size:           8
        .value_kind:     hidden_global_offset_z
      - .offset:         296
        .size:           2
        .value_kind:     hidden_grid_dims
      - .offset:         352
        .size:           4
        .value_kind:     hidden_dynamic_lds_size
    .group_segment_fixed_size: 0
    .kernarg_segment_align: 8
    .kernarg_segment_size: 488
    .language:       OpenCL C
    .language_version:
      - 2
      - 0
    .max_flat_workgroup_size: 512
    .name:           _Z10fwd_kernelILi2ELi3EEv4Args
    .private_segment_fixed_size: 0
    .sgpr_count:     106
    .sgpr_spill_count: 11
    .symbol:         _Z10fwd_kernelILi2ELi3EEv4Args.kd
    .uniform_work_group_size: 1
    .uses_dynamic_stack: false
    .vgpr_count:     252
    .vgpr_spill_count: 0
    .wavefront_size: 64
  - .agpr_count:     0
    .args:
      - .offset:         0
        .size:           232
        .value_kind:     by_value
      - .offset:         232
        .size:           4
        .value_kind:     hidden_block_count_x
      - .offset:         236
        .size:           4
        .value_kind:     hidden_block_count_y
      - .offset:         240
        .size:           4
        .value_kind:     hidden_block_count_z
      - .offset:         244
        .size:           2
        .value_kind:     hidden_group_size_x
      - .offset:         246
        .size:           2
        .value_kind:     hidden_group_size_y
      - .offset:         248
        .size:           2
        .value_kind:     hidden_group_size_z
      - .offset:         250
        .size:           2
        .value_kind:     hidden_remainder_x
      - .offset:         252
        .size:           2
        .value_kind:     hidden_remainder_y
      - .offset:         254
        .size:           2
        .value_kind:     hidden_remainder_z
      - .offset:         272
        .size:           8
        .value_kind:     hidden_global_offset_x
      - .offset:         280
        .size:           8
        .value_kind:     hidden_global_offset_y
      - .offset:         288
        .size:           8
        .value_kind:     hidden_global_offset_z
      - .offset:         296
        .size:           2
        .value_kind:     hidden_grid_dims
      - .offset:         352
        .size:           4
        .value_kind:     hidden_dynamic_lds_size
    .group_segment_fixed_size: 0
    .kernarg_segment_align: 8
    .kernarg_segment_size: 488
    .language:       OpenCL C
    .language_version:
      - 2
      - 0
    .max_flat_workgroup_size: 512
    .name:           _Z10fwd_kernelILi3ELi4EEv4Args
    .private_segment_fixed_size: 0
    .sgpr_count:     67
    .sgpr_spill_count: 0
    .symbol:         _Z10fwd_kernelILi3ELi4EEv4Args.kd
    .uniform_work_group_size: 1
    .uses_dynamic_stack: false
    .vgpr_count:     240
    .vgpr_spill_count: 0
    .wavefront_size: 64
  - .agpr_count:     0
    .args:
      - .offset:         0
        .size:           232
        .value_kind:     by_value
      - .offset:         232
        .size:           4
        .value_kind:     hidden_block_count_x
      - .offset:         236
        .size:           4
        .value_kind:     hidden_block_count_y
      - .offset:         240
        .size:           4
        .value_kind:     hidden_block_count_z
      - .offset:         244
        .size:           2
        .value_kind:     hidden_group_size_x
      - .offset:         246
        .size:           2
        .value_kind:     hidden_group_size_y
      - .offset:         248
        .size:           2
        .value_kind:     hidden_group_size_z
      - .offset:         250
        .size:           2
        .value_kind:     hidden_remainder_x
      - .offset:         252
        .size:           2
        .value_kind:     hidden_remainder_y
      - .offset:         254
        .size:           2
        .value_kind:     hidden_remainder_z
      - .offset:         272
        .size:           8
        .value_kind:     hidden_global_offset_x
      - .offset:         280
        .size:           8
        .value_kind:     hidden_global_offset_y
      - .offset:         288
        .size:           8
        .value_kind:     hidden_global_offset_z
      - .offset:         296
        .size:           2
        .value_kind:     hidden_grid_dims
    .group_segment_fixed_size: 0
    .kernarg_segment_align: 8
    .kernarg_segment_size: 488
    .language:       OpenCL C
    .language_version:
      - 2
      - 0
    .max_flat_workgroup_size: 512
    .name:           _Z10fwd_kernelILi4ELi5EEv4Args
    .private_segment_fixed_size: 0
    .sgpr_count:     62
    .sgpr_spill_count: 0
    .symbol:         _Z10fwd_kernelILi4ELi5EEv4Args.kd
    .uniform_work_group_size: 1
    .uses_dynamic_stack: false
    .vgpr_count:     208
    .vgpr_spill_count: 0
    .wavefront_size: 64
  - .agpr_count:     0
    .args:
      - .offset:         0
        .size:           232
        .value_kind:     by_value
      - .offset:         232
        .size:           4
        .value_kind:     hidden_block_count_x
      - .offset:         236
        .size:           4
        .value_kind:     hidden_block_count_y
      - .offset:         240
        .size:           4
        .value_kind:     hidden_block_count_z
      - .offset:         244
        .size:           2
        .value_kind:     hidden_group_size_x
      - .offset:         246
        .size:           2
        .value_kind:     hidden_group_size_y
      - .offset:         248
        .size:           2
        .value_kind:     hidden_group_size_z
      - .offset:         250
        .size:           2
        .value_kind:     hidden_remainder_x
      - .offset:         252
        .size:           2
        .value_kind:     hidden_remainder_y
      - .offset:         254
        .size:           2
        .value_kind:     hidden_remainder_z
      - .offset:         272
        .size:           8
        .value_kind:     hidden_global_offset_x
      - .offset:         280
        .size:           8
        .value_kind:     hidden_global_offset_y
      - .offset:         288
        .size:           8
        .value_kind:     hidden_global_offset_z
      - .offset:         296
        .size:           2
        .value_kind:     hidden_grid_dims
      - .offset:         352
        .size:           4
        .value_kind:     hidden_dynamic_lds_size
    .group_segment_fixed_size: 0
    .kernarg_segment_align: 8
    .kernarg_segment_size: 488
    .language:       OpenCL C
    .language_version:
      - 2
      - 0
    .max_flat_workgroup_size: 512
    .name:           _Z10fwd_kernelILi5ELi6EEv4Args
    .private_segment_fixed_size: 0
    .sgpr_count:     68
    .sgpr_spill_count: 0
    .symbol:         _Z10fwd_kernelILi5ELi6EEv4Args.kd
    .uniform_work_group_size: 1
    .uses_dynamic_stack: false
    .vgpr_count:     224
    .vgpr_spill_count: 0
    .wavefront_size: 64
  - .agpr_count:     0
    .args:
      - .offset:         0
        .size:           232
        .value_kind:     by_value
      - .offset:         232
        .size:           4
        .value_kind:     hidden_block_count_x
      - .offset:         236
        .size:           4
        .value_kind:     hidden_block_count_y
      - .offset:         240
        .size:           4
        .value_kind:     hidden_block_count_z
      - .offset:         244
        .size:           2
        .value_kind:     hidden_group_size_x
      - .offset:         246
        .size:           2
        .value_kind:     hidden_group_size_y
      - .offset:         248
        .size:           2
        .value_kind:     hidden_group_size_z
      - .offset:         250
        .size:           2
        .value_kind:     hidden_remainder_x
      - .offset:         252
        .size:           2
        .value_kind:     hidden_remainder_y
      - .offset:         254
        .size:           2
        .value_kind:     hidden_remainder_z
      - .offset:         272
        .size:           8
        .value_kind:     hidden_global_offset_x
      - .offset:         280
        .size:           8
        .value_kind:     hidden_global_offset_y
      - .offset:         288
        .size:           8
        .value_kind:     hidden_global_offset_z
      - .offset:         296
        .size:           2
        .value_kind:     hidden_grid_dims
      - .offset:         352
        .size:           4
        .value_kind:     hidden_dynamic_lds_size
    .group_segment_fixed_size: 0
    .kernarg_segment_align: 8
    .kernarg_segment_size: 488
    .language:       OpenCL C
    .language_version:
      - 2
      - 0
    .max_flat_workgroup_size: 512
    .name:           _Z10fwd_kernelILi6ELi7EEv4Args
    .private_segment_fixed_size: 0
    .sgpr_count:     67
    .sgpr_spill_count: 0
    .symbol:         _Z10fwd_kernelILi6ELi7EEv4Args.kd
    .uniform_work_group_size: 1
    .uses_dynamic_stack: false
    .vgpr_count:     240
    .vgpr_spill_count: 0
    .wavefront_size: 64
  - .agpr_count:     0
    .args:
      - .offset:         0
        .size:           232
        .value_kind:     by_value
      - .offset:         232
        .size:           4
        .value_kind:     hidden_block_count_x
      - .offset:         236
        .size:           4
        .value_kind:     hidden_block_count_y
      - .offset:         240
        .size:           4
        .value_kind:     hidden_block_count_z
      - .offset:         244
        .size:           2
        .value_kind:     hidden_group_size_x
      - .offset:         246
        .size:           2
        .value_kind:     hidden_group_size_y
      - .offset:         248
        .size:           2
        .value_kind:     hidden_group_size_z
      - .offset:         250
        .size:           2
        .value_kind:     hidden_remainder_x
      - .offset:         252
        .size:           2
        .value_kind:     hidden_remainder_y
      - .offset:         254
        .size:           2
        .value_kind:     hidden_remainder_z
      - .offset:         272
        .size:           8
        .value_kind:     hidden_global_offset_x
      - .offset:         280
        .size:           8
        .value_kind:     hidden_global_offset_y
      - .offset:         288
        .size:           8
        .value_kind:     hidden_global_offset_z
      - .offset:         296
        .size:           2
        .value_kind:     hidden_grid_dims
    .group_segment_fixed_size: 0
    .kernarg_segment_align: 8
    .kernarg_segment_size: 488
    .language:       OpenCL C
    .language_version:
      - 2
      - 0
    .max_flat_workgroup_size: 512
    .name:           _Z10fwd_kernelILi7ELi8EEv4Args
    .private_segment_fixed_size: 0
    .sgpr_count:     62
    .sgpr_spill_count: 0
    .symbol:         _Z10fwd_kernelILi7ELi8EEv4Args.kd
    .uniform_work_group_size: 1
    .uses_dynamic_stack: false
    .vgpr_count:     208
    .vgpr_spill_count: 0
    .wavefront_size: 64
  - .agpr_count:     0
    .args:
      - .offset:         0
        .size:           232
        .value_kind:     by_value
      - .offset:         232
        .size:           4
        .value_kind:     hidden_block_count_x
      - .offset:         236
        .size:           4
        .value_kind:     hidden_block_count_y
      - .offset:         240
        .size:           4
        .value_kind:     hidden_block_count_z
      - .offset:         244
        .size:           2
        .value_kind:     hidden_group_size_x
      - .offset:         246
        .size:           2
        .value_kind:     hidden_group_size_y
      - .offset:         248
        .size:           2
        .value_kind:     hidden_group_size_z
      - .offset:         250
        .size:           2
        .value_kind:     hidden_remainder_x
      - .offset:         252
        .size:           2
        .value_kind:     hidden_remainder_y
      - .offset:         254
        .size:           2
        .value_kind:     hidden_remainder_z
      - .offset:         272
        .size:           8
        .value_kind:     hidden_global_offset_x
      - .offset:         280
        .size:           8
        .value_kind:     hidden_global_offset_y
      - .offset:         288
        .size:           8
        .value_kind:     hidden_global_offset_z
      - .offset:         296
        .size:           2
        .value_kind:     hidden_grid_dims
      - .offset:         352
        .size:           4
        .value_kind:     hidden_dynamic_lds_size
    .group_segment_fixed_size: 0
    .kernarg_segment_align: 8
    .kernarg_segment_size: 488
    .language:       OpenCL C
    .language_version:
      - 2
      - 0
    .max_flat_workgroup_size: 512
    .name:           _Z10fwd_kernelILi8ELi9EEv4Args
    .private_segment_fixed_size: 0
    .sgpr_count:     75
    .sgpr_spill_count: 0
    .symbol:         _Z10fwd_kernelILi8ELi9EEv4Args.kd
    .uniform_work_group_size: 1
    .uses_dynamic_stack: false
    .vgpr_count:     226
    .vgpr_spill_count: 0
    .wavefront_size: 64
  - .agpr_count:     0
    .args:
      - .offset:         0
        .size:           232
        .value_kind:     by_value
      - .offset:         232
        .size:           4
        .value_kind:     hidden_block_count_x
      - .offset:         236
        .size:           4
        .value_kind:     hidden_block_count_y
      - .offset:         240
        .size:           4
        .value_kind:     hidden_block_count_z
      - .offset:         244
        .size:           2
        .value_kind:     hidden_group_size_x
      - .offset:         246
        .size:           2
        .value_kind:     hidden_group_size_y
      - .offset:         248
        .size:           2
        .value_kind:     hidden_group_size_z
      - .offset:         250
        .size:           2
        .value_kind:     hidden_remainder_x
      - .offset:         252
        .size:           2
        .value_kind:     hidden_remainder_y
      - .offset:         254
        .size:           2
        .value_kind:     hidden_remainder_z
      - .offset:         272
        .size:           8
        .value_kind:     hidden_global_offset_x
      - .offset:         280
        .size:           8
        .value_kind:     hidden_global_offset_y
      - .offset:         288
        .size:           8
        .value_kind:     hidden_global_offset_z
      - .offset:         296
        .size:           2
        .value_kind:     hidden_grid_dims
      - .offset:         352
        .size:           4
        .value_kind:     hidden_dynamic_lds_size
    .group_segment_fixed_size: 0
    .kernarg_segment_align: 8
    .kernarg_segment_size: 488
    .language:       OpenCL C
    .language_version:
      - 2
      - 0
    .max_flat_workgroup_size: 512
    .name:           _Z10fwd_kernelILi9ELi10EEv4Args
    .private_segment_fixed_size: 0
    .sgpr_count:     80
    .sgpr_spill_count: 0
    .symbol:         _Z10fwd_kernelILi9ELi10EEv4Args.kd
    .uniform_work_group_size: 1
    .uses_dynamic_stack: false
    .vgpr_count:     174
    .vgpr_spill_count: 0
    .wavefront_size: 64
  - .agpr_count:     0
    .args:
      - .offset:         0
        .size:           232
        .value_kind:     by_value
      - .offset:         232
        .size:           4
        .value_kind:     hidden_block_count_x
      - .offset:         236
        .size:           4
        .value_kind:     hidden_block_count_y
      - .offset:         240
        .size:           4
        .value_kind:     hidden_block_count_z
      - .offset:         244
        .size:           2
        .value_kind:     hidden_group_size_x
      - .offset:         246
        .size:           2
        .value_kind:     hidden_group_size_y
      - .offset:         248
        .size:           2
        .value_kind:     hidden_group_size_z
      - .offset:         250
        .size:           2
        .value_kind:     hidden_remainder_x
      - .offset:         252
        .size:           2
        .value_kind:     hidden_remainder_y
      - .offset:         254
        .size:           2
        .value_kind:     hidden_remainder_z
      - .offset:         272
        .size:           8
        .value_kind:     hidden_global_offset_x
      - .offset:         280
        .size:           8
        .value_kind:     hidden_global_offset_y
      - .offset:         288
        .size:           8
        .value_kind:     hidden_global_offset_z
      - .offset:         296
        .size:           2
        .value_kind:     hidden_grid_dims
      - .offset:         352
        .size:           4
        .value_kind:     hidden_dynamic_lds_size
    .group_segment_fixed_size: 0
    .kernarg_segment_align: 8
    .kernarg_segment_size: 488
    .language:       OpenCL C
    .language_version:
      - 2
      - 0
    .max_flat_workgroup_size: 512
    .name:           _Z10fwd_kernelILi10ELi11EEv4Args
    .private_segment_fixed_size: 0
    .sgpr_count:     67
    .sgpr_spill_count: 0
    .symbol:         _Z10fwd_kernelILi10ELi11EEv4Args.kd
    .uniform_work_group_size: 1
    .uses_dynamic_stack: false
    .vgpr_count:     240
    .vgpr_spill_count: 0
    .wavefront_size: 64
  - .agpr_count:     0
    .args:
      - .offset:         0
        .size:           232
        .value_kind:     by_value
      - .offset:         232
        .size:           4
        .value_kind:     hidden_block_count_x
      - .offset:         236
        .size:           4
        .value_kind:     hidden_block_count_y
      - .offset:         240
        .size:           4
        .value_kind:     hidden_block_count_z
      - .offset:         244
        .size:           2
        .value_kind:     hidden_group_size_x
      - .offset:         246
        .size:           2
        .value_kind:     hidden_group_size_y
      - .offset:         248
        .size:           2
        .value_kind:     hidden_group_size_z
      - .offset:         250
        .size:           2
        .value_kind:     hidden_remainder_x
      - .offset:         252
        .size:           2
        .value_kind:     hidden_remainder_y
      - .offset:         254
        .size:           2
        .value_kind:     hidden_remainder_z
      - .offset:         272
        .size:           8
        .value_kind:     hidden_global_offset_x
      - .offset:         280
        .size:           8
        .value_kind:     hidden_global_offset_y
      - .offset:         288
        .size:           8
        .value_kind:     hidden_global_offset_z
      - .offset:         296
        .size:           2
        .value_kind:     hidden_grid_dims
    .group_segment_fixed_size: 0
    .kernarg_segment_align: 8
    .kernarg_segment_size: 488
    .language:       OpenCL C
    .language_version:
      - 2
      - 0
    .max_flat_workgroup_size: 512
    .name:           _Z10fwd_kernelILi11ELi12EEv4Args
    .private_segment_fixed_size: 0
    .sgpr_count:     62
    .sgpr_spill_count: 0
    .symbol:         _Z10fwd_kernelILi11ELi12EEv4Args.kd
    .uniform_work_group_size: 1
    .uses_dynamic_stack: false
    .vgpr_count:     208
    .vgpr_spill_count: 0
    .wavefront_size: 64
  - .agpr_count:     0
    .args:
      - .offset:         0
        .size:           232
        .value_kind:     by_value
      - .offset:         232
        .size:           4
        .value_kind:     hidden_block_count_x
      - .offset:         236
        .size:           4
        .value_kind:     hidden_block_count_y
      - .offset:         240
        .size:           4
        .value_kind:     hidden_block_count_z
      - .offset:         244
        .size:           2
        .value_kind:     hidden_group_size_x
      - .offset:         246
        .size:           2
        .value_kind:     hidden_group_size_y
      - .offset:         248
        .size:           2
        .value_kind:     hidden_group_size_z
      - .offset:         250
        .size:           2
        .value_kind:     hidden_remainder_x
      - .offset:         252
        .size:           2
        .value_kind:     hidden_remainder_y
      - .offset:         254
        .size:           2
        .value_kind:     hidden_remainder_z
      - .offset:         272
        .size:           8
        .value_kind:     hidden_global_offset_x
      - .offset:         280
        .size:           8
        .value_kind:     hidden_global_offset_y
      - .offset:         288
        .size:           8
        .value_kind:     hidden_global_offset_z
      - .offset:         296
        .size:           2
        .value_kind:     hidden_grid_dims
      - .offset:         352
        .size:           4
        .value_kind:     hidden_dynamic_lds_size
    .group_segment_fixed_size: 0
    .kernarg_segment_align: 8
    .kernarg_segment_size: 488
    .language:       OpenCL C
    .language_version:
      - 2
      - 0
    .max_flat_workgroup_size: 512
    .name:           _Z10fwd_kernelILi12ELi13EEv4Args
    .private_segment_fixed_size: 0
    .sgpr_count:     68
    .sgpr_spill_count: 0
    .symbol:         _Z10fwd_kernelILi12ELi13EEv4Args.kd
    .uniform_work_group_size: 1
    .uses_dynamic_stack: false
    .vgpr_count:     224
    .vgpr_spill_count: 0
    .wavefront_size: 64
  - .agpr_count:     0
    .args:
      - .offset:         0
        .size:           232
        .value_kind:     by_value
      - .offset:         232
        .size:           4
        .value_kind:     hidden_block_count_x
      - .offset:         236
        .size:           4
        .value_kind:     hidden_block_count_y
      - .offset:         240
        .size:           4
        .value_kind:     hidden_block_count_z
      - .offset:         244
        .size:           2
        .value_kind:     hidden_group_size_x
      - .offset:         246
        .size:           2
        .value_kind:     hidden_group_size_y
      - .offset:         248
        .size:           2
        .value_kind:     hidden_group_size_z
      - .offset:         250
        .size:           2
        .value_kind:     hidden_remainder_x
      - .offset:         252
        .size:           2
        .value_kind:     hidden_remainder_y
      - .offset:         254
        .size:           2
        .value_kind:     hidden_remainder_z
      - .offset:         272
        .size:           8
        .value_kind:     hidden_global_offset_x
      - .offset:         280
        .size:           8
        .value_kind:     hidden_global_offset_y
      - .offset:         288
        .size:           8
        .value_kind:     hidden_global_offset_z
      - .offset:         296
        .size:           2
        .value_kind:     hidden_grid_dims
      - .offset:         352
        .size:           4
        .value_kind:     hidden_dynamic_lds_size
    .group_segment_fixed_size: 0
    .kernarg_segment_align: 8
    .kernarg_segment_size: 488
    .language:       OpenCL C
    .language_version:
      - 2
      - 0
    .max_flat_workgroup_size: 512
    .name:           _Z10fwd_kernelILi13ELi14EEv4Args
    .private_segment_fixed_size: 0
    .sgpr_count:     67
    .sgpr_spill_count: 0
    .symbol:         _Z10fwd_kernelILi13ELi14EEv4Args.kd
    .uniform_work_group_size: 1
    .uses_dynamic_stack: false
    .vgpr_count:     240
    .vgpr_spill_count: 0
    .wavefront_size: 64
  - .agpr_count:     0
    .args:
      - .offset:         0
        .size:           232
        .value_kind:     by_value
      - .offset:         232
        .size:           4
        .value_kind:     hidden_block_count_x
      - .offset:         236
        .size:           4
        .value_kind:     hidden_block_count_y
      - .offset:         240
        .size:           4
        .value_kind:     hidden_block_count_z
      - .offset:         244
        .size:           2
        .value_kind:     hidden_group_size_x
      - .offset:         246
        .size:           2
        .value_kind:     hidden_group_size_y
      - .offset:         248
        .size:           2
        .value_kind:     hidden_group_size_z
      - .offset:         250
        .size:           2
        .value_kind:     hidden_remainder_x
      - .offset:         252
        .size:           2
        .value_kind:     hidden_remainder_y
      - .offset:         254
        .size:           2
        .value_kind:     hidden_remainder_z
      - .offset:         272
        .size:           8
        .value_kind:     hidden_global_offset_x
      - .offset:         280
        .size:           8
        .value_kind:     hidden_global_offset_y
      - .offset:         288
        .size:           8
        .value_kind:     hidden_global_offset_z
      - .offset:         296
        .size:           2
        .value_kind:     hidden_grid_dims
    .group_segment_fixed_size: 0
    .kernarg_segment_align: 8
    .kernarg_segment_size: 488
    .language:       OpenCL C
    .language_version:
      - 2
      - 0
    .max_flat_workgroup_size: 512
    .name:           _Z10fwd_kernelILi14ELi15EEv4Args
    .private_segment_fixed_size: 0
    .sgpr_count:     62
    .sgpr_spill_count: 0
    .symbol:         _Z10fwd_kernelILi14ELi15EEv4Args.kd
    .uniform_work_group_size: 1
    .uses_dynamic_stack: false
    .vgpr_count:     208
    .vgpr_spill_count: 0
    .wavefront_size: 64
